# speedup vs baseline: 1.0589x; 1.0092x over previous
; #define P8_STAGE(P,BASE,br,kt) do{const bfr* _ub=(BASE)+((long)(br)*K+(long)(kt)*BK); \
;     __builtin_amdgcn_global_load_lds((const unsigned*)(_ub+so0),(unsigned*)((char*)(P)+wid*1024),16,0,0); \
;     __builtin_amdgcn_global_load_lds((const unsigned*)(_ub+so1),(unsigned*)((char*)(P)+wid*1024+8192),16,0,0);}while(0)
; #define P8_LDA(dst,b,h) _Pragma("unroll") for(int m=0;m<4;++m) _Pragma("unroll") for(int k=0;k<2;++k) \
;     dst[m][k]=*reinterpret_cast<const bf16x8*>((char*)P8_SA(b,h)+lds_byte(wr*64+m*16+fr,k*32+fq*8))
; #define P8_LDB(dst,b,h) _Pragma("unroll") for(int n=0;n<2;++n) _Pragma("unroll") for(int k=0;k<2;++k) \
;     dst[n][k]=*reinterpret_cast<const bf16x8*>((char*)P8_SB(b,h)+lds_byte(wc*32+n*16+fr,k*32+fq*8))
; #define P8_MMA(ai,bj,At,Bt) do{__builtin_amdgcn_s_setprio(1); \
;     _Pragma("unroll") for(int m=0;m<4;++m) _Pragma("unroll") for(int n=0;n<2;++n) _Pragma("unroll") for(int k=0;k<2;++k) \
;       acc[ai][bj][m][n]=__builtin_amdgcn_mfma_f32_16x16x32_bf16(At[m][k],Bt[n][k],acc[ai][bj][m][n],0,0,0); \
;     __builtin_amdgcn_s_setprio(0);}while(0)
; #define P8_WAIT_V(n) asm volatile("s_waitcnt vmcnt(" #n ")":::"memory")
; #define P8_WAIT_L(n) asm volatile("s_waitcnt lgkmcnt(" #n ")":::"memory")
; #define P8_BAR __builtin_amdgcn_s_barrier()
; #define P8_SCHED __builtin_amdgcn_sched_barrier(0)
; template <class EPI>
; DEVI void gemm8_tile(const bfr* __restrict__ A, const bfr* __restrict__ Bt, int K, int brow, int bcol, int nbrow, int nbcol, char* shmc, EPI epi) {
;     ...
;     P8_LDB(B0,0,0); P8_SCHED; P8_LDA(At,0,0); P8_STAGE(P8_SA(1,1),A,brow+128,t+1);
;     P8_WAIT_L(8); P8_BAR; P8_WAIT_L(0); P8_MMA(0,0,At,B0); P8_BAR; P8_SCHED;
;     P8_LDB(B1,0,1); P8_STAGE(P8_SB(0,0),Bt,bcol,t+2);
;     P8_BAR; P8_WAIT_L(0); P8_MMA(0,1,At,B1); P8_BAR;
;     P8_LDA(At,0,1); P8_STAGE(P8_SA(0,0),A,brow,t+2);
;     P8_BAR; P8_WAIT_L(0); P8_MMA(1,0,At,B0); P8_BAR; P8_SCHED;
;     P8_STAGE(P8_SB(0,1),Bt,bcol+128,t+2);
;     P8_WAIT_V(6); P8_BAR; P8_MMA(1,1,At,B1); P8_BAR;
.LBB0_66:
	ds_read_b128 v[174:177], v172
	ds_read_b128 v[178:181], v172 offset:1024
	ds_read_b128 v[182:185], v172 offset:2048
	ds_read_b128 v[186:189], v172 offset:3072
	v_add_u32_e32 v224, s54, v140
	s_add_i32 m0, s100, 0xc000
	ds_read_b128 v[190:193], v154
	ds_read_b128 v[196:199], v154 offset:1024
	ds_read_b128 v[200:203], v153
	ds_read_b128 v[204:207], v153 offset:1024
	ds_read_b128 v[208:211], v152
	ds_read_b128 v[212:215], v152 offset:1024
	ds_read_b128 v[216:219], v151
	ds_read_b128 v[220:223], v151 offset:1024
	global_load_lds_dwordx4 v224, s[86:87]
	v_add_u32_e32 v224, s54, v138
	s_add_i32 m0, s100, 0xe000
	s_nop 0
	global_load_lds_dwordx4 v224, s[86:87]
	s_waitcnt lgkmcnt(8)
	s_barrier
	s_waitcnt lgkmcnt(0)
	v_mfma_f32_16x16x32_bf16 v[124:127], v[190:193], v[174:177], v[124:127]
	v_mfma_f32_16x16x32_bf16 v[120:123], v[190:193], v[182:185], v[120:123]
	v_mfma_f32_16x16x32_bf16 v[116:119], v[200:203], v[174:177], v[116:119]
	v_mfma_f32_16x16x32_bf16 v[112:115], v[200:203], v[182:185], v[112:115]
	v_mfma_f32_16x16x32_bf16 v[108:111], v[208:211], v[174:177], v[108:111]
	v_mfma_f32_16x16x32_bf16 v[104:107], v[208:211], v[182:185], v[104:107]
	v_mfma_f32_16x16x32_bf16 v[100:103], v[216:219], v[174:177], v[100:103]
	v_mfma_f32_16x16x32_bf16 v[96:99], v[216:219], v[182:185], v[96:99]
	v_mfma_f32_16x16x32_bf16 v[124:127], v[196:199], v[178:181], v[124:127]
	v_mfma_f32_16x16x32_bf16 v[120:123], v[196:199], v[186:189], v[120:123]
	v_mfma_f32_16x16x32_bf16 v[116:119], v[204:207], v[178:181], v[116:119]
	v_mfma_f32_16x16x32_bf16 v[112:115], v[204:207], v[186:189], v[112:115]
	v_mfma_f32_16x16x32_bf16 v[108:111], v[212:215], v[178:181], v[108:111]
	v_mfma_f32_16x16x32_bf16 v[104:107], v[212:215], v[186:189], v[104:107]
	v_mfma_f32_16x16x32_bf16 v[100:103], v[220:223], v[178:181], v[100:103]
	v_mfma_f32_16x16x32_bf16 v[96:99], v[220:223], v[186:189], v[96:99]
	s_barrier
	v_add_u32_e32 v246, s66, v136
	s_add_i32 m0, s100, 0x10000
	ds_read_b128 v[224:227], v162
	ds_read_b128 v[228:231], v162 offset:1024
	ds_read_b128 v[232:235], v162 offset:2048
	ds_read_b128 v[236:239], v162 offset:3072
	global_load_lds_dwordx4 v246, s[86:87]
	v_add_u32_e32 v248, s66, v134
	s_add_i32 m0, s100, 0x12000
	s_nop 0
	global_load_lds_dwordx4 v248, s[86:87]
	s_barrier
	s_waitcnt lgkmcnt(0)
	v_mfma_f32_16x16x32_bf16 v[92:95], v[190:193], v[224:227], v[92:95]
	v_mfma_f32_16x16x32_bf16 v[88:91], v[190:193], v[232:235], v[88:91]
	v_mfma_f32_16x16x32_bf16 v[84:87], v[200:203], v[224:227], v[84:87]
	v_mfma_f32_16x16x32_bf16 v[80:83], v[200:203], v[232:235], v[80:83]
	v_mfma_f32_16x16x32_bf16 v[76:79], v[208:211], v[224:227], v[76:79]
	v_mfma_f32_16x16x32_bf16 v[72:75], v[208:211], v[232:235], v[72:75]
	v_mfma_f32_16x16x32_bf16 v[68:71], v[216:219], v[224:227], v[68:71]
	v_mfma_f32_16x16x32_bf16 v[64:67], v[216:219], v[232:235], v[64:67]
	v_mfma_f32_16x16x32_bf16 v[92:95], v[196:199], v[228:231], v[92:95]
	v_mfma_f32_16x16x32_bf16 v[88:91], v[196:199], v[236:239], v[88:91]
	v_mfma_f32_16x16x32_bf16 v[84:87], v[204:207], v[228:231], v[84:87]
	v_mfma_f32_16x16x32_bf16 v[80:83], v[204:207], v[236:239], v[80:83]
	v_mfma_f32_16x16x32_bf16 v[76:79], v[212:215], v[228:231], v[76:79]
	v_mfma_f32_16x16x32_bf16 v[72:75], v[212:215], v[236:239], v[72:75]
	v_mfma_f32_16x16x32_bf16 v[68:71], v[220:223], v[228:231], v[68:71]
	v_mfma_f32_16x16x32_bf16 v[64:67], v[220:223], v[236:239], v[64:67]
	v_add_u32_e32 v248, s60, v140
	s_mov_b32 m0, s100
	s_barrier
	ds_read_b128 v[190:193], v154 offset:16384
	ds_read_b128 v[196:199], v154 offset:17408
	ds_read_b128 v[200:203], v153 offset:16384
	ds_read_b128 v[204:207], v153 offset:17408
	ds_read_b128 v[208:211], v152 offset:16384
	ds_read_b128 v[212:215], v152 offset:17408
	ds_read_b128 v[216:219], v151 offset:16384
	ds_read_b128 v[220:223], v151 offset:17408
	global_load_lds_dwordx4 v248, s[86:87]
	v_add_u32_e32 v248, s60, v138
	s_add_i32 m0, s100, 0x2000
	s_nop 0
	global_load_lds_dwordx4 v248, s[86:87]
	s_barrier
	s_waitcnt lgkmcnt(0)
	v_mfma_f32_16x16x32_bf16 v[60:63], v[190:193], v[174:177], v[60:63]
	v_mfma_f32_16x16x32_bf16 v[56:59], v[190:193], v[182:185], v[56:59]
	v_mfma_f32_16x16x32_bf16 v[52:55], v[200:203], v[174:177], v[52:55]
	v_mfma_f32_16x16x32_bf16 v[48:51], v[200:203], v[182:185], v[48:51]
	v_mfma_f32_16x16x32_bf16 v[44:47], v[208:211], v[174:177], v[44:47]
	v_mfma_f32_16x16x32_bf16 v[40:43], v[208:211], v[182:185], v[40:43]
	v_mfma_f32_16x16x32_bf16 v[36:39], v[216:219], v[174:177], v[36:39]
	v_mfma_f32_16x16x32_bf16 v[32:35], v[216:219], v[182:185], v[32:35]
	v_mfma_f32_16x16x32_bf16 v[60:63], v[196:199], v[178:181], v[60:63]
	v_mfma_f32_16x16x32_bf16 v[56:59], v[196:199], v[186:189], v[56:59]
	v_mfma_f32_16x16x32_bf16 v[52:55], v[204:207], v[178:181], v[52:55]
	v_mfma_f32_16x16x32_bf16 v[48:51], v[204:207], v[186:189], v[48:51]
	v_mfma_f32_16x16x32_bf16 v[44:47], v[212:215], v[178:181], v[44:47]
	v_mfma_f32_16x16x32_bf16 v[40:43], v[212:215], v[186:189], v[40:43]
	v_mfma_f32_16x16x32_bf16 v[36:39], v[220:223], v[178:181], v[36:39]
	v_mfma_f32_16x16x32_bf16 v[32:35], v[220:223], v[186:189], v[32:35]
	s_barrier
	v_add_u32_e32 v174, s70, v136
	s_add_i32 m0, s100, 0x14000
	s_nop 0
	global_load_lds_dwordx4 v174, s[86:87]
	v_add_u32_e32 v174, s70, v134
	s_add_i32 m0, s100, 0x16000
	s_nop 0
	global_load_lds_dwordx4 v174, s[86:87]
	s_waitcnt vmcnt(6)
	s_barrier
; #define P8_STAGE(P,BASE,br,kt) do{const bfr* _ub=(BASE)+((long)(br)*K+(long)(kt)*BK); \
;     __builtin_amdgcn_global_load_lds((const unsigned*)(_ub+so0),(unsigned*)((char*)(P)+wid*1024),16,0,0); \
;     __builtin_amdgcn_global_load_lds((const unsigned*)(_ub+so1),(unsigned*)((char*)(P)+wid*1024+8192),16,0,0);}while(0)
; #define P8_LDA(dst,b,h) _Pragma("unroll") for(int m=0;m<4;++m) _Pragma("unroll") for(int k=0;k<2;++k) \
;     dst[m][k]=*reinterpret_cast<const bf16x8*>((char*)P8_SA(b,h)+lds_byte(wr*64+m*16+fr,k*32+fq*8))
; #define P8_LDB(dst,b,h) _Pragma("unroll") for(int n=0;n<2;++n) _Pragma("unroll") for(int k=0;k<2;++k) \
;     dst[n][k]=*reinterpret_cast<const bf16x8*>((char*)P8_SB(b,h)+lds_byte(wc*32+n*16+fr,k*32+fq*8))
; #define P8_MMA(ai,bj,At,Bt) do{__builtin_amdgcn_s_setprio(1); \
;     _Pragma("unroll") for(int m=0;m<4;++m) _Pragma("unroll") for(int n=0;n<2;++n) _Pragma("unroll") for(int k=0;k<2;++k) \
;       acc[ai][bj][m][n]=__builtin_amdgcn_mfma_f32_16x16x32_bf16(At[m][k],Bt[n][k],acc[ai][bj][m][n],0,0,0); \
;     __builtin_amdgcn_s_setprio(0);}while(0)
; #define P8_WAIT_V(n) asm volatile("s_waitcnt vmcnt(" #n ")":::"memory")
; #define P8_WAIT_L(n) asm volatile("s_waitcnt lgkmcnt(" #n ")":::"memory")
; #define P8_BAR __builtin_amdgcn_s_barrier()
; #define P8_SCHED __builtin_amdgcn_sched_barrier(0)
; template <class EPI>
; DEVI void gemm8_tile(const bfr* __restrict__ A, const bfr* __restrict__ Bt, int K, int brow, int bcol, int nbrow, int nbcol, char* shmc, EPI epi) {
;     ...
;     P8_WAIT_V(6); P8_BAR; P8_MMA(1,1,At,B1); P8_BAR;
;     P8_LDB(B0,1,0); P8_SCHED; P8_LDA(At,1,0); P8_STAGE(P8_SA(0,1),A,brow+128,t+2);
;     P8_WAIT_L(8); P8_BAR; P8_WAIT_L(0); P8_MMA(0,0,At,B0); P8_BAR; P8_SCHED;
;     P8_LDB(B1,1,1); P8_STAGE(P8_SB(1,0),Bt,bcol,t+3);
;     P8_BAR; P8_WAIT_L(0); P8_MMA(0,1,At,B1); P8_BAR;
;     P8_LDA(At,1,1); P8_STAGE(P8_SA(1,0),A,brow,t+3);
;     P8_BAR; P8_WAIT_L(0); P8_MMA(1,0,At,B0); P8_BAR; P8_SCHED;
	v_mfma_f32_16x16x32_bf16 v[28:31], v[190:193], v[224:227], v[28:31]
	v_mfma_f32_16x16x32_bf16 v[24:27], v[190:193], v[232:235], v[24:27]
	v_mfma_f32_16x16x32_bf16 v[20:23], v[200:203], v[224:227], v[20:23]
	v_mfma_f32_16x16x32_bf16 v[16:19], v[200:203], v[232:235], v[16:19]
	v_mfma_f32_16x16x32_bf16 v[12:15], v[208:211], v[224:227], v[12:15]
	v_mfma_f32_16x16x32_bf16 v[8:11], v[208:211], v[232:235], v[8:11]
	v_mfma_f32_16x16x32_bf16 v[4:7], v[216:219], v[224:227], v[4:7]
	v_mfma_f32_16x16x32_bf16 v[0:3], v[216:219], v[232:235], v[0:3]
	v_mfma_f32_16x16x32_bf16 v[28:31], v[196:199], v[228:231], v[28:31]
	v_mfma_f32_16x16x32_bf16 v[24:27], v[196:199], v[236:239], v[24:27]
	v_mfma_f32_16x16x32_bf16 v[20:23], v[204:207], v[228:231], v[20:23]
	v_mfma_f32_16x16x32_bf16 v[16:19], v[204:207], v[236:239], v[16:19]
	v_mfma_f32_16x16x32_bf16 v[12:15], v[212:215], v[228:231], v[12:15]
	v_mfma_f32_16x16x32_bf16 v[8:11], v[212:215], v[236:239], v[8:11]
	v_mfma_f32_16x16x32_bf16 v[4:7], v[220:223], v[228:231], v[4:7]
	v_mfma_f32_16x16x32_bf16 v[0:3], v[220:223], v[236:239], v[0:3]
	s_barrier
	ds_read_b128 v[174:177], v156
	ds_read_b128 v[178:181], v156 offset:1024
	ds_read_b128 v[182:185], v156 offset:2048
	ds_read_b128 v[186:189], v156 offset:3072
	v_add_u32_e32 v224, s72, v140
	s_add_i32 m0, s100, 0x4000
	ds_read_b128 v[190:193], v154 offset:32768
	ds_read_b128 v[196:199], v154 offset:33792
	ds_read_b128 v[200:203], v153 offset:32768
	ds_read_b128 v[204:207], v153 offset:33792
	ds_read_b128 v[208:211], v152 offset:32768
	ds_read_b128 v[212:215], v152 offset:33792
	ds_read_b128 v[216:219], v151 offset:32768
	ds_read_b128 v[220:223], v151 offset:33792
	global_load_lds_dwordx4 v224, s[86:87]
	v_add_u32_e32 v224, s72, v138
	s_add_i32 m0, s100, 0x6000
	s_nop 0
	global_load_lds_dwordx4 v224, s[86:87]
	s_waitcnt lgkmcnt(8)
	s_barrier
	s_waitcnt lgkmcnt(0)
	v_mfma_f32_16x16x32_bf16 v[124:127], v[190:193], v[174:177], v[124:127]
	v_mfma_f32_16x16x32_bf16 v[120:123], v[190:193], v[182:185], v[120:123]
	v_mfma_f32_16x16x32_bf16 v[116:119], v[200:203], v[174:177], v[116:119]
	v_mfma_f32_16x16x32_bf16 v[112:115], v[200:203], v[182:185], v[112:115]
	v_mfma_f32_16x16x32_bf16 v[108:111], v[208:211], v[174:177], v[108:111]
	v_mfma_f32_16x16x32_bf16 v[104:107], v[208:211], v[182:185], v[104:107]
	v_mfma_f32_16x16x32_bf16 v[100:103], v[216:219], v[174:177], v[100:103]
	v_mfma_f32_16x16x32_bf16 v[96:99], v[216:219], v[182:185], v[96:99]
	v_mfma_f32_16x16x32_bf16 v[124:127], v[196:199], v[178:181], v[124:127]
	v_mfma_f32_16x16x32_bf16 v[120:123], v[196:199], v[186:189], v[120:123]
	v_mfma_f32_16x16x32_bf16 v[116:119], v[204:207], v[178:181], v[116:119]
	v_mfma_f32_16x16x32_bf16 v[112:115], v[204:207], v[186:189], v[112:115]
	v_mfma_f32_16x16x32_bf16 v[108:111], v[212:215], v[178:181], v[108:111]
	v_mfma_f32_16x16x32_bf16 v[104:107], v[212:215], v[186:189], v[104:107]
	v_mfma_f32_16x16x32_bf16 v[100:103], v[220:223], v[178:181], v[100:103]
	v_mfma_f32_16x16x32_bf16 v[96:99], v[220:223], v[186:189], v[96:99]
	s_barrier
	v_add_u32_e32 v248, s74, v136
	s_add_i32 m0, s100, 0x18000
	ds_read_b128 v[224:227], v155
	ds_read_b128 v[228:231], v155 offset:1024
	ds_read_b128 v[232:235], v155 offset:2048
	ds_read_b128 v[236:239], v155 offset:3072
	global_load_lds_dwordx4 v248, s[86:87]
	v_add_u32_e32 v248, s74, v134
	s_add_i32 m0, s100, 0x1a000
	s_nop 0
	global_load_lds_dwordx4 v248, s[86:87]
	s_barrier
	s_waitcnt lgkmcnt(0)
	v_mfma_f32_16x16x32_bf16 v[92:95], v[190:193], v[224:227], v[92:95]
	v_mfma_f32_16x16x32_bf16 v[88:91], v[190:193], v[232:235], v[88:91]
	v_mfma_f32_16x16x32_bf16 v[84:87], v[200:203], v[224:227], v[84:87]
	v_mfma_f32_16x16x32_bf16 v[80:83], v[200:203], v[232:235], v[80:83]
	v_mfma_f32_16x16x32_bf16 v[76:79], v[208:211], v[224:227], v[76:79]
	v_mfma_f32_16x16x32_bf16 v[72:75], v[208:211], v[232:235], v[72:75]
	v_mfma_f32_16x16x32_bf16 v[68:71], v[216:219], v[224:227], v[68:71]
	v_mfma_f32_16x16x32_bf16 v[64:67], v[216:219], v[232:235], v[64:67]
	v_mfma_f32_16x16x32_bf16 v[92:95], v[196:199], v[228:231], v[92:95]
	v_mfma_f32_16x16x32_bf16 v[88:91], v[196:199], v[236:239], v[88:91]
	v_mfma_f32_16x16x32_bf16 v[84:87], v[204:207], v[228:231], v[84:87]
	v_mfma_f32_16x16x32_bf16 v[80:83], v[204:207], v[236:239], v[80:83]
	v_mfma_f32_16x16x32_bf16 v[76:79], v[212:215], v[228:231], v[76:79]
	v_mfma_f32_16x16x32_bf16 v[72:75], v[212:215], v[236:239], v[72:75]
	v_mfma_f32_16x16x32_bf16 v[68:71], v[220:223], v[228:231], v[68:71]
	v_mfma_f32_16x16x32_bf16 v[64:67], v[220:223], v[236:239], v[64:67]
	v_add_u32_e32 v240, s82, v140
	s_add_i32 m0, s100, 0x8000
	s_barrier
	ds_read_b128 v[190:193], v154 offset:49152
	ds_read_b128 v[196:199], v154 offset:50176
	ds_read_b128 v[200:203], v153 offset:49152
	ds_read_b128 v[204:207], v153 offset:50176
	ds_read_b128 v[208:211], v152 offset:49152
	ds_read_b128 v[212:215], v152 offset:50176
	ds_read_b128 v[216:219], v151 offset:49152
	ds_read_b128 v[220:223], v151 offset:50176
	global_load_lds_dwordx4 v240, s[86:87]
	v_add_u32_e32 v240, s82, v138
	s_add_i32 m0, s100, 0xa000
	s_nop 0
	global_load_lds_dwordx4 v240, s[86:87]
	s_barrier
; #define P8_STAGE(P,BASE,br,kt) do{const bfr* _ub=(BASE)+((long)(br)*K+(long)(kt)*BK); \
;     __builtin_amdgcn_global_load_lds((const unsigned*)(_ub+so0),(unsigned*)((char*)(P)+wid*1024),16,0,0); \
;     __builtin_amdgcn_global_load_lds((const unsigned*)(_ub+so1),(unsigned*)((char*)(P)+wid*1024+8192),16,0,0);}while(0)
; #define P8_LDA(dst,b,h) _Pragma("unroll") for(int m=0;m<4;++m) _Pragma("unroll") for(int k=0;k<2;++k) \
;     dst[m][k]=*reinterpret_cast<const bf16x8*>((char*)P8_SA(b,h)+lds_byte(wr*64+m*16+fr,k*32+fq*8))
; #define P8_LDB(dst,b,h) _Pragma("unroll") for(int n=0;n<2;++n) _Pragma("unroll") for(int k=0;k<2;++k) \
;     dst[n][k]=*reinterpret_cast<const bf16x8*>((char*)P8_SB(b,h)+lds_byte(wc*32+n*16+fr,k*32+fq*8))
; #define P8_MMA(ai,bj,At,Bt) do{__builtin_amdgcn_s_setprio(1); \
;     _Pragma("unroll") for(int m=0;m<4;++m) _Pragma("unroll") for(int n=0;n<2;++n) _Pragma("unroll") for(int k=0;k<2;++k) \
;       acc[ai][bj][m][n]=__builtin_amdgcn_mfma_f32_16x16x32_bf16(At[m][k],Bt[n][k],acc[ai][bj][m][n],0,0,0); \
;     __builtin_amdgcn_s_setprio(0);}while(0)
; #define P8_WAIT_V(n) asm volatile("s_waitcnt vmcnt(" #n ")":::"memory")
; #define P8_WAIT_L(n) asm volatile("s_waitcnt lgkmcnt(" #n ")":::"memory")
; #define P8_BAR __builtin_amdgcn_s_barrier()
; #define P8_SCHED __builtin_amdgcn_sched_barrier(0)
; template <class EPI>
; DEVI void gemm8_tile(const bfr* __restrict__ A, const bfr* __restrict__ Bt, int K, int brow, int bcol, int nbrow, int nbcol, char* shmc, EPI epi) {
;     ...
;     P8_BAR; P8_WAIT_L(0); P8_MMA(1,0,At,B0); P8_BAR; P8_SCHED;
;     P8_STAGE(P8_SB(1,1),Bt,bcol+128,t+3);
;     P8_WAIT_V(6); P8_BAR; P8_MMA(1,1,At,B1); P8_BAR;
;   }
;   { P8_LDB(B0,0,0); P8_LDA(At,0,0); P8_STAGE(P8_SA(1,1),A,brow+128,nt-1);
;     P8_BAR; P8_WAIT_L(0); P8_MMA(0,0,At,B0); P8_BAR;
;     P8_LDB(B1,0,1); P8_BAR; P8_WAIT_L(0); P8_MMA(0,1,At,B1); P8_BAR;
;     P8_LDA(At,0,1); P8_WAIT_V(4); P8_BAR; P8_WAIT_L(0); P8_MMA(1,0,At,B0); P8_MMA(1,1,At,B1); P8_BAR; }
	s_waitcnt lgkmcnt(0)
	v_mfma_f32_16x16x32_bf16 v[60:63], v[190:193], v[174:177], v[60:63]
	v_mfma_f32_16x16x32_bf16 v[56:59], v[190:193], v[182:185], v[56:59]
	v_mfma_f32_16x16x32_bf16 v[52:55], v[200:203], v[174:177], v[52:55]
	v_mfma_f32_16x16x32_bf16 v[48:51], v[200:203], v[182:185], v[48:51]
	v_mfma_f32_16x16x32_bf16 v[44:47], v[208:211], v[174:177], v[44:47]
	v_mfma_f32_16x16x32_bf16 v[40:43], v[208:211], v[182:185], v[40:43]
	v_mfma_f32_16x16x32_bf16 v[36:39], v[216:219], v[174:177], v[36:39]
	v_mfma_f32_16x16x32_bf16 v[32:35], v[216:219], v[182:185], v[32:35]
	v_mfma_f32_16x16x32_bf16 v[60:63], v[196:199], v[178:181], v[60:63]
	v_mfma_f32_16x16x32_bf16 v[56:59], v[196:199], v[186:189], v[56:59]
	v_mfma_f32_16x16x32_bf16 v[52:55], v[204:207], v[178:181], v[52:55]
	v_mfma_f32_16x16x32_bf16 v[48:51], v[204:207], v[186:189], v[48:51]
	v_mfma_f32_16x16x32_bf16 v[44:47], v[212:215], v[178:181], v[44:47]
	v_mfma_f32_16x16x32_bf16 v[40:43], v[212:215], v[186:189], v[40:43]
	v_mfma_f32_16x16x32_bf16 v[36:39], v[220:223], v[178:181], v[36:39]
	v_mfma_f32_16x16x32_bf16 v[32:35], v[220:223], v[186:189], v[32:35]
	s_barrier
	v_add_u32_e32 v174, s78, v136
	s_add_i32 m0, s100, 0x1c000
	s_nop 0
	global_load_lds_dwordx4 v174, s[86:87]
	v_add_u32_e32 v174, s78, v134
	s_add_i32 m0, s100, 0x1e000
	s_nop 0
	global_load_lds_dwordx4 v174, s[86:87]
	s_waitcnt vmcnt(6)
	s_barrier
	v_mfma_f32_16x16x32_bf16 v[28:31], v[190:193], v[224:227], v[28:31]
	v_mfma_f32_16x16x32_bf16 v[24:27], v[190:193], v[232:235], v[24:27]
	v_mfma_f32_16x16x32_bf16 v[20:23], v[200:203], v[224:227], v[20:23]
	v_mfma_f32_16x16x32_bf16 v[16:19], v[200:203], v[232:235], v[16:19]
	v_mfma_f32_16x16x32_bf16 v[12:15], v[208:211], v[224:227], v[12:15]
	v_mfma_f32_16x16x32_bf16 v[8:11], v[208:211], v[232:235], v[8:11]
	v_mfma_f32_16x16x32_bf16 v[4:7], v[216:219], v[224:227], v[4:7]
	v_mfma_f32_16x16x32_bf16 v[0:3], v[216:219], v[232:235], v[0:3]
	v_mfma_f32_16x16x32_bf16 v[28:31], v[196:199], v[228:231], v[28:31]
	v_mfma_f32_16x16x32_bf16 v[24:27], v[196:199], v[236:239], v[24:27]
	v_mfma_f32_16x16x32_bf16 v[20:23], v[204:207], v[228:231], v[20:23]
	v_mfma_f32_16x16x32_bf16 v[16:19], v[204:207], v[236:239], v[16:19]
	v_mfma_f32_16x16x32_bf16 v[12:15], v[212:215], v[228:231], v[12:15]
	v_mfma_f32_16x16x32_bf16 v[8:11], v[212:215], v[236:239], v[8:11]
	v_mfma_f32_16x16x32_bf16 v[4:7], v[220:223], v[228:231], v[4:7]
	v_mfma_f32_16x16x32_bf16 v[0:3], v[220:223], v[236:239], v[0:3]
	s_add_i32 s0, s0, 2
	v_lshl_add_u64 v[134:135], v[134:135], 0, s[80:81]
	v_lshl_add_u64 v[136:137], v[136:137], 0, s[80:81]
	v_lshl_add_u64 v[138:139], v[138:139], 0, s[80:81]
	s_cmp_lt_u32 s0, 28
	v_lshl_add_u64 v[140:141], v[140:141], 0, s[80:81]
	s_barrier
	s_cbranch_scc1 .LBB0_66
	s_or_b32 s0, s8, 0x80
	s_ashr_i32 s1, s0, 31
	s_lshl_b64 s[0:1], s[0:1], 12
	s_add_u32 s0, s28, s0
	s_addc_u32 s1, s29, s1
	v_lshl_add_u64 v[192:193], v[166:167], 1, s[0:1]
	s_mov_b64 s[54:55], 0xf80
	v_lshl_add_u64 v[192:193], v[192:193], 0, s[54:55]
	s_add_i32 m0, s100, 0xc000
	v_lshl_add_u64 v[132:133], v[132:133], 1, s[0:1]
	ds_read_b128 v[134:137], v172
	ds_read_b128 v[138:141], v172 offset:1024
	ds_read_b128 v[158:161], v172 offset:2048
	ds_read_b128 v[172:175], v172 offset:3072
	ds_read_b128 v[176:179], v154
	ds_read_b128 v[180:183], v154 offset:1024
	ds_read_b128 v[184:187], v153
	ds_read_b128 v[188:191], v153 offset:1024
	ds_read_b128 v[196:199], v152
	ds_read_b128 v[200:203], v152 offset:1024
	ds_read_b128 v[204:207], v151
	ds_read_b128 v[208:211], v151 offset:1024
	global_load_lds_dwordx4 v[192:193], off
	v_lshl_add_u64 v[132:133], v[132:133], 0, s[54:55]
	s_add_i32 m0, s100, 0xe000
	s_nop 0
	global_load_lds_dwordx4 v[132:133], off
	s_barrier
	s_waitcnt lgkmcnt(0)
	s_setprio 1
	s_waitcnt lgkmcnt(0)
	v_mfma_f32_16x16x32_bf16 v[124:127], v[176:179], v[134:137], v[124:127]
	v_mfma_f32_16x16x32_bf16 v[116:119], v[184:187], v[134:137], v[116:119]
	v_mfma_f32_16x16x32_bf16 v[112:115], v[184:187], v[158:161], v[112:115]
	v_mfma_f32_16x16x32_bf16 v[96:99], v[204:207], v[158:161], v[96:99]
	v_mfma_f32_16x16x32_bf16 v[124:127], v[180:183], v[138:141], v[124:127]
	v_mfma_f32_16x16x32_bf16 v[120:123], v[176:179], v[158:161], v[120:123]
	v_mfma_f32_16x16x32_bf16 v[116:119], v[188:191], v[138:141], v[116:119]
	v_mfma_f32_16x16x32_bf16 v[112:115], v[188:191], v[172:175], v[112:115]
	v_mfma_f32_16x16x32_bf16 v[108:111], v[196:199], v[134:137], v[108:111]
	v_mfma_f32_16x16x32_bf16 v[104:107], v[196:199], v[158:161], v[104:107]
	v_mfma_f32_16x16x32_bf16 v[100:103], v[204:207], v[134:137], v[100:103]
	v_mfma_f32_16x16x32_bf16 v[96:99], v[208:211], v[172:175], v[96:99]
	v_mfma_f32_16x16x32_bf16 v[212:215], v[180:183], v[172:175], v[120:123]
	v_mfma_f32_16x16x32_bf16 v[216:219], v[200:203], v[138:141], v[108:111]
	v_mfma_f32_16x16x32_bf16 v[220:223], v[200:203], v[172:175], v[104:107]
	v_mfma_f32_16x16x32_bf16 v[224:227], v[208:211], v[138:141], v[100:103]
	s_setprio 0
	s_barrier
	s_nop 0
	ds_read_b128 v[100:103], v162
	ds_read_b128 v[104:107], v162 offset:1024
	ds_read_b128 v[108:111], v162 offset:2048
	ds_read_b128 v[120:123], v162 offset:3072
	s_barrier
; #define P8_LDA(dst,b,h) _Pragma("unroll") for(int m=0;m<4;++m) _Pragma("unroll") for(int k=0;k<2;++k) \
;     dst[m][k]=*reinterpret_cast<const bf16x8*>((char*)P8_SA(b,h)+lds_byte(wr*64+m*16+fr,k*32+fq*8))
; #define P8_LDB(dst,b,h) _Pragma("unroll") for(int n=0;n<2;++n) _Pragma("unroll") for(int k=0;k<2;++k) \
;     dst[n][k]=*reinterpret_cast<const bf16x8*>((char*)P8_SB(b,h)+lds_byte(wc*32+n*16+fr,k*32+fq*8))
; #define P8_MMA(ai,bj,At,Bt) do{__builtin_amdgcn_s_setprio(1); \
;     _Pragma("unroll") for(int m=0;m<4;++m) _Pragma("unroll") for(int n=0;n<2;++n) _Pragma("unroll") for(int k=0;k<2;++k) \
;       acc[ai][bj][m][n]=__builtin_amdgcn_mfma_f32_16x16x32_bf16(At[m][k],Bt[n][k],acc[ai][bj][m][n],0,0,0); \
;     __builtin_amdgcn_s_setprio(0);}while(0)
; #define P8_WAIT_V(n) asm volatile("s_waitcnt vmcnt(" #n ")":::"memory")
; #define P8_WAIT_L(n) asm volatile("s_waitcnt lgkmcnt(" #n ")":::"memory")
; #define P8_BAR __builtin_amdgcn_s_barrier()
; template <class EPI>
; DEVI void gemm8_tile(const bfr* __restrict__ A, const bfr* __restrict__ Bt, int K, int brow, int bcol, int nbrow, int nbcol, char* shmc, EPI epi) {
;     ...
;     P8_LDB(B1,0,1); P8_BAR; P8_WAIT_L(0); P8_MMA(0,1,At,B1); P8_BAR;
;     P8_LDA(At,0,1); P8_WAIT_V(4); P8_BAR; P8_WAIT_L(0); P8_MMA(1,0,At,B0); P8_MMA(1,1,At,B1); P8_BAR; }
;   { P8_LDB(B0,1,0); P8_LDA(At,1,0); P8_WAIT_V(2); P8_BAR; P8_WAIT_L(0); P8_MMA(0,0,At,B0); P8_BAR;
	s_waitcnt lgkmcnt(0)
	s_setprio 1
	s_waitcnt lgkmcnt(0)
	v_mfma_f32_16x16x32_bf16 v[92:95], v[176:179], v[100:103], v[92:95]
	v_mfma_f32_16x16x32_bf16 v[84:87], v[184:187], v[100:103], v[84:87]
	v_mfma_f32_16x16x32_bf16 v[80:83], v[184:187], v[108:111], v[80:83]
	v_mfma_f32_16x16x32_bf16 v[64:67], v[204:207], v[108:111], v[64:67]
	v_mfma_f32_16x16x32_bf16 v[92:95], v[180:183], v[104:107], v[92:95]
	v_mfma_f32_16x16x32_bf16 v[88:91], v[176:179], v[108:111], v[88:91]
	v_mfma_f32_16x16x32_bf16 v[84:87], v[188:191], v[104:107], v[84:87]
	v_mfma_f32_16x16x32_bf16 v[80:83], v[188:191], v[120:123], v[80:83]
	v_mfma_f32_16x16x32_bf16 v[76:79], v[196:199], v[100:103], v[76:79]
	v_mfma_f32_16x16x32_bf16 v[72:75], v[196:199], v[108:111], v[72:75]
	v_mfma_f32_16x16x32_bf16 v[68:71], v[204:207], v[100:103], v[68:71]
	v_mfma_f32_16x16x32_bf16 v[64:67], v[208:211], v[120:123], v[64:67]
	v_mfma_f32_16x16x32_bf16 v[176:179], v[180:183], v[120:123], v[88:91]
	v_mfma_f32_16x16x32_bf16 v[180:183], v[200:203], v[104:107], v[76:79]
	v_mfma_f32_16x16x32_bf16 v[184:187], v[200:203], v[120:123], v[72:75]
	v_mfma_f32_16x16x32_bf16 v[188:191], v[208:211], v[104:107], v[68:71]
	s_setprio 0
	s_barrier
	s_nop 0
	ds_read_b128 v[68:71], v154 offset:16384
	ds_read_b128 v[72:75], v154 offset:17408
	ds_read_b128 v[76:79], v153 offset:16384
	ds_read_b128 v[88:91], v153 offset:17408
	ds_read_b128 v[196:199], v152 offset:16384
	ds_read_b128 v[200:203], v152 offset:17408
	ds_read_b128 v[204:207], v151 offset:16384
	ds_read_b128 v[208:211], v151 offset:17408
	s_waitcnt vmcnt(4)
	s_barrier
	s_waitcnt lgkmcnt(0)
	s_setprio 1
	s_waitcnt lgkmcnt(0)
	v_mfma_f32_16x16x32_bf16 v[60:63], v[68:71], v[134:137], v[60:63]
	v_mfma_f32_16x16x32_bf16 v[52:55], v[76:79], v[134:137], v[52:55]
	v_mfma_f32_16x16x32_bf16 v[48:51], v[76:79], v[158:161], v[48:51]
	v_mfma_f32_16x16x32_bf16 v[32:35], v[204:207], v[158:161], v[32:35]
	v_mfma_f32_16x16x32_bf16 v[60:63], v[72:75], v[138:141], v[60:63]
	v_mfma_f32_16x16x32_bf16 v[56:59], v[68:71], v[158:161], v[56:59]
	v_mfma_f32_16x16x32_bf16 v[52:55], v[88:91], v[138:141], v[52:55]
	v_mfma_f32_16x16x32_bf16 v[48:51], v[88:91], v[172:175], v[48:51]
	v_mfma_f32_16x16x32_bf16 v[44:47], v[196:199], v[134:137], v[44:47]
	v_mfma_f32_16x16x32_bf16 v[40:43], v[196:199], v[158:161], v[40:43]
	v_mfma_f32_16x16x32_bf16 v[36:39], v[204:207], v[134:137], v[36:39]
	v_mfma_f32_16x16x32_bf16 v[32:35], v[208:211], v[172:175], v[32:35]
	v_mfma_f32_16x16x32_bf16 v[228:231], v[72:75], v[172:175], v[56:59]
	v_mfma_f32_16x16x32_bf16 v[232:235], v[200:203], v[138:141], v[44:47]
	v_mfma_f32_16x16x32_bf16 v[236:239], v[200:203], v[172:175], v[40:43]
	v_mfma_f32_16x16x32_bf16 v[132:135], v[208:211], v[138:141], v[36:39]
	s_setprio 0
	s_setprio 1
	v_mfma_f32_16x16x32_bf16 v[28:31], v[68:71], v[100:103], v[28:31]
	v_mfma_f32_16x16x32_bf16 v[20:23], v[76:79], v[100:103], v[20:23]
	v_mfma_f32_16x16x32_bf16 v[16:19], v[76:79], v[108:111], v[16:19]
	v_mfma_f32_16x16x32_bf16 v[0:3], v[204:207], v[108:111], v[0:3]
	v_mfma_f32_16x16x32_bf16 v[28:31], v[72:75], v[104:107], v[28:31]
	v_mfma_f32_16x16x32_bf16 v[24:27], v[68:71], v[108:111], v[24:27]
	v_mfma_f32_16x16x32_bf16 v[20:23], v[88:91], v[104:107], v[20:23]
	v_mfma_f32_16x16x32_bf16 v[16:19], v[88:91], v[120:123], v[16:19]
	v_mfma_f32_16x16x32_bf16 v[12:15], v[196:199], v[100:103], v[12:15]
	v_mfma_f32_16x16x32_bf16 v[8:11], v[196:199], v[108:111], v[8:11]
	v_mfma_f32_16x16x32_bf16 v[4:7], v[204:207], v[100:103], v[4:7]
	v_mfma_f32_16x16x32_bf16 v[0:3], v[208:211], v[120:123], v[0:3]
	v_mfma_f32_16x16x32_bf16 v[136:139], v[72:75], v[120:123], v[24:27]
	v_mfma_f32_16x16x32_bf16 v[158:161], v[200:203], v[104:107], v[12:15]
	v_mfma_f32_16x16x32_bf16 v[170:173], v[200:203], v[120:123], v[8:11]
	v_mfma_f32_16x16x32_bf16 v[196:199], v[208:211], v[104:107], v[4:7]
	s_setprio 0
	s_barrier
	s_nop 0
	ds_read_b128 v[4:7], v156
	ds_read_b128 v[8:11], v156 offset:1024
	ds_read_b128 v[12:15], v156 offset:2048
	ds_read_b128 v[24:27], v156 offset:3072
	ds_read_b128 v[36:39], v154 offset:32768
	ds_read_b128 v[40:43], v154 offset:33792
	ds_read_b128 v[44:47], v153 offset:32768
	ds_read_b128 v[56:59], v153 offset:33792
	ds_read_b128 v[68:71], v152 offset:32768
	ds_read_b128 v[200:203], v152 offset:33792
	ds_read_b128 v[204:207], v151 offset:32768
	ds_read_b128 v[208:211], v151 offset:33792
	s_waitcnt vmcnt(2)
	s_barrier
; #define P8_LDA(dst,b,h) _Pragma("unroll") for(int m=0;m<4;++m) _Pragma("unroll") for(int k=0;k<2;++k) \
;     dst[m][k]=*reinterpret_cast<const bf16x8*>((char*)P8_SA(b,h)+lds_byte(wr*64+m*16+fr,k*32+fq*8))
; #define P8_LDB(dst,b,h) _Pragma("unroll") for(int n=0;n<2;++n) _Pragma("unroll") for(int k=0;k<2;++k) \
;     dst[n][k]=*reinterpret_cast<const bf16x8*>((char*)P8_SB(b,h)+lds_byte(wc*32+n*16+fr,k*32+fq*8))
; #define P8_MMA(ai,bj,At,Bt) do{__builtin_amdgcn_s_setprio(1); \
;     _Pragma("unroll") for(int m=0;m<4;++m) _Pragma("unroll") for(int n=0;n<2;++n) _Pragma("unroll") for(int k=0;k<2;++k) \
;       acc[ai][bj][m][n]=__builtin_amdgcn_mfma_f32_16x16x32_bf16(At[m][k],Bt[n][k],acc[ai][bj][m][n],0,0,0); \
;     __builtin_amdgcn_s_setprio(0);}while(0)
; #define P8_WAIT_V(n) asm volatile("s_waitcnt vmcnt(" #n ")":::"memory")
; #define P8_WAIT_L(n) asm volatile("s_waitcnt lgkmcnt(" #n ")":::"memory")
; #define P8_BAR __builtin_amdgcn_s_barrier()
; template <class EPI>
; DEVI void gemm8_tile(const bfr* __restrict__ A, const bfr* __restrict__ Bt, int K, int brow, int bcol, int nbrow, int nbcol, char* shmc, EPI epi) {
;     ...
;   { P8_LDB(B0,1,0); P8_LDA(At,1,0); P8_WAIT_V(2); P8_BAR; P8_WAIT_L(0); P8_MMA(0,0,At,B0); P8_BAR;
;     P8_LDB(B1,1,1); P8_WAIT_V(0); P8_BAR; P8_WAIT_L(0); P8_MMA(0,1,At,B1); P8_BAR;
;     P8_LDA(At,1,1); P8_BAR; P8_WAIT_L(0); P8_MMA(1,0,At,B0); P8_MMA(1,1,At,B1); P8_BAR; }
;   if(wr==0)P8_BAR;
	s_waitcnt lgkmcnt(0)
	s_setprio 1
	s_waitcnt lgkmcnt(0)
	v_mfma_f32_16x16x32_bf16 v[72:75], v[36:39], v[4:7], v[124:127]
	v_mfma_f32_16x16x32_bf16 v[120:123], v[40:43], v[8:11], v[72:75]
	v_mfma_f32_16x16x32_bf16 v[72:75], v[36:39], v[12:15], v[212:215]
	v_mfma_f32_16x16x32_bf16 v[104:107], v[40:43], v[24:27], v[72:75]
	v_mfma_f32_16x16x32_bf16 v[72:75], v[44:47], v[4:7], v[116:119]
	v_mfma_f32_16x16x32_bf16 v[124:127], v[56:59], v[8:11], v[72:75]
	v_mfma_f32_16x16x32_bf16 v[72:75], v[44:47], v[12:15], v[112:115]
	v_mfma_f32_16x16x32_bf16 v[108:111], v[56:59], v[24:27], v[72:75]
	v_mfma_f32_16x16x32_bf16 v[72:75], v[68:71], v[4:7], v[216:219]
	v_mfma_f32_16x16x32_bf16 v[112:115], v[200:203], v[8:11], v[72:75]
	v_mfma_f32_16x16x32_bf16 v[72:75], v[68:71], v[12:15], v[220:223]
	v_mfma_f32_16x16x32_bf16 v[100:103], v[200:203], v[24:27], v[72:75]
	v_mfma_f32_16x16x32_bf16 v[72:75], v[204:207], v[4:7], v[224:227]
	v_mfma_f32_16x16x32_bf16 v[116:119], v[208:211], v[8:11], v[72:75]
	v_mfma_f32_16x16x32_bf16 v[72:75], v[204:207], v[12:15], v[96:99]
	v_mfma_f32_16x16x32_bf16 v[96:99], v[208:211], v[24:27], v[72:75]
	s_setprio 0
	s_barrier
	ds_read_b128 v[212:215], v155
	ds_read_b128 v[216:219], v155 offset:1024
	ds_read_b128 v[220:223], v155 offset:2048
	ds_read_b128 v[224:227], v155 offset:3072
	s_waitcnt vmcnt(0)
	s_barrier
	s_waitcnt lgkmcnt(0)
	s_setprio 1
	s_waitcnt lgkmcnt(0)
	v_mfma_f32_16x16x32_bf16 v[72:75], v[36:39], v[212:215], v[92:95]
	v_mfma_f32_16x16x32_bf16 v[36:39], v[36:39], v[220:223], v[176:179]
	v_mfma_f32_16x16x32_bf16 v[88:91], v[40:43], v[216:219], v[72:75]
	v_mfma_f32_16x16x32_bf16 v[72:75], v[40:43], v[224:227], v[36:39]
	v_mfma_f32_16x16x32_bf16 v[36:39], v[44:47], v[212:215], v[84:87]
	v_mfma_f32_16x16x32_bf16 v[92:95], v[56:59], v[216:219], v[36:39]
	v_mfma_f32_16x16x32_bf16 v[36:39], v[44:47], v[220:223], v[80:83]
	v_mfma_f32_16x16x32_bf16 v[76:79], v[56:59], v[224:227], v[36:39]
	v_mfma_f32_16x16x32_bf16 v[36:39], v[68:71], v[212:215], v[180:183]
	v_mfma_f32_16x16x32_bf16 v[80:83], v[200:203], v[216:219], v[36:39]
	v_mfma_f32_16x16x32_bf16 v[36:39], v[68:71], v[220:223], v[184:187]
	v_mfma_f32_16x16x32_bf16 v[68:71], v[200:203], v[224:227], v[36:39]
	v_mfma_f32_16x16x32_bf16 v[36:39], v[204:207], v[212:215], v[188:191]
	v_mfma_f32_16x16x32_bf16 v[84:87], v[208:211], v[216:219], v[36:39]
	v_mfma_f32_16x16x32_bf16 v[36:39], v[204:207], v[220:223], v[64:67]
	v_mfma_f32_16x16x32_bf16 v[64:67], v[208:211], v[224:227], v[36:39]
	s_setprio 0
	s_barrier
	ds_read_b128 v[174:177], v154 offset:49152
	ds_read_b128 v[154:157], v154 offset:50176
	ds_read_b128 v[178:181], v153 offset:49152
	ds_read_b128 v[182:185], v153 offset:50176
	ds_read_b128 v[186:189], v152 offset:49152
	ds_read_b128 v[190:193], v152 offset:50176
	ds_read_b128 v[200:203], v151 offset:49152
	ds_read_b128 v[204:207], v151 offset:50176
	s_barrier
	s_waitcnt lgkmcnt(0)
	s_setprio 1
	s_waitcnt lgkmcnt(0)
	v_mfma_f32_16x16x32_bf16 v[36:39], v[174:177], v[4:7], v[60:63]
	v_mfma_f32_16x16x32_bf16 v[56:59], v[154:157], v[8:11], v[36:39]
	v_mfma_f32_16x16x32_bf16 v[36:39], v[174:177], v[12:15], v[228:231]
	v_mfma_f32_16x16x32_bf16 v[40:43], v[154:157], v[24:27], v[36:39]
	v_mfma_f32_16x16x32_bf16 v[36:39], v[178:181], v[4:7], v[52:55]
	v_mfma_f32_16x16x32_bf16 v[60:63], v[182:185], v[8:11], v[36:39]
	v_mfma_f32_16x16x32_bf16 v[36:39], v[178:181], v[12:15], v[48:51]
	v_mfma_f32_16x16x32_bf16 v[44:47], v[182:185], v[24:27], v[36:39]
	v_mfma_f32_16x16x32_bf16 v[36:39], v[186:189], v[4:7], v[232:235]
	v_mfma_f32_16x16x32_bf16 v[4:7], v[200:203], v[4:7], v[132:135]
	v_mfma_f32_16x16x32_bf16 v[48:51], v[190:193], v[8:11], v[36:39]
	v_mfma_f32_16x16x32_bf16 v[36:39], v[186:189], v[12:15], v[236:239]
	v_mfma_f32_16x16x32_bf16 v[52:55], v[204:207], v[8:11], v[4:7]
	v_mfma_f32_16x16x32_bf16 v[4:7], v[200:203], v[12:15], v[32:35]
	v_mfma_f32_16x16x32_bf16 v[36:39], v[190:193], v[24:27], v[36:39]
	v_mfma_f32_16x16x32_bf16 v[32:35], v[204:207], v[24:27], v[4:7]
	s_setprio 0
	s_setprio 1
	v_mfma_f32_16x16x32_bf16 v[4:7], v[174:177], v[212:215], v[28:31]
	v_mfma_f32_16x16x32_bf16 v[24:27], v[154:157], v[216:219], v[4:7]
	v_mfma_f32_16x16x32_bf16 v[4:7], v[174:177], v[220:223], v[136:139]
	v_mfma_f32_16x16x32_bf16 v[8:11], v[154:157], v[224:227], v[4:7]
	v_mfma_f32_16x16x32_bf16 v[4:7], v[178:181], v[212:215], v[20:23]
	v_mfma_f32_16x16x32_bf16 v[28:31], v[182:185], v[216:219], v[4:7]
	v_mfma_f32_16x16x32_bf16 v[4:7], v[178:181], v[220:223], v[16:19]
	v_mfma_f32_16x16x32_bf16 v[12:15], v[182:185], v[224:227], v[4:7]
	v_mfma_f32_16x16x32_bf16 v[4:7], v[186:189], v[212:215], v[158:161]
	v_mfma_f32_16x16x32_bf16 v[16:19], v[190:193], v[216:219], v[4:7]
	v_mfma_f32_16x16x32_bf16 v[4:7], v[186:189], v[220:223], v[170:173]
	v_mfma_f32_16x16x32_bf16 v[20:23], v[200:203], v[212:215], v[196:199]
	v_mfma_f32_16x16x32_bf16 v[0:3], v[200:203], v[220:223], v[0:3]
	v_mfma_f32_16x16x32_bf16 v[4:7], v[190:193], v[224:227], v[4:7]
	v_mfma_f32_16x16x32_bf16 v[20:23], v[204:207], v[216:219], v[20:23]
	v_mfma_f32_16x16x32_bf16 v[0:3], v[204:207], v[224:227], v[0:3]
	s_setprio 0
	v_cmp_gt_u32_e32 vcc, s57, v142
	s_barrier
	s_and_saveexec_b64 s[0:1], vcc
	s_cbranch_execz .LBB0_69
	s_barrier

; #define P8_STAGE(P,BASE,br,kt) do{const bfr* _ub=(BASE)+((long)(br)*K+(long)(kt)*BK); \
;     __builtin_amdgcn_global_load_lds((const unsigned*)(_ub+so0),(unsigned*)((char*)(P)+wid*1024),16,0,0); \
;     __builtin_amdgcn_global_load_lds((const unsigned*)(_ub+so1),(unsigned*)((char*)(P)+wid*1024+8192),16,0,0);}while(0)
; #define P8_LDA(dst,b,h) _Pragma("unroll") for(int m=0;m<4;++m) _Pragma("unroll") for(int k=0;k<2;++k) \
;     dst[m][k]=*reinterpret_cast<const bf16x8*>((char*)P8_SA(b,h)+lds_byte(wr*64+m*16+fr,k*32+fq*8))
; #define P8_LDB(dst,b,h) _Pragma("unroll") for(int n=0;n<2;++n) _Pragma("unroll") for(int k=0;k<2;++k) \
;     dst[n][k]=*reinterpret_cast<const bf16x8*>((char*)P8_SB(b,h)+lds_byte(wc*32+n*16+fr,k*32+fq*8))
; #define P8_MMA(ai,bj,At,Bt) do{__builtin_amdgcn_s_setprio(1); \
;     _Pragma("unroll") for(int m=0;m<4;++m) _Pragma("unroll") for(int n=0;n<2;++n) _Pragma("unroll") for(int k=0;k<2;++k) \
;       acc[ai][bj][m][n]=__builtin_amdgcn_mfma_f32_16x16x32_bf16(At[m][k],Bt[n][k],acc[ai][bj][m][n],0,0,0); \
;     __builtin_amdgcn_s_setprio(0);}while(0)
; #define P8_WAIT_V(n) asm volatile("s_waitcnt vmcnt(" #n ")":::"memory")
; #define P8_WAIT_L(n) asm volatile("s_waitcnt lgkmcnt(" #n ")":::"memory")
; #define P8_BAR __builtin_amdgcn_s_barrier()
; #define P8_SCHED __builtin_amdgcn_sched_barrier(0)
; template <class EPI>
; DEVI void gemm8_tile(const bfr* __restrict__ A, const bfr* __restrict__ Bt, int K, int brow, int bcol, int nbrow, int nbcol, char* shmc, EPI epi) {
;     ...
;     P8_LDB(B0,0,0); P8_SCHED; P8_LDA(At,0,0); P8_STAGE(P8_SA(1,1),A,brow+128,t+1);
;     P8_WAIT_L(8); P8_BAR; P8_WAIT_L(0); P8_MMA(0,0,At,B0); P8_BAR; P8_SCHED;
;     P8_LDB(B1,0,1); P8_STAGE(P8_SB(0,0),Bt,bcol,t+2);
;     P8_BAR; P8_WAIT_L(0); P8_MMA(0,1,At,B1); P8_BAR;
;     P8_LDA(At,0,1); P8_STAGE(P8_SA(0,0),A,brow,t+2);
;     P8_BAR; P8_WAIT_L(0); P8_MMA(1,0,At,B0); P8_BAR; P8_SCHED;
;     P8_STAGE(P8_SB(0,1),Bt,bcol+128,t+2);
;     P8_WAIT_V(6); P8_BAR; P8_MMA(1,1,At,B1); P8_BAR;
.LBB0_85:
	ds_read_b128 v[174:177], v157
	ds_read_b128 v[178:181], v157 offset:1024
	ds_read_b128 v[182:185], v157 offset:2048
	ds_read_b128 v[186:189], v157 offset:3072
	v_add_u32_e32 v171, 0xc000, v143
	v_add_u32_e32 v172, 0xe000, v143
	v_add_u32_e32 v158, s54, v140
	s_add_i32 m0, s100, 0xc000
	ds_read_b128 v[160:163], v147
	ds_read_b128 v[190:193], v147 offset:1024
	ds_read_b128 v[196:199], v146
	ds_read_b128 v[200:203], v146 offset:1024
	ds_read_b128 v[204:207], v145
	ds_read_b128 v[208:211], v145 offset:1024
	ds_read_b128 v[212:215], v144
	ds_read_b128 v[216:219], v144 offset:1024
	global_load_lds_dwordx4 v158, s[86:87]
	v_add_u32_e32 v158, s54, v138
	s_add_i32 m0, s100, 0xe000
	s_nop 0
	global_load_lds_dwordx4 v158, s[86:87]
	s_waitcnt lgkmcnt(8)
	s_barrier
	s_waitcnt lgkmcnt(0)
	v_mfma_f32_16x16x32_bf16 v[124:127], v[160:163], v[174:177], v[124:127]
	v_mfma_f32_16x16x32_bf16 v[120:123], v[160:163], v[182:185], v[120:123]
	v_mfma_f32_16x16x32_bf16 v[116:119], v[196:199], v[174:177], v[116:119]
	v_mfma_f32_16x16x32_bf16 v[112:115], v[196:199], v[182:185], v[112:115]
	v_mfma_f32_16x16x32_bf16 v[108:111], v[204:207], v[174:177], v[108:111]
	v_mfma_f32_16x16x32_bf16 v[104:107], v[204:207], v[182:185], v[104:107]
	v_mfma_f32_16x16x32_bf16 v[100:103], v[212:215], v[174:177], v[100:103]
	v_mfma_f32_16x16x32_bf16 v[96:99], v[212:215], v[182:185], v[96:99]
	v_mfma_f32_16x16x32_bf16 v[124:127], v[190:193], v[178:181], v[124:127]
	v_mfma_f32_16x16x32_bf16 v[120:123], v[190:193], v[186:189], v[120:123]
	v_mfma_f32_16x16x32_bf16 v[116:119], v[200:203], v[178:181], v[116:119]
	v_mfma_f32_16x16x32_bf16 v[112:115], v[200:203], v[186:189], v[112:115]
	v_mfma_f32_16x16x32_bf16 v[108:111], v[208:211], v[178:181], v[108:111]
	v_mfma_f32_16x16x32_bf16 v[104:107], v[208:211], v[186:189], v[104:107]
	v_mfma_f32_16x16x32_bf16 v[100:103], v[216:219], v[178:181], v[100:103]
	v_mfma_f32_16x16x32_bf16 v[96:99], v[216:219], v[186:189], v[96:99]
	s_barrier
	v_add_u32_e32 v158, 0x10000, v143
	v_add_u32_e32 v159, 0x12000, v143
	v_add_u32_e32 v236, s66, v136
	s_add_i32 m0, s100, 0x10000
	ds_read_b128 v[220:223], v155
	ds_read_b128 v[224:227], v155 offset:1024
	ds_read_b128 v[228:231], v155 offset:2048
	ds_read_b128 v[232:235], v155 offset:3072
	global_load_lds_dwordx4 v236, s[86:87]
	v_add_u32_e32 v236, s66, v134
	s_add_i32 m0, s100, 0x12000
	s_nop 0
	global_load_lds_dwordx4 v236, s[86:87]
	s_barrier
	s_waitcnt lgkmcnt(0)
	v_mfma_f32_16x16x32_bf16 v[92:95], v[160:163], v[220:223], v[92:95]
	v_mfma_f32_16x16x32_bf16 v[88:91], v[160:163], v[228:231], v[88:91]
	v_mfma_f32_16x16x32_bf16 v[84:87], v[196:199], v[220:223], v[84:87]
	v_mfma_f32_16x16x32_bf16 v[80:83], v[196:199], v[228:231], v[80:83]
	v_mfma_f32_16x16x32_bf16 v[76:79], v[204:207], v[220:223], v[76:79]
	v_mfma_f32_16x16x32_bf16 v[72:75], v[204:207], v[228:231], v[72:75]
	v_mfma_f32_16x16x32_bf16 v[68:71], v[212:215], v[220:223], v[68:71]
	v_mfma_f32_16x16x32_bf16 v[64:67], v[212:215], v[228:231], v[64:67]
	v_mfma_f32_16x16x32_bf16 v[92:95], v[190:193], v[224:227], v[92:95]
	v_mfma_f32_16x16x32_bf16 v[88:91], v[190:193], v[232:235], v[88:91]
	v_mfma_f32_16x16x32_bf16 v[84:87], v[200:203], v[224:227], v[84:87]
	v_mfma_f32_16x16x32_bf16 v[80:83], v[200:203], v[232:235], v[80:83]
	v_mfma_f32_16x16x32_bf16 v[76:79], v[208:211], v[224:227], v[76:79]
	v_mfma_f32_16x16x32_bf16 v[72:75], v[208:211], v[232:235], v[72:75]
	v_mfma_f32_16x16x32_bf16 v[68:71], v[216:219], v[224:227], v[68:71]
	v_mfma_f32_16x16x32_bf16 v[64:67], v[216:219], v[232:235], v[64:67]
	v_add_u32_e32 v160, s60, v140
	s_mov_b32 m0, s100
	s_barrier
	ds_read_b128 v[190:193], v147 offset:16384
	ds_read_b128 v[196:199], v147 offset:17408
	ds_read_b128 v[200:203], v146 offset:16384
	ds_read_b128 v[204:207], v146 offset:17408
	ds_read_b128 v[208:211], v145 offset:16384
	ds_read_b128 v[212:215], v145 offset:17408
	ds_read_b128 v[216:219], v144 offset:16384
	ds_read_b128 v[236:239], v144 offset:17408
	global_load_lds_dwordx4 v160, s[86:87]
	v_add_u32_e32 v160, 0x2000, v143
	v_add_u32_e32 v162, s60, v138
	s_add_i32 m0, s100, 0x2000
	s_nop 0
	global_load_lds_dwordx4 v162, s[86:87]
	s_barrier
	s_waitcnt lgkmcnt(0)
	v_mfma_f32_16x16x32_bf16 v[60:63], v[190:193], v[174:177], v[60:63]
	v_mfma_f32_16x16x32_bf16 v[56:59], v[190:193], v[182:185], v[56:59]
	v_mfma_f32_16x16x32_bf16 v[52:55], v[200:203], v[174:177], v[52:55]
	v_mfma_f32_16x16x32_bf16 v[48:51], v[200:203], v[182:185], v[48:51]
	v_mfma_f32_16x16x32_bf16 v[44:47], v[208:211], v[174:177], v[44:47]
	v_mfma_f32_16x16x32_bf16 v[40:43], v[208:211], v[182:185], v[40:43]
	v_mfma_f32_16x16x32_bf16 v[36:39], v[216:219], v[174:177], v[36:39]
	v_mfma_f32_16x16x32_bf16 v[32:35], v[216:219], v[182:185], v[32:35]
	v_mfma_f32_16x16x32_bf16 v[60:63], v[196:199], v[178:181], v[60:63]
	v_mfma_f32_16x16x32_bf16 v[56:59], v[196:199], v[186:189], v[56:59]
	v_mfma_f32_16x16x32_bf16 v[52:55], v[204:207], v[178:181], v[52:55]
	v_mfma_f32_16x16x32_bf16 v[48:51], v[204:207], v[186:189], v[48:51]
	v_mfma_f32_16x16x32_bf16 v[44:47], v[212:215], v[178:181], v[44:47]
	v_mfma_f32_16x16x32_bf16 v[40:43], v[212:215], v[186:189], v[40:43]
	v_mfma_f32_16x16x32_bf16 v[36:39], v[236:239], v[178:181], v[36:39]
	v_mfma_f32_16x16x32_bf16 v[32:35], v[236:239], v[186:189], v[32:35]
	s_barrier
	v_add_u32_e32 v161, 0x14000, v143
	v_add_u32_e32 v162, s70, v136
	s_add_i32 m0, s100, 0x14000
	v_add_u32_e32 v174, s70, v134
	global_load_lds_dwordx4 v162, s[86:87]
	v_add_u32_e32 v162, 0x16000, v143
	s_nop 0
	s_add_i32 m0, s100, 0x16000
	s_nop 0
	global_load_lds_dwordx4 v174, s[86:87]
	s_waitcnt vmcnt(6)
	s_barrier
; #define P8_STAGE(P,BASE,br,kt) do{const bfr* _ub=(BASE)+((long)(br)*K+(long)(kt)*BK); \
;     __builtin_amdgcn_global_load_lds((const unsigned*)(_ub+so0),(unsigned*)((char*)(P)+wid*1024),16,0,0); \
;     __builtin_amdgcn_global_load_lds((const unsigned*)(_ub+so1),(unsigned*)((char*)(P)+wid*1024+8192),16,0,0);}while(0)
; #define P8_LDA(dst,b,h) _Pragma("unroll") for(int m=0;m<4;++m) _Pragma("unroll") for(int k=0;k<2;++k) \
;     dst[m][k]=*reinterpret_cast<const bf16x8*>((char*)P8_SA(b,h)+lds_byte(wr*64+m*16+fr,k*32+fq*8))
; #define P8_LDB(dst,b,h) _Pragma("unroll") for(int n=0;n<2;++n) _Pragma("unroll") for(int k=0;k<2;++k) \
;     dst[n][k]=*reinterpret_cast<const bf16x8*>((char*)P8_SB(b,h)+lds_byte(wc*32+n*16+fr,k*32+fq*8))
; #define P8_MMA(ai,bj,At,Bt) do{__builtin_amdgcn_s_setprio(1); \
;     _Pragma("unroll") for(int m=0;m<4;++m) _Pragma("unroll") for(int n=0;n<2;++n) _Pragma("unroll") for(int k=0;k<2;++k) \
;       acc[ai][bj][m][n]=__builtin_amdgcn_mfma_f32_16x16x32_bf16(At[m][k],Bt[n][k],acc[ai][bj][m][n],0,0,0); \
;     __builtin_amdgcn_s_setprio(0);}while(0)
; #define P8_WAIT_V(n) asm volatile("s_waitcnt vmcnt(" #n ")":::"memory")
; #define P8_WAIT_L(n) asm volatile("s_waitcnt lgkmcnt(" #n ")":::"memory")
; #define P8_BAR __builtin_amdgcn_s_barrier()
; #define P8_SCHED __builtin_amdgcn_sched_barrier(0)
; template <class EPI>
; DEVI void gemm8_tile(const bfr* __restrict__ A, const bfr* __restrict__ Bt, int K, int brow, int bcol, int nbrow, int nbcol, char* shmc, EPI epi) {
;     ...
;     P8_WAIT_V(6); P8_BAR; P8_MMA(1,1,At,B1); P8_BAR;
;     P8_LDB(B0,1,0); P8_SCHED; P8_LDA(At,1,0); P8_STAGE(P8_SA(0,1),A,brow+128,t+2);
;     P8_WAIT_L(8); P8_BAR; P8_WAIT_L(0); P8_MMA(0,0,At,B0); P8_BAR; P8_SCHED;
;     P8_LDB(B1,1,1); P8_STAGE(P8_SB(1,0),Bt,bcol,t+3);
;     P8_BAR; P8_WAIT_L(0); P8_MMA(0,1,At,B1); P8_BAR;
;     P8_LDA(At,1,1); P8_STAGE(P8_SA(1,0),A,brow,t+3);
	v_mfma_f32_16x16x32_bf16 v[28:31], v[190:193], v[220:223], v[28:31]
	v_mfma_f32_16x16x32_bf16 v[24:27], v[190:193], v[228:231], v[24:27]
	v_mfma_f32_16x16x32_bf16 v[20:23], v[200:203], v[220:223], v[20:23]
	v_mfma_f32_16x16x32_bf16 v[16:19], v[200:203], v[228:231], v[16:19]
	v_mfma_f32_16x16x32_bf16 v[12:15], v[208:211], v[220:223], v[12:15]
	v_mfma_f32_16x16x32_bf16 v[8:11], v[208:211], v[228:231], v[8:11]
	v_mfma_f32_16x16x32_bf16 v[4:7], v[216:219], v[220:223], v[4:7]
	v_mfma_f32_16x16x32_bf16 v[0:3], v[216:219], v[228:231], v[0:3]
	v_mfma_f32_16x16x32_bf16 v[28:31], v[196:199], v[224:227], v[28:31]
	v_mfma_f32_16x16x32_bf16 v[24:27], v[196:199], v[232:235], v[24:27]
	v_mfma_f32_16x16x32_bf16 v[20:23], v[204:207], v[224:227], v[20:23]
	v_mfma_f32_16x16x32_bf16 v[16:19], v[204:207], v[232:235], v[16:19]
	v_mfma_f32_16x16x32_bf16 v[12:15], v[212:215], v[224:227], v[12:15]
	v_mfma_f32_16x16x32_bf16 v[8:11], v[212:215], v[232:235], v[8:11]
	v_mfma_f32_16x16x32_bf16 v[4:7], v[236:239], v[224:227], v[4:7]
	v_mfma_f32_16x16x32_bf16 v[0:3], v[236:239], v[232:235], v[0:3]
	s_barrier
	ds_read_b128 v[174:177], v149
	ds_read_b128 v[178:181], v149 offset:1024
	ds_read_b128 v[182:185], v149 offset:2048
	ds_read_b128 v[186:189], v149 offset:3072
	v_add_u32_e32 v163, 0x4000, v143
	v_add_u32_e32 v170, 0x6000, v143
	v_add_u32_e32 v224, s72, v140
	s_add_i32 m0, s100, 0x4000
	ds_read_b128 v[190:193], v147 offset:32768
	ds_read_b128 v[196:199], v147 offset:33792
	ds_read_b128 v[200:203], v146 offset:32768
	ds_read_b128 v[204:207], v146 offset:33792
	ds_read_b128 v[208:211], v145 offset:32768
	ds_read_b128 v[212:215], v145 offset:33792
	ds_read_b128 v[216:219], v144 offset:32768
	ds_read_b128 v[220:223], v144 offset:33792
	global_load_lds_dwordx4 v224, s[86:87]
	v_add_u32_e32 v224, s72, v138
	s_add_i32 m0, s100, 0x6000
	s_nop 0
	global_load_lds_dwordx4 v224, s[86:87]
	s_waitcnt lgkmcnt(8)
	s_barrier
	s_waitcnt lgkmcnt(0)
	v_mfma_f32_16x16x32_bf16 v[124:127], v[190:193], v[174:177], v[124:127]
	v_mfma_f32_16x16x32_bf16 v[120:123], v[190:193], v[182:185], v[120:123]
	v_mfma_f32_16x16x32_bf16 v[116:119], v[200:203], v[174:177], v[116:119]
	v_mfma_f32_16x16x32_bf16 v[112:115], v[200:203], v[182:185], v[112:115]
	v_mfma_f32_16x16x32_bf16 v[108:111], v[208:211], v[174:177], v[108:111]
	v_mfma_f32_16x16x32_bf16 v[104:107], v[208:211], v[182:185], v[104:107]
	v_mfma_f32_16x16x32_bf16 v[100:103], v[216:219], v[174:177], v[100:103]
	v_mfma_f32_16x16x32_bf16 v[96:99], v[216:219], v[182:185], v[96:99]
	v_mfma_f32_16x16x32_bf16 v[124:127], v[196:199], v[178:181], v[124:127]
	v_mfma_f32_16x16x32_bf16 v[120:123], v[196:199], v[186:189], v[120:123]
	v_mfma_f32_16x16x32_bf16 v[116:119], v[204:207], v[178:181], v[116:119]
	v_mfma_f32_16x16x32_bf16 v[112:115], v[204:207], v[186:189], v[112:115]
	v_mfma_f32_16x16x32_bf16 v[108:111], v[212:215], v[178:181], v[108:111]
	v_mfma_f32_16x16x32_bf16 v[104:107], v[212:215], v[186:189], v[104:107]
	v_mfma_f32_16x16x32_bf16 v[100:103], v[220:223], v[178:181], v[100:103]
	v_mfma_f32_16x16x32_bf16 v[96:99], v[220:223], v[186:189], v[96:99]
	s_barrier
	v_add_u32_e32 v248, s74, v136
	s_add_i32 m0, s100, 0x18000
	ds_read_b128 v[224:227], v148
	ds_read_b128 v[228:231], v148 offset:1024
	ds_read_b128 v[232:235], v148 offset:2048
	ds_read_b128 v[236:239], v148 offset:3072
	global_load_lds_dwordx4 v248, s[86:87]
	v_add_u32_e32 v248, s74, v134
	s_add_i32 m0, s100, 0x1a000
	s_nop 0
	global_load_lds_dwordx4 v248, s[86:87]
	s_barrier
	s_waitcnt lgkmcnt(0)
	v_mfma_f32_16x16x32_bf16 v[92:95], v[190:193], v[224:227], v[92:95]
	v_mfma_f32_16x16x32_bf16 v[88:91], v[190:193], v[232:235], v[88:91]
	v_mfma_f32_16x16x32_bf16 v[84:87], v[200:203], v[224:227], v[84:87]
	v_mfma_f32_16x16x32_bf16 v[80:83], v[200:203], v[232:235], v[80:83]
	v_mfma_f32_16x16x32_bf16 v[76:79], v[208:211], v[224:227], v[76:79]
	v_mfma_f32_16x16x32_bf16 v[72:75], v[208:211], v[232:235], v[72:75]
	v_mfma_f32_16x16x32_bf16 v[68:71], v[216:219], v[224:227], v[68:71]
	v_mfma_f32_16x16x32_bf16 v[64:67], v[216:219], v[232:235], v[64:67]
	v_mfma_f32_16x16x32_bf16 v[92:95], v[196:199], v[228:231], v[92:95]
	v_mfma_f32_16x16x32_bf16 v[88:91], v[196:199], v[236:239], v[88:91]
	v_mfma_f32_16x16x32_bf16 v[84:87], v[204:207], v[228:231], v[84:87]
	v_mfma_f32_16x16x32_bf16 v[80:83], v[204:207], v[236:239], v[80:83]
	v_mfma_f32_16x16x32_bf16 v[76:79], v[212:215], v[228:231], v[76:79]
	v_mfma_f32_16x16x32_bf16 v[72:75], v[212:215], v[236:239], v[72:75]
	v_mfma_f32_16x16x32_bf16 v[68:71], v[220:223], v[228:231], v[68:71]
	v_mfma_f32_16x16x32_bf16 v[64:67], v[220:223], v[236:239], v[64:67]
	v_add_u32_e32 v240, s82, v140
	s_add_i32 m0, s100, 0x8000
	s_barrier
	ds_read_b128 v[190:193], v147 offset:49152
	ds_read_b128 v[196:199], v147 offset:50176
	ds_read_b128 v[200:203], v146 offset:49152
	ds_read_b128 v[204:207], v146 offset:50176
	ds_read_b128 v[208:211], v145 offset:49152
	ds_read_b128 v[212:215], v145 offset:50176
	ds_read_b128 v[216:219], v144 offset:49152
	ds_read_b128 v[220:223], v144 offset:50176
	global_load_lds_dwordx4 v240, s[86:87]
	v_add_u32_e32 v240, s82, v138
	s_add_i32 m0, s100, 0xa000
	s_nop 0
	global_load_lds_dwordx4 v240, s[86:87]
	s_barrier
; #define P8_STAGE(P,BASE,br,kt) do{const bfr* _ub=(BASE)+((long)(br)*K+(long)(kt)*BK); \
;     __builtin_amdgcn_global_load_lds((const unsigned*)(_ub+so0),(unsigned*)((char*)(P)+wid*1024),16,0,0); \
;     __builtin_amdgcn_global_load_lds((const unsigned*)(_ub+so1),(unsigned*)((char*)(P)+wid*1024+8192),16,0,0);}while(0)
; #define P8_LDA(dst,b,h) _Pragma("unroll") for(int m=0;m<4;++m) _Pragma("unroll") for(int k=0;k<2;++k) \
;     dst[m][k]=*reinterpret_cast<const bf16x8*>((char*)P8_SA(b,h)+lds_byte(wr*64+m*16+fr,k*32+fq*8))
; #define P8_LDB(dst,b,h) _Pragma("unroll") for(int n=0;n<2;++n) _Pragma("unroll") for(int k=0;k<2;++k) \
;     dst[n][k]=*reinterpret_cast<const bf16x8*>((char*)P8_SB(b,h)+lds_byte(wc*32+n*16+fr,k*32+fq*8))
; #define P8_MMA(ai,bj,At,Bt) do{__builtin_amdgcn_s_setprio(1); \
;     _Pragma("unroll") for(int m=0;m<4;++m) _Pragma("unroll") for(int n=0;n<2;++n) _Pragma("unroll") for(int k=0;k<2;++k) \
;       acc[ai][bj][m][n]=__builtin_amdgcn_mfma_f32_16x16x32_bf16(At[m][k],Bt[n][k],acc[ai][bj][m][n],0,0,0); \
;     __builtin_amdgcn_s_setprio(0);}while(0)
; #define P8_WAIT_V(n) asm volatile("s_waitcnt vmcnt(" #n ")":::"memory")
; #define P8_WAIT_L(n) asm volatile("s_waitcnt lgkmcnt(" #n ")":::"memory")
; #define P8_BAR __builtin_amdgcn_s_barrier()
; #define P8_SCHED __builtin_amdgcn_sched_barrier(0)
; template <class EPI>
; DEVI void gemm8_tile(const bfr* __restrict__ A, const bfr* __restrict__ Bt, int K, int brow, int bcol, int nbrow, int nbcol, char* shmc, EPI epi) {
;     ...
;     P8_BAR; P8_WAIT_L(0); P8_MMA(1,0,At,B0); P8_BAR; P8_SCHED;
;     P8_STAGE(P8_SB(1,1),Bt,bcol+128,t+3);
;     P8_WAIT_V(6); P8_BAR; P8_MMA(1,1,At,B1); P8_BAR;
;   }
;   { P8_LDB(B0,0,0); P8_LDA(At,0,0); P8_STAGE(P8_SA(1,1),A,brow+128,nt-1);
;     P8_BAR; P8_WAIT_L(0); P8_MMA(0,0,At,B0); P8_BAR;
;     P8_LDB(B1,0,1); P8_BAR; P8_WAIT_L(0); P8_MMA(0,1,At,B1); P8_BAR;
	s_waitcnt lgkmcnt(0)
	v_mfma_f32_16x16x32_bf16 v[60:63], v[190:193], v[174:177], v[60:63]
	v_mfma_f32_16x16x32_bf16 v[56:59], v[190:193], v[182:185], v[56:59]
	v_mfma_f32_16x16x32_bf16 v[52:55], v[200:203], v[174:177], v[52:55]
	v_mfma_f32_16x16x32_bf16 v[48:51], v[200:203], v[182:185], v[48:51]
	v_mfma_f32_16x16x32_bf16 v[44:47], v[208:211], v[174:177], v[44:47]
	v_mfma_f32_16x16x32_bf16 v[40:43], v[208:211], v[182:185], v[40:43]
	v_mfma_f32_16x16x32_bf16 v[36:39], v[216:219], v[174:177], v[36:39]
	v_mfma_f32_16x16x32_bf16 v[32:35], v[216:219], v[182:185], v[32:35]
	v_mfma_f32_16x16x32_bf16 v[60:63], v[196:199], v[178:181], v[60:63]
	v_mfma_f32_16x16x32_bf16 v[56:59], v[196:199], v[186:189], v[56:59]
	v_mfma_f32_16x16x32_bf16 v[52:55], v[204:207], v[178:181], v[52:55]
	v_mfma_f32_16x16x32_bf16 v[48:51], v[204:207], v[186:189], v[48:51]
	v_mfma_f32_16x16x32_bf16 v[44:47], v[212:215], v[178:181], v[44:47]
	v_mfma_f32_16x16x32_bf16 v[40:43], v[212:215], v[186:189], v[40:43]
	v_mfma_f32_16x16x32_bf16 v[36:39], v[220:223], v[178:181], v[36:39]
	v_mfma_f32_16x16x32_bf16 v[32:35], v[220:223], v[186:189], v[32:35]
	s_barrier
	v_add_u32_e32 v174, s78, v136
	s_add_i32 m0, s100, 0x1c000
	s_nop 0
	global_load_lds_dwordx4 v174, s[86:87]
	v_add_u32_e32 v174, s78, v134
	s_add_i32 m0, s100, 0x1e000
	s_nop 0
	global_load_lds_dwordx4 v174, s[86:87]
	s_waitcnt vmcnt(6)
	s_barrier
	v_mfma_f32_16x16x32_bf16 v[28:31], v[190:193], v[224:227], v[28:31]
	v_mfma_f32_16x16x32_bf16 v[24:27], v[190:193], v[232:235], v[24:27]
	v_mfma_f32_16x16x32_bf16 v[20:23], v[200:203], v[224:227], v[20:23]
	v_mfma_f32_16x16x32_bf16 v[16:19], v[200:203], v[232:235], v[16:19]
	v_mfma_f32_16x16x32_bf16 v[12:15], v[208:211], v[224:227], v[12:15]
	v_mfma_f32_16x16x32_bf16 v[8:11], v[208:211], v[232:235], v[8:11]
	v_mfma_f32_16x16x32_bf16 v[4:7], v[216:219], v[224:227], v[4:7]
	v_mfma_f32_16x16x32_bf16 v[0:3], v[216:219], v[232:235], v[0:3]
	v_mfma_f32_16x16x32_bf16 v[28:31], v[196:199], v[228:231], v[28:31]
	v_mfma_f32_16x16x32_bf16 v[24:27], v[196:199], v[236:239], v[24:27]
	v_mfma_f32_16x16x32_bf16 v[20:23], v[204:207], v[228:231], v[20:23]
	v_mfma_f32_16x16x32_bf16 v[16:19], v[204:207], v[236:239], v[16:19]
	v_mfma_f32_16x16x32_bf16 v[12:15], v[212:215], v[228:231], v[12:15]
	v_mfma_f32_16x16x32_bf16 v[8:11], v[212:215], v[236:239], v[8:11]
	v_mfma_f32_16x16x32_bf16 v[4:7], v[220:223], v[228:231], v[4:7]
	v_mfma_f32_16x16x32_bf16 v[0:3], v[220:223], v[236:239], v[0:3]
	s_add_i32 s0, s0, 2
	v_lshl_add_u64 v[134:135], v[134:135], 0, s[80:81]
	v_lshl_add_u64 v[136:137], v[136:137], 0, s[80:81]
	v_lshl_add_u64 v[138:139], v[138:139], 0, s[80:81]
	s_cmp_lt_u32 s0, 28
	v_lshl_add_u64 v[140:141], v[140:141], 0, s[80:81]
	s_barrier
	s_cbranch_scc1 .LBB0_85
	s_or_b32 s0, s8, 0x80
	s_ashr_i32 s1, s0, 31
	s_lshl_b64 s[0:1], s[0:1], 12
	s_add_u32 s0, s28, s0
	s_addc_u32 s1, s29, s1
	ds_read_b128 v[134:137], v157
	ds_read_b128 v[138:141], v157 offset:1024
	ds_read_b128 v[150:153], v157 offset:2048
	ds_read_b128 v[174:177], v157 offset:3072
	ds_read_b128 v[178:181], v147
	ds_read_b128 v[182:185], v147 offset:1024
	ds_read_b128 v[186:189], v146
	ds_read_b128 v[190:193], v146 offset:1024
	ds_read_b128 v[196:199], v145
	ds_read_b128 v[200:203], v145 offset:1024
	ds_read_b128 v[204:207], v144
	ds_read_b128 v[208:211], v144 offset:1024
	v_lshl_add_u64 v[156:157], v[166:167], 1, s[0:1]
	s_mov_b64 s[54:55], 0xf80
	v_lshl_add_u64 v[156:157], v[156:157], 0, s[54:55]
	s_add_i32 m0, s100, 0xc000
	v_lshl_add_u64 v[132:133], v[132:133], 1, s[0:1]
	global_load_lds_dwordx4 v[156:157], off
	v_lshl_add_u64 v[132:133], v[132:133], 0, s[54:55]
	s_add_i32 m0, s100, 0xe000
	s_nop 0
	global_load_lds_dwordx4 v[132:133], off
	s_barrier
	s_waitcnt lgkmcnt(0)
	s_setprio 1
	s_waitcnt lgkmcnt(0)
	v_mfma_f32_16x16x32_bf16 v[124:127], v[178:181], v[134:137], v[124:127]
	v_mfma_f32_16x16x32_bf16 v[116:119], v[186:189], v[134:137], v[116:119]
	v_mfma_f32_16x16x32_bf16 v[112:115], v[186:189], v[150:153], v[112:115]
	v_mfma_f32_16x16x32_bf16 v[96:99], v[204:207], v[150:153], v[96:99]
	v_mfma_f32_16x16x32_bf16 v[124:127], v[182:185], v[138:141], v[124:127]
	v_mfma_f32_16x16x32_bf16 v[120:123], v[178:181], v[150:153], v[120:123]
	v_mfma_f32_16x16x32_bf16 v[116:119], v[190:193], v[138:141], v[116:119]
	v_mfma_f32_16x16x32_bf16 v[112:115], v[190:193], v[174:177], v[112:115]
	v_mfma_f32_16x16x32_bf16 v[108:111], v[196:199], v[134:137], v[108:111]
	v_mfma_f32_16x16x32_bf16 v[104:107], v[196:199], v[150:153], v[104:107]
	v_mfma_f32_16x16x32_bf16 v[100:103], v[204:207], v[134:137], v[100:103]
	v_mfma_f32_16x16x32_bf16 v[96:99], v[208:211], v[174:177], v[96:99]
	v_mfma_f32_16x16x32_bf16 v[212:215], v[182:185], v[174:177], v[120:123]
	v_mfma_f32_16x16x32_bf16 v[216:219], v[200:203], v[138:141], v[108:111]
	v_mfma_f32_16x16x32_bf16 v[220:223], v[200:203], v[174:177], v[104:107]
	v_mfma_f32_16x16x32_bf16 v[224:227], v[208:211], v[138:141], v[100:103]
	s_setprio 0
	s_barrier
	s_nop 0
	ds_read_b128 v[100:103], v155
	ds_read_b128 v[104:107], v155 offset:1024
	ds_read_b128 v[108:111], v155 offset:2048
	ds_read_b128 v[120:123], v155 offset:3072
	s_barrier
; #define P8_LDA(dst,b,h) _Pragma("unroll") for(int m=0;m<4;++m) _Pragma("unroll") for(int k=0;k<2;++k) \
;     dst[m][k]=*reinterpret_cast<const bf16x8*>((char*)P8_SA(b,h)+lds_byte(wr*64+m*16+fr,k*32+fq*8))
; #define P8_LDB(dst,b,h) _Pragma("unroll") for(int n=0;n<2;++n) _Pragma("unroll") for(int k=0;k<2;++k) \
;     dst[n][k]=*reinterpret_cast<const bf16x8*>((char*)P8_SB(b,h)+lds_byte(wc*32+n*16+fr,k*32+fq*8))
; #define P8_MMA(ai,bj,At,Bt) do{__builtin_amdgcn_s_setprio(1); \
;     _Pragma("unroll") for(int m=0;m<4;++m) _Pragma("unroll") for(int n=0;n<2;++n) _Pragma("unroll") for(int k=0;k<2;++k) \
;       acc[ai][bj][m][n]=__builtin_amdgcn_mfma_f32_16x16x32_bf16(At[m][k],Bt[n][k],acc[ai][bj][m][n],0,0,0); \
;     __builtin_amdgcn_s_setprio(0);}while(0)
; #define P8_WAIT_V(n) asm volatile("s_waitcnt vmcnt(" #n ")":::"memory")
; #define P8_WAIT_L(n) asm volatile("s_waitcnt lgkmcnt(" #n ")":::"memory")
; #define P8_BAR __builtin_amdgcn_s_barrier()
; template <class EPI>
; DEVI void gemm8_tile(const bfr* __restrict__ A, const bfr* __restrict__ Bt, int K, int brow, int bcol, int nbrow, int nbcol, char* shmc, EPI epi) {
;     ...
;     P8_LDB(B1,0,1); P8_BAR; P8_WAIT_L(0); P8_MMA(0,1,At,B1); P8_BAR;
;     P8_LDA(At,0,1); P8_WAIT_V(4); P8_BAR; P8_WAIT_L(0); P8_MMA(1,0,At,B0); P8_MMA(1,1,At,B1); P8_BAR; }
;   { P8_LDB(B0,1,0); P8_LDA(At,1,0); P8_WAIT_V(2); P8_BAR; P8_WAIT_L(0); P8_MMA(0,0,At,B0); P8_BAR;
	s_waitcnt lgkmcnt(0)
	s_setprio 1
	s_waitcnt lgkmcnt(0)
	v_mfma_f32_16x16x32_bf16 v[92:95], v[178:181], v[100:103], v[92:95]
	v_mfma_f32_16x16x32_bf16 v[84:87], v[186:189], v[100:103], v[84:87]
	v_mfma_f32_16x16x32_bf16 v[80:83], v[186:189], v[108:111], v[80:83]
	v_mfma_f32_16x16x32_bf16 v[64:67], v[204:207], v[108:111], v[64:67]
	v_mfma_f32_16x16x32_bf16 v[92:95], v[182:185], v[104:107], v[92:95]
	v_mfma_f32_16x16x32_bf16 v[88:91], v[178:181], v[108:111], v[88:91]
	v_mfma_f32_16x16x32_bf16 v[84:87], v[190:193], v[104:107], v[84:87]
	v_mfma_f32_16x16x32_bf16 v[80:83], v[190:193], v[120:123], v[80:83]
	v_mfma_f32_16x16x32_bf16 v[76:79], v[196:199], v[100:103], v[76:79]
	v_mfma_f32_16x16x32_bf16 v[72:75], v[196:199], v[108:111], v[72:75]
	v_mfma_f32_16x16x32_bf16 v[68:71], v[204:207], v[100:103], v[68:71]
	v_mfma_f32_16x16x32_bf16 v[64:67], v[208:211], v[120:123], v[64:67]
	v_mfma_f32_16x16x32_bf16 v[154:157], v[182:185], v[120:123], v[88:91]
	v_mfma_f32_16x16x32_bf16 v[178:181], v[200:203], v[104:107], v[76:79]
	v_mfma_f32_16x16x32_bf16 v[182:185], v[200:203], v[120:123], v[72:75]
	v_mfma_f32_16x16x32_bf16 v[186:189], v[208:211], v[104:107], v[68:71]
	s_setprio 0
	s_barrier
	s_nop 0
	ds_read_b128 v[68:71], v147 offset:16384
	ds_read_b128 v[72:75], v147 offset:17408
	ds_read_b128 v[76:79], v146 offset:16384
	ds_read_b128 v[88:91], v146 offset:17408
	ds_read_b128 v[190:193], v145 offset:16384
	ds_read_b128 v[196:199], v145 offset:17408
	ds_read_b128 v[200:203], v144 offset:16384
	ds_read_b128 v[204:207], v144 offset:17408
	s_waitcnt vmcnt(4)
	s_barrier
	s_waitcnt lgkmcnt(0)
	s_setprio 1
	s_waitcnt lgkmcnt(0)
	v_mfma_f32_16x16x32_bf16 v[60:63], v[68:71], v[134:137], v[60:63]
	v_mfma_f32_16x16x32_bf16 v[52:55], v[76:79], v[134:137], v[52:55]
	v_mfma_f32_16x16x32_bf16 v[48:51], v[76:79], v[150:153], v[48:51]
	v_mfma_f32_16x16x32_bf16 v[32:35], v[200:203], v[150:153], v[32:35]
	v_mfma_f32_16x16x32_bf16 v[60:63], v[72:75], v[138:141], v[60:63]
	v_mfma_f32_16x16x32_bf16 v[56:59], v[68:71], v[150:153], v[56:59]
	v_mfma_f32_16x16x32_bf16 v[52:55], v[88:91], v[138:141], v[52:55]
	v_mfma_f32_16x16x32_bf16 v[48:51], v[88:91], v[174:177], v[48:51]
	v_mfma_f32_16x16x32_bf16 v[44:47], v[190:193], v[134:137], v[44:47]
	v_mfma_f32_16x16x32_bf16 v[40:43], v[190:193], v[150:153], v[40:43]
	v_mfma_f32_16x16x32_bf16 v[36:39], v[200:203], v[134:137], v[36:39]
	v_mfma_f32_16x16x32_bf16 v[32:35], v[204:207], v[174:177], v[32:35]
	v_mfma_f32_16x16x32_bf16 v[208:211], v[72:75], v[174:177], v[56:59]
	v_mfma_f32_16x16x32_bf16 v[228:231], v[196:199], v[138:141], v[44:47]
	v_mfma_f32_16x16x32_bf16 v[232:235], v[196:199], v[174:177], v[40:43]
	v_mfma_f32_16x16x32_bf16 v[132:135], v[204:207], v[138:141], v[36:39]
	s_setprio 0
	s_setprio 1
	v_mfma_f32_16x16x32_bf16 v[28:31], v[68:71], v[100:103], v[28:31]
	v_mfma_f32_16x16x32_bf16 v[20:23], v[76:79], v[100:103], v[20:23]
	v_mfma_f32_16x16x32_bf16 v[16:19], v[76:79], v[108:111], v[16:19]
	v_mfma_f32_16x16x32_bf16 v[0:3], v[200:203], v[108:111], v[0:3]
	v_mfma_f32_16x16x32_bf16 v[28:31], v[72:75], v[104:107], v[28:31]
	v_mfma_f32_16x16x32_bf16 v[24:27], v[68:71], v[108:111], v[24:27]
	v_mfma_f32_16x16x32_bf16 v[20:23], v[88:91], v[104:107], v[20:23]
	v_mfma_f32_16x16x32_bf16 v[16:19], v[88:91], v[120:123], v[16:19]
	v_mfma_f32_16x16x32_bf16 v[12:15], v[190:193], v[100:103], v[12:15]
	v_mfma_f32_16x16x32_bf16 v[8:11], v[190:193], v[108:111], v[8:11]
	v_mfma_f32_16x16x32_bf16 v[4:7], v[200:203], v[100:103], v[4:7]
	v_mfma_f32_16x16x32_bf16 v[0:3], v[204:207], v[120:123], v[0:3]
	v_mfma_f32_16x16x32_bf16 v[136:139], v[72:75], v[120:123], v[24:27]
	v_mfma_f32_16x16x32_bf16 v[150:153], v[196:199], v[104:107], v[12:15]
	v_mfma_f32_16x16x32_bf16 v[172:175], v[196:199], v[120:123], v[8:11]
	v_mfma_f32_16x16x32_bf16 v[190:193], v[204:207], v[104:107], v[4:7]
	s_setprio 0
	s_barrier
	s_nop 0
	ds_read_b128 v[4:7], v149
	ds_read_b128 v[8:11], v149 offset:1024
	ds_read_b128 v[12:15], v149 offset:2048
	ds_read_b128 v[24:27], v149 offset:3072
	ds_read_b128 v[36:39], v147 offset:32768
	ds_read_b128 v[40:43], v147 offset:33792
	ds_read_b128 v[44:47], v146 offset:32768
	ds_read_b128 v[56:59], v146 offset:33792
	ds_read_b128 v[68:71], v145 offset:32768
	ds_read_b128 v[196:199], v145 offset:33792
	ds_read_b128 v[200:203], v144 offset:32768
	ds_read_b128 v[204:207], v144 offset:33792
	s_waitcnt vmcnt(2)
	s_barrier
; #define P8_LDA(dst,b,h) _Pragma("unroll") for(int m=0;m<4;++m) _Pragma("unroll") for(int k=0;k<2;++k) \
;     dst[m][k]=*reinterpret_cast<const bf16x8*>((char*)P8_SA(b,h)+lds_byte(wr*64+m*16+fr,k*32+fq*8))
; #define P8_LDB(dst,b,h) _Pragma("unroll") for(int n=0;n<2;++n) _Pragma("unroll") for(int k=0;k<2;++k) \
;     dst[n][k]=*reinterpret_cast<const bf16x8*>((char*)P8_SB(b,h)+lds_byte(wc*32+n*16+fr,k*32+fq*8))
; #define P8_MMA(ai,bj,At,Bt) do{__builtin_amdgcn_s_setprio(1); \
;     _Pragma("unroll") for(int m=0;m<4;++m) _Pragma("unroll") for(int n=0;n<2;++n) _Pragma("unroll") for(int k=0;k<2;++k) \
;       acc[ai][bj][m][n]=__builtin_amdgcn_mfma_f32_16x16x32_bf16(At[m][k],Bt[n][k],acc[ai][bj][m][n],0,0,0); \
;     __builtin_amdgcn_s_setprio(0);}while(0)
; #define P8_WAIT_V(n) asm volatile("s_waitcnt vmcnt(" #n ")":::"memory")
; #define P8_WAIT_L(n) asm volatile("s_waitcnt lgkmcnt(" #n ")":::"memory")
; #define P8_BAR __builtin_amdgcn_s_barrier()
; template <class EPI>
; DEVI void gemm8_tile(const bfr* __restrict__ A, const bfr* __restrict__ Bt, int K, int brow, int bcol, int nbrow, int nbcol, char* shmc, EPI epi) {
;     ...
;   { P8_LDB(B0,1,0); P8_LDA(At,1,0); P8_WAIT_V(2); P8_BAR; P8_WAIT_L(0); P8_MMA(0,0,At,B0); P8_BAR;
;     P8_LDB(B1,1,1); P8_WAIT_V(0); P8_BAR; P8_WAIT_L(0); P8_MMA(0,1,At,B1); P8_BAR;
;     P8_LDA(At,1,1); P8_BAR; P8_WAIT_L(0); P8_MMA(1,0,At,B0); P8_MMA(1,1,At,B1); P8_BAR; }
;   if(wr==0)P8_BAR;
	s_waitcnt lgkmcnt(0)
	s_setprio 1
	s_waitcnt lgkmcnt(0)
	v_mfma_f32_16x16x32_bf16 v[72:75], v[36:39], v[4:7], v[124:127]
	v_mfma_f32_16x16x32_bf16 v[120:123], v[40:43], v[8:11], v[72:75]
	v_mfma_f32_16x16x32_bf16 v[72:75], v[36:39], v[12:15], v[212:215]
	v_mfma_f32_16x16x32_bf16 v[104:107], v[40:43], v[24:27], v[72:75]
	v_mfma_f32_16x16x32_bf16 v[72:75], v[44:47], v[4:7], v[116:119]
	v_mfma_f32_16x16x32_bf16 v[124:127], v[56:59], v[8:11], v[72:75]
	v_mfma_f32_16x16x32_bf16 v[72:75], v[44:47], v[12:15], v[112:115]
	v_mfma_f32_16x16x32_bf16 v[108:111], v[56:59], v[24:27], v[72:75]
	v_mfma_f32_16x16x32_bf16 v[72:75], v[68:71], v[4:7], v[216:219]
	v_mfma_f32_16x16x32_bf16 v[112:115], v[196:199], v[8:11], v[72:75]
	v_mfma_f32_16x16x32_bf16 v[72:75], v[68:71], v[12:15], v[220:223]
	v_mfma_f32_16x16x32_bf16 v[100:103], v[196:199], v[24:27], v[72:75]
	v_mfma_f32_16x16x32_bf16 v[72:75], v[200:203], v[4:7], v[224:227]
	v_mfma_f32_16x16x32_bf16 v[116:119], v[204:207], v[8:11], v[72:75]
	v_mfma_f32_16x16x32_bf16 v[72:75], v[200:203], v[12:15], v[96:99]
	v_mfma_f32_16x16x32_bf16 v[96:99], v[204:207], v[24:27], v[72:75]
	s_setprio 0
	s_barrier
	ds_read_b128 v[212:215], v148
	ds_read_b128 v[216:219], v148 offset:1024
	ds_read_b128 v[220:223], v148 offset:2048
	ds_read_b128 v[224:227], v148 offset:3072
	s_waitcnt vmcnt(0)
	s_barrier
	s_waitcnt lgkmcnt(0)
	s_setprio 1
	s_waitcnt lgkmcnt(0)
	v_mfma_f32_16x16x32_bf16 v[72:75], v[36:39], v[212:215], v[92:95]
	v_mfma_f32_16x16x32_bf16 v[36:39], v[36:39], v[220:223], v[154:157]
	v_mfma_f32_16x16x32_bf16 v[88:91], v[40:43], v[216:219], v[72:75]
	v_mfma_f32_16x16x32_bf16 v[72:75], v[40:43], v[224:227], v[36:39]
	v_mfma_f32_16x16x32_bf16 v[36:39], v[44:47], v[212:215], v[84:87]
	v_mfma_f32_16x16x32_bf16 v[92:95], v[56:59], v[216:219], v[36:39]
	v_mfma_f32_16x16x32_bf16 v[36:39], v[44:47], v[220:223], v[80:83]
	v_mfma_f32_16x16x32_bf16 v[76:79], v[56:59], v[224:227], v[36:39]
	v_mfma_f32_16x16x32_bf16 v[36:39], v[68:71], v[212:215], v[178:181]
	v_mfma_f32_16x16x32_bf16 v[80:83], v[196:199], v[216:219], v[36:39]
	v_mfma_f32_16x16x32_bf16 v[36:39], v[68:71], v[220:223], v[182:185]
	v_mfma_f32_16x16x32_bf16 v[68:71], v[196:199], v[224:227], v[36:39]
	v_mfma_f32_16x16x32_bf16 v[36:39], v[200:203], v[212:215], v[186:189]
	v_mfma_f32_16x16x32_bf16 v[84:87], v[204:207], v[216:219], v[36:39]
	v_mfma_f32_16x16x32_bf16 v[36:39], v[200:203], v[220:223], v[64:67]
	v_mfma_f32_16x16x32_bf16 v[64:67], v[204:207], v[224:227], v[36:39]
	s_setprio 0
	s_barrier
	ds_read_b128 v[154:157], v147 offset:49152
	ds_read_b128 v[176:179], v147 offset:50176
	ds_read_b128 v[180:183], v146 offset:49152
	ds_read_b128 v[146:149], v146 offset:50176
	ds_read_b128 v[184:187], v145 offset:49152
	ds_read_b128 v[196:199], v145 offset:50176
	ds_read_b128 v[200:203], v144 offset:49152
	ds_read_b128 v[204:207], v144 offset:50176
	s_barrier
	s_waitcnt lgkmcnt(0)
	s_setprio 1
	s_waitcnt lgkmcnt(0)
	v_mfma_f32_16x16x32_bf16 v[36:39], v[154:157], v[4:7], v[60:63]
	v_mfma_f32_16x16x32_bf16 v[56:59], v[176:179], v[8:11], v[36:39]
	v_mfma_f32_16x16x32_bf16 v[36:39], v[154:157], v[12:15], v[208:211]
	v_mfma_f32_16x16x32_bf16 v[40:43], v[176:179], v[24:27], v[36:39]
	v_mfma_f32_16x16x32_bf16 v[36:39], v[180:183], v[4:7], v[52:55]
	v_mfma_f32_16x16x32_bf16 v[60:63], v[146:149], v[8:11], v[36:39]
	v_mfma_f32_16x16x32_bf16 v[36:39], v[180:183], v[12:15], v[48:51]
	v_mfma_f32_16x16x32_bf16 v[44:47], v[146:149], v[24:27], v[36:39]
	v_mfma_f32_16x16x32_bf16 v[36:39], v[184:187], v[4:7], v[228:231]
	v_mfma_f32_16x16x32_bf16 v[4:7], v[200:203], v[4:7], v[132:135]
	v_mfma_f32_16x16x32_bf16 v[48:51], v[196:199], v[8:11], v[36:39]
	v_mfma_f32_16x16x32_bf16 v[36:39], v[184:187], v[12:15], v[232:235]
	v_mfma_f32_16x16x32_bf16 v[52:55], v[204:207], v[8:11], v[4:7]
	v_mfma_f32_16x16x32_bf16 v[4:7], v[200:203], v[12:15], v[32:35]
	v_mfma_f32_16x16x32_bf16 v[36:39], v[196:199], v[24:27], v[36:39]
	v_mfma_f32_16x16x32_bf16 v[32:35], v[204:207], v[24:27], v[4:7]
	s_setprio 0
	s_setprio 1
	v_mfma_f32_16x16x32_bf16 v[4:7], v[154:157], v[212:215], v[28:31]
	v_mfma_f32_16x16x32_bf16 v[24:27], v[176:179], v[216:219], v[4:7]
	v_mfma_f32_16x16x32_bf16 v[4:7], v[154:157], v[220:223], v[136:139]
	v_mfma_f32_16x16x32_bf16 v[8:11], v[176:179], v[224:227], v[4:7]
	v_mfma_f32_16x16x32_bf16 v[4:7], v[180:183], v[212:215], v[20:23]
	v_mfma_f32_16x16x32_bf16 v[28:31], v[146:149], v[216:219], v[4:7]
	v_mfma_f32_16x16x32_bf16 v[4:7], v[180:183], v[220:223], v[16:19]
	v_mfma_f32_16x16x32_bf16 v[12:15], v[146:149], v[224:227], v[4:7]
	v_mfma_f32_16x16x32_bf16 v[4:7], v[184:187], v[212:215], v[150:153]
	v_mfma_f32_16x16x32_bf16 v[16:19], v[196:199], v[216:219], v[4:7]
	v_mfma_f32_16x16x32_bf16 v[4:7], v[184:187], v[220:223], v[172:175]
	v_mfma_f32_16x16x32_bf16 v[20:23], v[200:203], v[212:215], v[190:193]
	v_mfma_f32_16x16x32_bf16 v[0:3], v[200:203], v[220:223], v[0:3]
	v_mfma_f32_16x16x32_bf16 v[4:7], v[196:199], v[224:227], v[4:7]
	v_mfma_f32_16x16x32_bf16 v[20:23], v[204:207], v[216:219], v[20:23]
	v_mfma_f32_16x16x32_bf16 v[0:3], v[204:207], v[224:227], v[0:3]
	s_setprio 0
	v_cmp_gt_u32_e32 vcc, s57, v142
	s_barrier
	s_and_saveexec_b64 s[0:1], vcc
	s_cbranch_execz .LBB0_88
	s_barrier

; DEVI int otid() { int t = threadIdx.x; asm volatile("" : "+v"(t)); return t; }
; DEVI int v_st(int k, int c) { const int kk = (k & ~0xC) | ((k & 4) << 1) | ((k & 8) >> 1); return ((kk >> 3) * 4 + (c >> 5)) * 512 + ((kk & 7) * 32 + (c & 31)) * 2; }
; DEVI int v_rd_base(int lane) { return ((lane & 3) << 3) | (((lane >> 2) & 3) << 6) | (((lane >> 4) & 1) << 5) | (((lane >> 5) & 1) << 8); }
; template <bool FIX>
; DEVI void attn_item(const bfr* __restrict__ Qb, const bfr* __restrict__ Kh, const bfr* __restrict__ Vh, bfr* __restrict__ Ob, int seq, char* lds, float negBC) {
;   const int tid = otid(), wid = tid >> 6, lane = tid & 63, r32 = lane & 31, hi = lane >> 5;
;   char* V_lds = lds; char* K_lds = lds + 2 * SHM_V;
;   float* ws = (float*)(lds + 2 * SHM_V + 2 * SHM_K) + wid * 64; float* li_l = ws; float* al_l = ws + 32;
;   float m_reg = -1e30f, l_reg = 0; f32x16 o[4] = {}; bf16x8 qr[12];
;   const bfr* Qw = Qb + (long)(wid * QBLK + r32) * LDQ + hi * 8;
; #pragma unroll
;   for (int d0 = 0; d0 < 12; ++d0) qr[d0] = *reinterpret_cast<const bf16x8*>(Qw + d0 * 16);
;   const int sr = tid >> 4, sc = (tid & 15) * 8, vst0 = v_st(sr, sc), vst1 = v_st(32 + sr, sc);
;   const int kr = tid >> 3, kc = 128 + (tid & 7) * 8;
;   const int vb0 = (int)(uintptr_t)V_lds + v_rd_base(lane);
;   struct { bf16x8 vs0, vs1, ks0, ks1, ks2; } sr_[1];
;     ...
;   f32x16 pA0, pA1; float mnA, alA; bf16x8 pa0, pa1, pa2, pa3; const int NT = seq / KVBLK;
;   SLOAD(0, 0); asm volatile("s_waitcnt vmcnt(0)" ::: "memory"); SWRITE(0, 0); SLOAD(0, KVBLK); __syncthreads();
.LBB0_118:
	s_and_b64 vcc, exec, s[0:1]
	s_cbranch_vccz .LBB0_95
	v_mov_b32_e32 v184, v164
	s_movk_i32 s0, 0xffe0
	v_ashrrev_i32_e32 v0, 1, v184
	v_bfe_u32 v183, v184, 5, 1
	v_and_b32_e32 v170, 0xffffffe0, v0
	v_bfi_b32 v2, s0, v0, v184
	v_mov_b64_e32 v[0:1], s[8:9]
	s_movk_i32 s2, 0x1800
	v_mad_i64_i32 v[0:1], s[0:1], v2, s2, v[0:1]
	v_lshlrev_b32_e32 v166, 4, v183
	v_lshl_add_u64 v[0:1], v[0:1], 0, v[166:167]
	global_load_dwordx4 v[140:143], v[0:1], off
	global_load_dwordx4 v[136:139], v[0:1], off offset:32
	global_load_dwordx4 v[132:135], v[0:1], off offset:64
	global_load_dwordx4 v[128:131], v[0:1], off offset:96
	global_load_dwordx4 v[124:127], v[0:1], off offset:128
	global_load_dwordx4 v[120:123], v[0:1], off offset:160
	global_load_dwordx4 v[116:119], v[0:1], off offset:192
	global_load_dwordx4 v[112:115], v[0:1], off offset:224
	global_load_dwordx4 v[108:111], v[0:1], off offset:256
	global_load_dwordx4 v[104:107], v[0:1], off offset:288
	global_load_dwordx4 v[100:103], v[0:1], off offset:320
	global_load_dwordx4 v[96:99], v[0:1], off offset:352
	v_ashrrev_i32_e32 v0, 4, v184
	v_and_b32_e32 v2, 0xfffff0, v0
	v_lshlrev_b32_e32 v3, 1, v0
	v_lshlrev_b32_e32 v28, 3, v184
	v_and_or_b32 v2, v3, 8, v2
	v_lshrrev_b32_e32 v2, 1, v2
	v_bfe_u32 v4, v28, 5, 2
	v_or_b32_e32 v2, v2, v4
	v_lshrrev_b32_e32 v3, 1, v0
	v_lshlrev_b32_e32 v5, 9, v2
	v_and_b32_e32 v2, 3, v0
	v_and_b32_e32 v1, 0x78, v28
	v_and_or_b32 v2, v3, 4, v2
	v_lshlrev_b32_e32 v3, 6, v2
	v_lshlrev_b32_e32 v2, 1, v1
	v_and_b32_e32 v1, 48, v2
	v_add_u32_e32 v20, 32, v0
	v_or3_b32 v185, v5, v3, v1
	v_and_b32_e32 v5, 0xfffff0, v20
	v_lshlrev_b32_e32 v6, 1, v20
	v_and_or_b32 v5, v6, 8, v5
	v_lshrrev_b32_e32 v5, 1, v5
	v_or_b32_e32 v4, v5, v4
	v_lshlrev_b32_e32 v4, 9, v4
	v_or3_b32 v186, v4, v3, v1
	v_lshrrev_b32_e32 v191, 7, v184
	v_lshlrev_b32_e32 v185, 11, v191
	v_bfe_u32 v191, v184, 2, 2
	v_lshl_or_b32 v185, v191, 9, v185
	v_bfe_u32 v191, v184, 4, 3
	v_lshl_or_b32 v185, v191, 6, v185
	v_and_b32_e32 v191, 3, v184
	v_lshl_or_b32 v185, v191, 4, v185
	v_add_u32_e32 v186, 0x2000, v185
	v_ashrrev_i32_e32 v1, 31, v0
	v_lshlrev_b64 v[6:7], 12, v[0:1]
	v_lshl_add_u64 v[6:7], s[82:83], 0, v[6:7]
	v_mov_b32_e32 v3, v167
	v_lshl_add_u64 v[6:7], v[6:7], 0, v[2:3]
	v_ashrrev_i32_e32 v21, 31, v20
	global_load_dwordx4 v[8:11], v[6:7], off
	v_lshlrev_b64 v[6:7], 12, v[20:21]
	v_lshl_add_u64 v[6:7], s[82:83], 0, v[6:7]
	v_lshl_add_u64 v[6:7], v[6:7], 0, v[2:3]
	v_ashrrev_i32_e32 v29, 3, v184
	v_lshlrev_b32_e32 v30, 4, v184
	global_load_dwordx4 v[12:15], v[6:7], off
	v_mov_b64_e32 v[6:7], s[34:35]
	v_and_b32_e32 v4, 0x70, v30
	v_mad_i64_i32 v[16:17], s[0:1], v0, s2, v[6:7]
	v_mad_i64_i32 v[24:25], s[0:1], v29, s2, v[6:7]
	v_mov_b32_e32 v5, v167
	v_lshl_add_u64 v[16:17], v[16:17], 0, v[2:3]
	v_mad_i64_i32 v[20:21], s[0:1], v20, s2, v[6:7]
	v_lshl_add_u64 v[24:25], v[24:25], 0, v[4:5]
	global_load_dwordx4 v[16:19], v[16:17], off
	v_lshl_add_u64 v[20:21], v[20:21], 0, v[2:3]
	global_load_dwordx4 v[24:27], v[24:25], off offset:256
	s_movk_i32 s4, 0x190
	global_load_dwordx4 v[20:23], v[20:21], off
	s_waitcnt vmcnt(0)
	v_mad_u64_u32 v[172:173], s[0:1], v0, s4, v[2:3]
	v_add_u32_e32 v1, 64, v29
	v_and_b32_e32 v182, 31, v184
	v_mov_b32_e32 v173, 0
	v_and_b32_e32 v171, 63, v184
	v_lshl_add_u32 v174, v0, 12, v2
	v_add_u32_e32 v175, 0x20000, v174
	v_mad_u32_u24 v176, v0, s2, v2
	v_add_u32_e32 v177, 0x30000, v176
	v_mad_u32_u24 v178, v29, s2, v4
	v_mul_u32_u24_e32 v189, 0x190, v182
	v_mov_b32_e32 v31, v173
	v_mov_b32_e32 v32, 0
	v_mov_b32_e32 v33, v173
	v_mov_b32_e32 v34, v173
	v_mov_b32_e32 v35, v173
	v_mov_b32_e32 v36, v173
	v_mov_b32_e32 v37, v173
	v_mov_b32_e32 v38, v173
	v_mov_b32_e32 v39, v173
	v_mov_b32_e32 v40, v173
	v_mov_b32_e32 v41, v173
	v_mov_b32_e32 v42, v173
	v_mov_b32_e32 v43, v173
	v_mov_b32_e32 v44, v173
	v_mov_b32_e32 v45, v173
	v_mov_b32_e32 v46, v173
	v_mov_b32_e32 v47, v173
	v_mov_b32_e32 v48, 0
	v_mov_b32_e32 v49, v173
	v_mov_b32_e32 v50, v173
	v_mov_b32_e32 v51, v173
	v_mov_b32_e32 v52, v173
	v_mov_b32_e32 v53, v173
	v_mov_b32_e32 v54, v173
	s_waitcnt vmcnt(0) lgkmcnt(0)
	ds_write_b128 v185, v[8:11]
	ds_write_b128 v186, v[12:15]
	v_mad_u64_u32 v[8:9], s[0:1], v29, s4, v[4:5]
	ds_write_b128 v172, v[16:19] offset:32768
	ds_write_b128 v172, v[20:23] offset:45568
	v_add_u32_e32 v188, 0x100, v8
	ds_write_b128 v8, v[24:27] offset:33024
	v_add_u32_e32 v8, 64, v0
	v_ashrrev_i32_e32 v9, 31, v8
	v_lshlrev_b64 v[10:11], 12, v[8:9]
	v_lshl_add_u64 v[10:11], s[82:83], 0, v[10:11]
	v_mad_i64_i32 v[8:9], s[0:1], v8, s2, v[6:7]
	v_lshl_add_u64 v[10:11], v[10:11], 0, v[2:3]
	v_lshl_add_u64 v[8:9], v[8:9], 0, v[2:3]
	global_load_dwordx4 v[144:147], v[10:11], off
	global_load_dwordx4 v[152:155], v[8:9], off
	v_add_u32_e32 v10, 0x60, v0
	v_ashrrev_i32_e32 v11, 31, v10
	v_lshlrev_b64 v[12:13], 12, v[10:11]
	v_lshl_add_u64 v[12:13], s[82:83], 0, v[12:13]
	v_mad_i64_i32 v[8:9], s[0:1], v10, s2, v[6:7]
	v_mad_i64_i32 v[6:7], s[0:1], v1, s2, v[6:7]
	v_lshl_add_u64 v[12:13], v[12:13], 0, v[2:3]
	v_lshl_add_u64 v[8:9], v[8:9], 0, v[2:3]
	v_lshl_add_u64 v[6:7], v[6:7], 0, v[4:5]
	global_load_dwordx4 v[148:151], v[12:13], off
	global_load_dwordx4 v[156:159], v[8:9], off
	global_load_dwordx4 v[160:163], v[6:7], off offset:256
	v_lshlrev_b32_e32 v1, 1, v184
	v_and_b32_e32 v1, 32, v1
	s_movk_i32 s0, 0x118
	v_and_or_b32 v1, v28, s0, v1
	v_and_or_b32 v187, v30, s77, v1
	s_add_i32 s0, s64, -1
	s_mov_b32 s1, 0
	v_mov_b32_e32 v0, 0
	v_mov_b32_e32 v1, v173
	v_mov_b32_e32 v2, v173
	v_mov_b32_e32 v3, v173
	v_mov_b32_e32 v4, v173
	v_mov_b32_e32 v5, v173
	v_mov_b32_e32 v6, v173
	v_mov_b32_e32 v7, v173
	v_mov_b32_e32 v8, v173
	v_mov_b32_e32 v9, v173
	v_mov_b32_e32 v10, v173
	v_mov_b32_e32 v11, v173
	v_mov_b32_e32 v12, v173
	v_mov_b32_e32 v13, v173
	v_mov_b32_e32 v14, v173
	v_mov_b32_e32 v15, v173
	v_mov_b32_e32 v16, 0
	v_mov_b32_e32 v17, v173
	v_mov_b32_e32 v18, v173
	v_mov_b32_e32 v19, v173
	v_mov_b32_e32 v20, v173
	v_mov_b32_e32 v21, v173
	v_mov_b32_e32 v22, v173
	v_mov_b32_e32 v23, v173
	v_mov_b32_e32 v24, v173
	v_mov_b32_e32 v25, v173
	v_mov_b32_e32 v26, v173
	v_mov_b32_e32 v27, v173
	v_mov_b32_e32 v28, v173
	v_mov_b32_e32 v29, v173
	v_mov_b32_e32 v30, v173
	v_mov_b32_e32 v55, v173
	v_mov_b32_e32 v56, v173
	v_mov_b32_e32 v57, v173
	v_mov_b32_e32 v58, v173
	v_mov_b32_e32 v59, v173
	v_mov_b32_e32 v60, v173
	v_mov_b32_e32 v61, v173
	v_mov_b32_e32 v62, v173
	v_mov_b32_e32 v63, v173
	s_waitcnt lgkmcnt(0)
	s_barrier
	s_add_u32 s34, s34, 0xc0000
	s_addc_u32 s35, s35, 0
	s_add_u32 s82, s82, 0x80000
	s_addc_u32 s83, s83, 0
	s_mov_b32 s100, 0x4000
	s_branch .LBB0_121
; #define SCHEDB() __builtin_amdgcn_sched_barrier(0)
; DEVI void qkt(f32x16& p0, f32x16& p1, const char* Ks, const bf16x8* qr, int r32, int hi) {
;   p0 = f32x16{}; p1 = f32x16{};
; #pragma unroll
;   for (int d0 = 0; d0 < 12; ++d0) { int cb = (d0 * 16 + hi * 8) * 2;
;     bf16x8 b0 = *reinterpret_cast<const bf16x8*>(Ks + KSWZ(r32, cb));
;     bf16x8 b1 = *reinterpret_cast<const bf16x8*>(Ks + KSWZ(32 + r32, cb));
;     p0 = __builtin_amdgcn_mfma_f32_32x32x16_bf16(b0, qr[d0], p0, 0, 0, 0);
;     p1 = __builtin_amdgcn_mfma_f32_32x32x16_bf16(b1, qr[d0], p1, 0, 0, 0); }
; template <bool FIX>
; DEVI void attn_item(const bfr* __restrict__ Qb, const bfr* __restrict__ Kh, const bfr* __restrict__ Vh, bfr* __restrict__ Ob, int seq, char* lds, float negBC) {
;     ...
;   for (int j = 0; j < NT; ++j) {
;     const int buf = j & 1;
;     SCHEDB(); qkt(pA0, pA1, K_lds + buf * SHM_K, qr, r32, hi);
;     if (j + 1 < NT) { SWRITE(buf ^ 1, 0); if (j + 2 < NT) SLOAD(0, (j + 2) * KVBLK); }
.LBB0_121:
	s_and_b32 s2, s1, 1
	s_mul_i32 s4, s2, 0x6400
	v_add3_u32 v191, s4, v189, v166
	s_xor_b32 s4, s2, 1
	s_mulk_i32 s4, 0x6400
	s_cmp_eq_u32 s100, 0x4000
	s_cselect_b32 s101, 0x15000, 0
	s_cmp_eq_u32 s100, 0
	s_cselect_b32 s101, 0x4000, s101
	v_add_u32_e32 v194, s101, v187
	ds_read_b128 v[196:199], v191 offset:32768
	ds_read_b128 v[200:203], v191 offset:32800
	ds_read_b128 v[204:207], v191 offset:32832
	ds_read_b128 v[224:227], v191 offset:32864
	ds_read_b128 v[228:231], v191 offset:32896
	ds_read_b128 v[232:235], v191 offset:32928
	ds_read_b128 v[236:239], v191 offset:32960
	ds_read_b128 v[240:243], v191 offset:32992
	v_cvt_pk_bf16_f32 v208, v80, v81
	v_cvt_pk_bf16_f32 v209, v82, v83
	v_cvt_pk_bf16_f32 v210, v84, v85
	v_cvt_pk_bf16_f32 v211, v86, v87
	v_cvt_pk_bf16_f32 v212, v88, v89
	v_cvt_pk_bf16_f32 v213, v90, v91
	v_cvt_pk_bf16_f32 v214, v92, v93
	v_cvt_pk_bf16_f32 v215, v94, v95
	v_cvt_pk_bf16_f32 v216, v64, v65
	v_cvt_pk_bf16_f32 v217, v66, v67
	v_cvt_pk_bf16_f32 v218, v68, v69
	v_cvt_pk_bf16_f32 v219, v70, v71
	v_cvt_pk_bf16_f32 v220, v72, v73
	v_cvt_pk_bf16_f32 v221, v74, v75
	v_cvt_pk_bf16_f32 v222, v76, v77
	v_cvt_pk_bf16_f32 v223, v78, v79
	s_nop 1
	s_waitcnt lgkmcnt(7)
	v_mfma_f32_32x32x16_bf16 v[80:95], v[196:199], v[140:143], 0
	ds_read_b128 v[244:247], v191 offset:33024
	s_waitcnt lgkmcnt(7)
	v_mfma_f32_32x32x16_bf16 v[80:95], v[200:203], v[136:139], v[80:95]
	ds_read_b128 v[248:251], v191 offset:33056
	v_add_u32_e32 v181, s100, v185
	s_waitcnt vmcnt(0)
	ds_write_b128 v181, v[144:147]
	s_waitcnt lgkmcnt(8)
	v_mfma_f32_32x32x16_bf16 v[80:95], v[204:207], v[132:135], v[80:95]
	ds_read_b128 v[196:199], v191 offset:33088
	v_add_u32_e32 v181, s100, v186
	ds_write_b128 v181, v[148:151]
	s_waitcnt lgkmcnt(9)
	v_mfma_f32_32x32x16_bf16 v[80:95], v[224:227], v[128:131], v[80:95]
	ds_read_b128 v[200:203], v191 offset:33120
	v_add_u32_e32 v181, s4, v172
	ds_write_b128 v181, v[152:155] offset:32768
	s_waitcnt lgkmcnt(10)
	v_mfma_f32_32x32x16_bf16 v[80:95], v[228:231], v[124:127], v[80:95]
	ds_read_b128 v[204:207], v191 offset:45568
	ds_write_b128 v181, v[156:159] offset:45568
	s_waitcnt lgkmcnt(11)
	v_mfma_f32_32x32x16_bf16 v[80:95], v[232:235], v[120:123], v[80:95]
	ds_read_b128 v[224:227], v191 offset:45600
	v_add_u32_e32 v181, s4, v188
	ds_write_b128 v181, v[160:163] offset:32768
	s_waitcnt lgkmcnt(12)
	v_mfma_f32_32x32x16_bf16 v[80:95], v[236:239], v[116:119], v[80:95]
	ds_read_b128 v[228:231], v191 offset:45632
	s_add_i32 s5, s1, 2
	s_cmp_ge_u32 s5, s64
	s_cbranch_scc1 .Lfa_skipload
	global_load_dwordx4 v[144:147], v174, s[82:83]
	global_load_dwordx4 v[148:151], v175, s[82:83]
	global_load_dwordx4 v[152:155], v176, s[34:35]
	global_load_dwordx4 v[156:159], v177, s[34:35]
	global_load_dwordx4 v[160:163], v178, s[34:35] offset:256
	s_add_u32 s34, s34, 0x60000
	s_addc_u32 s35, s35, 0
	s_add_u32 s82, s82, 0x40000
	s_addc_u32 s83, s83, 0

; #define SCHEDB() __builtin_amdgcn_sched_barrier(0)
; DEVI void qkt(f32x16& p0, f32x16& p1, const char* Ks, const bf16x8* qr, int r32, int hi) {
;   p0 = f32x16{}; p1 = f32x16{};
; #pragma unroll
;   for (int d0 = 0; d0 < 12; ++d0) { int cb = (d0 * 16 + hi * 8) * 2;
;     bf16x8 b0 = *reinterpret_cast<const bf16x8*>(Ks + KSWZ(r32, cb));
;     bf16x8 b1 = *reinterpret_cast<const bf16x8*>(Ks + KSWZ(32 + r32, cb));
;     p0 = __builtin_amdgcn_mfma_f32_32x32x16_bf16(b0, qr[d0], p0, 0, 0, 0);
;     p1 = __builtin_amdgcn_mfma_f32_32x32x16_bf16(b1, qr[d0], p1, 0, 0, 0); }
; template <int D0> DEVI void pv_one(f32x16& od, int vb, bf16x8 pa0, bf16x8 pa1, bf16x8 pa2, bf16x8 pa3) {
;   const s16x4 l0 = tr_read<v_rd_off(D0, 0, 0)>(vb), h0 = tr_read<v_rd_off(D0, 0, 1)>(vb), l1 = tr_read<v_rd_off(D0, 1, 0)>(vb), h1 = tr_read<v_rd_off(D0, 1, 1)>(vb);
;   const s16x4 l2 = tr_read<v_rd_off(D0, 2, 0)>(vb), h2 = tr_read<v_rd_off(D0, 2, 1)>(vb), l3 = tr_read<v_rd_off(D0, 3, 0)>(vb), h3 = tr_read<v_rd_off(D0, 3, 1)>(vb);
;   asm volatile("s_waitcnt lgkmcnt(0)" ::: "memory"); SCHEDB();
;     ...
;   od = __builtin_amdgcn_mfma_f32_32x32x16_bf16(pa0, PK(l0, h0), od, 0, 0, 0);
;   od = __builtin_amdgcn_mfma_f32_32x32x16_bf16(pa1, PK(l1, h1), od, 0, 0, 0);
;   od = __builtin_amdgcn_mfma_f32_32x32x16_bf16(pa2, PK(l2, h2), od, 0, 0, 0);
;   od = __builtin_amdgcn_mfma_f32_32x32x16_bf16(pa3, PK(l3, h3), od, 0, 0, 0);
;     ...
; }
; DEVI void pv_d0(f32x16* o, int vb, bf16x8 pa0, bf16x8 pa1, bf16x8 pa2, bf16x8 pa3) {
;   pv_one<0>(o[0], vb, pa0, pa1, pa2, pa3); pv_one<1>(o[1], vb, pa0, pa1, pa2, pa3); pv_one<2>(o[2], vb, pa0, pa1, pa2, pa3); pv_one<3>(o[3], vb, pa0, pa1, pa2, pa3);
.Lfa_drain:
	s_cmp_eq_u32 s100, 0x4000
	s_cselect_b32 s101, 0x15000, 0
	s_cmp_eq_u32 s100, 0
	s_cselect_b32 s101, 0x4000, s101
	v_add_u32_e32 v194, s101, v187
	ds_read_b64_tr_b16 v[196:197], v194 offset:0
	ds_read_b64_tr_b16 v[198:199], v194 offset:2048
	ds_read_b64_tr_b16 v[200:201], v194 offset:4096
	ds_read_b64_tr_b16 v[202:203], v194 offset:6144
	ds_read_b64_tr_b16 v[204:205], v194 offset:8192
	ds_read_b64_tr_b16 v[206:207], v194 offset:10240
	ds_read_b64_tr_b16 v[224:225], v194 offset:12288
	ds_read_b64_tr_b16 v[226:227], v194 offset:14336
	ds_read_b64_tr_b16 v[228:229], v194 offset:512
	ds_read_b64_tr_b16 v[230:231], v194 offset:2560
	v_cvt_pk_bf16_f32 v208, v80, v81
	v_cvt_pk_bf16_f32 v209, v82, v83
	v_cvt_pk_bf16_f32 v210, v84, v85
	v_cvt_pk_bf16_f32 v211, v86, v87
	v_cvt_pk_bf16_f32 v212, v88, v89
	v_cvt_pk_bf16_f32 v213, v90, v91
	v_cvt_pk_bf16_f32 v214, v92, v93
	v_cvt_pk_bf16_f32 v215, v94, v95
	v_cvt_pk_bf16_f32 v216, v64, v65
	v_cvt_pk_bf16_f32 v217, v66, v67
	v_cvt_pk_bf16_f32 v218, v68, v69
	v_cvt_pk_bf16_f32 v219, v70, v71
	v_cvt_pk_bf16_f32 v220, v72, v73
	v_cvt_pk_bf16_f32 v221, v74, v75
	v_cvt_pk_bf16_f32 v222, v76, v77
	v_cvt_pk_bf16_f32 v223, v78, v79
	s_nop 1
	s_nop 1
	s_waitcnt lgkmcnt(8)
	v_mfma_f32_32x32x16_bf16 v[0:15], v[208:211], v[196:199], v[0:15]
	ds_read_b64_tr_b16 v[232:233], v194 offset:4608
	ds_read_b64_tr_b16 v[234:235], v194 offset:6656
	s_waitcnt lgkmcnt(8)
	v_mfma_f32_32x32x16_bf16 v[0:15], v[212:215], v[200:203], v[0:15]
	ds_read_b64_tr_b16 v[236:237], v194 offset:8704
	ds_read_b64_tr_b16 v[238:239], v194 offset:10752
	s_waitcnt lgkmcnt(8)
	v_mfma_f32_32x32x16_bf16 v[0:15], v[216:219], v[204:207], v[0:15]
	ds_read_b64_tr_b16 v[240:241], v194 offset:12800
	ds_read_b64_tr_b16 v[242:243], v194 offset:14848
	s_waitcnt lgkmcnt(8)
	v_mfma_f32_32x32x16_bf16 v[0:15], v[220:223], v[224:227], v[0:15]
	ds_read_b64_tr_b16 v[244:245], v194 offset:1024
	ds_read_b64_tr_b16 v[246:247], v194 offset:3072
	s_waitcnt lgkmcnt(8)
	v_mfma_f32_32x32x16_bf16 v[16:31], v[208:211], v[228:231], v[16:31]
	ds_read_b64_tr_b16 v[248:249], v194 offset:5120
	ds_read_b64_tr_b16 v[250:251], v194 offset:7168
	s_waitcnt lgkmcnt(8)
	v_mfma_f32_32x32x16_bf16 v[16:31], v[212:215], v[232:235], v[16:31]
	ds_read_b64_tr_b16 v[196:197], v194 offset:9216
	ds_read_b64_tr_b16 v[198:199], v194 offset:11264
	s_waitcnt lgkmcnt(8)
	v_mfma_f32_32x32x16_bf16 v[16:31], v[216:219], v[236:239], v[16:31]
	ds_read_b64_tr_b16 v[200:201], v194 offset:13312
	ds_read_b64_tr_b16 v[202:203], v194 offset:15360
	s_waitcnt lgkmcnt(8)
	v_mfma_f32_32x32x16_bf16 v[16:31], v[220:223], v[240:243], v[16:31]
	ds_read_b64_tr_b16 v[204:205], v194 offset:1536
	ds_read_b64_tr_b16 v[206:207], v194 offset:3584
	s_waitcnt lgkmcnt(8)
	v_mfma_f32_32x32x16_bf16 v[32:47], v[208:211], v[244:247], v[32:47]
	ds_read_b64_tr_b16 v[224:225], v194 offset:5632
	ds_read_b64_tr_b16 v[226:227], v194 offset:7680
	s_waitcnt lgkmcnt(8)
	v_mfma_f32_32x32x16_bf16 v[32:47], v[212:215], v[248:251], v[32:47]
	ds_read_b64_tr_b16 v[228:229], v194 offset:9728
	ds_read_b64_tr_b16 v[230:231], v194 offset:11776
	s_waitcnt lgkmcnt(8)
	v_mfma_f32_32x32x16_bf16 v[32:47], v[216:219], v[196:199], v[32:47]
	ds_read_b64_tr_b16 v[232:233], v194 offset:13824
	ds_read_b64_tr_b16 v[234:235], v194 offset:15872
	s_waitcnt lgkmcnt(8)
	v_mfma_f32_32x32x16_bf16 v[32:47], v[220:223], v[200:203], v[32:47]
	s_waitcnt lgkmcnt(6)
	v_mfma_f32_32x32x16_bf16 v[48:63], v[208:211], v[204:207], v[48:63]
	s_waitcnt lgkmcnt(4)
	v_mfma_f32_32x32x16_bf16 v[48:63], v[212:215], v[224:227], v[48:63]
	s_waitcnt lgkmcnt(2)
	v_mfma_f32_32x32x16_bf16 v[48:63], v[216:219], v[228:231], v[48:63]
	s_waitcnt lgkmcnt(0)
	v_mfma_f32_32x32x16_bf16 v[48:63], v[220:223], v[232:235], v[48:63]
	s_mov_b32 s100, s101
	s_cmp_eq_u32 s100, 0x4000
	s_cselect_b32 s101, 0x15000, 0
	s_cmp_eq_u32 s100, 0
	s_cselect_b32 s101, 0x4000, s101
.LBB0_123:
	v_and_b32_e32 v64, 0x3fffffc0, v184
	v_mov_b32_e32 v65, 0x14800
	s_waitcnt vmcnt(0)
	v_lshl_add_u32 v144, v64, 2, v65
	s_and_b32 s0, s0, 1
	s_mul_i32 s1, s0, 0x6400
	v_or_b32_e32 v64, s1, v166
	v_add_u32_e32 v145, v64, v189
	ds_read_b128 v[64:67], v145 offset:32768
	v_add3_u32 v146, s1, v189, v166
	s_waitcnt lgkmcnt(0)
	v_mfma_f32_32x32x16_bf16 v[80:95], v[64:67], v[140:143], 0
	ds_read_b128 v[64:67], v146 offset:45568
	s_waitcnt lgkmcnt(0)
	v_mfma_f32_32x32x16_bf16 v[64:79], v[64:67], v[140:143], 0
	ds_read_b128 v[140:143], v145 offset:32800
	s_waitcnt lgkmcnt(0)
	v_mfma_f32_32x32x16_bf16 v[80:95], v[140:143], v[136:139], v[80:95]
	ds_read_b128 v[140:143], v146 offset:45600
	s_waitcnt lgkmcnt(0)
	v_mfma_f32_32x32x16_bf16 v[64:79], v[140:143], v[136:139], v[64:79]
	ds_read_b128 v[136:139], v145 offset:32832
	s_waitcnt lgkmcnt(0)
	v_mfma_f32_32x32x16_bf16 v[80:95], v[136:139], v[132:135], v[80:95]
	ds_read_b128 v[136:139], v146 offset:45632
	s_waitcnt lgkmcnt(0)
	v_mfma_f32_32x32x16_bf16 v[64:79], v[136:139], v[132:135], v[64:79]
	ds_read_b128 v[132:135], v145 offset:32864
	s_waitcnt lgkmcnt(0)
	v_mfma_f32_32x32x16_bf16 v[80:95], v[132:135], v[128:131], v[80:95]
	ds_read_b128 v[132:135], v146 offset:45664
	s_waitcnt lgkmcnt(0)
	v_mfma_f32_32x32x16_bf16 v[64:79], v[132:135], v[128:131], v[64:79]
	ds_read_b128 v[128:131], v145 offset:32896
	s_waitcnt lgkmcnt(0)
	v_mfma_f32_32x32x16_bf16 v[80:95], v[128:131], v[124:127], v[80:95]
	ds_read_b128 v[128:131], v146 offset:45696
	s_waitcnt lgkmcnt(0)
	v_mfma_f32_32x32x16_bf16 v[64:79], v[128:131], v[124:127], v[64:79]
	ds_read_b128 v[124:127], v145 offset:32928
	s_waitcnt lgkmcnt(0)
	v_mfma_f32_32x32x16_bf16 v[80:95], v[124:127], v[120:123], v[80:95]
	ds_read_b128 v[124:127], v146 offset:45728
	s_waitcnt lgkmcnt(0)
; DEVI void partialSM_fix(f32x16& p0, f32x16& p1) {
; #pragma unroll
;   for (int r = 0; r < 16; ++r) p0[r] = __builtin_amdgcn_exp2f(p0[r]);
; }
; DEVI void finishSM(f32x16& p0, f32x16& p1, float alpha, float& l_reg, bf16x8& pa0, bf16x8& pa1, bf16x8& pa2, bf16x8& pa3) {
; #pragma unroll
;   for (int r = 0; r < 16; ++r) p1[r] = __builtin_amdgcn_exp2f(p1[r]);
;   float ps = 0;
; #pragma unroll
;   for (int r = 0; r < 16; ++r) ps += p0[r];
; #pragma unroll
;   for (int r = 0; r < 16; ++r) ps += p1[r];
;   { auto rr = __builtin_amdgcn_permlane32_swap(__float_as_uint(ps), __float_as_uint(ps), false, false);
;     ps = __uint_as_float(rr[0]) + __uint_as_float(rr[1]); }
;   l_reg = l_reg * alpha + ps;
;     ...
;   PK4(p0, 0, pa0); PK4(p0, 8, pa1); PK4(p1, 0, pa2); PK4(p1, 8, pa3);
;     ...
; }
; template <bool FIX>
; DEVI void attn_item(const bfr* __restrict__ Qb, const bfr* __restrict__ Kh, const bfr* __restrict__ Vh, bfr* __restrict__ Ob, int seq, char* lds, float negBC) {
;     ...
;     __builtin_amdgcn_s_setprio(1); pv_d0(o, vb0 + buf * SHM_V, pa0, pa1, pa2, pa3); __builtin_amdgcn_s_setprio(0);
;     __syncthreads();
;   }
;   if (hi == 0) li_l[r32] = l_reg; asm volatile("s_waitcnt lgkmcnt(0)" ::: "memory");
	v_mfma_f32_32x32x16_bf16 v[64:79], v[124:127], v[120:123], v[64:79]
	ds_read_b128 v[120:123], v145 offset:32960
	s_waitcnt lgkmcnt(0)
	v_mfma_f32_32x32x16_bf16 v[80:95], v[120:123], v[116:119], v[80:95]
	ds_read_b128 v[120:123], v146 offset:45760
	s_waitcnt lgkmcnt(0)
	v_mfma_f32_32x32x16_bf16 v[64:79], v[120:123], v[116:119], v[64:79]
	ds_read_b128 v[116:119], v145 offset:32992
	s_waitcnt lgkmcnt(0)
	v_mfma_f32_32x32x16_bf16 v[80:95], v[116:119], v[112:115], v[80:95]
	ds_read_b128 v[116:119], v146 offset:45792
	s_waitcnt lgkmcnt(0)
	v_mfma_f32_32x32x16_bf16 v[64:79], v[116:119], v[112:115], v[64:79]
	ds_read_b128 v[112:115], v145 offset:33024
	s_waitcnt lgkmcnt(0)
	v_mfma_f32_32x32x16_bf16 v[80:95], v[112:115], v[108:111], v[80:95]
	ds_read_b128 v[112:115], v146 offset:45824
	s_waitcnt lgkmcnt(0)
	v_mfma_f32_32x32x16_bf16 v[64:79], v[112:115], v[108:111], v[64:79]
	ds_read_b128 v[108:111], v145 offset:33056
	s_waitcnt lgkmcnt(0)
	v_mfma_f32_32x32x16_bf16 v[80:95], v[108:111], v[104:107], v[80:95]
	ds_read_b128 v[108:111], v145 offset:33088
	s_waitcnt lgkmcnt(0)
	v_mfma_f32_32x32x16_bf16 v[80:95], v[108:111], v[100:103], v[80:95]
	ds_read_b128 v[108:111], v145 offset:33120
	s_waitcnt lgkmcnt(0)
	v_mfma_f32_32x32x16_bf16 v[80:95], v[108:111], v[96:99], v[80:95]
	ds_read_b128 v[108:111], v146 offset:45856
	ds_read_b128 v[112:115], v146 offset:45888
	ds_read_b128 v[116:119], v146 offset:45920
	s_nop 8
	v_exp_f32_e32 v80, v80
	s_waitcnt lgkmcnt(2)
	v_mfma_f32_32x32x16_bf16 v[64:79], v[108:111], v[104:107], v[64:79]
	v_exp_f32_e32 v81, v81
	v_exp_f32_e32 v82, v82
	v_exp_f32_e32 v83, v83
	v_exp_f32_e32 v84, v84
	v_exp_f32_e32 v85, v85
	v_exp_f32_e32 v86, v86
	v_exp_f32_e32 v87, v87
	s_waitcnt lgkmcnt(1)
	v_mfma_f32_32x32x16_bf16 v[64:79], v[112:115], v[100:103], v[64:79]
	v_exp_f32_e32 v88, v88
	v_exp_f32_e32 v89, v89
	v_exp_f32_e32 v90, v90
	v_exp_f32_e32 v91, v91
	v_exp_f32_e32 v92, v92
	v_exp_f32_e32 v93, v93
	v_exp_f32_e32 v94, v94
	s_waitcnt lgkmcnt(0)
	v_mfma_f32_32x32x16_bf16 v[64:79], v[116:119], v[96:99], v[64:79]
	v_exp_f32_e32 v95, v95
	s_nop 10
	v_exp_f32_e32 v96, v64
	v_add_f32_e32 v64, 0, v80
	v_add_f32_e32 v64, v81, v64
	v_add_f32_e32 v64, v82, v64
	v_add_f32_e32 v64, v83, v64
	v_add_f32_e32 v64, v84, v64
	v_add_f32_e32 v64, v85, v64
	v_add_f32_e32 v64, v86, v64
	v_add_f32_e32 v64, v87, v64
	v_add_f32_e32 v64, v88, v64
	v_add_f32_e32 v64, v89, v64
	v_add_f32_e32 v64, v90, v64
	v_add_f32_e32 v64, v91, v64
	v_add_f32_e32 v64, v92, v64
	v_exp_f32_e32 v97, v65
	v_add_f32_e32 v64, v93, v64
	v_exp_f32_e32 v98, v66
	v_add_f32_e32 v64, v94, v64
	v_exp_f32_e32 v99, v67
	v_add_f32_e32 v64, v95, v64
	v_exp_f32_e32 v100, v68
	v_add_f32_e32 v64, v96, v64
	v_exp_f32_e32 v101, v69
	v_add_f32_e32 v64, v97, v64
	v_exp_f32_e32 v102, v70
	v_add_f32_e32 v64, v98, v64
	v_exp_f32_e32 v103, v71
	v_add_f32_e32 v64, v99, v64
	v_exp_f32_e32 v104, v72
	v_add_f32_e32 v64, v100, v64
	v_exp_f32_e32 v105, v73
	v_add_f32_e32 v64, v101, v64
	v_exp_f32_e32 v106, v74
	v_add_f32_e32 v64, v102, v64
	v_exp_f32_e32 v107, v75
	v_add_f32_e32 v64, v103, v64
	v_exp_f32_e32 v108, v76
	v_add_f32_e32 v64, v104, v64
	v_exp_f32_e32 v109, v77
	v_add_f32_e32 v64, v105, v64
	v_exp_f32_e32 v110, v78
	v_add_f32_e32 v64, v106, v64
	v_exp_f32_e32 v111, v79
	v_add_f32_e32 v64, v107, v64
	v_add_f32_e32 v64, v108, v64
	v_add_f32_e32 v64, v109, v64
	v_add_f32_e32 v64, v110, v64
	v_add_f32_e32 v64, v111, v64
	v_mov_b32_e32 v65, v64
	s_nop 1
	v_permlane32_swap_b32_e32 v64, v65
	v_cvt_pk_bf16_f32 v66, v80, v81
	v_cvt_pk_bf16_f32 v67, v82, v83
	v_cvt_pk_bf16_f32 v68, v84, v85
	v_cvt_pk_bf16_f32 v69, v86, v87
	v_cvt_pk_bf16_f32 v70, v88, v89
	v_cvt_pk_bf16_f32 v71, v90, v91
	v_cvt_pk_bf16_f32 v72, v92, v93
	v_cvt_pk_bf16_f32 v73, v94, v95
	v_cvt_pk_bf16_f32 v74, v96, v97
	v_cvt_pk_bf16_f32 v75, v98, v99
	v_cvt_pk_bf16_f32 v76, v100, v101
	v_cvt_pk_bf16_f32 v77, v102, v103
	v_cvt_pk_bf16_f32 v78, v104, v105
	v_cvt_pk_bf16_f32 v79, v106, v107
	v_cvt_pk_bf16_f32 v80, v108, v109
	v_cvt_pk_bf16_f32 v81, v110, v111
	s_nop 0
	s_setprio 1
	v_add_u32_e32 v98, s101, v187
	ds_read_b64_tr_b16 v[82:83], v98 offset:0
	ds_read_b64_tr_b16 v[84:85], v98 offset:0x800
	ds_read_b64_tr_b16 v[86:87], v98 offset:0x1000
	ds_read_b64_tr_b16 v[88:89], v98 offset:0x1800
	ds_read_b64_tr_b16 v[90:91], v98 offset:0x2000
	ds_read_b64_tr_b16 v[92:93], v98 offset:0x2800
	ds_read_b64_tr_b16 v[94:95], v98 offset:0x3000
	ds_read_b64_tr_b16 v[96:97], v98 offset:0x3800
	s_waitcnt lgkmcnt(0)
	s_nop 0
	v_mfma_f32_32x32x16_bf16 v[0:15], v[66:69], v[82:85], v[0:15]
	ds_read_b64_tr_b16 v[82:83], v98 offset:0x200
	ds_read_b64_tr_b16 v[84:85], v98 offset:0xa00
	v_mfma_f32_32x32x16_bf16 v[0:15], v[70:73], v[86:89], v[0:15]
	ds_read_b64_tr_b16 v[86:87], v98 offset:0x1200
	ds_read_b64_tr_b16 v[88:89], v98 offset:0x1a00
	v_mfma_f32_32x32x16_bf16 v[0:15], v[74:77], v[90:93], v[0:15]
	ds_read_b64_tr_b16 v[90:91], v98 offset:0x2200
	ds_read_b64_tr_b16 v[92:93], v98 offset:0x2a00
	v_mfma_f32_32x32x16_bf16 v[0:15], v[78:81], v[94:97], v[0:15]
	ds_read_b64_tr_b16 v[94:95], v98 offset:0x3200
	ds_read_b64_tr_b16 v[96:97], v98 offset:0x3a00
	s_waitcnt lgkmcnt(0)
	v_mfma_f32_32x32x16_bf16 v[16:31], v[66:69], v[82:85], v[16:31]
	ds_read_b64_tr_b16 v[82:83], v98 offset:0x400
	ds_read_b64_tr_b16 v[84:85], v98 offset:0xc00
	v_mfma_f32_32x32x16_bf16 v[16:31], v[70:73], v[86:89], v[16:31]
	ds_read_b64_tr_b16 v[86:87], v98 offset:0x1400
	ds_read_b64_tr_b16 v[88:89], v98 offset:0x1c00
	v_mfma_f32_32x32x16_bf16 v[16:31], v[74:77], v[90:93], v[16:31]
	ds_read_b64_tr_b16 v[90:91], v98 offset:0x2400
	ds_read_b64_tr_b16 v[92:93], v98 offset:0x2c00
	v_mfma_f32_32x32x16_bf16 v[16:31], v[78:81], v[94:97], v[16:31]
	ds_read_b64_tr_b16 v[94:95], v98 offset:0x3400
	ds_read_b64_tr_b16 v[96:97], v98 offset:0x3c00
	s_waitcnt lgkmcnt(0)
	v_mfma_f32_32x32x16_bf16 v[32:47], v[66:69], v[82:85], v[32:47]
	ds_read_b64_tr_b16 v[82:83], v98 offset:0x600
	ds_read_b64_tr_b16 v[84:85], v98 offset:0xe00
	v_mfma_f32_32x32x16_bf16 v[32:47], v[70:73], v[86:89], v[32:47]
	ds_read_b64_tr_b16 v[86:87], v98 offset:0x1600
	ds_read_b64_tr_b16 v[88:89], v98 offset:0x1e00
	v_mfma_f32_32x32x16_bf16 v[32:47], v[74:77], v[90:93], v[32:47]
	ds_read_b64_tr_b16 v[90:91], v98 offset:0x2600
	ds_read_b64_tr_b16 v[92:93], v98 offset:0x2e00
	v_mfma_f32_32x32x16_bf16 v[32:47], v[78:81], v[94:97], v[32:47]
	ds_read_b64_tr_b16 v[94:95], v98 offset:0x3600
	ds_read_b64_tr_b16 v[96:97], v98 offset:0x3e00
	s_waitcnt lgkmcnt(0)
	v_mfma_f32_32x32x16_bf16 v[48:63], v[66:69], v[82:85], v[48:63]
	v_mfma_f32_32x32x16_bf16 v[48:63], v[70:73], v[86:89], v[48:63]
	v_mfma_f32_32x32x16_bf16 v[48:63], v[74:77], v[90:93], v[48:63]
	v_mfma_f32_32x32x16_bf16 v[48:63], v[78:81], v[94:97], v[48:63]
	s_setprio 0
	v_cmp_gt_u32_e32 vcc, 32, v171
	s_barrier
	s_and_saveexec_b64 s[0:1], vcc
	s_cbranch_execz .LBB0_94
	v_add_f32_e32 v64, v64, v65
	v_lshl_add_u32 v66, v182, 2, v144
	v_add_f32_e32 v64, v173, v64
	ds_write_b32 v66, v64
	s_branch .LBB0_94

; #define P8_STAGE(P,BASE,br,kt) do{const bfr* _ub=(BASE)+((long)(br)*K+(long)(kt)*BK); \
;     __builtin_amdgcn_global_load_lds((const unsigned*)(_ub+so0),(unsigned*)((char*)(P)+wid*1024),16,0,0); \
;     __builtin_amdgcn_global_load_lds((const unsigned*)(_ub+so1),(unsigned*)((char*)(P)+wid*1024+8192),16,0,0);}while(0)
; #define P8_LDA(dst,b,h) _Pragma("unroll") for(int m=0;m<4;++m) _Pragma("unroll") for(int k=0;k<2;++k) \
;     dst[m][k]=*reinterpret_cast<const bf16x8*>((char*)P8_SA(b,h)+lds_byte(wr*64+m*16+fr,k*32+fq*8))
; #define P8_LDB(dst,b,h) _Pragma("unroll") for(int n=0;n<2;++n) _Pragma("unroll") for(int k=0;k<2;++k) \
;     dst[n][k]=*reinterpret_cast<const bf16x8*>((char*)P8_SB(b,h)+lds_byte(wc*32+n*16+fr,k*32+fq*8))
; #define P8_MMA(ai,bj,At,Bt) do{__builtin_amdgcn_s_setprio(1); \
;     _Pragma("unroll") for(int m=0;m<4;++m) _Pragma("unroll") for(int n=0;n<2;++n) _Pragma("unroll") for(int k=0;k<2;++k) \
;       acc[ai][bj][m][n]=__builtin_amdgcn_mfma_f32_16x16x32_bf16(At[m][k],Bt[n][k],acc[ai][bj][m][n],0,0,0); \
;     __builtin_amdgcn_s_setprio(0);}while(0)
; #define P8_WAIT_V(n) asm volatile("s_waitcnt vmcnt(" #n ")":::"memory")
; #define P8_WAIT_L(n) asm volatile("s_waitcnt lgkmcnt(" #n ")":::"memory")
; #define P8_BAR __builtin_amdgcn_s_barrier()
; #define P8_SCHED __builtin_amdgcn_sched_barrier(0)
; template <class EPI>
; DEVI void gemm8_tile(const bfr* __restrict__ A, const bfr* __restrict__ Bt, int K, int brow, int bcol, int nbrow, int nbcol, char* shmc, EPI epi) {
;     ...
;     P8_LDB(B0,0,0); P8_SCHED; P8_LDA(At,0,0); P8_STAGE(P8_SA(1,1),A,brow+128,t+1);
;     P8_WAIT_L(8); P8_BAR; P8_WAIT_L(0); P8_MMA(0,0,At,B0); P8_BAR; P8_SCHED;
;     P8_LDB(B1,0,1); P8_STAGE(P8_SB(0,0),Bt,bcol,t+2);
;     P8_BAR; P8_WAIT_L(0); P8_MMA(0,1,At,B1); P8_BAR;
;     P8_LDA(At,0,1); P8_STAGE(P8_SA(0,0),A,brow,t+2);
;     P8_BAR; P8_WAIT_L(0); P8_MMA(1,0,At,B0); P8_BAR; P8_SCHED;
;     P8_STAGE(P8_SB(0,1),Bt,bcol+128,t+2);
;     P8_WAIT_V(6); P8_BAR; P8_MMA(1,1,At,B1); P8_BAR;
.LBB0_141:
	ds_read_b128 v[174:177], v157
	ds_read_b128 v[178:181], v157 offset:1024
	ds_read_b128 v[182:185], v157 offset:2048
	ds_read_b128 v[186:189], v157 offset:3072
	v_add_u32_e32 v171, 0xc000, v143
	v_add_u32_e32 v172, 0xe000, v143
	v_add_u32_e32 v158, s8, v136
	s_add_i32 m0, s100, 0xc000
	ds_read_b128 v[160:163], v147
	ds_read_b128 v[190:193], v147 offset:1024
	ds_read_b128 v[196:199], v146
	ds_read_b128 v[208:211], v146 offset:1024
	ds_read_b128 v[212:215], v145
	ds_read_b128 v[216:219], v145 offset:1024
	ds_read_b128 v[220:223], v144
	ds_read_b128 v[224:227], v144 offset:1024
	global_load_lds_dwordx4 v158, s[86:87]
	v_add_u32_e32 v158, s8, v134
	s_add_i32 m0, s100, 0xe000
	s_nop 0
	global_load_lds_dwordx4 v158, s[86:87]
	s_waitcnt lgkmcnt(8)
	s_barrier
	s_waitcnt lgkmcnt(0)
	v_mfma_f32_16x16x32_bf16 v[124:127], v[160:163], v[174:177], v[124:127]
	v_mfma_f32_16x16x32_bf16 v[120:123], v[160:163], v[182:185], v[120:123]
	v_mfma_f32_16x16x32_bf16 v[116:119], v[196:199], v[174:177], v[116:119]
	v_mfma_f32_16x16x32_bf16 v[112:115], v[196:199], v[182:185], v[112:115]
	v_mfma_f32_16x16x32_bf16 v[108:111], v[212:215], v[174:177], v[108:111]
	v_mfma_f32_16x16x32_bf16 v[104:107], v[212:215], v[182:185], v[104:107]
	v_mfma_f32_16x16x32_bf16 v[100:103], v[220:223], v[174:177], v[100:103]
	v_mfma_f32_16x16x32_bf16 v[96:99], v[220:223], v[182:185], v[96:99]
	v_mfma_f32_16x16x32_bf16 v[124:127], v[190:193], v[178:181], v[124:127]
	v_mfma_f32_16x16x32_bf16 v[120:123], v[190:193], v[186:189], v[120:123]
	v_mfma_f32_16x16x32_bf16 v[116:119], v[208:211], v[178:181], v[116:119]
	v_mfma_f32_16x16x32_bf16 v[112:115], v[208:211], v[186:189], v[112:115]
	v_mfma_f32_16x16x32_bf16 v[108:111], v[216:219], v[178:181], v[108:111]
	v_mfma_f32_16x16x32_bf16 v[104:107], v[216:219], v[186:189], v[104:107]
	v_mfma_f32_16x16x32_bf16 v[100:103], v[224:227], v[178:181], v[100:103]
	v_mfma_f32_16x16x32_bf16 v[96:99], v[224:227], v[186:189], v[96:99]
	s_barrier
	v_add_u32_e32 v158, 0x10000, v143
	v_add_u32_e32 v206, s66, v140
	s_add_i32 m0, s100, 0x10000
	v_add_u32_e32 v159, 0x12000, v143
	ds_read_b128 v[228:231], v154
	ds_read_b128 v[232:235], v154 offset:1024
	ds_read_b128 v[236:239], v154 offset:2048
	ds_read_b128 v[240:243], v154 offset:3072
	global_load_lds_dwordx4 v206, s[86:87]
	v_add_u32_e32 v244, s66, v138
	s_add_i32 m0, s100, 0x12000
	s_nop 0
	global_load_lds_dwordx4 v244, s[86:87]
	s_barrier
	s_waitcnt lgkmcnt(0)
	v_mfma_f32_16x16x32_bf16 v[92:95], v[160:163], v[228:231], v[92:95]
	v_mfma_f32_16x16x32_bf16 v[88:91], v[160:163], v[236:239], v[88:91]
	v_mfma_f32_16x16x32_bf16 v[84:87], v[196:199], v[228:231], v[84:87]
	v_mfma_f32_16x16x32_bf16 v[80:83], v[196:199], v[236:239], v[80:83]
	v_mfma_f32_16x16x32_bf16 v[76:79], v[212:215], v[228:231], v[76:79]
	v_mfma_f32_16x16x32_bf16 v[72:75], v[212:215], v[236:239], v[72:75]
	v_mfma_f32_16x16x32_bf16 v[68:71], v[220:223], v[228:231], v[68:71]
	v_mfma_f32_16x16x32_bf16 v[64:67], v[220:223], v[236:239], v[64:67]
	v_mfma_f32_16x16x32_bf16 v[92:95], v[190:193], v[232:235], v[92:95]
	v_mfma_f32_16x16x32_bf16 v[88:91], v[190:193], v[240:243], v[88:91]
	v_mfma_f32_16x16x32_bf16 v[84:87], v[208:211], v[232:235], v[84:87]
	v_mfma_f32_16x16x32_bf16 v[80:83], v[208:211], v[240:243], v[80:83]
	v_mfma_f32_16x16x32_bf16 v[76:79], v[216:219], v[232:235], v[76:79]
	v_mfma_f32_16x16x32_bf16 v[72:75], v[216:219], v[240:243], v[72:75]
	v_mfma_f32_16x16x32_bf16 v[68:71], v[224:227], v[232:235], v[68:71]
	v_mfma_f32_16x16x32_bf16 v[64:67], v[224:227], v[240:243], v[64:67]
	v_add_u32_e32 v160, s54, v136
	s_mov_b32 m0, s100
	s_barrier
	ds_read_b128 v[190:193], v147 offset:16384
	ds_read_b128 v[196:199], v147 offset:17408
	ds_read_b128 v[208:211], v146 offset:16384
	ds_read_b128 v[212:215], v146 offset:17408
	ds_read_b128 v[216:219], v145 offset:16384
	ds_read_b128 v[220:223], v145 offset:17408
	ds_read_b128 v[224:227], v144 offset:16384
	ds_read_b128 v[244:247], v144 offset:17408
	global_load_lds_dwordx4 v160, s[86:87]
	v_add_u32_e32 v160, 0x2000, v143
	v_add_u32_e32 v162, s54, v134
	s_add_i32 m0, s100, 0x2000
	s_nop 0
	global_load_lds_dwordx4 v162, s[86:87]
	s_barrier
	s_waitcnt lgkmcnt(0)
	v_mfma_f32_16x16x32_bf16 v[60:63], v[190:193], v[174:177], v[60:63]
	v_mfma_f32_16x16x32_bf16 v[56:59], v[190:193], v[182:185], v[56:59]
	v_mfma_f32_16x16x32_bf16 v[52:55], v[208:211], v[174:177], v[52:55]
	v_mfma_f32_16x16x32_bf16 v[48:51], v[208:211], v[182:185], v[48:51]
	v_mfma_f32_16x16x32_bf16 v[44:47], v[216:219], v[174:177], v[44:47]
	v_mfma_f32_16x16x32_bf16 v[40:43], v[216:219], v[182:185], v[40:43]
	v_mfma_f32_16x16x32_bf16 v[36:39], v[224:227], v[174:177], v[36:39]
	v_mfma_f32_16x16x32_bf16 v[32:35], v[224:227], v[182:185], v[32:35]
	v_mfma_f32_16x16x32_bf16 v[60:63], v[196:199], v[178:181], v[60:63]
	v_mfma_f32_16x16x32_bf16 v[56:59], v[196:199], v[186:189], v[56:59]
	v_mfma_f32_16x16x32_bf16 v[52:55], v[212:215], v[178:181], v[52:55]
	v_mfma_f32_16x16x32_bf16 v[48:51], v[212:215], v[186:189], v[48:51]
	v_mfma_f32_16x16x32_bf16 v[44:47], v[220:223], v[178:181], v[44:47]
	v_mfma_f32_16x16x32_bf16 v[40:43], v[220:223], v[186:189], v[40:43]
	v_mfma_f32_16x16x32_bf16 v[36:39], v[244:247], v[178:181], v[36:39]
	v_mfma_f32_16x16x32_bf16 v[32:35], v[244:247], v[186:189], v[32:35]
	s_barrier
	v_add_u32_e32 v161, 0x14000, v143
	v_add_u32_e32 v162, s60, v140
	s_add_i32 m0, s100, 0x14000
	v_add_u32_e32 v174, s60, v138
	global_load_lds_dwordx4 v162, s[86:87]
	v_add_u32_e32 v162, 0x16000, v143
	s_nop 0
	s_add_i32 m0, s100, 0x16000
	s_nop 0
	global_load_lds_dwordx4 v174, s[86:87]
	s_waitcnt vmcnt(6)
	s_barrier
; #define P8_STAGE(P,BASE,br,kt) do{const bfr* _ub=(BASE)+((long)(br)*K+(long)(kt)*BK); \
;     __builtin_amdgcn_global_load_lds((const unsigned*)(_ub+so0),(unsigned*)((char*)(P)+wid*1024),16,0,0); \
;     __builtin_amdgcn_global_load_lds((const unsigned*)(_ub+so1),(unsigned*)((char*)(P)+wid*1024+8192),16,0,0);}while(0)
; #define P8_LDA(dst,b,h) _Pragma("unroll") for(int m=0;m<4;++m) _Pragma("unroll") for(int k=0;k<2;++k) \
;     dst[m][k]=*reinterpret_cast<const bf16x8*>((char*)P8_SA(b,h)+lds_byte(wr*64+m*16+fr,k*32+fq*8))
; #define P8_LDB(dst,b,h) _Pragma("unroll") for(int n=0;n<2;++n) _Pragma("unroll") for(int k=0;k<2;++k) \
;     dst[n][k]=*reinterpret_cast<const bf16x8*>((char*)P8_SB(b,h)+lds_byte(wc*32+n*16+fr,k*32+fq*8))
; #define P8_MMA(ai,bj,At,Bt) do{__builtin_amdgcn_s_setprio(1); \
;     _Pragma("unroll") for(int m=0;m<4;++m) _Pragma("unroll") for(int n=0;n<2;++n) _Pragma("unroll") for(int k=0;k<2;++k) \
;       acc[ai][bj][m][n]=__builtin_amdgcn_mfma_f32_16x16x32_bf16(At[m][k],Bt[n][k],acc[ai][bj][m][n],0,0,0); \
;     __builtin_amdgcn_s_setprio(0);}while(0)
; #define P8_WAIT_V(n) asm volatile("s_waitcnt vmcnt(" #n ")":::"memory")
; #define P8_WAIT_L(n) asm volatile("s_waitcnt lgkmcnt(" #n ")":::"memory")
; #define P8_BAR __builtin_amdgcn_s_barrier()
; #define P8_SCHED __builtin_amdgcn_sched_barrier(0)
; template <class EPI>
; DEVI void gemm8_tile(const bfr* __restrict__ A, const bfr* __restrict__ Bt, int K, int brow, int bcol, int nbrow, int nbcol, char* shmc, EPI epi) {
;     ...
;     P8_WAIT_V(6); P8_BAR; P8_MMA(1,1,At,B1); P8_BAR;
;     P8_LDB(B0,1,0); P8_SCHED; P8_LDA(At,1,0); P8_STAGE(P8_SA(0,1),A,brow+128,t+2);
;     P8_WAIT_L(8); P8_BAR; P8_WAIT_L(0); P8_MMA(0,0,At,B0); P8_BAR; P8_SCHED;
;     P8_LDB(B1,1,1); P8_STAGE(P8_SB(1,0),Bt,bcol,t+3);
;     P8_BAR; P8_WAIT_L(0); P8_MMA(0,1,At,B1); P8_BAR;
;     P8_LDA(At,1,1); P8_STAGE(P8_SA(1,0),A,brow,t+3);
	v_mfma_f32_16x16x32_bf16 v[28:31], v[190:193], v[228:231], v[28:31]
	v_mfma_f32_16x16x32_bf16 v[24:27], v[190:193], v[236:239], v[24:27]
	v_mfma_f32_16x16x32_bf16 v[20:23], v[208:211], v[228:231], v[20:23]
	v_mfma_f32_16x16x32_bf16 v[16:19], v[208:211], v[236:239], v[16:19]
	v_mfma_f32_16x16x32_bf16 v[12:15], v[216:219], v[228:231], v[12:15]
	v_mfma_f32_16x16x32_bf16 v[8:11], v[216:219], v[236:239], v[8:11]
	v_mfma_f32_16x16x32_bf16 v[4:7], v[224:227], v[228:231], v[4:7]
	v_mfma_f32_16x16x32_bf16 v[0:3], v[224:227], v[236:239], v[0:3]
	v_mfma_f32_16x16x32_bf16 v[28:31], v[196:199], v[232:235], v[28:31]
	v_mfma_f32_16x16x32_bf16 v[24:27], v[196:199], v[240:243], v[24:27]
	v_mfma_f32_16x16x32_bf16 v[20:23], v[212:215], v[232:235], v[20:23]
	v_mfma_f32_16x16x32_bf16 v[16:19], v[212:215], v[240:243], v[16:19]
	v_mfma_f32_16x16x32_bf16 v[12:15], v[220:223], v[232:235], v[12:15]
	v_mfma_f32_16x16x32_bf16 v[8:11], v[220:223], v[240:243], v[8:11]
	v_mfma_f32_16x16x32_bf16 v[4:7], v[244:247], v[232:235], v[4:7]
	v_mfma_f32_16x16x32_bf16 v[0:3], v[244:247], v[240:243], v[0:3]
	s_barrier
	ds_read_b128 v[174:177], v149
	ds_read_b128 v[178:181], v149 offset:1024
	ds_read_b128 v[182:185], v149 offset:2048
	ds_read_b128 v[186:189], v149 offset:3072
	v_add_u32_e32 v163, 0x4000, v143
	v_add_u32_e32 v170, 0x6000, v143
	v_add_u32_e32 v232, s72, v136
	s_add_i32 m0, s100, 0x4000
	ds_read_b128 v[190:193], v147 offset:32768
	ds_read_b128 v[196:199], v147 offset:33792
	ds_read_b128 v[208:211], v146 offset:32768
	ds_read_b128 v[212:215], v146 offset:33792
	ds_read_b128 v[216:219], v145 offset:32768
	ds_read_b128 v[220:223], v145 offset:33792
	ds_read_b128 v[224:227], v144 offset:32768
	ds_read_b128 v[228:231], v144 offset:33792
	global_load_lds_dwordx4 v232, s[86:87]
	v_add_u32_e32 v232, s72, v134
	s_add_i32 m0, s100, 0x6000
	s_nop 0
	global_load_lds_dwordx4 v232, s[86:87]
	s_waitcnt lgkmcnt(8)
	s_barrier
	s_waitcnt lgkmcnt(0)
	v_mfma_f32_16x16x32_bf16 v[124:127], v[190:193], v[174:177], v[124:127]
	v_mfma_f32_16x16x32_bf16 v[120:123], v[190:193], v[182:185], v[120:123]
	v_mfma_f32_16x16x32_bf16 v[116:119], v[208:211], v[174:177], v[116:119]
	v_mfma_f32_16x16x32_bf16 v[112:115], v[208:211], v[182:185], v[112:115]
	v_mfma_f32_16x16x32_bf16 v[108:111], v[216:219], v[174:177], v[108:111]
	v_mfma_f32_16x16x32_bf16 v[104:107], v[216:219], v[182:185], v[104:107]
	v_mfma_f32_16x16x32_bf16 v[100:103], v[224:227], v[174:177], v[100:103]
	v_mfma_f32_16x16x32_bf16 v[96:99], v[224:227], v[182:185], v[96:99]
	v_mfma_f32_16x16x32_bf16 v[124:127], v[196:199], v[178:181], v[124:127]
	v_mfma_f32_16x16x32_bf16 v[120:123], v[196:199], v[186:189], v[120:123]
	v_mfma_f32_16x16x32_bf16 v[116:119], v[212:215], v[178:181], v[116:119]
	v_mfma_f32_16x16x32_bf16 v[112:115], v[212:215], v[186:189], v[112:115]
	v_mfma_f32_16x16x32_bf16 v[108:111], v[220:223], v[178:181], v[108:111]
	v_mfma_f32_16x16x32_bf16 v[104:107], v[220:223], v[186:189], v[104:107]
	v_mfma_f32_16x16x32_bf16 v[100:103], v[228:231], v[178:181], v[100:103]
	v_mfma_f32_16x16x32_bf16 v[96:99], v[228:231], v[186:189], v[96:99]
	s_barrier
	v_add_u32_e32 v248, s74, v140
	s_add_i32 m0, s100, 0x18000
	ds_read_b128 v[232:235], v148
	ds_read_b128 v[236:239], v148 offset:1024
	ds_read_b128 v[240:243], v148 offset:2048
	ds_read_b128 v[244:247], v148 offset:3072
	global_load_lds_dwordx4 v248, s[86:87]
	v_add_u32_e32 v248, s74, v138
	s_add_i32 m0, s100, 0x1a000
	s_nop 0
	global_load_lds_dwordx4 v248, s[86:87]
	s_barrier
	s_waitcnt lgkmcnt(0)
	v_mfma_f32_16x16x32_bf16 v[92:95], v[190:193], v[232:235], v[92:95]
	v_mfma_f32_16x16x32_bf16 v[88:91], v[190:193], v[240:243], v[88:91]
	v_mfma_f32_16x16x32_bf16 v[84:87], v[208:211], v[232:235], v[84:87]
	v_mfma_f32_16x16x32_bf16 v[80:83], v[208:211], v[240:243], v[80:83]
	v_mfma_f32_16x16x32_bf16 v[76:79], v[216:219], v[232:235], v[76:79]
	v_mfma_f32_16x16x32_bf16 v[72:75], v[216:219], v[240:243], v[72:75]
	v_mfma_f32_16x16x32_bf16 v[68:71], v[224:227], v[232:235], v[68:71]
	v_mfma_f32_16x16x32_bf16 v[64:67], v[224:227], v[240:243], v[64:67]
	v_mfma_f32_16x16x32_bf16 v[92:95], v[196:199], v[236:239], v[92:95]
	v_mfma_f32_16x16x32_bf16 v[88:91], v[196:199], v[244:247], v[88:91]
	v_mfma_f32_16x16x32_bf16 v[84:87], v[212:215], v[236:239], v[84:87]
	v_mfma_f32_16x16x32_bf16 v[80:83], v[212:215], v[244:247], v[80:83]
	v_mfma_f32_16x16x32_bf16 v[76:79], v[220:223], v[236:239], v[76:79]
	v_mfma_f32_16x16x32_bf16 v[72:75], v[220:223], v[244:247], v[72:75]
	v_mfma_f32_16x16x32_bf16 v[68:71], v[228:231], v[236:239], v[68:71]
	v_mfma_f32_16x16x32_bf16 v[64:67], v[228:231], v[244:247], v[64:67]
	v_add_u32_e32 v200, s92, v136
	s_add_i32 m0, s100, 0x8000
	s_barrier
	ds_read_b128 v[190:193], v147 offset:49152
	ds_read_b128 v[196:199], v147 offset:50176
	ds_read_b128 v[208:211], v146 offset:49152
	ds_read_b128 v[212:215], v146 offset:50176
	ds_read_b128 v[216:219], v145 offset:49152
	ds_read_b128 v[220:223], v145 offset:50176
	ds_read_b128 v[224:227], v144 offset:49152
	ds_read_b128 v[228:231], v144 offset:50176
	global_load_lds_dwordx4 v200, s[86:87]
	v_add_u32_e32 v200, s92, v134
	s_add_i32 m0, s100, 0xa000
	s_nop 0
	global_load_lds_dwordx4 v200, s[86:87]
	s_barrier
; #define P8_STAGE(P,BASE,br,kt) do{const bfr* _ub=(BASE)+((long)(br)*K+(long)(kt)*BK); \
;     __builtin_amdgcn_global_load_lds((const unsigned*)(_ub+so0),(unsigned*)((char*)(P)+wid*1024),16,0,0); \
;     __builtin_amdgcn_global_load_lds((const unsigned*)(_ub+so1),(unsigned*)((char*)(P)+wid*1024+8192),16,0,0);}while(0)
; #define P8_LDA(dst,b,h) _Pragma("unroll") for(int m=0;m<4;++m) _Pragma("unroll") for(int k=0;k<2;++k) \
;     dst[m][k]=*reinterpret_cast<const bf16x8*>((char*)P8_SA(b,h)+lds_byte(wr*64+m*16+fr,k*32+fq*8))
; #define P8_LDB(dst,b,h) _Pragma("unroll") for(int n=0;n<2;++n) _Pragma("unroll") for(int k=0;k<2;++k) \
;     dst[n][k]=*reinterpret_cast<const bf16x8*>((char*)P8_SB(b,h)+lds_byte(wc*32+n*16+fr,k*32+fq*8))
; #define P8_MMA(ai,bj,At,Bt) do{__builtin_amdgcn_s_setprio(1); \
;     _Pragma("unroll") for(int m=0;m<4;++m) _Pragma("unroll") for(int n=0;n<2;++n) _Pragma("unroll") for(int k=0;k<2;++k) \
;       acc[ai][bj][m][n]=__builtin_amdgcn_mfma_f32_16x16x32_bf16(At[m][k],Bt[n][k],acc[ai][bj][m][n],0,0,0); \
;     __builtin_amdgcn_s_setprio(0);}while(0)
; #define P8_WAIT_V(n) asm volatile("s_waitcnt vmcnt(" #n ")":::"memory")
; #define P8_WAIT_L(n) asm volatile("s_waitcnt lgkmcnt(" #n ")":::"memory")
; #define P8_BAR __builtin_amdgcn_s_barrier()
; #define P8_SCHED __builtin_amdgcn_sched_barrier(0)
; template <class EPI>
; DEVI void gemm8_tile(const bfr* __restrict__ A, const bfr* __restrict__ Bt, int K, int brow, int bcol, int nbrow, int nbcol, char* shmc, EPI epi) {
;     ...
;     P8_BAR; P8_WAIT_L(0); P8_MMA(1,0,At,B0); P8_BAR; P8_SCHED;
;     P8_STAGE(P8_SB(1,1),Bt,bcol+128,t+3);
;     P8_WAIT_V(6); P8_BAR; P8_MMA(1,1,At,B1); P8_BAR;
;   }
;   { P8_LDB(B0,0,0); P8_LDA(At,0,0); P8_STAGE(P8_SA(1,1),A,brow+128,nt-1);
;     P8_BAR; P8_WAIT_L(0); P8_MMA(0,0,At,B0); P8_BAR;
;     P8_LDB(B1,0,1); P8_BAR; P8_WAIT_L(0); P8_MMA(0,1,At,B1); P8_BAR;
	s_waitcnt lgkmcnt(0)
	v_mfma_f32_16x16x32_bf16 v[60:63], v[190:193], v[174:177], v[60:63]
	v_mfma_f32_16x16x32_bf16 v[56:59], v[190:193], v[182:185], v[56:59]
	v_mfma_f32_16x16x32_bf16 v[52:55], v[208:211], v[174:177], v[52:55]
	v_mfma_f32_16x16x32_bf16 v[48:51], v[208:211], v[182:185], v[48:51]
	v_mfma_f32_16x16x32_bf16 v[44:47], v[216:219], v[174:177], v[44:47]
	v_mfma_f32_16x16x32_bf16 v[40:43], v[216:219], v[182:185], v[40:43]
	v_mfma_f32_16x16x32_bf16 v[36:39], v[224:227], v[174:177], v[36:39]
	v_mfma_f32_16x16x32_bf16 v[32:35], v[224:227], v[182:185], v[32:35]
	v_mfma_f32_16x16x32_bf16 v[60:63], v[196:199], v[178:181], v[60:63]
	v_mfma_f32_16x16x32_bf16 v[56:59], v[196:199], v[186:189], v[56:59]
	v_mfma_f32_16x16x32_bf16 v[52:55], v[212:215], v[178:181], v[52:55]
	v_mfma_f32_16x16x32_bf16 v[48:51], v[212:215], v[186:189], v[48:51]
	v_mfma_f32_16x16x32_bf16 v[44:47], v[220:223], v[178:181], v[44:47]
	v_mfma_f32_16x16x32_bf16 v[40:43], v[220:223], v[186:189], v[40:43]
	v_mfma_f32_16x16x32_bf16 v[36:39], v[228:231], v[178:181], v[36:39]
	v_mfma_f32_16x16x32_bf16 v[32:35], v[228:231], v[186:189], v[32:35]
	s_barrier
	v_add_u32_e32 v174, s94, v140
	s_add_i32 m0, s100, 0x1c000
	s_nop 0
	global_load_lds_dwordx4 v174, s[86:87]
	v_add_u32_e32 v174, s94, v138
	s_add_i32 m0, s100, 0x1e000
	s_nop 0
	global_load_lds_dwordx4 v174, s[86:87]
	s_waitcnt vmcnt(6)
	s_barrier
	v_mfma_f32_16x16x32_bf16 v[28:31], v[190:193], v[232:235], v[28:31]
	v_mfma_f32_16x16x32_bf16 v[24:27], v[190:193], v[240:243], v[24:27]
	v_mfma_f32_16x16x32_bf16 v[20:23], v[208:211], v[232:235], v[20:23]
	v_mfma_f32_16x16x32_bf16 v[16:19], v[208:211], v[240:243], v[16:19]
	v_mfma_f32_16x16x32_bf16 v[12:15], v[216:219], v[232:235], v[12:15]
	v_mfma_f32_16x16x32_bf16 v[8:11], v[216:219], v[240:243], v[8:11]
	v_mfma_f32_16x16x32_bf16 v[4:7], v[224:227], v[232:235], v[4:7]
	v_mfma_f32_16x16x32_bf16 v[0:3], v[224:227], v[240:243], v[0:3]
	v_mfma_f32_16x16x32_bf16 v[28:31], v[196:199], v[236:239], v[28:31]
	v_mfma_f32_16x16x32_bf16 v[24:27], v[196:199], v[244:247], v[24:27]
	v_mfma_f32_16x16x32_bf16 v[20:23], v[212:215], v[236:239], v[20:23]
	v_mfma_f32_16x16x32_bf16 v[16:19], v[212:215], v[244:247], v[16:19]
	v_mfma_f32_16x16x32_bf16 v[12:15], v[220:223], v[236:239], v[12:15]
	v_mfma_f32_16x16x32_bf16 v[8:11], v[220:223], v[244:247], v[8:11]
	v_mfma_f32_16x16x32_bf16 v[4:7], v[228:231], v[236:239], v[4:7]
	v_mfma_f32_16x16x32_bf16 v[0:3], v[228:231], v[244:247], v[0:3]
	s_add_i32 s0, s0, 2
	v_lshl_add_u64 v[134:135], v[134:135], 0, s[80:81]
	v_lshl_add_u64 v[136:137], v[136:137], 0, s[80:81]
	v_lshl_add_u64 v[138:139], v[138:139], 0, s[80:81]
	s_cmp_lt_u32 s0, 4
	v_lshl_add_u64 v[140:141], v[140:141], 0, s[80:81]
	s_barrier
	s_cbranch_scc1 .LBB0_141
	s_or_b32 s0, s6, 0x80
	s_ashr_i32 s1, s0, 31
	s_lshl_b64 s[0:1], s[0:1], 10
	s_add_u32 s0, s28, s0
	s_addc_u32 s1, s29, s1
	ds_read_b128 v[134:137], v157
	ds_read_b128 v[138:141], v157 offset:1024
	ds_read_b128 v[150:153], v157 offset:2048
	ds_read_b128 v[174:177], v157 offset:3072
	ds_read_b128 v[178:181], v147
	ds_read_b128 v[182:185], v147 offset:1024
	ds_read_b128 v[186:189], v146
	ds_read_b128 v[190:193], v146 offset:1024
	ds_read_b128 v[196:199], v145
	ds_read_b128 v[208:211], v145 offset:1024
	ds_read_b128 v[212:215], v144
	ds_read_b128 v[216:219], v144 offset:1024
	v_lshl_add_u64 v[156:157], v[166:167], 1, s[0:1]
	s_mov_b64 s[6:7], 0x380
	v_lshl_add_u64 v[156:157], v[156:157], 0, s[6:7]
	s_add_i32 m0, s100, 0xc000
	v_lshl_add_u64 v[132:133], v[132:133], 1, s[0:1]
	global_load_lds_dwordx4 v[156:157], off
	v_lshl_add_u64 v[132:133], v[132:133], 0, s[6:7]
	s_add_i32 m0, s100, 0xe000
	s_nop 0
	global_load_lds_dwordx4 v[132:133], off
	s_barrier
	s_waitcnt lgkmcnt(0)
	s_setprio 1
	s_waitcnt lgkmcnt(0)
	v_mfma_f32_16x16x32_bf16 v[124:127], v[178:181], v[134:137], v[124:127]
	v_mfma_f32_16x16x32_bf16 v[120:123], v[178:181], v[150:153], v[120:123]
	v_mfma_f32_16x16x32_bf16 v[116:119], v[186:189], v[134:137], v[116:119]
	v_mfma_f32_16x16x32_bf16 v[112:115], v[186:189], v[150:153], v[112:115]
	v_mfma_f32_16x16x32_bf16 v[108:111], v[196:199], v[134:137], v[108:111]
	v_mfma_f32_16x16x32_bf16 v[104:107], v[196:199], v[150:153], v[104:107]
	v_mfma_f32_16x16x32_bf16 v[100:103], v[212:215], v[134:137], v[100:103]
	v_mfma_f32_16x16x32_bf16 v[96:99], v[212:215], v[150:153], v[96:99]
	v_mfma_f32_16x16x32_bf16 v[124:127], v[182:185], v[138:141], v[124:127]
	v_mfma_f32_16x16x32_bf16 v[120:123], v[182:185], v[174:177], v[120:123]
	v_mfma_f32_16x16x32_bf16 v[116:119], v[190:193], v[138:141], v[116:119]
	v_mfma_f32_16x16x32_bf16 v[112:115], v[190:193], v[174:177], v[112:115]
	v_mfma_f32_16x16x32_bf16 v[108:111], v[208:211], v[138:141], v[108:111]
	v_mfma_f32_16x16x32_bf16 v[104:107], v[208:211], v[174:177], v[104:107]
	v_mfma_f32_16x16x32_bf16 v[100:103], v[216:219], v[138:141], v[100:103]
	v_mfma_f32_16x16x32_bf16 v[96:99], v[216:219], v[174:177], v[96:99]
	s_setprio 0
	s_barrier
	ds_read_b128 v[220:223], v154
	ds_read_b128 v[224:227], v154 offset:1024
	ds_read_b128 v[228:231], v154 offset:2048
	ds_read_b128 v[154:157], v154 offset:3072
	s_barrier
; #define P8_LDA(dst,b,h) _Pragma("unroll") for(int m=0;m<4;++m) _Pragma("unroll") for(int k=0;k<2;++k) \
;     dst[m][k]=*reinterpret_cast<const bf16x8*>((char*)P8_SA(b,h)+lds_byte(wr*64+m*16+fr,k*32+fq*8))
; #define P8_LDB(dst,b,h) _Pragma("unroll") for(int n=0;n<2;++n) _Pragma("unroll") for(int k=0;k<2;++k) \
;     dst[n][k]=*reinterpret_cast<const bf16x8*>((char*)P8_SB(b,h)+lds_byte(wc*32+n*16+fr,k*32+fq*8))
; #define P8_MMA(ai,bj,At,Bt) do{__builtin_amdgcn_s_setprio(1); \
;     _Pragma("unroll") for(int m=0;m<4;++m) _Pragma("unroll") for(int n=0;n<2;++n) _Pragma("unroll") for(int k=0;k<2;++k) \
;       acc[ai][bj][m][n]=__builtin_amdgcn_mfma_f32_16x16x32_bf16(At[m][k],Bt[n][k],acc[ai][bj][m][n],0,0,0); \
;     __builtin_amdgcn_s_setprio(0);}while(0)
; #define P8_WAIT_V(n) asm volatile("s_waitcnt vmcnt(" #n ")":::"memory")
; #define P8_WAIT_L(n) asm volatile("s_waitcnt lgkmcnt(" #n ")":::"memory")
; #define P8_BAR __builtin_amdgcn_s_barrier()
; template <class EPI>
; DEVI void gemm8_tile(const bfr* __restrict__ A, const bfr* __restrict__ Bt, int K, int brow, int bcol, int nbrow, int nbcol, char* shmc, EPI epi) {
;     ...
;     P8_LDB(B1,0,1); P8_BAR; P8_WAIT_L(0); P8_MMA(0,1,At,B1); P8_BAR;
;     P8_LDA(At,0,1); P8_WAIT_V(4); P8_BAR; P8_WAIT_L(0); P8_MMA(1,0,At,B0); P8_MMA(1,1,At,B1); P8_BAR; }
;   { P8_LDB(B0,1,0); P8_LDA(At,1,0); P8_WAIT_V(2); P8_BAR; P8_WAIT_L(0); P8_MMA(0,0,At,B0); P8_BAR;
	s_waitcnt lgkmcnt(0)
	s_setprio 1
	s_waitcnt lgkmcnt(0)
	v_mfma_f32_16x16x32_bf16 v[88:91], v[178:181], v[228:231], v[88:91]
	v_mfma_f32_16x16x32_bf16 v[76:79], v[196:199], v[220:223], v[76:79]
	v_mfma_f32_16x16x32_bf16 v[72:75], v[196:199], v[228:231], v[72:75]
	v_mfma_f32_16x16x32_bf16 v[68:71], v[212:215], v[220:223], v[68:71]
	v_mfma_f32_16x16x32_bf16 v[64:67], v[212:215], v[228:231], v[64:67]
	v_mfma_f32_16x16x32_bf16 v[92:95], v[178:181], v[220:223], v[92:95]
	v_mfma_f32_16x16x32_bf16 v[178:181], v[182:185], v[154:157], v[88:91]
	v_mfma_f32_16x16x32_bf16 v[84:87], v[186:189], v[220:223], v[84:87]
	v_mfma_f32_16x16x32_bf16 v[80:83], v[186:189], v[228:231], v[80:83]
	v_mfma_f32_16x16x32_bf16 v[76:79], v[208:211], v[224:227], v[76:79]
	v_mfma_f32_16x16x32_bf16 v[72:75], v[208:211], v[154:157], v[72:75]
	v_mfma_f32_16x16x32_bf16 v[68:71], v[216:219], v[224:227], v[68:71]
	v_mfma_f32_16x16x32_bf16 v[64:67], v[216:219], v[154:157], v[64:67]
	v_mfma_f32_16x16x32_bf16 v[232:235], v[182:185], v[224:227], v[92:95]
	v_mfma_f32_16x16x32_bf16 v[182:185], v[190:193], v[224:227], v[84:87]
	v_mfma_f32_16x16x32_bf16 v[186:189], v[190:193], v[154:157], v[80:83]
	s_setprio 0
	s_barrier
	s_nop 0
	ds_read_b128 v[80:83], v147 offset:16384
	ds_read_b128 v[84:87], v147 offset:17408
	ds_read_b128 v[88:91], v146 offset:16384
	ds_read_b128 v[92:95], v146 offset:17408
	ds_read_b128 v[190:193], v145 offset:16384
	ds_read_b128 v[196:199], v145 offset:17408
	ds_read_b128 v[208:211], v144 offset:16384
	ds_read_b128 v[212:215], v144 offset:17408
	s_waitcnt vmcnt(4)
	s_barrier
	s_waitcnt lgkmcnt(0)
	s_setprio 1
	s_waitcnt lgkmcnt(0)
	v_mfma_f32_16x16x32_bf16 v[44:47], v[190:193], v[134:137], v[44:47]
	v_mfma_f32_16x16x32_bf16 v[40:43], v[190:193], v[150:153], v[40:43]
	v_mfma_f32_16x16x32_bf16 v[36:39], v[208:211], v[134:137], v[36:39]
	v_mfma_f32_16x16x32_bf16 v[32:35], v[208:211], v[150:153], v[32:35]
	v_mfma_f32_16x16x32_bf16 v[60:63], v[80:83], v[134:137], v[60:63]
	v_mfma_f32_16x16x32_bf16 v[56:59], v[80:83], v[150:153], v[56:59]
	v_mfma_f32_16x16x32_bf16 v[52:55], v[88:91], v[134:137], v[52:55]
	v_mfma_f32_16x16x32_bf16 v[48:51], v[88:91], v[150:153], v[48:51]
	v_mfma_f32_16x16x32_bf16 v[44:47], v[196:199], v[138:141], v[44:47]
	v_mfma_f32_16x16x32_bf16 v[40:43], v[196:199], v[174:177], v[40:43]
	v_mfma_f32_16x16x32_bf16 v[36:39], v[212:215], v[138:141], v[36:39]
	v_mfma_f32_16x16x32_bf16 v[32:35], v[212:215], v[174:177], v[32:35]
	v_mfma_f32_16x16x32_bf16 v[216:219], v[84:87], v[138:141], v[60:63]
	v_mfma_f32_16x16x32_bf16 v[236:239], v[84:87], v[174:177], v[56:59]
	v_mfma_f32_16x16x32_bf16 v[240:243], v[92:95], v[138:141], v[52:55]
	v_mfma_f32_16x16x32_bf16 v[244:247], v[92:95], v[174:177], v[48:51]
	s_setprio 0
	s_setprio 1
	v_mfma_f32_16x16x32_bf16 v[12:15], v[190:193], v[220:223], v[12:15]
	v_mfma_f32_16x16x32_bf16 v[4:7], v[208:211], v[220:223], v[4:7]
	v_mfma_f32_16x16x32_bf16 v[28:31], v[80:83], v[220:223], v[28:31]
	v_mfma_f32_16x16x32_bf16 v[24:27], v[80:83], v[228:231], v[24:27]
	v_mfma_f32_16x16x32_bf16 v[20:23], v[88:91], v[220:223], v[20:23]
	v_mfma_f32_16x16x32_bf16 v[16:19], v[88:91], v[228:231], v[16:19]
	v_mfma_f32_16x16x32_bf16 v[12:15], v[196:199], v[224:227], v[12:15]
	v_mfma_f32_16x16x32_bf16 v[8:11], v[190:193], v[228:231], v[8:11]
	v_mfma_f32_16x16x32_bf16 v[4:7], v[212:215], v[224:227], v[4:7]
	v_mfma_f32_16x16x32_bf16 v[0:3], v[208:211], v[228:231], v[0:3]
	v_mfma_f32_16x16x32_bf16 v[132:135], v[84:87], v[224:227], v[28:31]
	v_mfma_f32_16x16x32_bf16 v[136:139], v[84:87], v[154:157], v[24:27]
	v_mfma_f32_16x16x32_bf16 v[150:153], v[92:95], v[224:227], v[20:23]
	v_mfma_f32_16x16x32_bf16 v[172:175], v[92:95], v[154:157], v[16:19]
	v_mfma_f32_16x16x32_bf16 v[190:193], v[196:199], v[154:157], v[8:11]
	v_mfma_f32_16x16x32_bf16 v[154:157], v[212:215], v[154:157], v[0:3]
	s_setprio 0
	s_barrier
	s_nop 0
	ds_read_b128 v[0:3], v149
	ds_read_b128 v[8:11], v149 offset:1024
	ds_read_b128 v[196:199], v149 offset:2048
	ds_read_b128 v[208:211], v149 offset:3072
	ds_read_b128 v[16:19], v147 offset:32768
	ds_read_b128 v[20:23], v147 offset:33792
	ds_read_b128 v[24:27], v146 offset:32768
	ds_read_b128 v[48:51], v146 offset:33792
	ds_read_b128 v[212:215], v145 offset:32768
	ds_read_b128 v[220:223], v145 offset:33792
	ds_read_b128 v[224:227], v144 offset:32768
	ds_read_b128 v[228:231], v144 offset:33792
	s_waitcnt vmcnt(2)
	s_barrier
; #define P8_LDA(dst,b,h) _Pragma("unroll") for(int m=0;m<4;++m) _Pragma("unroll") for(int k=0;k<2;++k) \
;     dst[m][k]=*reinterpret_cast<const bf16x8*>((char*)P8_SA(b,h)+lds_byte(wr*64+m*16+fr,k*32+fq*8))
; #define P8_LDB(dst,b,h) _Pragma("unroll") for(int n=0;n<2;++n) _Pragma("unroll") for(int k=0;k<2;++k) \
;     dst[n][k]=*reinterpret_cast<const bf16x8*>((char*)P8_SB(b,h)+lds_byte(wc*32+n*16+fr,k*32+fq*8))
; #define P8_MMA(ai,bj,At,Bt) do{__builtin_amdgcn_s_setprio(1); \
;     _Pragma("unroll") for(int m=0;m<4;++m) _Pragma("unroll") for(int n=0;n<2;++n) _Pragma("unroll") for(int k=0;k<2;++k) \
;       acc[ai][bj][m][n]=__builtin_amdgcn_mfma_f32_16x16x32_bf16(At[m][k],Bt[n][k],acc[ai][bj][m][n],0,0,0); \
;     __builtin_amdgcn_s_setprio(0);}while(0)
; #define P8_WAIT_V(n) asm volatile("s_waitcnt vmcnt(" #n ")":::"memory")
; #define P8_WAIT_L(n) asm volatile("s_waitcnt lgkmcnt(" #n ")":::"memory")
; #define P8_BAR __builtin_amdgcn_s_barrier()
; template <class EPI>
; DEVI void gemm8_tile(const bfr* __restrict__ A, const bfr* __restrict__ Bt, int K, int brow, int bcol, int nbrow, int nbcol, char* shmc, EPI epi) {
;     ...
;   { P8_LDB(B0,1,0); P8_LDA(At,1,0); P8_WAIT_V(2); P8_BAR; P8_WAIT_L(0); P8_MMA(0,0,At,B0); P8_BAR;
;     P8_LDB(B1,1,1); P8_WAIT_V(0); P8_BAR; P8_WAIT_L(0); P8_MMA(0,1,At,B1); P8_BAR;
;     P8_LDA(At,1,1); P8_BAR; P8_WAIT_L(0); P8_MMA(1,0,At,B0); P8_MMA(1,1,At,B1); P8_BAR; }
;   if(wr==0)P8_BAR;
	s_waitcnt lgkmcnt(0)
	s_setprio 1
	s_waitcnt lgkmcnt(0)
	v_mfma_f32_16x16x32_bf16 v[28:31], v[16:19], v[0:3], v[124:127]
	v_mfma_f32_16x16x32_bf16 v[124:127], v[20:23], v[8:11], v[28:31]
	v_mfma_f32_16x16x32_bf16 v[28:31], v[16:19], v[196:199], v[120:123]
	v_mfma_f32_16x16x32_bf16 v[92:95], v[20:23], v[208:211], v[28:31]
	v_mfma_f32_16x16x32_bf16 v[28:31], v[24:27], v[0:3], v[116:119]
	v_mfma_f32_16x16x32_bf16 v[120:123], v[48:51], v[8:11], v[28:31]
	v_mfma_f32_16x16x32_bf16 v[28:31], v[24:27], v[196:199], v[112:115]
	v_mfma_f32_16x16x32_bf16 v[88:91], v[48:51], v[208:211], v[28:31]
	v_mfma_f32_16x16x32_bf16 v[28:31], v[212:215], v[0:3], v[108:111]
	v_mfma_f32_16x16x32_bf16 v[116:119], v[220:223], v[8:11], v[28:31]
	v_mfma_f32_16x16x32_bf16 v[28:31], v[212:215], v[196:199], v[104:107]
	v_mfma_f32_16x16x32_bf16 v[84:87], v[220:223], v[208:211], v[28:31]
	v_mfma_f32_16x16x32_bf16 v[28:31], v[224:227], v[0:3], v[100:103]
	v_mfma_f32_16x16x32_bf16 v[112:115], v[228:231], v[8:11], v[28:31]
	v_mfma_f32_16x16x32_bf16 v[28:31], v[224:227], v[196:199], v[96:99]
	v_mfma_f32_16x16x32_bf16 v[80:83], v[228:231], v[208:211], v[28:31]
	s_setprio 0
	s_barrier
	ds_read_b128 v[248:251], v148
	ds_read_b128 v[200:203], v148 offset:1024
	ds_read_b128 v[204:207], v148 offset:2048
	s_nop 1
	ds_read_b128 v[28:31], v148 offset:3072
	s_waitcnt vmcnt(0)
	s_barrier
	s_waitcnt lgkmcnt(0)
	s_setprio 1
	s_waitcnt lgkmcnt(0)
	v_mfma_f32_16x16x32_bf16 v[52:55], v[16:19], v[248:251], v[232:235]
	v_mfma_f32_16x16x32_bf16 v[16:19], v[16:19], v[204:207], v[178:181]
	v_mfma_f32_16x16x32_bf16 v[176:179], v[20:23], v[28:31], v[16:19]
	v_mfma_f32_16x16x32_bf16 v[16:19], v[24:27], v[248:251], v[182:185]
	v_mfma_f32_16x16x32_bf16 v[56:59], v[48:51], v[200:203], v[16:19]
	v_mfma_f32_16x16x32_bf16 v[16:19], v[24:27], v[204:207], v[186:189]
	v_mfma_f32_16x16x32_bf16 v[24:27], v[48:51], v[28:31], v[16:19]
	v_mfma_f32_16x16x32_bf16 v[16:19], v[212:215], v[248:251], v[76:79]
	v_mfma_f32_16x16x32_bf16 v[60:63], v[20:23], v[200:203], v[52:55]
	v_mfma_f32_16x16x32_bf16 v[52:55], v[220:223], v[200:203], v[16:19]
	v_mfma_f32_16x16x32_bf16 v[16:19], v[212:215], v[204:207], v[72:75]
	v_mfma_f32_16x16x32_bf16 v[20:23], v[220:223], v[28:31], v[16:19]
	v_mfma_f32_16x16x32_bf16 v[16:19], v[224:227], v[248:251], v[68:71]
	v_mfma_f32_16x16x32_bf16 v[48:51], v[228:231], v[200:203], v[16:19]
	v_mfma_f32_16x16x32_bf16 v[16:19], v[224:227], v[204:207], v[64:67]
	v_mfma_f32_16x16x32_bf16 v[16:19], v[228:231], v[28:31], v[16:19]
	s_setprio 0
	s_barrier
	ds_read_b128 v[180:183], v147 offset:49152
	ds_read_b128 v[184:187], v147 offset:50176
	ds_read_b128 v[212:215], v146 offset:49152
	ds_read_b128 v[146:149], v146 offset:50176
	ds_read_b128 v[220:223], v145 offset:49152
	ds_read_b128 v[224:227], v145 offset:50176
	ds_read_b128 v[228:231], v144 offset:49152
	ds_read_b128 v[232:235], v144 offset:50176
	s_barrier
	s_waitcnt lgkmcnt(0)
	s_setprio 1
	s_waitcnt lgkmcnt(0)
	v_mfma_f32_16x16x32_bf16 v[64:67], v[180:183], v[0:3], v[216:219]
	v_mfma_f32_16x16x32_bf16 v[104:107], v[184:187], v[8:11], v[64:67]
	v_mfma_f32_16x16x32_bf16 v[64:67], v[180:183], v[196:199], v[236:239]
	v_mfma_f32_16x16x32_bf16 v[72:75], v[184:187], v[208:211], v[64:67]
	v_mfma_f32_16x16x32_bf16 v[64:67], v[212:215], v[0:3], v[240:243]
	v_mfma_f32_16x16x32_bf16 v[44:47], v[220:223], v[0:3], v[44:47]
	v_mfma_f32_16x16x32_bf16 v[0:3], v[228:231], v[0:3], v[36:39]
	v_mfma_f32_16x16x32_bf16 v[96:99], v[146:149], v[8:11], v[64:67]
	v_mfma_f32_16x16x32_bf16 v[64:67], v[212:215], v[196:199], v[244:247]
	v_mfma_f32_16x16x32_bf16 v[40:43], v[220:223], v[196:199], v[40:43]
	v_mfma_f32_16x16x32_bf16 v[100:103], v[232:235], v[8:11], v[0:3]
	v_mfma_f32_16x16x32_bf16 v[0:3], v[228:231], v[196:199], v[32:35]
	v_mfma_f32_16x16x32_bf16 v[64:67], v[146:149], v[208:211], v[64:67]
	v_mfma_f32_16x16x32_bf16 v[108:111], v[224:227], v[8:11], v[44:47]
	v_mfma_f32_16x16x32_bf16 v[76:79], v[224:227], v[208:211], v[40:43]
	v_mfma_f32_16x16x32_bf16 v[68:71], v[232:235], v[208:211], v[0:3]
	s_setprio 0
	s_setprio 1
	v_mfma_f32_16x16x32_bf16 v[0:3], v[180:183], v[248:251], v[132:135]
	v_mfma_f32_16x16x32_bf16 v[40:43], v[184:187], v[200:203], v[0:3]
	v_mfma_f32_16x16x32_bf16 v[0:3], v[180:183], v[204:207], v[136:139]
	v_mfma_f32_16x16x32_bf16 v[8:11], v[184:187], v[28:31], v[0:3]
	v_mfma_f32_16x16x32_bf16 v[0:3], v[212:215], v[248:251], v[150:153]
	v_mfma_f32_16x16x32_bf16 v[12:15], v[220:223], v[248:251], v[12:15]
	v_mfma_f32_16x16x32_bf16 v[4:7], v[228:231], v[248:251], v[4:7]
	v_mfma_f32_16x16x32_bf16 v[32:35], v[146:149], v[200:203], v[0:3]
	v_mfma_f32_16x16x32_bf16 v[0:3], v[212:215], v[204:207], v[172:175]
	v_mfma_f32_16x16x32_bf16 v[44:47], v[224:227], v[200:203], v[12:15]
	v_mfma_f32_16x16x32_bf16 v[12:15], v[220:223], v[204:207], v[190:193]
	v_mfma_f32_16x16x32_bf16 v[36:39], v[232:235], v[200:203], v[4:7]
	v_mfma_f32_16x16x32_bf16 v[4:7], v[228:231], v[204:207], v[154:157]
	v_mfma_f32_16x16x32_bf16 v[0:3], v[146:149], v[28:31], v[0:3]
	v_mfma_f32_16x16x32_bf16 v[12:15], v[224:227], v[28:31], v[12:15]
	v_mfma_f32_16x16x32_bf16 v[4:7], v[232:235], v[28:31], v[4:7]
	s_setprio 0
	v_cmp_gt_u32_e32 vcc, s57, v142
	s_barrier
	s_and_saveexec_b64 s[0:1], vcc
	s_cbranch_execz .LBB0_144
	s_barrier

; #define P8_STAGE(P,BASE,br,kt) do{const bfr* _ub=(BASE)+((long)(br)*K+(long)(kt)*BK); \
;     __builtin_amdgcn_global_load_lds((const unsigned*)(_ub+so0),(unsigned*)((char*)(P)+wid*1024),16,0,0); \
;     __builtin_amdgcn_global_load_lds((const unsigned*)(_ub+so1),(unsigned*)((char*)(P)+wid*1024+8192),16,0,0);}while(0)
; #define P8_LDA(dst,b,h) _Pragma("unroll") for(int m=0;m<4;++m) _Pragma("unroll") for(int k=0;k<2;++k) \
;     dst[m][k]=*reinterpret_cast<const bf16x8*>((char*)P8_SA(b,h)+lds_byte(wr*64+m*16+fr,k*32+fq*8))
; #define P8_LDB(dst,b,h) _Pragma("unroll") for(int n=0;n<2;++n) _Pragma("unroll") for(int k=0;k<2;++k) \
;     dst[n][k]=*reinterpret_cast<const bf16x8*>((char*)P8_SB(b,h)+lds_byte(wc*32+n*16+fr,k*32+fq*8))
; #define P8_MMA(ai,bj,At,Bt) do{__builtin_amdgcn_s_setprio(1); \
;     _Pragma("unroll") for(int m=0;m<4;++m) _Pragma("unroll") for(int n=0;n<2;++n) _Pragma("unroll") for(int k=0;k<2;++k) \
;       acc[ai][bj][m][n]=__builtin_amdgcn_mfma_f32_16x16x32_bf16(At[m][k],Bt[n][k],acc[ai][bj][m][n],0,0,0); \
;     __builtin_amdgcn_s_setprio(0);}while(0)
; #define P8_WAIT_V(n) asm volatile("s_waitcnt vmcnt(" #n ")":::"memory")
; #define P8_WAIT_L(n) asm volatile("s_waitcnt lgkmcnt(" #n ")":::"memory")
; #define P8_BAR __builtin_amdgcn_s_barrier()
; #define P8_SCHED __builtin_amdgcn_sched_barrier(0)
; template <class EPI>
; DEVI void gemm8_tile(const bfr* __restrict__ A, const bfr* __restrict__ Bt, int K, int brow, int bcol, int nbrow, int nbcol, char* shmc, EPI epi) {
;     ...
;     P8_LDB(B0,0,0); P8_SCHED; P8_LDA(At,0,0); P8_STAGE(P8_SA(1,1),A,brow+128,t+1);
;     P8_WAIT_L(8); P8_BAR; P8_WAIT_L(0); P8_MMA(0,0,At,B0); P8_BAR; P8_SCHED;
;     P8_LDB(B1,0,1); P8_STAGE(P8_SB(0,0),Bt,bcol,t+2);
;     P8_BAR; P8_WAIT_L(0); P8_MMA(0,1,At,B1); P8_BAR;
;     P8_LDA(At,0,1); P8_STAGE(P8_SA(0,0),A,brow,t+2);
;     P8_BAR; P8_WAIT_L(0); P8_MMA(1,0,At,B0); P8_BAR; P8_SCHED;
;     P8_STAGE(P8_SB(0,1),Bt,bcol+128,t+2);
;     P8_WAIT_V(6); P8_BAR; P8_MMA(1,1,At,B1); P8_BAR;
.LBB0_175:
	ds_read_b128 v[174:177], v157
	ds_read_b128 v[178:181], v157 offset:1024
	ds_read_b128 v[182:185], v157 offset:2048
	ds_read_b128 v[186:189], v157 offset:3072
	v_add_u32_e32 v171, 0xc000, v143
	v_add_u32_e32 v172, 0xe000, v143
	v_add_u32_e32 v158, s54, v136
	s_add_i32 m0, s100, 0xc000
	ds_read_b128 v[160:163], v147
	ds_read_b128 v[190:193], v147 offset:1024
	ds_read_b128 v[196:199], v146
	ds_read_b128 v[200:203], v146 offset:1024
	ds_read_b128 v[204:207], v145
	ds_read_b128 v[208:211], v145 offset:1024
	ds_read_b128 v[212:215], v144
	ds_read_b128 v[216:219], v144 offset:1024
	global_load_lds_dwordx4 v158, s[86:87]
	v_add_u32_e32 v158, s54, v134
	s_add_i32 m0, s100, 0xe000
	s_nop 0
	global_load_lds_dwordx4 v158, s[86:87]
	s_waitcnt lgkmcnt(8)
	s_barrier
	s_waitcnt lgkmcnt(0)
	v_mfma_f32_16x16x32_bf16 v[124:127], v[160:163], v[174:177], v[124:127]
	v_mfma_f32_16x16x32_bf16 v[120:123], v[160:163], v[182:185], v[120:123]
	v_mfma_f32_16x16x32_bf16 v[116:119], v[196:199], v[174:177], v[116:119]
	v_mfma_f32_16x16x32_bf16 v[112:115], v[196:199], v[182:185], v[112:115]
	v_mfma_f32_16x16x32_bf16 v[108:111], v[204:207], v[174:177], v[108:111]
	v_mfma_f32_16x16x32_bf16 v[104:107], v[204:207], v[182:185], v[104:107]
	v_mfma_f32_16x16x32_bf16 v[100:103], v[212:215], v[174:177], v[100:103]
	v_mfma_f32_16x16x32_bf16 v[96:99], v[212:215], v[182:185], v[96:99]
	v_mfma_f32_16x16x32_bf16 v[124:127], v[190:193], v[178:181], v[124:127]
	v_mfma_f32_16x16x32_bf16 v[120:123], v[190:193], v[186:189], v[120:123]
	v_mfma_f32_16x16x32_bf16 v[116:119], v[200:203], v[178:181], v[116:119]
	v_mfma_f32_16x16x32_bf16 v[112:115], v[200:203], v[186:189], v[112:115]
	v_mfma_f32_16x16x32_bf16 v[108:111], v[208:211], v[178:181], v[108:111]
	v_mfma_f32_16x16x32_bf16 v[104:107], v[208:211], v[186:189], v[104:107]
	v_mfma_f32_16x16x32_bf16 v[100:103], v[216:219], v[178:181], v[100:103]
	v_mfma_f32_16x16x32_bf16 v[96:99], v[216:219], v[186:189], v[96:99]
	s_barrier
	v_add_u32_e32 v158, 0x10000, v143
	v_add_u32_e32 v159, 0x12000, v143
	v_add_u32_e32 v236, s60, v140
	s_add_i32 m0, s100, 0x10000
	ds_read_b128 v[220:223], v154
	ds_read_b128 v[224:227], v154 offset:1024
	ds_read_b128 v[228:231], v154 offset:2048
	ds_read_b128 v[232:235], v154 offset:3072
	global_load_lds_dwordx4 v236, s[86:87]
	v_add_u32_e32 v236, s60, v138
	s_add_i32 m0, s100, 0x12000
	s_nop 0
	global_load_lds_dwordx4 v236, s[86:87]
	s_barrier
	s_waitcnt lgkmcnt(0)
	v_mfma_f32_16x16x32_bf16 v[92:95], v[160:163], v[220:223], v[92:95]
	v_mfma_f32_16x16x32_bf16 v[88:91], v[160:163], v[228:231], v[88:91]
	v_mfma_f32_16x16x32_bf16 v[84:87], v[196:199], v[220:223], v[84:87]
	v_mfma_f32_16x16x32_bf16 v[80:83], v[196:199], v[228:231], v[80:83]
	v_mfma_f32_16x16x32_bf16 v[76:79], v[204:207], v[220:223], v[76:79]
	v_mfma_f32_16x16x32_bf16 v[72:75], v[204:207], v[228:231], v[72:75]
	v_mfma_f32_16x16x32_bf16 v[68:71], v[212:215], v[220:223], v[68:71]
	v_mfma_f32_16x16x32_bf16 v[64:67], v[212:215], v[228:231], v[64:67]
	v_mfma_f32_16x16x32_bf16 v[92:95], v[190:193], v[224:227], v[92:95]
	v_mfma_f32_16x16x32_bf16 v[88:91], v[190:193], v[232:235], v[88:91]
	v_mfma_f32_16x16x32_bf16 v[84:87], v[200:203], v[224:227], v[84:87]
	v_mfma_f32_16x16x32_bf16 v[80:83], v[200:203], v[232:235], v[80:83]
	v_mfma_f32_16x16x32_bf16 v[76:79], v[208:211], v[224:227], v[76:79]
	v_mfma_f32_16x16x32_bf16 v[72:75], v[208:211], v[232:235], v[72:75]
	v_mfma_f32_16x16x32_bf16 v[68:71], v[216:219], v[224:227], v[68:71]
	v_mfma_f32_16x16x32_bf16 v[64:67], v[216:219], v[232:235], v[64:67]
	v_add_u32_e32 v160, s72, v136
	s_mov_b32 m0, s100
	s_barrier
	ds_read_b128 v[190:193], v147 offset:16384
	ds_read_b128 v[196:199], v147 offset:17408
	ds_read_b128 v[200:203], v146 offset:16384
	ds_read_b128 v[204:207], v146 offset:17408
	ds_read_b128 v[208:211], v145 offset:16384
	ds_read_b128 v[212:215], v145 offset:17408
	ds_read_b128 v[216:219], v144 offset:16384
	ds_read_b128 v[236:239], v144 offset:17408
	global_load_lds_dwordx4 v160, s[86:87]
	v_add_u32_e32 v160, 0x2000, v143
	v_add_u32_e32 v162, s72, v134
	s_add_i32 m0, s100, 0x2000
	s_nop 0
	global_load_lds_dwordx4 v162, s[86:87]
	s_barrier
	s_waitcnt lgkmcnt(0)
	v_mfma_f32_16x16x32_bf16 v[60:63], v[190:193], v[174:177], v[60:63]
	v_mfma_f32_16x16x32_bf16 v[56:59], v[190:193], v[182:185], v[56:59]
	v_mfma_f32_16x16x32_bf16 v[52:55], v[200:203], v[174:177], v[52:55]
	v_mfma_f32_16x16x32_bf16 v[48:51], v[200:203], v[182:185], v[48:51]
	v_mfma_f32_16x16x32_bf16 v[44:47], v[208:211], v[174:177], v[44:47]
	v_mfma_f32_16x16x32_bf16 v[40:43], v[208:211], v[182:185], v[40:43]
	v_mfma_f32_16x16x32_bf16 v[36:39], v[216:219], v[174:177], v[36:39]
	v_mfma_f32_16x16x32_bf16 v[32:35], v[216:219], v[182:185], v[32:35]
	v_mfma_f32_16x16x32_bf16 v[60:63], v[196:199], v[178:181], v[60:63]
	v_mfma_f32_16x16x32_bf16 v[56:59], v[196:199], v[186:189], v[56:59]
	v_mfma_f32_16x16x32_bf16 v[52:55], v[204:207], v[178:181], v[52:55]
	v_mfma_f32_16x16x32_bf16 v[48:51], v[204:207], v[186:189], v[48:51]
	v_mfma_f32_16x16x32_bf16 v[44:47], v[212:215], v[178:181], v[44:47]
	v_mfma_f32_16x16x32_bf16 v[40:43], v[212:215], v[186:189], v[40:43]
	v_mfma_f32_16x16x32_bf16 v[36:39], v[236:239], v[178:181], v[36:39]
	v_mfma_f32_16x16x32_bf16 v[32:35], v[236:239], v[186:189], v[32:35]
	s_barrier
	v_add_u32_e32 v161, 0x14000, v143
	v_add_u32_e32 v162, s82, v140
	s_add_i32 m0, s100, 0x14000
	v_add_u32_e32 v174, s82, v138
	global_load_lds_dwordx4 v162, s[86:87]
	v_add_u32_e32 v162, 0x16000, v143
	s_nop 0
	s_add_i32 m0, s100, 0x16000
	s_nop 0
	global_load_lds_dwordx4 v174, s[86:87]
	s_waitcnt vmcnt(6)
	s_barrier
; #define P8_STAGE(P,BASE,br,kt) do{const bfr* _ub=(BASE)+((long)(br)*K+(long)(kt)*BK); \
;     __builtin_amdgcn_global_load_lds((const unsigned*)(_ub+so0),(unsigned*)((char*)(P)+wid*1024),16,0,0); \
;     __builtin_amdgcn_global_load_lds((const unsigned*)(_ub+so1),(unsigned*)((char*)(P)+wid*1024+8192),16,0,0);}while(0)
; #define P8_LDA(dst,b,h) _Pragma("unroll") for(int m=0;m<4;++m) _Pragma("unroll") for(int k=0;k<2;++k) \
;     dst[m][k]=*reinterpret_cast<const bf16x8*>((char*)P8_SA(b,h)+lds_byte(wr*64+m*16+fr,k*32+fq*8))
; #define P8_LDB(dst,b,h) _Pragma("unroll") for(int n=0;n<2;++n) _Pragma("unroll") for(int k=0;k<2;++k) \
;     dst[n][k]=*reinterpret_cast<const bf16x8*>((char*)P8_SB(b,h)+lds_byte(wc*32+n*16+fr,k*32+fq*8))
; #define P8_MMA(ai,bj,At,Bt) do{__builtin_amdgcn_s_setprio(1); \
;     _Pragma("unroll") for(int m=0;m<4;++m) _Pragma("unroll") for(int n=0;n<2;++n) _Pragma("unroll") for(int k=0;k<2;++k) \
;       acc[ai][bj][m][n]=__builtin_amdgcn_mfma_f32_16x16x32_bf16(At[m][k],Bt[n][k],acc[ai][bj][m][n],0,0,0); \
;     __builtin_amdgcn_s_setprio(0);}while(0)
; #define P8_WAIT_V(n) asm volatile("s_waitcnt vmcnt(" #n ")":::"memory")
; #define P8_WAIT_L(n) asm volatile("s_waitcnt lgkmcnt(" #n ")":::"memory")
; #define P8_BAR __builtin_amdgcn_s_barrier()
; #define P8_SCHED __builtin_amdgcn_sched_barrier(0)
; template <class EPI>
; DEVI void gemm8_tile(const bfr* __restrict__ A, const bfr* __restrict__ Bt, int K, int brow, int bcol, int nbrow, int nbcol, char* shmc, EPI epi) {
;     ...
;     P8_WAIT_V(6); P8_BAR; P8_MMA(1,1,At,B1); P8_BAR;
;     P8_LDB(B0,1,0); P8_SCHED; P8_LDA(At,1,0); P8_STAGE(P8_SA(0,1),A,brow+128,t+2);
;     P8_WAIT_L(8); P8_BAR; P8_WAIT_L(0); P8_MMA(0,0,At,B0); P8_BAR; P8_SCHED;
;     P8_LDB(B1,1,1); P8_STAGE(P8_SB(1,0),Bt,bcol,t+3);
;     P8_BAR; P8_WAIT_L(0); P8_MMA(0,1,At,B1); P8_BAR;
;     P8_LDA(At,1,1); P8_STAGE(P8_SA(1,0),A,brow,t+3);
	v_mfma_f32_16x16x32_bf16 v[28:31], v[190:193], v[220:223], v[28:31]
	v_mfma_f32_16x16x32_bf16 v[24:27], v[190:193], v[228:231], v[24:27]
	v_mfma_f32_16x16x32_bf16 v[20:23], v[200:203], v[220:223], v[20:23]
	v_mfma_f32_16x16x32_bf16 v[16:19], v[200:203], v[228:231], v[16:19]
	v_mfma_f32_16x16x32_bf16 v[12:15], v[208:211], v[220:223], v[12:15]
	v_mfma_f32_16x16x32_bf16 v[8:11], v[208:211], v[228:231], v[8:11]
	v_mfma_f32_16x16x32_bf16 v[4:7], v[216:219], v[220:223], v[4:7]
	v_mfma_f32_16x16x32_bf16 v[0:3], v[216:219], v[228:231], v[0:3]
	v_mfma_f32_16x16x32_bf16 v[28:31], v[196:199], v[224:227], v[28:31]
	v_mfma_f32_16x16x32_bf16 v[24:27], v[196:199], v[232:235], v[24:27]
	v_mfma_f32_16x16x32_bf16 v[20:23], v[204:207], v[224:227], v[20:23]
	v_mfma_f32_16x16x32_bf16 v[16:19], v[204:207], v[232:235], v[16:19]
	v_mfma_f32_16x16x32_bf16 v[12:15], v[212:215], v[224:227], v[12:15]
	v_mfma_f32_16x16x32_bf16 v[8:11], v[212:215], v[232:235], v[8:11]
	v_mfma_f32_16x16x32_bf16 v[4:7], v[236:239], v[224:227], v[4:7]
	v_mfma_f32_16x16x32_bf16 v[0:3], v[236:239], v[232:235], v[0:3]
	s_barrier
	ds_read_b128 v[174:177], v149
	ds_read_b128 v[178:181], v149 offset:1024
	ds_read_b128 v[182:185], v149 offset:2048
	ds_read_b128 v[186:189], v149 offset:3072
	v_add_u32_e32 v163, 0x4000, v143
	v_add_u32_e32 v170, 0x6000, v143
	v_add_u32_e32 v224, s92, v136
	s_add_i32 m0, s100, 0x4000
	ds_read_b128 v[190:193], v147 offset:32768
	ds_read_b128 v[196:199], v147 offset:33792
	ds_read_b128 v[200:203], v146 offset:32768
	ds_read_b128 v[204:207], v146 offset:33792
	ds_read_b128 v[208:211], v145 offset:32768
	ds_read_b128 v[212:215], v145 offset:33792
	ds_read_b128 v[216:219], v144 offset:32768
	ds_read_b128 v[220:223], v144 offset:33792
	global_load_lds_dwordx4 v224, s[86:87]
	v_add_u32_e32 v224, s92, v134
	s_add_i32 m0, s100, 0x6000
	s_nop 0
	global_load_lds_dwordx4 v224, s[86:87]
	s_waitcnt lgkmcnt(8)
	s_barrier
	s_waitcnt lgkmcnt(0)
	v_mfma_f32_16x16x32_bf16 v[124:127], v[190:193], v[174:177], v[124:127]
	v_mfma_f32_16x16x32_bf16 v[120:123], v[190:193], v[182:185], v[120:123]
	v_mfma_f32_16x16x32_bf16 v[116:119], v[200:203], v[174:177], v[116:119]
	v_mfma_f32_16x16x32_bf16 v[112:115], v[200:203], v[182:185], v[112:115]
	v_mfma_f32_16x16x32_bf16 v[108:111], v[208:211], v[174:177], v[108:111]
	v_mfma_f32_16x16x32_bf16 v[104:107], v[208:211], v[182:185], v[104:107]
	v_mfma_f32_16x16x32_bf16 v[100:103], v[216:219], v[174:177], v[100:103]
	v_mfma_f32_16x16x32_bf16 v[96:99], v[216:219], v[182:185], v[96:99]
	v_mfma_f32_16x16x32_bf16 v[124:127], v[196:199], v[178:181], v[124:127]
	v_mfma_f32_16x16x32_bf16 v[120:123], v[196:199], v[186:189], v[120:123]
	v_mfma_f32_16x16x32_bf16 v[116:119], v[204:207], v[178:181], v[116:119]
	v_mfma_f32_16x16x32_bf16 v[112:115], v[204:207], v[186:189], v[112:115]
	v_mfma_f32_16x16x32_bf16 v[108:111], v[212:215], v[178:181], v[108:111]
	v_mfma_f32_16x16x32_bf16 v[104:107], v[212:215], v[186:189], v[104:107]
	v_mfma_f32_16x16x32_bf16 v[100:103], v[220:223], v[178:181], v[100:103]
	v_mfma_f32_16x16x32_bf16 v[96:99], v[220:223], v[186:189], v[96:99]
	s_barrier
	v_add_u32_e32 v248, s94, v140
	s_add_i32 m0, s100, 0x18000
	ds_read_b128 v[224:227], v148
	ds_read_b128 v[228:231], v148 offset:1024
	ds_read_b128 v[232:235], v148 offset:2048
	ds_read_b128 v[236:239], v148 offset:3072
	global_load_lds_dwordx4 v248, s[86:87]
	v_add_u32_e32 v248, s94, v138
	s_add_i32 m0, s100, 0x1a000
	s_nop 0
	global_load_lds_dwordx4 v248, s[86:87]
	s_barrier
	s_waitcnt lgkmcnt(0)
	v_mfma_f32_16x16x32_bf16 v[92:95], v[190:193], v[224:227], v[92:95]
	v_mfma_f32_16x16x32_bf16 v[88:91], v[190:193], v[232:235], v[88:91]
	v_mfma_f32_16x16x32_bf16 v[84:87], v[200:203], v[224:227], v[84:87]
	v_mfma_f32_16x16x32_bf16 v[80:83], v[200:203], v[232:235], v[80:83]
	v_mfma_f32_16x16x32_bf16 v[76:79], v[208:211], v[224:227], v[76:79]
	v_mfma_f32_16x16x32_bf16 v[72:75], v[208:211], v[232:235], v[72:75]
	v_mfma_f32_16x16x32_bf16 v[68:71], v[216:219], v[224:227], v[68:71]
	v_mfma_f32_16x16x32_bf16 v[64:67], v[216:219], v[232:235], v[64:67]
	v_mfma_f32_16x16x32_bf16 v[92:95], v[196:199], v[228:231], v[92:95]
	v_mfma_f32_16x16x32_bf16 v[88:91], v[196:199], v[236:239], v[88:91]
	v_mfma_f32_16x16x32_bf16 v[84:87], v[204:207], v[228:231], v[84:87]
	v_mfma_f32_16x16x32_bf16 v[80:83], v[204:207], v[236:239], v[80:83]
	v_mfma_f32_16x16x32_bf16 v[76:79], v[212:215], v[228:231], v[76:79]
	v_mfma_f32_16x16x32_bf16 v[72:75], v[212:215], v[236:239], v[72:75]
	v_mfma_f32_16x16x32_bf16 v[68:71], v[220:223], v[228:231], v[68:71]
	v_mfma_f32_16x16x32_bf16 v[64:67], v[220:223], v[236:239], v[64:67]
	v_add_u32_e32 v240, vcc_lo, v136
	s_add_i32 m0, s100, 0x8000
	s_barrier
	ds_read_b128 v[190:193], v147 offset:49152
	ds_read_b128 v[196:199], v147 offset:50176
	ds_read_b128 v[200:203], v146 offset:49152
	ds_read_b128 v[204:207], v146 offset:50176
	ds_read_b128 v[208:211], v145 offset:49152
	ds_read_b128 v[212:215], v145 offset:50176
	ds_read_b128 v[216:219], v144 offset:49152
	ds_read_b128 v[220:223], v144 offset:50176
	global_load_lds_dwordx4 v240, s[86:87]
	v_add_u32_e32 v240, vcc_lo, v134
	s_add_i32 m0, s100, 0xa000
	s_nop 0
	global_load_lds_dwordx4 v240, s[86:87]
	s_barrier
; #define P8_STAGE(P,BASE,br,kt) do{const bfr* _ub=(BASE)+((long)(br)*K+(long)(kt)*BK); \
;     __builtin_amdgcn_global_load_lds((const unsigned*)(_ub+so0),(unsigned*)((char*)(P)+wid*1024),16,0,0); \
;     __builtin_amdgcn_global_load_lds((const unsigned*)(_ub+so1),(unsigned*)((char*)(P)+wid*1024+8192),16,0,0);}while(0)
; #define P8_LDA(dst,b,h) _Pragma("unroll") for(int m=0;m<4;++m) _Pragma("unroll") for(int k=0;k<2;++k) \
;     dst[m][k]=*reinterpret_cast<const bf16x8*>((char*)P8_SA(b,h)+lds_byte(wr*64+m*16+fr,k*32+fq*8))
; #define P8_LDB(dst,b,h) _Pragma("unroll") for(int n=0;n<2;++n) _Pragma("unroll") for(int k=0;k<2;++k) \
;     dst[n][k]=*reinterpret_cast<const bf16x8*>((char*)P8_SB(b,h)+lds_byte(wc*32+n*16+fr,k*32+fq*8))
; #define P8_MMA(ai,bj,At,Bt) do{__builtin_amdgcn_s_setprio(1); \
;     _Pragma("unroll") for(int m=0;m<4;++m) _Pragma("unroll") for(int n=0;n<2;++n) _Pragma("unroll") for(int k=0;k<2;++k) \
;       acc[ai][bj][m][n]=__builtin_amdgcn_mfma_f32_16x16x32_bf16(At[m][k],Bt[n][k],acc[ai][bj][m][n],0,0,0); \
;     __builtin_amdgcn_s_setprio(0);}while(0)
; #define P8_WAIT_V(n) asm volatile("s_waitcnt vmcnt(" #n ")":::"memory")
; #define P8_WAIT_L(n) asm volatile("s_waitcnt lgkmcnt(" #n ")":::"memory")
; #define P8_BAR __builtin_amdgcn_s_barrier()
; #define P8_SCHED __builtin_amdgcn_sched_barrier(0)
; template <class EPI>
; DEVI void gemm8_tile(const bfr* __restrict__ A, const bfr* __restrict__ Bt, int K, int brow, int bcol, int nbrow, int nbcol, char* shmc, EPI epi) {
;     ...
;     P8_BAR; P8_WAIT_L(0); P8_MMA(1,0,At,B0); P8_BAR; P8_SCHED;
;     P8_STAGE(P8_SB(1,1),Bt,bcol+128,t+3);
;     P8_WAIT_V(6); P8_BAR; P8_MMA(1,1,At,B1); P8_BAR;
;   }
;   { P8_LDB(B0,0,0); P8_LDA(At,0,0); P8_STAGE(P8_SA(1,1),A,brow+128,nt-1);
;     P8_BAR; P8_WAIT_L(0); P8_MMA(0,0,At,B0); P8_BAR;
;     P8_LDB(B1,0,1); P8_BAR; P8_WAIT_L(0); P8_MMA(0,1,At,B1); P8_BAR;
	s_waitcnt lgkmcnt(0)
	v_mfma_f32_16x16x32_bf16 v[60:63], v[190:193], v[174:177], v[60:63]
	v_mfma_f32_16x16x32_bf16 v[56:59], v[190:193], v[182:185], v[56:59]
	v_mfma_f32_16x16x32_bf16 v[52:55], v[200:203], v[174:177], v[52:55]
	v_mfma_f32_16x16x32_bf16 v[48:51], v[200:203], v[182:185], v[48:51]
	v_mfma_f32_16x16x32_bf16 v[44:47], v[208:211], v[174:177], v[44:47]
	v_mfma_f32_16x16x32_bf16 v[40:43], v[208:211], v[182:185], v[40:43]
	v_mfma_f32_16x16x32_bf16 v[36:39], v[216:219], v[174:177], v[36:39]
	v_mfma_f32_16x16x32_bf16 v[32:35], v[216:219], v[182:185], v[32:35]
	v_mfma_f32_16x16x32_bf16 v[60:63], v[196:199], v[178:181], v[60:63]
	v_mfma_f32_16x16x32_bf16 v[56:59], v[196:199], v[186:189], v[56:59]
	v_mfma_f32_16x16x32_bf16 v[52:55], v[204:207], v[178:181], v[52:55]
	v_mfma_f32_16x16x32_bf16 v[48:51], v[204:207], v[186:189], v[48:51]
	v_mfma_f32_16x16x32_bf16 v[44:47], v[212:215], v[178:181], v[44:47]
	v_mfma_f32_16x16x32_bf16 v[40:43], v[212:215], v[186:189], v[40:43]
	v_mfma_f32_16x16x32_bf16 v[36:39], v[220:223], v[178:181], v[36:39]
	v_mfma_f32_16x16x32_bf16 v[32:35], v[220:223], v[186:189], v[32:35]
	s_barrier
	v_add_u32_e32 v174, s96, v140
	s_add_i32 m0, s100, 0x1c000
	s_nop 0
	global_load_lds_dwordx4 v174, s[86:87]
	v_add_u32_e32 v174, s96, v138
	s_add_i32 m0, s100, 0x1e000
	s_nop 0
	global_load_lds_dwordx4 v174, s[86:87]
	s_waitcnt vmcnt(6)
	s_barrier
	v_mfma_f32_16x16x32_bf16 v[28:31], v[190:193], v[224:227], v[28:31]
	v_mfma_f32_16x16x32_bf16 v[24:27], v[190:193], v[232:235], v[24:27]
	v_mfma_f32_16x16x32_bf16 v[20:23], v[200:203], v[224:227], v[20:23]
	v_mfma_f32_16x16x32_bf16 v[16:19], v[200:203], v[232:235], v[16:19]
	v_mfma_f32_16x16x32_bf16 v[12:15], v[208:211], v[224:227], v[12:15]
	v_mfma_f32_16x16x32_bf16 v[8:11], v[208:211], v[232:235], v[8:11]
	v_mfma_f32_16x16x32_bf16 v[4:7], v[216:219], v[224:227], v[4:7]
	v_mfma_f32_16x16x32_bf16 v[0:3], v[216:219], v[232:235], v[0:3]
	v_mfma_f32_16x16x32_bf16 v[28:31], v[196:199], v[228:231], v[28:31]
	v_mfma_f32_16x16x32_bf16 v[24:27], v[196:199], v[236:239], v[24:27]
	v_mfma_f32_16x16x32_bf16 v[20:23], v[204:207], v[228:231], v[20:23]
	v_mfma_f32_16x16x32_bf16 v[16:19], v[204:207], v[236:239], v[16:19]
	v_mfma_f32_16x16x32_bf16 v[12:15], v[212:215], v[228:231], v[12:15]
	v_mfma_f32_16x16x32_bf16 v[8:11], v[212:215], v[236:239], v[8:11]
	v_mfma_f32_16x16x32_bf16 v[4:7], v[220:223], v[228:231], v[4:7]
	v_mfma_f32_16x16x32_bf16 v[0:3], v[220:223], v[236:239], v[0:3]
	s_add_i32 s0, s0, 2
	v_lshl_add_u64 v[134:135], v[134:135], 0, s[80:81]
	v_lshl_add_u64 v[136:137], v[136:137], 0, s[80:81]
	v_lshl_add_u64 v[138:139], v[138:139], 0, s[80:81]
	s_cmp_lt_u32 s0, 4
	v_lshl_add_u64 v[140:141], v[140:141], 0, s[80:81]
	s_barrier
	s_cbranch_scc1 .LBB0_175
	s_or_b32 s0, s34, 0x80
	s_ashr_i32 s1, s0, 31
	s_lshl_b64 s[0:1], s[0:1], 10
	s_add_u32 s0, s29, s0
	s_addc_u32 s1, s64, s1
	ds_read_b128 v[134:137], v157
	ds_read_b128 v[138:141], v157 offset:1024
	ds_read_b128 v[150:153], v157 offset:2048
	ds_read_b128 v[174:177], v157 offset:3072
	ds_read_b128 v[178:181], v147
	ds_read_b128 v[182:185], v147 offset:1024
	ds_read_b128 v[186:189], v146
	ds_read_b128 v[190:193], v146 offset:1024
	ds_read_b128 v[196:199], v145
	ds_read_b128 v[200:203], v145 offset:1024
	ds_read_b128 v[204:207], v144
	ds_read_b128 v[208:211], v144 offset:1024
	v_lshl_add_u64 v[156:157], v[166:167], 1, s[0:1]
	s_mov_b64 s[34:35], 0x380
	v_lshl_add_u64 v[156:157], v[156:157], 0, s[34:35]
	s_add_i32 m0, s100, 0xc000
	v_lshl_add_u64 v[132:133], v[132:133], 1, s[0:1]
	global_load_lds_dwordx4 v[156:157], off
	v_lshl_add_u64 v[132:133], v[132:133], 0, s[34:35]
	s_add_i32 m0, s100, 0xe000
	s_nop 0
	global_load_lds_dwordx4 v[132:133], off
	s_barrier
	s_waitcnt lgkmcnt(0)
	s_setprio 1
	s_waitcnt lgkmcnt(0)
	v_mfma_f32_16x16x32_bf16 v[124:127], v[178:181], v[134:137], v[124:127]
	v_mfma_f32_16x16x32_bf16 v[120:123], v[178:181], v[150:153], v[120:123]
	v_mfma_f32_16x16x32_bf16 v[116:119], v[186:189], v[134:137], v[116:119]
	v_mfma_f32_16x16x32_bf16 v[108:111], v[196:199], v[134:137], v[108:111]
	v_mfma_f32_16x16x32_bf16 v[124:127], v[182:185], v[138:141], v[124:127]
	v_mfma_f32_16x16x32_bf16 v[120:123], v[182:185], v[174:177], v[120:123]
	v_mfma_f32_16x16x32_bf16 v[116:119], v[190:193], v[138:141], v[116:119]
	v_mfma_f32_16x16x32_bf16 v[112:115], v[186:189], v[150:153], v[112:115]
	v_mfma_f32_16x16x32_bf16 v[108:111], v[200:203], v[138:141], v[108:111]
	v_mfma_f32_16x16x32_bf16 v[104:107], v[196:199], v[150:153], v[104:107]
	v_mfma_f32_16x16x32_bf16 v[100:103], v[204:207], v[134:137], v[100:103]
	v_mfma_f32_16x16x32_bf16 v[96:99], v[204:207], v[150:153], v[96:99]
	v_mfma_f32_16x16x32_bf16 v[212:215], v[190:193], v[174:177], v[112:115]
	v_mfma_f32_16x16x32_bf16 v[104:107], v[200:203], v[174:177], v[104:107]
	v_mfma_f32_16x16x32_bf16 v[216:219], v[208:211], v[138:141], v[100:103]
	v_mfma_f32_16x16x32_bf16 v[220:223], v[208:211], v[174:177], v[96:99]
	s_setprio 0
	s_barrier
	s_nop 1
	ds_read_b128 v[96:99], v154
	ds_read_b128 v[100:103], v154 offset:1024
	ds_read_b128 v[112:115], v154 offset:2048
	ds_read_b128 v[154:157], v154 offset:3072
	s_barrier
; #define P8_LDA(dst,b,h) _Pragma("unroll") for(int m=0;m<4;++m) _Pragma("unroll") for(int k=0;k<2;++k) \
;     dst[m][k]=*reinterpret_cast<const bf16x8*>((char*)P8_SA(b,h)+lds_byte(wr*64+m*16+fr,k*32+fq*8))
; #define P8_LDB(dst,b,h) _Pragma("unroll") for(int n=0;n<2;++n) _Pragma("unroll") for(int k=0;k<2;++k) \
;     dst[n][k]=*reinterpret_cast<const bf16x8*>((char*)P8_SB(b,h)+lds_byte(wc*32+n*16+fr,k*32+fq*8))
; #define P8_MMA(ai,bj,At,Bt) do{__builtin_amdgcn_s_setprio(1); \
;     _Pragma("unroll") for(int m=0;m<4;++m) _Pragma("unroll") for(int n=0;n<2;++n) _Pragma("unroll") for(int k=0;k<2;++k) \
;       acc[ai][bj][m][n]=__builtin_amdgcn_mfma_f32_16x16x32_bf16(At[m][k],Bt[n][k],acc[ai][bj][m][n],0,0,0); \
;     __builtin_amdgcn_s_setprio(0);}while(0)
; #define P8_WAIT_V(n) asm volatile("s_waitcnt vmcnt(" #n ")":::"memory")
; #define P8_WAIT_L(n) asm volatile("s_waitcnt lgkmcnt(" #n ")":::"memory")
; #define P8_BAR __builtin_amdgcn_s_barrier()
; template <class EPI>
; DEVI void gemm8_tile(const bfr* __restrict__ A, const bfr* __restrict__ Bt, int K, int brow, int bcol, int nbrow, int nbcol, char* shmc, EPI epi) {
;     ...
;     P8_LDB(B1,0,1); P8_BAR; P8_WAIT_L(0); P8_MMA(0,1,At,B1); P8_BAR;
;     P8_LDA(At,0,1); P8_WAIT_V(4); P8_BAR; P8_WAIT_L(0); P8_MMA(1,0,At,B0); P8_MMA(1,1,At,B1); P8_BAR; }
;   { P8_LDB(B0,1,0); P8_LDA(At,1,0); P8_WAIT_V(2); P8_BAR; P8_WAIT_L(0); P8_MMA(0,0,At,B0); P8_BAR;
	s_waitcnt lgkmcnt(0)
	s_setprio 1
	s_waitcnt lgkmcnt(0)
	v_mfma_f32_16x16x32_bf16 v[88:91], v[178:181], v[112:115], v[88:91]
	v_mfma_f32_16x16x32_bf16 v[84:87], v[186:189], v[96:99], v[84:87]
	v_mfma_f32_16x16x32_bf16 v[76:79], v[196:199], v[96:99], v[76:79]
	v_mfma_f32_16x16x32_bf16 v[72:75], v[196:199], v[112:115], v[72:75]
	v_mfma_f32_16x16x32_bf16 v[92:95], v[178:181], v[96:99], v[92:95]
	v_mfma_f32_16x16x32_bf16 v[88:91], v[182:185], v[154:157], v[88:91]
	v_mfma_f32_16x16x32_bf16 v[84:87], v[190:193], v[100:103], v[84:87]
	v_mfma_f32_16x16x32_bf16 v[80:83], v[186:189], v[112:115], v[80:83]
	v_mfma_f32_16x16x32_bf16 v[76:79], v[200:203], v[100:103], v[76:79]
	v_mfma_f32_16x16x32_bf16 v[72:75], v[200:203], v[154:157], v[72:75]
	v_mfma_f32_16x16x32_bf16 v[68:71], v[204:207], v[96:99], v[68:71]
	v_mfma_f32_16x16x32_bf16 v[64:67], v[204:207], v[112:115], v[64:67]
	v_mfma_f32_16x16x32_bf16 v[224:227], v[182:185], v[100:103], v[92:95]
	v_mfma_f32_16x16x32_bf16 v[178:181], v[190:193], v[154:157], v[80:83]
	v_mfma_f32_16x16x32_bf16 v[182:185], v[208:211], v[100:103], v[68:71]
	v_mfma_f32_16x16x32_bf16 v[186:189], v[208:211], v[154:157], v[64:67]
	s_setprio 0
	s_barrier
	s_nop 1
	ds_read_b128 v[64:67], v147 offset:16384
	ds_read_b128 v[68:71], v147 offset:17408
	ds_read_b128 v[80:83], v146 offset:16384
	ds_read_b128 v[92:95], v146 offset:17408
	ds_read_b128 v[190:193], v145 offset:16384
	ds_read_b128 v[196:199], v145 offset:17408
	ds_read_b128 v[200:203], v144 offset:16384
	ds_read_b128 v[204:207], v144 offset:17408
	s_waitcnt vmcnt(4)
	s_barrier
	s_waitcnt lgkmcnt(0)
	s_setprio 1
	s_waitcnt lgkmcnt(0)
	v_mfma_f32_16x16x32_bf16 v[60:63], v[64:67], v[134:137], v[60:63]
	v_mfma_f32_16x16x32_bf16 v[56:59], v[64:67], v[150:153], v[56:59]
	v_mfma_f32_16x16x32_bf16 v[52:55], v[80:83], v[134:137], v[52:55]
	v_mfma_f32_16x16x32_bf16 v[40:43], v[190:193], v[150:153], v[40:43]
	v_mfma_f32_16x16x32_bf16 v[36:39], v[200:203], v[134:137], v[36:39]
	v_mfma_f32_16x16x32_bf16 v[208:211], v[68:71], v[138:141], v[60:63]
	v_mfma_f32_16x16x32_bf16 v[56:59], v[68:71], v[174:177], v[56:59]
	v_mfma_f32_16x16x32_bf16 v[52:55], v[92:95], v[138:141], v[52:55]
	v_mfma_f32_16x16x32_bf16 v[48:51], v[80:83], v[150:153], v[48:51]
	v_mfma_f32_16x16x32_bf16 v[44:47], v[190:193], v[134:137], v[44:47]
	v_mfma_f32_16x16x32_bf16 v[40:43], v[196:199], v[174:177], v[40:43]
	v_mfma_f32_16x16x32_bf16 v[36:39], v[204:207], v[138:141], v[36:39]
	v_mfma_f32_16x16x32_bf16 v[32:35], v[200:203], v[150:153], v[32:35]
	v_mfma_f32_16x16x32_bf16 v[228:231], v[92:95], v[174:177], v[48:51]
	v_mfma_f32_16x16x32_bf16 v[232:235], v[196:199], v[138:141], v[44:47]
	v_mfma_f32_16x16x32_bf16 v[132:135], v[204:207], v[174:177], v[32:35]
	s_setprio 0
	s_setprio 1
	v_mfma_f32_16x16x32_bf16 v[24:27], v[64:67], v[112:115], v[24:27]
	v_mfma_f32_16x16x32_bf16 v[20:23], v[80:83], v[96:99], v[20:23]
	v_mfma_f32_16x16x32_bf16 v[8:11], v[190:193], v[112:115], v[8:11]
	v_mfma_f32_16x16x32_bf16 v[28:31], v[64:67], v[96:99], v[28:31]
	v_mfma_f32_16x16x32_bf16 v[24:27], v[68:71], v[154:157], v[24:27]
	v_mfma_f32_16x16x32_bf16 v[20:23], v[92:95], v[100:103], v[20:23]
	v_mfma_f32_16x16x32_bf16 v[16:19], v[80:83], v[112:115], v[16:19]
	v_mfma_f32_16x16x32_bf16 v[12:15], v[190:193], v[96:99], v[12:15]
	v_mfma_f32_16x16x32_bf16 v[8:11], v[196:199], v[154:157], v[8:11]
	v_mfma_f32_16x16x32_bf16 v[4:7], v[200:203], v[96:99], v[4:7]
	v_mfma_f32_16x16x32_bf16 v[0:3], v[200:203], v[112:115], v[0:3]
	v_mfma_f32_16x16x32_bf16 v[136:139], v[68:71], v[100:103], v[28:31]
	v_mfma_f32_16x16x32_bf16 v[150:153], v[92:95], v[154:157], v[16:19]
	v_mfma_f32_16x16x32_bf16 v[172:175], v[196:199], v[100:103], v[12:15]
	v_mfma_f32_16x16x32_bf16 v[190:193], v[204:207], v[100:103], v[4:7]
	v_mfma_f32_16x16x32_bf16 v[154:157], v[204:207], v[154:157], v[0:3]
	s_setprio 0
	s_barrier
	ds_read_b128 v[4:7], v149
	ds_read_b128 v[196:199], v149 offset:1024
	ds_read_b128 v[200:203], v149 offset:2048
	ds_read_b128 v[204:207], v149 offset:3072
	ds_read_b128 v[0:3], v147 offset:32768
	ds_read_b128 v[12:15], v147 offset:33792
	ds_read_b128 v[16:19], v146 offset:32768
	ds_read_b128 v[32:35], v146 offset:33792
	ds_read_b128 v[236:239], v145 offset:32768
	ds_read_b128 v[240:243], v145 offset:33792
	ds_read_b128 v[244:247], v144 offset:32768
	ds_read_b128 v[248:251], v144 offset:33792
	s_waitcnt vmcnt(2)
	s_barrier
; #define P8_LDA(dst,b,h) _Pragma("unroll") for(int m=0;m<4;++m) _Pragma("unroll") for(int k=0;k<2;++k) \
;     dst[m][k]=*reinterpret_cast<const bf16x8*>((char*)P8_SA(b,h)+lds_byte(wr*64+m*16+fr,k*32+fq*8))
; #define P8_LDB(dst,b,h) _Pragma("unroll") for(int n=0;n<2;++n) _Pragma("unroll") for(int k=0;k<2;++k) \
;     dst[n][k]=*reinterpret_cast<const bf16x8*>((char*)P8_SB(b,h)+lds_byte(wc*32+n*16+fr,k*32+fq*8))
; #define P8_MMA(ai,bj,At,Bt) do{__builtin_amdgcn_s_setprio(1); \
;     _Pragma("unroll") for(int m=0;m<4;++m) _Pragma("unroll") for(int n=0;n<2;++n) _Pragma("unroll") for(int k=0;k<2;++k) \
;       acc[ai][bj][m][n]=__builtin_amdgcn_mfma_f32_16x16x32_bf16(At[m][k],Bt[n][k],acc[ai][bj][m][n],0,0,0); \
;     __builtin_amdgcn_s_setprio(0);}while(0)
; #define P8_WAIT_V(n) asm volatile("s_waitcnt vmcnt(" #n ")":::"memory")
; #define P8_WAIT_L(n) asm volatile("s_waitcnt lgkmcnt(" #n ")":::"memory")
; #define P8_BAR __builtin_amdgcn_s_barrier()
; template <class EPI>
; DEVI void gemm8_tile(const bfr* __restrict__ A, const bfr* __restrict__ Bt, int K, int brow, int bcol, int nbrow, int nbcol, char* shmc, EPI epi) {
;     ...
;   { P8_LDB(B0,1,0); P8_LDA(At,1,0); P8_WAIT_V(2); P8_BAR; P8_WAIT_L(0); P8_MMA(0,0,At,B0); P8_BAR;
;     P8_LDB(B1,1,1); P8_WAIT_V(0); P8_BAR; P8_WAIT_L(0); P8_MMA(0,1,At,B1); P8_BAR;
;     P8_LDA(At,1,1); P8_BAR; P8_WAIT_L(0); P8_MMA(1,0,At,B0); P8_MMA(1,1,At,B1); P8_BAR; }
;   if(wr==0)P8_BAR;
	s_waitcnt lgkmcnt(0)
	s_setprio 1
	s_waitcnt lgkmcnt(0)
	v_mfma_f32_16x16x32_bf16 v[28:31], v[0:3], v[4:7], v[124:127]
	v_mfma_f32_16x16x32_bf16 v[124:127], v[12:15], v[196:199], v[28:31]
	v_mfma_f32_16x16x32_bf16 v[28:31], v[0:3], v[200:203], v[120:123]
	v_mfma_f32_16x16x32_bf16 v[92:95], v[12:15], v[204:207], v[28:31]
	v_mfma_f32_16x16x32_bf16 v[28:31], v[16:19], v[4:7], v[116:119]
	v_mfma_f32_16x16x32_bf16 v[112:115], v[32:35], v[196:199], v[28:31]
	v_mfma_f32_16x16x32_bf16 v[28:31], v[16:19], v[200:203], v[212:215]
	v_mfma_f32_16x16x32_bf16 v[80:83], v[32:35], v[204:207], v[28:31]
	v_mfma_f32_16x16x32_bf16 v[28:31], v[236:239], v[4:7], v[108:111]
	v_mfma_f32_16x16x32_bf16 v[100:103], v[240:243], v[196:199], v[28:31]
	v_mfma_f32_16x16x32_bf16 v[28:31], v[236:239], v[200:203], v[104:107]
	v_mfma_f32_16x16x32_bf16 v[68:71], v[240:243], v[204:207], v[28:31]
	v_mfma_f32_16x16x32_bf16 v[28:31], v[244:247], v[4:7], v[216:219]
	v_mfma_f32_16x16x32_bf16 v[96:99], v[248:251], v[196:199], v[28:31]
	v_mfma_f32_16x16x32_bf16 v[28:31], v[244:247], v[200:203], v[220:223]
	v_mfma_f32_16x16x32_bf16 v[64:67], v[248:251], v[204:207], v[28:31]
	s_setprio 0
	s_barrier
	ds_read_b128 v[212:215], v148
	ds_read_b128 v[216:219], v148 offset:1024
	ds_read_b128 v[220:223], v148 offset:2048
	ds_read_b128 v[104:107], v148 offset:3072
	s_waitcnt vmcnt(0)
	s_barrier
	s_waitcnt lgkmcnt(0)
	s_setprio 1
	s_waitcnt lgkmcnt(0)
	v_mfma_f32_16x16x32_bf16 v[28:31], v[0:3], v[212:215], v[224:227]
	v_mfma_f32_16x16x32_bf16 v[0:3], v[0:3], v[220:223], v[88:91]
	v_mfma_f32_16x16x32_bf16 v[60:63], v[12:15], v[216:219], v[28:31]
	v_mfma_f32_16x16x32_bf16 v[28:31], v[12:15], v[104:107], v[0:3]
	v_mfma_f32_16x16x32_bf16 v[0:3], v[16:19], v[212:215], v[84:87]
	v_mfma_f32_16x16x32_bf16 v[48:51], v[32:35], v[216:219], v[0:3]
	v_mfma_f32_16x16x32_bf16 v[0:3], v[16:19], v[220:223], v[178:181]
	v_mfma_f32_16x16x32_bf16 v[16:19], v[32:35], v[104:107], v[0:3]
	v_mfma_f32_16x16x32_bf16 v[0:3], v[236:239], v[212:215], v[76:79]
	v_mfma_f32_16x16x32_bf16 v[44:47], v[240:243], v[216:219], v[0:3]
	v_mfma_f32_16x16x32_bf16 v[0:3], v[236:239], v[220:223], v[72:75]
	v_mfma_f32_16x16x32_bf16 v[12:15], v[240:243], v[104:107], v[0:3]
	v_mfma_f32_16x16x32_bf16 v[0:3], v[244:247], v[212:215], v[182:185]
	v_mfma_f32_16x16x32_bf16 v[32:35], v[248:251], v[216:219], v[0:3]
	v_mfma_f32_16x16x32_bf16 v[0:3], v[244:247], v[220:223], v[186:189]
	v_mfma_f32_16x16x32_bf16 v[0:3], v[248:251], v[104:107], v[0:3]
	s_setprio 0
	s_barrier
	ds_read_b128 v[176:179], v147 offset:49152
	ds_read_b128 v[180:183], v147 offset:50176
	ds_read_b128 v[184:187], v146 offset:49152
	ds_read_b128 v[146:149], v146 offset:50176
	ds_read_b128 v[224:227], v145 offset:49152
	ds_read_b128 v[236:239], v145 offset:50176
	ds_read_b128 v[240:243], v144 offset:49152
	ds_read_b128 v[244:247], v144 offset:50176
	s_barrier
	s_waitcnt lgkmcnt(0)
	s_setprio 1
	s_waitcnt lgkmcnt(0)
	v_mfma_f32_16x16x32_bf16 v[52:55], v[184:187], v[4:7], v[52:55]
	v_mfma_f32_16x16x32_bf16 v[116:119], v[146:149], v[196:199], v[52:55]
	v_mfma_f32_16x16x32_bf16 v[52:55], v[184:187], v[200:203], v[228:231]
	v_mfma_f32_16x16x32_bf16 v[72:75], v[176:179], v[4:7], v[208:211]
	v_mfma_f32_16x16x32_bf16 v[84:87], v[146:149], v[204:207], v[52:55]
	v_mfma_f32_16x16x32_bf16 v[52:55], v[224:227], v[4:7], v[232:235]
	v_mfma_f32_16x16x32_bf16 v[4:7], v[240:243], v[4:7], v[36:39]
	v_mfma_f32_16x16x32_bf16 v[56:59], v[176:179], v[200:203], v[56:59]
	v_mfma_f32_16x16x32_bf16 v[40:43], v[224:227], v[200:203], v[40:43]
	v_mfma_f32_16x16x32_bf16 v[108:111], v[244:247], v[196:199], v[4:7]
	v_mfma_f32_16x16x32_bf16 v[4:7], v[240:243], v[200:203], v[132:135]
	v_mfma_f32_16x16x32_bf16 v[120:123], v[180:183], v[196:199], v[72:75]
	v_mfma_f32_16x16x32_bf16 v[88:91], v[180:183], v[204:207], v[56:59]
	v_mfma_f32_16x16x32_bf16 v[208:211], v[236:239], v[196:199], v[52:55]
	v_mfma_f32_16x16x32_bf16 v[72:75], v[236:239], v[204:207], v[40:43]
	v_mfma_f32_16x16x32_bf16 v[76:79], v[244:247], v[204:207], v[4:7]
	s_setprio 0
	s_setprio 1
	v_mfma_f32_16x16x32_bf16 v[4:7], v[176:179], v[212:215], v[136:139]
	v_mfma_f32_16x16x32_bf16 v[56:59], v[180:183], v[216:219], v[4:7]
	v_mfma_f32_16x16x32_bf16 v[4:7], v[176:179], v[220:223], v[24:27]
	v_mfma_f32_16x16x32_bf16 v[24:27], v[180:183], v[104:107], v[4:7]
	v_mfma_f32_16x16x32_bf16 v[4:7], v[184:187], v[212:215], v[20:23]
	v_mfma_f32_16x16x32_bf16 v[52:55], v[146:149], v[216:219], v[4:7]
	v_mfma_f32_16x16x32_bf16 v[4:7], v[184:187], v[220:223], v[150:153]
	v_mfma_f32_16x16x32_bf16 v[20:23], v[146:149], v[104:107], v[4:7]
	v_mfma_f32_16x16x32_bf16 v[4:7], v[224:227], v[212:215], v[172:175]
	v_mfma_f32_16x16x32_bf16 v[36:39], v[236:239], v[216:219], v[4:7]
	v_mfma_f32_16x16x32_bf16 v[4:7], v[224:227], v[220:223], v[8:11]
	v_mfma_f32_16x16x32_bf16 v[8:11], v[240:243], v[212:215], v[190:193]
	v_mfma_f32_16x16x32_bf16 v[40:43], v[244:247], v[216:219], v[8:11]
	v_mfma_f32_16x16x32_bf16 v[8:11], v[240:243], v[220:223], v[154:157]
	v_mfma_f32_16x16x32_bf16 v[4:7], v[236:239], v[104:107], v[4:7]
	v_mfma_f32_16x16x32_bf16 v[8:11], v[244:247], v[104:107], v[8:11]
	s_setprio 0
	v_cmp_gt_u32_e32 vcc, s57, v142
	s_barrier
	s_and_saveexec_b64 s[0:1], vcc
	s_cbranch_execz .LBB0_178
	s_barrier

; #define P8_STAGE(P,BASE,br,kt) do{const bfr* _ub=(BASE)+((long)(br)*K+(long)(kt)*BK); \
;     __builtin_amdgcn_global_load_lds((const unsigned*)(_ub+so0),(unsigned*)((char*)(P)+wid*1024),16,0,0); \
;     __builtin_amdgcn_global_load_lds((const unsigned*)(_ub+so1),(unsigned*)((char*)(P)+wid*1024+8192),16,0,0);}while(0)
; #define P8_LDA(dst,b,h) _Pragma("unroll") for(int m=0;m<4;++m) _Pragma("unroll") for(int k=0;k<2;++k) \
;     dst[m][k]=*reinterpret_cast<const bf16x8*>((char*)P8_SA(b,h)+lds_byte(wr*64+m*16+fr,k*32+fq*8))
; #define P8_LDB(dst,b,h) _Pragma("unroll") for(int n=0;n<2;++n) _Pragma("unroll") for(int k=0;k<2;++k) \
;     dst[n][k]=*reinterpret_cast<const bf16x8*>((char*)P8_SB(b,h)+lds_byte(wc*32+n*16+fr,k*32+fq*8))
; #define P8_MMA(ai,bj,At,Bt) do{__builtin_amdgcn_s_setprio(1); \
;     _Pragma("unroll") for(int m=0;m<4;++m) _Pragma("unroll") for(int n=0;n<2;++n) _Pragma("unroll") for(int k=0;k<2;++k) \
;       acc[ai][bj][m][n]=__builtin_amdgcn_mfma_f32_16x16x32_bf16(At[m][k],Bt[n][k],acc[ai][bj][m][n],0,0,0); \
;     __builtin_amdgcn_s_setprio(0);}while(0)
; #define P8_WAIT_V(n) asm volatile("s_waitcnt vmcnt(" #n ")":::"memory")
; #define P8_WAIT_L(n) asm volatile("s_waitcnt lgkmcnt(" #n ")":::"memory")
; #define P8_BAR __builtin_amdgcn_s_barrier()
; #define P8_SCHED __builtin_amdgcn_sched_barrier(0)
; template <class EPI>
; DEVI void gemm8_tile(const bfr* __restrict__ A, const bfr* __restrict__ Bt, int K, int brow, int bcol, int nbrow, int nbcol, char* shmc, EPI epi) {
;     ...
;     P8_LDB(B0,0,0); P8_SCHED; P8_LDA(At,0,0); P8_STAGE(P8_SA(1,1),A,brow+128,t+1);
;     P8_WAIT_L(8); P8_BAR; P8_WAIT_L(0); P8_MMA(0,0,At,B0); P8_BAR; P8_SCHED;
;     P8_LDB(B1,0,1); P8_STAGE(P8_SB(0,0),Bt,bcol,t+2);
;     P8_BAR; P8_WAIT_L(0); P8_MMA(0,1,At,B1); P8_BAR;
;     P8_LDA(At,0,1); P8_STAGE(P8_SA(0,0),A,brow,t+2);
;     P8_BAR; P8_WAIT_L(0); P8_MMA(1,0,At,B0); P8_BAR; P8_SCHED;
;     P8_STAGE(P8_SB(0,1),Bt,bcol+128,t+2);
;     P8_WAIT_V(6); P8_BAR; P8_MMA(1,1,At,B1); P8_BAR;
.LBB0_221:
	ds_read_b128 v[174:177], v157
	ds_read_b128 v[178:181], v157 offset:1024
	ds_read_b128 v[182:185], v157 offset:2048
	ds_read_b128 v[186:189], v157 offset:3072
	v_add_u32_e32 v171, 0xc000, v143
	v_add_u32_e32 v172, 0xe000, v143
	v_add_u32_e32 v158, s54, v136
	s_add_i32 m0, s100, 0xc000
	ds_read_b128 v[160:163], v147
	ds_read_b128 v[190:193], v147 offset:1024
	ds_read_b128 v[196:199], v146
	ds_read_b128 v[208:211], v146 offset:1024
	ds_read_b128 v[212:215], v145
	ds_read_b128 v[216:219], v145 offset:1024
	ds_read_b128 v[220:223], v144
	ds_read_b128 v[224:227], v144 offset:1024
	global_load_lds_dwordx4 v158, s[86:87]
	v_add_u32_e32 v158, s54, v134
	s_add_i32 m0, s100, 0xe000
	s_nop 0
	global_load_lds_dwordx4 v158, s[86:87]
	s_waitcnt lgkmcnt(8)
	s_barrier
	s_waitcnt lgkmcnt(0)
	v_mfma_f32_16x16x32_bf16 v[124:127], v[160:163], v[174:177], v[124:127]
	v_mfma_f32_16x16x32_bf16 v[120:123], v[160:163], v[182:185], v[120:123]
	v_mfma_f32_16x16x32_bf16 v[116:119], v[196:199], v[174:177], v[116:119]
	v_mfma_f32_16x16x32_bf16 v[112:115], v[196:199], v[182:185], v[112:115]
	v_mfma_f32_16x16x32_bf16 v[108:111], v[212:215], v[174:177], v[108:111]
	v_mfma_f32_16x16x32_bf16 v[104:107], v[212:215], v[182:185], v[104:107]
	v_mfma_f32_16x16x32_bf16 v[100:103], v[220:223], v[174:177], v[100:103]
	v_mfma_f32_16x16x32_bf16 v[96:99], v[220:223], v[182:185], v[96:99]
	v_mfma_f32_16x16x32_bf16 v[124:127], v[190:193], v[178:181], v[124:127]
	v_mfma_f32_16x16x32_bf16 v[120:123], v[190:193], v[186:189], v[120:123]
	v_mfma_f32_16x16x32_bf16 v[116:119], v[208:211], v[178:181], v[116:119]
	v_mfma_f32_16x16x32_bf16 v[112:115], v[208:211], v[186:189], v[112:115]
	v_mfma_f32_16x16x32_bf16 v[108:111], v[216:219], v[178:181], v[108:111]
	v_mfma_f32_16x16x32_bf16 v[104:107], v[216:219], v[186:189], v[104:107]
	v_mfma_f32_16x16x32_bf16 v[100:103], v[224:227], v[178:181], v[100:103]
	v_mfma_f32_16x16x32_bf16 v[96:99], v[224:227], v[186:189], v[96:99]
	s_barrier
	v_add_u32_e32 v158, 0x10000, v143
	v_add_u32_e32 v206, s66, v140
	s_add_i32 m0, s100, 0x10000
	v_add_u32_e32 v159, 0x12000, v143
	ds_read_b128 v[228:231], v155
	ds_read_b128 v[232:235], v155 offset:1024
	ds_read_b128 v[236:239], v155 offset:2048
	ds_read_b128 v[240:243], v155 offset:3072
	global_load_lds_dwordx4 v206, s[86:87]
	v_add_u32_e32 v244, s66, v138
	s_add_i32 m0, s100, 0x12000
	s_nop 0
	global_load_lds_dwordx4 v244, s[86:87]
	s_barrier
	s_waitcnt lgkmcnt(0)
	v_mfma_f32_16x16x32_bf16 v[92:95], v[160:163], v[228:231], v[92:95]
	v_mfma_f32_16x16x32_bf16 v[88:91], v[160:163], v[236:239], v[88:91]
	v_mfma_f32_16x16x32_bf16 v[84:87], v[196:199], v[228:231], v[84:87]
	v_mfma_f32_16x16x32_bf16 v[80:83], v[196:199], v[236:239], v[80:83]
	v_mfma_f32_16x16x32_bf16 v[76:79], v[212:215], v[228:231], v[76:79]
	v_mfma_f32_16x16x32_bf16 v[72:75], v[212:215], v[236:239], v[72:75]
	v_mfma_f32_16x16x32_bf16 v[68:71], v[220:223], v[228:231], v[68:71]
	v_mfma_f32_16x16x32_bf16 v[64:67], v[220:223], v[236:239], v[64:67]
	v_mfma_f32_16x16x32_bf16 v[92:95], v[190:193], v[232:235], v[92:95]
	v_mfma_f32_16x16x32_bf16 v[88:91], v[190:193], v[240:243], v[88:91]
	v_mfma_f32_16x16x32_bf16 v[84:87], v[208:211], v[232:235], v[84:87]
	v_mfma_f32_16x16x32_bf16 v[80:83], v[208:211], v[240:243], v[80:83]
	v_mfma_f32_16x16x32_bf16 v[76:79], v[216:219], v[232:235], v[76:79]
	v_mfma_f32_16x16x32_bf16 v[72:75], v[216:219], v[240:243], v[72:75]
	v_mfma_f32_16x16x32_bf16 v[68:71], v[224:227], v[232:235], v[68:71]
	v_mfma_f32_16x16x32_bf16 v[64:67], v[224:227], v[240:243], v[64:67]
	v_add_u32_e32 v160, s80, v136
	s_mov_b32 m0, s100
	s_barrier
	ds_read_b128 v[190:193], v147 offset:16384
	ds_read_b128 v[196:199], v147 offset:17408
	ds_read_b128 v[208:211], v146 offset:16384
	ds_read_b128 v[212:215], v146 offset:17408
	ds_read_b128 v[216:219], v145 offset:16384
	ds_read_b128 v[220:223], v145 offset:17408
	ds_read_b128 v[224:227], v144 offset:16384
	ds_read_b128 v[244:247], v144 offset:17408
	global_load_lds_dwordx4 v160, s[86:87]
	v_add_u32_e32 v160, 0x2000, v143
	v_add_u32_e32 v162, s80, v134
	s_add_i32 m0, s100, 0x2000
	s_nop 0
	global_load_lds_dwordx4 v162, s[86:87]
	s_barrier
	s_waitcnt lgkmcnt(0)
	v_mfma_f32_16x16x32_bf16 v[60:63], v[190:193], v[174:177], v[60:63]
	v_mfma_f32_16x16x32_bf16 v[56:59], v[190:193], v[182:185], v[56:59]
	v_mfma_f32_16x16x32_bf16 v[52:55], v[208:211], v[174:177], v[52:55]
	v_mfma_f32_16x16x32_bf16 v[48:51], v[208:211], v[182:185], v[48:51]
	v_mfma_f32_16x16x32_bf16 v[44:47], v[216:219], v[174:177], v[44:47]
	v_mfma_f32_16x16x32_bf16 v[40:43], v[216:219], v[182:185], v[40:43]
	v_mfma_f32_16x16x32_bf16 v[36:39], v[224:227], v[174:177], v[36:39]
	v_mfma_f32_16x16x32_bf16 v[32:35], v[224:227], v[182:185], v[32:35]
	v_mfma_f32_16x16x32_bf16 v[60:63], v[196:199], v[178:181], v[60:63]
	v_mfma_f32_16x16x32_bf16 v[56:59], v[196:199], v[186:189], v[56:59]
	v_mfma_f32_16x16x32_bf16 v[52:55], v[212:215], v[178:181], v[52:55]
	v_mfma_f32_16x16x32_bf16 v[48:51], v[212:215], v[186:189], v[48:51]
	v_mfma_f32_16x16x32_bf16 v[44:47], v[220:223], v[178:181], v[44:47]
	v_mfma_f32_16x16x32_bf16 v[40:43], v[220:223], v[186:189], v[40:43]
	v_mfma_f32_16x16x32_bf16 v[36:39], v[244:247], v[178:181], v[36:39]
	v_mfma_f32_16x16x32_bf16 v[32:35], v[244:247], v[186:189], v[32:35]
	s_barrier
	v_add_u32_e32 v161, 0x14000, v143
	v_add_u32_e32 v162, s70, v140
	s_add_i32 m0, s100, 0x14000
	v_add_u32_e32 v174, s70, v138
	global_load_lds_dwordx4 v162, s[86:87]
	v_add_u32_e32 v162, 0x16000, v143
	s_nop 0
	s_add_i32 m0, s100, 0x16000
	s_nop 0
	global_load_lds_dwordx4 v174, s[86:87]
	s_waitcnt vmcnt(6)
	s_barrier
; #define P8_STAGE(P,BASE,br,kt) do{const bfr* _ub=(BASE)+((long)(br)*K+(long)(kt)*BK); \
;     __builtin_amdgcn_global_load_lds((const unsigned*)(_ub+so0),(unsigned*)((char*)(P)+wid*1024),16,0,0); \
;     __builtin_amdgcn_global_load_lds((const unsigned*)(_ub+so1),(unsigned*)((char*)(P)+wid*1024+8192),16,0,0);}while(0)
; #define P8_LDA(dst,b,h) _Pragma("unroll") for(int m=0;m<4;++m) _Pragma("unroll") for(int k=0;k<2;++k) \
;     dst[m][k]=*reinterpret_cast<const bf16x8*>((char*)P8_SA(b,h)+lds_byte(wr*64+m*16+fr,k*32+fq*8))
; #define P8_LDB(dst,b,h) _Pragma("unroll") for(int n=0;n<2;++n) _Pragma("unroll") for(int k=0;k<2;++k) \
;     dst[n][k]=*reinterpret_cast<const bf16x8*>((char*)P8_SB(b,h)+lds_byte(wc*32+n*16+fr,k*32+fq*8))
; #define P8_MMA(ai,bj,At,Bt) do{__builtin_amdgcn_s_setprio(1); \
;     _Pragma("unroll") for(int m=0;m<4;++m) _Pragma("unroll") for(int n=0;n<2;++n) _Pragma("unroll") for(int k=0;k<2;++k) \
;       acc[ai][bj][m][n]=__builtin_amdgcn_mfma_f32_16x16x32_bf16(At[m][k],Bt[n][k],acc[ai][bj][m][n],0,0,0); \
;     __builtin_amdgcn_s_setprio(0);}while(0)
; #define P8_WAIT_V(n) asm volatile("s_waitcnt vmcnt(" #n ")":::"memory")
; #define P8_WAIT_L(n) asm volatile("s_waitcnt lgkmcnt(" #n ")":::"memory")
; #define P8_BAR __builtin_amdgcn_s_barrier()
; #define P8_SCHED __builtin_amdgcn_sched_barrier(0)
; template <class EPI>
; DEVI void gemm8_tile(const bfr* __restrict__ A, const bfr* __restrict__ Bt, int K, int brow, int bcol, int nbrow, int nbcol, char* shmc, EPI epi) {
;     ...
;     P8_WAIT_V(6); P8_BAR; P8_MMA(1,1,At,B1); P8_BAR;
;     P8_LDB(B0,1,0); P8_SCHED; P8_LDA(At,1,0); P8_STAGE(P8_SA(0,1),A,brow+128,t+2);
;     P8_WAIT_L(8); P8_BAR; P8_WAIT_L(0); P8_MMA(0,0,At,B0); P8_BAR; P8_SCHED;
;     P8_LDB(B1,1,1); P8_STAGE(P8_SB(1,0),Bt,bcol,t+3);
;     P8_BAR; P8_WAIT_L(0); P8_MMA(0,1,At,B1); P8_BAR;
;     P8_LDA(At,1,1); P8_STAGE(P8_SA(1,0),A,brow,t+3);
	v_mfma_f32_16x16x32_bf16 v[28:31], v[190:193], v[228:231], v[28:31]
	v_mfma_f32_16x16x32_bf16 v[24:27], v[190:193], v[236:239], v[24:27]
	v_mfma_f32_16x16x32_bf16 v[20:23], v[208:211], v[228:231], v[20:23]
	v_mfma_f32_16x16x32_bf16 v[16:19], v[208:211], v[236:239], v[16:19]
	v_mfma_f32_16x16x32_bf16 v[12:15], v[216:219], v[228:231], v[12:15]
	v_mfma_f32_16x16x32_bf16 v[8:11], v[216:219], v[236:239], v[8:11]
	v_mfma_f32_16x16x32_bf16 v[4:7], v[224:227], v[228:231], v[4:7]
	v_mfma_f32_16x16x32_bf16 v[0:3], v[224:227], v[236:239], v[0:3]
	v_mfma_f32_16x16x32_bf16 v[28:31], v[196:199], v[232:235], v[28:31]
	v_mfma_f32_16x16x32_bf16 v[24:27], v[196:199], v[240:243], v[24:27]
	v_mfma_f32_16x16x32_bf16 v[20:23], v[212:215], v[232:235], v[20:23]
	v_mfma_f32_16x16x32_bf16 v[16:19], v[212:215], v[240:243], v[16:19]
	v_mfma_f32_16x16x32_bf16 v[12:15], v[220:223], v[232:235], v[12:15]
	v_mfma_f32_16x16x32_bf16 v[8:11], v[220:223], v[240:243], v[8:11]
	v_mfma_f32_16x16x32_bf16 v[4:7], v[244:247], v[232:235], v[4:7]
	v_mfma_f32_16x16x32_bf16 v[0:3], v[244:247], v[240:243], v[0:3]
	s_barrier
	ds_read_b128 v[174:177], v149
	ds_read_b128 v[178:181], v149 offset:1024
	ds_read_b128 v[182:185], v149 offset:2048
	ds_read_b128 v[186:189], v149 offset:3072
	v_add_u32_e32 v163, 0x4000, v143
	v_add_u32_e32 v170, 0x6000, v143
	v_add_u32_e32 v232, s60, v136
	s_add_i32 m0, s100, 0x4000
	ds_read_b128 v[190:193], v147 offset:32768
	ds_read_b128 v[196:199], v147 offset:33792
	ds_read_b128 v[208:211], v146 offset:32768
	ds_read_b128 v[212:215], v146 offset:33792
	ds_read_b128 v[216:219], v145 offset:32768
	ds_read_b128 v[220:223], v145 offset:33792
	ds_read_b128 v[224:227], v144 offset:32768
	ds_read_b128 v[228:231], v144 offset:33792
	global_load_lds_dwordx4 v232, s[86:87]
	v_add_u32_e32 v232, s60, v134
	s_add_i32 m0, s100, 0x6000
	s_nop 0
	global_load_lds_dwordx4 v232, s[86:87]
	s_waitcnt lgkmcnt(8)
	s_barrier
	s_waitcnt lgkmcnt(0)
	v_mfma_f32_16x16x32_bf16 v[124:127], v[190:193], v[174:177], v[124:127]
	v_mfma_f32_16x16x32_bf16 v[120:123], v[190:193], v[182:185], v[120:123]
	v_mfma_f32_16x16x32_bf16 v[116:119], v[208:211], v[174:177], v[116:119]
	v_mfma_f32_16x16x32_bf16 v[112:115], v[208:211], v[182:185], v[112:115]
	v_mfma_f32_16x16x32_bf16 v[108:111], v[216:219], v[174:177], v[108:111]
	v_mfma_f32_16x16x32_bf16 v[104:107], v[216:219], v[182:185], v[104:107]
	v_mfma_f32_16x16x32_bf16 v[100:103], v[224:227], v[174:177], v[100:103]
	v_mfma_f32_16x16x32_bf16 v[96:99], v[224:227], v[182:185], v[96:99]
	v_mfma_f32_16x16x32_bf16 v[124:127], v[196:199], v[178:181], v[124:127]
	v_mfma_f32_16x16x32_bf16 v[120:123], v[196:199], v[186:189], v[120:123]
	v_mfma_f32_16x16x32_bf16 v[116:119], v[212:215], v[178:181], v[116:119]
	v_mfma_f32_16x16x32_bf16 v[112:115], v[212:215], v[186:189], v[112:115]
	v_mfma_f32_16x16x32_bf16 v[108:111], v[220:223], v[178:181], v[108:111]
	v_mfma_f32_16x16x32_bf16 v[104:107], v[220:223], v[186:189], v[104:107]
	v_mfma_f32_16x16x32_bf16 v[100:103], v[228:231], v[178:181], v[100:103]
	v_mfma_f32_16x16x32_bf16 v[96:99], v[228:231], v[186:189], v[96:99]
	s_barrier
	v_add_u32_e32 v248, s74, v140
	s_add_i32 m0, s100, 0x18000
	ds_read_b128 v[232:235], v148
	ds_read_b128 v[236:239], v148 offset:1024
	ds_read_b128 v[240:243], v148 offset:2048
	ds_read_b128 v[244:247], v148 offset:3072
	global_load_lds_dwordx4 v248, s[86:87]
	v_add_u32_e32 v248, s74, v138
	s_add_i32 m0, s100, 0x1a000
	s_nop 0
	global_load_lds_dwordx4 v248, s[86:87]
	s_barrier
	s_waitcnt lgkmcnt(0)
	v_mfma_f32_16x16x32_bf16 v[92:95], v[190:193], v[232:235], v[92:95]
	v_mfma_f32_16x16x32_bf16 v[88:91], v[190:193], v[240:243], v[88:91]
	v_mfma_f32_16x16x32_bf16 v[84:87], v[208:211], v[232:235], v[84:87]
	v_mfma_f32_16x16x32_bf16 v[80:83], v[208:211], v[240:243], v[80:83]
	v_mfma_f32_16x16x32_bf16 v[76:79], v[216:219], v[232:235], v[76:79]
	v_mfma_f32_16x16x32_bf16 v[72:75], v[216:219], v[240:243], v[72:75]
	v_mfma_f32_16x16x32_bf16 v[68:71], v[224:227], v[232:235], v[68:71]
	v_mfma_f32_16x16x32_bf16 v[64:67], v[224:227], v[240:243], v[64:67]
	v_mfma_f32_16x16x32_bf16 v[92:95], v[196:199], v[236:239], v[92:95]
	v_mfma_f32_16x16x32_bf16 v[88:91], v[196:199], v[244:247], v[88:91]
	v_mfma_f32_16x16x32_bf16 v[84:87], v[212:215], v[236:239], v[84:87]
	v_mfma_f32_16x16x32_bf16 v[80:83], v[212:215], v[244:247], v[80:83]
	v_mfma_f32_16x16x32_bf16 v[76:79], v[220:223], v[236:239], v[76:79]
	v_mfma_f32_16x16x32_bf16 v[72:75], v[220:223], v[244:247], v[72:75]
	v_mfma_f32_16x16x32_bf16 v[68:71], v[228:231], v[236:239], v[68:71]
	v_mfma_f32_16x16x32_bf16 v[64:67], v[228:231], v[244:247], v[64:67]
	v_add_u32_e32 v200, s72, v136
	s_add_i32 m0, s100, 0x8000
	s_barrier
	ds_read_b128 v[190:193], v147 offset:49152
	ds_read_b128 v[196:199], v147 offset:50176
	ds_read_b128 v[208:211], v146 offset:49152
	ds_read_b128 v[212:215], v146 offset:50176
	ds_read_b128 v[216:219], v145 offset:49152
	ds_read_b128 v[220:223], v145 offset:50176
	ds_read_b128 v[224:227], v144 offset:49152
	ds_read_b128 v[228:231], v144 offset:50176
	global_load_lds_dwordx4 v200, s[86:87]
	v_add_u32_e32 v200, s72, v134
	s_add_i32 m0, s100, 0xa000
	s_nop 0
	global_load_lds_dwordx4 v200, s[86:87]
	s_barrier
; #define P8_STAGE(P,BASE,br,kt) do{const bfr* _ub=(BASE)+((long)(br)*K+(long)(kt)*BK); \
;     __builtin_amdgcn_global_load_lds((const unsigned*)(_ub+so0),(unsigned*)((char*)(P)+wid*1024),16,0,0); \
;     __builtin_amdgcn_global_load_lds((const unsigned*)(_ub+so1),(unsigned*)((char*)(P)+wid*1024+8192),16,0,0);}while(0)
; #define P8_LDA(dst,b,h) _Pragma("unroll") for(int m=0;m<4;++m) _Pragma("unroll") for(int k=0;k<2;++k) \
;     dst[m][k]=*reinterpret_cast<const bf16x8*>((char*)P8_SA(b,h)+lds_byte(wr*64+m*16+fr,k*32+fq*8))
; #define P8_LDB(dst,b,h) _Pragma("unroll") for(int n=0;n<2;++n) _Pragma("unroll") for(int k=0;k<2;++k) \
;     dst[n][k]=*reinterpret_cast<const bf16x8*>((char*)P8_SB(b,h)+lds_byte(wc*32+n*16+fr,k*32+fq*8))
; #define P8_MMA(ai,bj,At,Bt) do{__builtin_amdgcn_s_setprio(1); \
;     _Pragma("unroll") for(int m=0;m<4;++m) _Pragma("unroll") for(int n=0;n<2;++n) _Pragma("unroll") for(int k=0;k<2;++k) \
;       acc[ai][bj][m][n]=__builtin_amdgcn_mfma_f32_16x16x32_bf16(At[m][k],Bt[n][k],acc[ai][bj][m][n],0,0,0); \
;     __builtin_amdgcn_s_setprio(0);}while(0)
; #define P8_WAIT_V(n) asm volatile("s_waitcnt vmcnt(" #n ")":::"memory")
; #define P8_WAIT_L(n) asm volatile("s_waitcnt lgkmcnt(" #n ")":::"memory")
; #define P8_BAR __builtin_amdgcn_s_barrier()
; #define P8_SCHED __builtin_amdgcn_sched_barrier(0)
; template <class EPI>
; DEVI void gemm8_tile(const bfr* __restrict__ A, const bfr* __restrict__ Bt, int K, int brow, int bcol, int nbrow, int nbcol, char* shmc, EPI epi) {
;     ...
;     P8_BAR; P8_WAIT_L(0); P8_MMA(1,0,At,B0); P8_BAR; P8_SCHED;
;     P8_STAGE(P8_SB(1,1),Bt,bcol+128,t+3);
;     P8_WAIT_V(6); P8_BAR; P8_MMA(1,1,At,B1); P8_BAR;
;   }
;   { P8_LDB(B0,0,0); P8_LDA(At,0,0); P8_STAGE(P8_SA(1,1),A,brow+128,nt-1);
;     P8_BAR; P8_WAIT_L(0); P8_MMA(0,0,At,B0); P8_BAR;
;     P8_LDB(B1,0,1); P8_BAR; P8_WAIT_L(0); P8_MMA(0,1,At,B1); P8_BAR;
	s_waitcnt lgkmcnt(0)
	v_mfma_f32_16x16x32_bf16 v[60:63], v[190:193], v[174:177], v[60:63]
	v_mfma_f32_16x16x32_bf16 v[56:59], v[190:193], v[182:185], v[56:59]
	v_mfma_f32_16x16x32_bf16 v[52:55], v[208:211], v[174:177], v[52:55]
	v_mfma_f32_16x16x32_bf16 v[48:51], v[208:211], v[182:185], v[48:51]
	v_mfma_f32_16x16x32_bf16 v[44:47], v[216:219], v[174:177], v[44:47]
	v_mfma_f32_16x16x32_bf16 v[40:43], v[216:219], v[182:185], v[40:43]
	v_mfma_f32_16x16x32_bf16 v[36:39], v[224:227], v[174:177], v[36:39]
	v_mfma_f32_16x16x32_bf16 v[32:35], v[224:227], v[182:185], v[32:35]
	v_mfma_f32_16x16x32_bf16 v[60:63], v[196:199], v[178:181], v[60:63]
	v_mfma_f32_16x16x32_bf16 v[56:59], v[196:199], v[186:189], v[56:59]
	v_mfma_f32_16x16x32_bf16 v[52:55], v[212:215], v[178:181], v[52:55]
	v_mfma_f32_16x16x32_bf16 v[48:51], v[212:215], v[186:189], v[48:51]
	v_mfma_f32_16x16x32_bf16 v[44:47], v[220:223], v[178:181], v[44:47]
	v_mfma_f32_16x16x32_bf16 v[40:43], v[220:223], v[186:189], v[40:43]
	v_mfma_f32_16x16x32_bf16 v[36:39], v[228:231], v[178:181], v[36:39]
	v_mfma_f32_16x16x32_bf16 v[32:35], v[228:231], v[186:189], v[32:35]
	s_barrier
	v_add_u32_e32 v174, s78, v140
	s_add_i32 m0, s100, 0x1c000
	s_nop 0
	global_load_lds_dwordx4 v174, s[86:87]
	v_add_u32_e32 v174, s78, v138
	s_add_i32 m0, s100, 0x1e000
	s_nop 0
	global_load_lds_dwordx4 v174, s[86:87]
	s_waitcnt vmcnt(6)
	s_barrier
	v_mfma_f32_16x16x32_bf16 v[28:31], v[190:193], v[232:235], v[28:31]
	v_mfma_f32_16x16x32_bf16 v[24:27], v[190:193], v[240:243], v[24:27]
	v_mfma_f32_16x16x32_bf16 v[20:23], v[208:211], v[232:235], v[20:23]
	v_mfma_f32_16x16x32_bf16 v[16:19], v[208:211], v[240:243], v[16:19]
	v_mfma_f32_16x16x32_bf16 v[12:15], v[216:219], v[232:235], v[12:15]
	v_mfma_f32_16x16x32_bf16 v[8:11], v[216:219], v[240:243], v[8:11]
	v_mfma_f32_16x16x32_bf16 v[4:7], v[224:227], v[232:235], v[4:7]
	v_mfma_f32_16x16x32_bf16 v[0:3], v[224:227], v[240:243], v[0:3]
	v_mfma_f32_16x16x32_bf16 v[28:31], v[196:199], v[236:239], v[28:31]
	v_mfma_f32_16x16x32_bf16 v[24:27], v[196:199], v[244:247], v[24:27]
	v_mfma_f32_16x16x32_bf16 v[20:23], v[212:215], v[236:239], v[20:23]
	v_mfma_f32_16x16x32_bf16 v[16:19], v[212:215], v[244:247], v[16:19]
	v_mfma_f32_16x16x32_bf16 v[12:15], v[220:223], v[236:239], v[12:15]
	v_mfma_f32_16x16x32_bf16 v[8:11], v[220:223], v[244:247], v[8:11]
	v_mfma_f32_16x16x32_bf16 v[4:7], v[228:231], v[236:239], v[4:7]
	v_mfma_f32_16x16x32_bf16 v[0:3], v[228:231], v[244:247], v[0:3]
	s_add_i32 s0, s0, 2
	v_lshl_add_u64 v[134:135], v[134:135], 0, s[80:81]
	v_lshl_add_u64 v[136:137], v[136:137], 0, s[80:81]
	v_lshl_add_u64 v[138:139], v[138:139], 0, s[80:81]
	s_cmp_lt_u32 s0, 28
	v_lshl_add_u64 v[140:141], v[140:141], 0, s[80:81]
	s_barrier
	s_cbranch_scc1 .LBB0_221
	s_or_b32 s0, s8, 0x80
	s_ashr_i32 s1, s0, 31
	s_lshl_b64 s[0:1], s[0:1], 12
	s_add_u32 s0, s34, s0
	s_addc_u32 s1, s35, s1
	ds_read_b128 v[134:137], v157
	ds_read_b128 v[138:141], v157 offset:1024
	ds_read_b128 v[150:153], v157 offset:2048
	ds_read_b128 v[174:177], v157 offset:3072
	ds_read_b128 v[178:181], v147
	ds_read_b128 v[182:185], v147 offset:1024
	ds_read_b128 v[186:189], v146
	ds_read_b128 v[190:193], v146 offset:1024
	ds_read_b128 v[196:199], v145
	ds_read_b128 v[208:211], v145 offset:1024
	ds_read_b128 v[212:215], v144
	ds_read_b128 v[216:219], v144 offset:1024
	v_lshl_add_u64 v[156:157], v[166:167], 1, s[0:1]
	s_mov_b64 s[54:55], 0xf80
	v_lshl_add_u64 v[156:157], v[156:157], 0, s[54:55]
	s_add_i32 m0, s100, 0xc000
	v_lshl_add_u64 v[132:133], v[132:133], 1, s[0:1]
	global_load_lds_dwordx4 v[156:157], off
	v_lshl_add_u64 v[132:133], v[132:133], 0, s[54:55]
	s_add_i32 m0, s100, 0xe000
	s_nop 0
	global_load_lds_dwordx4 v[132:133], off
	s_barrier
	s_waitcnt lgkmcnt(0)
	s_setprio 1
	s_waitcnt lgkmcnt(0)
	v_mfma_f32_16x16x32_bf16 v[124:127], v[178:181], v[134:137], v[124:127]
	v_mfma_f32_16x16x32_bf16 v[120:123], v[178:181], v[150:153], v[120:123]
	v_mfma_f32_16x16x32_bf16 v[116:119], v[186:189], v[134:137], v[116:119]
	v_mfma_f32_16x16x32_bf16 v[112:115], v[186:189], v[150:153], v[112:115]
	v_mfma_f32_16x16x32_bf16 v[96:99], v[212:215], v[150:153], v[96:99]
	v_mfma_f32_16x16x32_bf16 v[124:127], v[182:185], v[138:141], v[124:127]
	v_mfma_f32_16x16x32_bf16 v[120:123], v[182:185], v[174:177], v[120:123]
	v_mfma_f32_16x16x32_bf16 v[116:119], v[190:193], v[138:141], v[116:119]
	v_mfma_f32_16x16x32_bf16 v[112:115], v[190:193], v[174:177], v[112:115]
	v_mfma_f32_16x16x32_bf16 v[108:111], v[196:199], v[134:137], v[108:111]
	v_mfma_f32_16x16x32_bf16 v[104:107], v[196:199], v[150:153], v[104:107]
	v_mfma_f32_16x16x32_bf16 v[100:103], v[212:215], v[134:137], v[100:103]
	v_mfma_f32_16x16x32_bf16 v[96:99], v[216:219], v[174:177], v[96:99]
	v_mfma_f32_16x16x32_bf16 v[220:223], v[208:211], v[138:141], v[108:111]
	v_mfma_f32_16x16x32_bf16 v[224:227], v[208:211], v[174:177], v[104:107]
	v_mfma_f32_16x16x32_bf16 v[228:231], v[216:219], v[138:141], v[100:103]
	s_setprio 0
	s_barrier
	s_nop 1
	ds_read_b128 v[100:103], v155
	ds_read_b128 v[104:107], v155 offset:1024
	ds_read_b128 v[108:111], v155 offset:2048
	ds_read_b128 v[154:157], v155 offset:3072
	s_barrier
; #define P8_LDA(dst,b,h) _Pragma("unroll") for(int m=0;m<4;++m) _Pragma("unroll") for(int k=0;k<2;++k) \
;     dst[m][k]=*reinterpret_cast<const bf16x8*>((char*)P8_SA(b,h)+lds_byte(wr*64+m*16+fr,k*32+fq*8))
; #define P8_LDB(dst,b,h) _Pragma("unroll") for(int n=0;n<2;++n) _Pragma("unroll") for(int k=0;k<2;++k) \
;     dst[n][k]=*reinterpret_cast<const bf16x8*>((char*)P8_SB(b,h)+lds_byte(wc*32+n*16+fr,k*32+fq*8))
; #define P8_MMA(ai,bj,At,Bt) do{__builtin_amdgcn_s_setprio(1); \
;     _Pragma("unroll") for(int m=0;m<4;++m) _Pragma("unroll") for(int n=0;n<2;++n) _Pragma("unroll") for(int k=0;k<2;++k) \
;       acc[ai][bj][m][n]=__builtin_amdgcn_mfma_f32_16x16x32_bf16(At[m][k],Bt[n][k],acc[ai][bj][m][n],0,0,0); \
;     __builtin_amdgcn_s_setprio(0);}while(0)
; #define P8_WAIT_V(n) asm volatile("s_waitcnt vmcnt(" #n ")":::"memory")
; #define P8_WAIT_L(n) asm volatile("s_waitcnt lgkmcnt(" #n ")":::"memory")
; #define P8_BAR __builtin_amdgcn_s_barrier()
; template <class EPI>
; DEVI void gemm8_tile(const bfr* __restrict__ A, const bfr* __restrict__ Bt, int K, int brow, int bcol, int nbrow, int nbcol, char* shmc, EPI epi) {
;     ...
;     P8_LDB(B1,0,1); P8_BAR; P8_WAIT_L(0); P8_MMA(0,1,At,B1); P8_BAR;
;     P8_LDA(At,0,1); P8_WAIT_V(4); P8_BAR; P8_WAIT_L(0); P8_MMA(1,0,At,B0); P8_MMA(1,1,At,B1); P8_BAR; }
;   { P8_LDB(B0,1,0); P8_LDA(At,1,0); P8_WAIT_V(2); P8_BAR; P8_WAIT_L(0); P8_MMA(0,0,At,B0); P8_BAR;
	s_waitcnt lgkmcnt(0)
	s_setprio 1
	s_waitcnt lgkmcnt(0)
	v_mfma_f32_16x16x32_bf16 v[92:95], v[178:181], v[100:103], v[92:95]
	v_mfma_f32_16x16x32_bf16 v[88:91], v[178:181], v[108:111], v[88:91]
	v_mfma_f32_16x16x32_bf16 v[84:87], v[186:189], v[100:103], v[84:87]
	v_mfma_f32_16x16x32_bf16 v[80:83], v[186:189], v[108:111], v[80:83]
	v_mfma_f32_16x16x32_bf16 v[64:67], v[212:215], v[108:111], v[64:67]
	v_mfma_f32_16x16x32_bf16 v[92:95], v[182:185], v[104:107], v[92:95]
	v_mfma_f32_16x16x32_bf16 v[88:91], v[182:185], v[154:157], v[88:91]
	v_mfma_f32_16x16x32_bf16 v[84:87], v[190:193], v[104:107], v[84:87]
	v_mfma_f32_16x16x32_bf16 v[80:83], v[190:193], v[154:157], v[80:83]
	v_mfma_f32_16x16x32_bf16 v[76:79], v[196:199], v[100:103], v[76:79]
	v_mfma_f32_16x16x32_bf16 v[72:75], v[196:199], v[108:111], v[72:75]
	v_mfma_f32_16x16x32_bf16 v[68:71], v[212:215], v[100:103], v[68:71]
	v_mfma_f32_16x16x32_bf16 v[64:67], v[216:219], v[154:157], v[64:67]
	v_mfma_f32_16x16x32_bf16 v[178:181], v[208:211], v[104:107], v[76:79]
	v_mfma_f32_16x16x32_bf16 v[182:185], v[208:211], v[154:157], v[72:75]
	v_mfma_f32_16x16x32_bf16 v[186:189], v[216:219], v[104:107], v[68:71]
	s_setprio 0
	s_barrier
	s_nop 1
	ds_read_b128 v[68:71], v147 offset:16384
	ds_read_b128 v[72:75], v147 offset:17408
	ds_read_b128 v[76:79], v146 offset:16384
	ds_read_b128 v[190:193], v146 offset:17408
	ds_read_b128 v[196:199], v145 offset:16384
	ds_read_b128 v[208:211], v145 offset:17408
	ds_read_b128 v[212:215], v144 offset:16384
	ds_read_b128 v[216:219], v144 offset:17408
	s_waitcnt vmcnt(4)
	s_barrier
	s_waitcnt lgkmcnt(0)
	s_setprio 1
	s_waitcnt lgkmcnt(0)
	v_mfma_f32_16x16x32_bf16 v[60:63], v[68:71], v[134:137], v[60:63]
	v_mfma_f32_16x16x32_bf16 v[56:59], v[68:71], v[150:153], v[56:59]
	v_mfma_f32_16x16x32_bf16 v[52:55], v[76:79], v[134:137], v[52:55]
	v_mfma_f32_16x16x32_bf16 v[48:51], v[76:79], v[150:153], v[48:51]
	v_mfma_f32_16x16x32_bf16 v[32:35], v[212:215], v[150:153], v[32:35]
	v_mfma_f32_16x16x32_bf16 v[60:63], v[72:75], v[138:141], v[60:63]
	v_mfma_f32_16x16x32_bf16 v[56:59], v[72:75], v[174:177], v[56:59]
	v_mfma_f32_16x16x32_bf16 v[52:55], v[190:193], v[138:141], v[52:55]
	v_mfma_f32_16x16x32_bf16 v[48:51], v[190:193], v[174:177], v[48:51]
	v_mfma_f32_16x16x32_bf16 v[44:47], v[196:199], v[134:137], v[44:47]
	v_mfma_f32_16x16x32_bf16 v[40:43], v[196:199], v[150:153], v[40:43]
	v_mfma_f32_16x16x32_bf16 v[36:39], v[212:215], v[134:137], v[36:39]
	v_mfma_f32_16x16x32_bf16 v[32:35], v[216:219], v[174:177], v[32:35]
	v_mfma_f32_16x16x32_bf16 v[232:235], v[208:211], v[138:141], v[44:47]
	v_mfma_f32_16x16x32_bf16 v[236:239], v[208:211], v[174:177], v[40:43]
	v_mfma_f32_16x16x32_bf16 v[132:135], v[216:219], v[138:141], v[36:39]
	s_setprio 0
	s_setprio 1
	v_mfma_f32_16x16x32_bf16 v[28:31], v[68:71], v[100:103], v[28:31]
	v_mfma_f32_16x16x32_bf16 v[24:27], v[68:71], v[108:111], v[24:27]
	v_mfma_f32_16x16x32_bf16 v[20:23], v[76:79], v[100:103], v[20:23]
	v_mfma_f32_16x16x32_bf16 v[16:19], v[76:79], v[108:111], v[16:19]
	v_mfma_f32_16x16x32_bf16 v[0:3], v[212:215], v[108:111], v[0:3]
	v_mfma_f32_16x16x32_bf16 v[28:31], v[72:75], v[104:107], v[28:31]
	v_mfma_f32_16x16x32_bf16 v[24:27], v[72:75], v[154:157], v[24:27]
	v_mfma_f32_16x16x32_bf16 v[20:23], v[190:193], v[104:107], v[20:23]
	v_mfma_f32_16x16x32_bf16 v[16:19], v[190:193], v[154:157], v[16:19]
	v_mfma_f32_16x16x32_bf16 v[12:15], v[196:199], v[100:103], v[12:15]
	v_mfma_f32_16x16x32_bf16 v[8:11], v[196:199], v[108:111], v[8:11]
	v_mfma_f32_16x16x32_bf16 v[4:7], v[212:215], v[100:103], v[4:7]
	v_mfma_f32_16x16x32_bf16 v[0:3], v[216:219], v[154:157], v[0:3]
	v_mfma_f32_16x16x32_bf16 v[136:139], v[208:211], v[104:107], v[12:15]
	v_mfma_f32_16x16x32_bf16 v[150:153], v[208:211], v[154:157], v[8:11]
	v_mfma_f32_16x16x32_bf16 v[172:175], v[216:219], v[104:107], v[4:7]
	s_setprio 0
	s_barrier
	s_nop 1
	ds_read_b128 v[4:7], v149
	ds_read_b128 v[8:11], v149 offset:1024
	ds_read_b128 v[12:15], v149 offset:2048
	ds_read_b128 v[154:157], v149 offset:3072
	ds_read_b128 v[36:39], v147 offset:32768
	ds_read_b128 v[40:43], v147 offset:33792
	ds_read_b128 v[44:47], v146 offset:32768
	ds_read_b128 v[68:71], v146 offset:33792
	ds_read_b128 v[190:193], v145 offset:32768
	ds_read_b128 v[196:199], v145 offset:33792
	ds_read_b128 v[208:211], v144 offset:32768
	ds_read_b128 v[212:215], v144 offset:33792
	s_waitcnt vmcnt(2)
	s_barrier
; #define P8_LDA(dst,b,h) _Pragma("unroll") for(int m=0;m<4;++m) _Pragma("unroll") for(int k=0;k<2;++k) \
;     dst[m][k]=*reinterpret_cast<const bf16x8*>((char*)P8_SA(b,h)+lds_byte(wr*64+m*16+fr,k*32+fq*8))
; #define P8_LDB(dst,b,h) _Pragma("unroll") for(int n=0;n<2;++n) _Pragma("unroll") for(int k=0;k<2;++k) \
;     dst[n][k]=*reinterpret_cast<const bf16x8*>((char*)P8_SB(b,h)+lds_byte(wc*32+n*16+fr,k*32+fq*8))
; #define P8_MMA(ai,bj,At,Bt) do{__builtin_amdgcn_s_setprio(1); \
;     _Pragma("unroll") for(int m=0;m<4;++m) _Pragma("unroll") for(int n=0;n<2;++n) _Pragma("unroll") for(int k=0;k<2;++k) \
;       acc[ai][bj][m][n]=__builtin_amdgcn_mfma_f32_16x16x32_bf16(At[m][k],Bt[n][k],acc[ai][bj][m][n],0,0,0); \
;     __builtin_amdgcn_s_setprio(0);}while(0)
; #define P8_WAIT_V(n) asm volatile("s_waitcnt vmcnt(" #n ")":::"memory")
; #define P8_WAIT_L(n) asm volatile("s_waitcnt lgkmcnt(" #n ")":::"memory")
; #define P8_BAR __builtin_amdgcn_s_barrier()
; template <class EPI>
; DEVI void gemm8_tile(const bfr* __restrict__ A, const bfr* __restrict__ Bt, int K, int brow, int bcol, int nbrow, int nbcol, char* shmc, EPI epi) {
;     ...
;   { P8_LDB(B0,1,0); P8_LDA(At,1,0); P8_WAIT_V(2); P8_BAR; P8_WAIT_L(0); P8_MMA(0,0,At,B0); P8_BAR;
;     P8_LDB(B1,1,1); P8_WAIT_V(0); P8_BAR; P8_WAIT_L(0); P8_MMA(0,1,At,B1); P8_BAR;
;     P8_LDA(At,1,1); P8_BAR; P8_WAIT_L(0); P8_MMA(1,0,At,B0); P8_MMA(1,1,At,B1); P8_BAR; }
;   if(wr==0)P8_BAR;
	s_waitcnt lgkmcnt(0)
	s_setprio 1
	s_waitcnt lgkmcnt(0)
	v_mfma_f32_16x16x32_bf16 v[72:75], v[36:39], v[4:7], v[124:127]
	v_mfma_f32_16x16x32_bf16 v[124:127], v[40:43], v[8:11], v[72:75]
	v_mfma_f32_16x16x32_bf16 v[72:75], v[36:39], v[12:15], v[120:123]
	v_mfma_f32_16x16x32_bf16 v[108:111], v[40:43], v[154:157], v[72:75]
	v_mfma_f32_16x16x32_bf16 v[72:75], v[44:47], v[4:7], v[116:119]
	v_mfma_f32_16x16x32_bf16 v[120:123], v[68:71], v[8:11], v[72:75]
	v_mfma_f32_16x16x32_bf16 v[72:75], v[44:47], v[12:15], v[112:115]
	v_mfma_f32_16x16x32_bf16 v[104:107], v[68:71], v[154:157], v[72:75]
	v_mfma_f32_16x16x32_bf16 v[72:75], v[190:193], v[4:7], v[220:223]
	v_mfma_f32_16x16x32_bf16 v[116:119], v[196:199], v[8:11], v[72:75]
	v_mfma_f32_16x16x32_bf16 v[72:75], v[190:193], v[12:15], v[224:227]
	v_mfma_f32_16x16x32_bf16 v[100:103], v[196:199], v[154:157], v[72:75]
	v_mfma_f32_16x16x32_bf16 v[72:75], v[208:211], v[4:7], v[228:231]
	v_mfma_f32_16x16x32_bf16 v[112:115], v[212:215], v[8:11], v[72:75]
	v_mfma_f32_16x16x32_bf16 v[72:75], v[208:211], v[12:15], v[96:99]
	v_mfma_f32_16x16x32_bf16 v[96:99], v[212:215], v[154:157], v[72:75]
	s_setprio 0
	s_barrier
	ds_read_b128 v[216:219], v148
	ds_read_b128 v[220:223], v148 offset:1024
	ds_read_b128 v[224:227], v148 offset:2048
	ds_read_b128 v[228:231], v148 offset:3072
	s_waitcnt vmcnt(0)
	s_barrier
	s_waitcnt lgkmcnt(0)
	s_setprio 1
	s_waitcnt lgkmcnt(0)
	v_mfma_f32_16x16x32_bf16 v[72:75], v[36:39], v[216:219], v[92:95]
	v_mfma_f32_16x16x32_bf16 v[36:39], v[36:39], v[224:227], v[88:91]
	v_mfma_f32_16x16x32_bf16 v[76:79], v[40:43], v[228:231], v[36:39]
	v_mfma_f32_16x16x32_bf16 v[36:39], v[44:47], v[216:219], v[84:87]
	v_mfma_f32_16x16x32_bf16 v[88:91], v[68:71], v[220:223], v[36:39]
	v_mfma_f32_16x16x32_bf16 v[36:39], v[44:47], v[224:227], v[80:83]
	v_mfma_f32_16x16x32_bf16 v[92:95], v[40:43], v[220:223], v[72:75]
	v_mfma_f32_16x16x32_bf16 v[72:75], v[68:71], v[228:231], v[36:39]
	v_mfma_f32_16x16x32_bf16 v[36:39], v[190:193], v[216:219], v[178:181]
	v_mfma_f32_16x16x32_bf16 v[84:87], v[196:199], v[220:223], v[36:39]
	v_mfma_f32_16x16x32_bf16 v[36:39], v[190:193], v[224:227], v[182:185]
	v_mfma_f32_16x16x32_bf16 v[68:71], v[196:199], v[228:231], v[36:39]
	v_mfma_f32_16x16x32_bf16 v[36:39], v[208:211], v[216:219], v[186:189]
	v_mfma_f32_16x16x32_bf16 v[80:83], v[212:215], v[220:223], v[36:39]
	v_mfma_f32_16x16x32_bf16 v[36:39], v[208:211], v[224:227], v[64:67]
	v_mfma_f32_16x16x32_bf16 v[64:67], v[212:215], v[228:231], v[36:39]
	s_setprio 0
	s_barrier
	ds_read_b128 v[176:179], v147 offset:49152
	ds_read_b128 v[180:183], v147 offset:50176
	ds_read_b128 v[184:187], v146 offset:49152
	ds_read_b128 v[146:149], v146 offset:50176
	ds_read_b128 v[188:191], v145 offset:49152
	ds_read_b128 v[196:199], v145 offset:50176
	ds_read_b128 v[208:211], v144 offset:49152
	ds_read_b128 v[212:215], v144 offset:50176
	s_barrier
	s_waitcnt lgkmcnt(0)
	s_setprio 1
	s_waitcnt lgkmcnt(0)
	v_mfma_f32_16x16x32_bf16 v[36:39], v[176:179], v[4:7], v[60:63]
	v_mfma_f32_16x16x32_bf16 v[60:63], v[180:183], v[8:11], v[36:39]
	v_mfma_f32_16x16x32_bf16 v[36:39], v[176:179], v[12:15], v[56:59]
	v_mfma_f32_16x16x32_bf16 v[44:47], v[180:183], v[154:157], v[36:39]
	v_mfma_f32_16x16x32_bf16 v[36:39], v[184:187], v[4:7], v[52:55]
	v_mfma_f32_16x16x32_bf16 v[56:59], v[146:149], v[8:11], v[36:39]
	v_mfma_f32_16x16x32_bf16 v[36:39], v[184:187], v[12:15], v[48:51]
	v_mfma_f32_16x16x32_bf16 v[40:43], v[146:149], v[154:157], v[36:39]
	v_mfma_f32_16x16x32_bf16 v[36:39], v[188:191], v[4:7], v[232:235]
	v_mfma_f32_16x16x32_bf16 v[4:7], v[208:211], v[4:7], v[132:135]
	v_mfma_f32_16x16x32_bf16 v[52:55], v[196:199], v[8:11], v[36:39]
	v_mfma_f32_16x16x32_bf16 v[36:39], v[188:191], v[12:15], v[236:239]
	v_mfma_f32_16x16x32_bf16 v[48:51], v[212:215], v[8:11], v[4:7]
	v_mfma_f32_16x16x32_bf16 v[4:7], v[208:211], v[12:15], v[32:35]
	v_mfma_f32_16x16x32_bf16 v[36:39], v[196:199], v[154:157], v[36:39]
	v_mfma_f32_16x16x32_bf16 v[32:35], v[212:215], v[154:157], v[4:7]
	s_setprio 0
	s_setprio 1
	v_mfma_f32_16x16x32_bf16 v[4:7], v[176:179], v[216:219], v[28:31]
	v_mfma_f32_16x16x32_bf16 v[28:31], v[180:183], v[220:223], v[4:7]
	v_mfma_f32_16x16x32_bf16 v[4:7], v[176:179], v[224:227], v[24:27]
	v_mfma_f32_16x16x32_bf16 v[12:15], v[180:183], v[228:231], v[4:7]
	v_mfma_f32_16x16x32_bf16 v[4:7], v[184:187], v[216:219], v[20:23]
	v_mfma_f32_16x16x32_bf16 v[24:27], v[146:149], v[220:223], v[4:7]
	v_mfma_f32_16x16x32_bf16 v[4:7], v[184:187], v[224:227], v[16:19]
	v_mfma_f32_16x16x32_bf16 v[8:11], v[146:149], v[228:231], v[4:7]
	v_mfma_f32_16x16x32_bf16 v[4:7], v[188:191], v[216:219], v[136:139]
	v_mfma_f32_16x16x32_bf16 v[20:23], v[196:199], v[220:223], v[4:7]
	v_mfma_f32_16x16x32_bf16 v[4:7], v[188:191], v[224:227], v[150:153]
	v_mfma_f32_16x16x32_bf16 v[16:19], v[208:211], v[216:219], v[172:175]
	v_mfma_f32_16x16x32_bf16 v[0:3], v[208:211], v[224:227], v[0:3]
	v_mfma_f32_16x16x32_bf16 v[4:7], v[196:199], v[228:231], v[4:7]
	v_mfma_f32_16x16x32_bf16 v[16:19], v[212:215], v[220:223], v[16:19]
	v_mfma_f32_16x16x32_bf16 v[0:3], v[212:215], v[228:231], v[0:3]
	s_setprio 0
	v_cmp_gt_u32_e32 vcc, s57, v142
	s_barrier
	s_and_saveexec_b64 s[0:1], vcc
	s_cbranch_execz .LBB0_224
	s_barrier

; #define P8_STAGE(P,BASE,br,kt) do{const bfr* _ub=(BASE)+((long)(br)*K+(long)(kt)*BK); \
;     __builtin_amdgcn_global_load_lds((const unsigned*)(_ub+so0),(unsigned*)((char*)(P)+wid*1024),16,0,0); \
;     __builtin_amdgcn_global_load_lds((const unsigned*)(_ub+so1),(unsigned*)((char*)(P)+wid*1024+8192),16,0,0);}while(0)
; #define P8_LDA(dst,b,h) _Pragma("unroll") for(int m=0;m<4;++m) _Pragma("unroll") for(int k=0;k<2;++k) \
;     dst[m][k]=*reinterpret_cast<const bf16x8*>((char*)P8_SA(b,h)+lds_byte(wr*64+m*16+fr,k*32+fq*8))
; #define P8_LDB(dst,b,h) _Pragma("unroll") for(int n=0;n<2;++n) _Pragma("unroll") for(int k=0;k<2;++k) \
;     dst[n][k]=*reinterpret_cast<const bf16x8*>((char*)P8_SB(b,h)+lds_byte(wc*32+n*16+fr,k*32+fq*8))
; #define P8_MMA(ai,bj,At,Bt) do{__builtin_amdgcn_s_setprio(1); \
;     _Pragma("unroll") for(int m=0;m<4;++m) _Pragma("unroll") for(int n=0;n<2;++n) _Pragma("unroll") for(int k=0;k<2;++k) \
;       acc[ai][bj][m][n]=__builtin_amdgcn_mfma_f32_16x16x32_bf16(At[m][k],Bt[n][k],acc[ai][bj][m][n],0,0,0); \
;     __builtin_amdgcn_s_setprio(0);}while(0)
; #define P8_WAIT_V(n) asm volatile("s_waitcnt vmcnt(" #n ")":::"memory")
; #define P8_WAIT_L(n) asm volatile("s_waitcnt lgkmcnt(" #n ")":::"memory")
; #define P8_BAR __builtin_amdgcn_s_barrier()
; #define P8_SCHED __builtin_amdgcn_sched_barrier(0)
; template <class EPI>
; DEVI void gemm8_tile(const bfr* __restrict__ A, const bfr* __restrict__ Bt, int K, int brow, int bcol, int nbrow, int nbcol, char* shmc, EPI epi) {
;     ...
;     P8_LDB(B0,0,0); P8_SCHED; P8_LDA(At,0,0); P8_STAGE(P8_SA(1,1),A,brow+128,t+1);
;     P8_WAIT_L(8); P8_BAR; P8_WAIT_L(0); P8_MMA(0,0,At,B0); P8_BAR; P8_SCHED;
;     P8_LDB(B1,0,1); P8_STAGE(P8_SB(0,0),Bt,bcol,t+2);
;     P8_BAR; P8_WAIT_L(0); P8_MMA(0,1,At,B1); P8_BAR;
;     P8_LDA(At,0,1); P8_STAGE(P8_SA(0,0),A,brow,t+2);
;     P8_BAR; P8_WAIT_L(0); P8_MMA(1,0,At,B0); P8_BAR; P8_SCHED;
;     P8_STAGE(P8_SB(0,1),Bt,bcol+128,t+2);
;     P8_WAIT_V(6); P8_BAR; P8_MMA(1,1,At,B1); P8_BAR;
.LBB0_286:
	ds_read_b128 v[174:177], v157
	ds_read_b128 v[178:181], v157 offset:1024
	ds_read_b128 v[182:185], v157 offset:2048
	ds_read_b128 v[186:189], v157 offset:3072
	v_add_u32_e32 v171, 0xc000, v143
	v_add_u32_e32 v172, 0xe000, v143
	v_add_u32_e32 v158, s54, v140
	s_add_i32 m0, s100, 0xc000
	ds_read_b128 v[160:163], v147
	ds_read_b128 v[190:193], v147 offset:1024
	ds_read_b128 v[196:199], v146
	ds_read_b128 v[200:203], v146 offset:1024
	ds_read_b128 v[204:207], v145
	ds_read_b128 v[208:211], v145 offset:1024
	ds_read_b128 v[212:215], v144
	ds_read_b128 v[216:219], v144 offset:1024
	global_load_lds_dwordx4 v158, s[86:87]
	v_add_u32_e32 v158, s54, v138
	s_add_i32 m0, s100, 0xe000
	s_nop 0
	global_load_lds_dwordx4 v158, s[86:87]
	s_waitcnt lgkmcnt(8)
	s_barrier
	s_waitcnt lgkmcnt(0)
	v_mfma_f32_16x16x32_bf16 v[124:127], v[160:163], v[174:177], v[124:127]
	v_mfma_f32_16x16x32_bf16 v[120:123], v[160:163], v[182:185], v[120:123]
	v_mfma_f32_16x16x32_bf16 v[116:119], v[196:199], v[174:177], v[116:119]
	v_mfma_f32_16x16x32_bf16 v[112:115], v[196:199], v[182:185], v[112:115]
	v_mfma_f32_16x16x32_bf16 v[108:111], v[204:207], v[174:177], v[108:111]
	v_mfma_f32_16x16x32_bf16 v[104:107], v[204:207], v[182:185], v[104:107]
	v_mfma_f32_16x16x32_bf16 v[100:103], v[212:215], v[174:177], v[100:103]
	v_mfma_f32_16x16x32_bf16 v[96:99], v[212:215], v[182:185], v[96:99]
	v_mfma_f32_16x16x32_bf16 v[124:127], v[190:193], v[178:181], v[124:127]
	v_mfma_f32_16x16x32_bf16 v[120:123], v[190:193], v[186:189], v[120:123]
	v_mfma_f32_16x16x32_bf16 v[116:119], v[200:203], v[178:181], v[116:119]
	v_mfma_f32_16x16x32_bf16 v[112:115], v[200:203], v[186:189], v[112:115]
	v_mfma_f32_16x16x32_bf16 v[108:111], v[208:211], v[178:181], v[108:111]
	v_mfma_f32_16x16x32_bf16 v[104:107], v[208:211], v[186:189], v[104:107]
	v_mfma_f32_16x16x32_bf16 v[100:103], v[216:219], v[178:181], v[100:103]
	v_mfma_f32_16x16x32_bf16 v[96:99], v[216:219], v[186:189], v[96:99]
	s_barrier
	v_add_u32_e32 v158, 0x10000, v143
	v_add_u32_e32 v159, 0x12000, v143
	v_add_u32_e32 v236, s66, v136
	s_add_i32 m0, s100, 0x10000
	ds_read_b128 v[220:223], v155
	ds_read_b128 v[224:227], v155 offset:1024
	ds_read_b128 v[228:231], v155 offset:2048
	ds_read_b128 v[232:235], v155 offset:3072
	global_load_lds_dwordx4 v236, s[86:87]
	v_add_u32_e32 v236, s66, v134
	s_add_i32 m0, s100, 0x12000
	s_nop 0
	global_load_lds_dwordx4 v236, s[86:87]
	s_barrier
	s_waitcnt lgkmcnt(0)
	v_mfma_f32_16x16x32_bf16 v[92:95], v[160:163], v[220:223], v[92:95]
	v_mfma_f32_16x16x32_bf16 v[88:91], v[160:163], v[228:231], v[88:91]
	v_mfma_f32_16x16x32_bf16 v[84:87], v[196:199], v[220:223], v[84:87]
	v_mfma_f32_16x16x32_bf16 v[80:83], v[196:199], v[228:231], v[80:83]
	v_mfma_f32_16x16x32_bf16 v[76:79], v[204:207], v[220:223], v[76:79]
	v_mfma_f32_16x16x32_bf16 v[72:75], v[204:207], v[228:231], v[72:75]
	v_mfma_f32_16x16x32_bf16 v[68:71], v[212:215], v[220:223], v[68:71]
	v_mfma_f32_16x16x32_bf16 v[64:67], v[212:215], v[228:231], v[64:67]
	v_mfma_f32_16x16x32_bf16 v[92:95], v[190:193], v[224:227], v[92:95]
	v_mfma_f32_16x16x32_bf16 v[88:91], v[190:193], v[232:235], v[88:91]
	v_mfma_f32_16x16x32_bf16 v[84:87], v[200:203], v[224:227], v[84:87]
	v_mfma_f32_16x16x32_bf16 v[80:83], v[200:203], v[232:235], v[80:83]
	v_mfma_f32_16x16x32_bf16 v[76:79], v[208:211], v[224:227], v[76:79]
	v_mfma_f32_16x16x32_bf16 v[72:75], v[208:211], v[232:235], v[72:75]
	v_mfma_f32_16x16x32_bf16 v[68:71], v[216:219], v[224:227], v[68:71]
	v_mfma_f32_16x16x32_bf16 v[64:67], v[216:219], v[232:235], v[64:67]
	v_add_u32_e32 v160, s60, v140
	s_mov_b32 m0, s100
	s_barrier
	ds_read_b128 v[190:193], v147 offset:16384
	ds_read_b128 v[196:199], v147 offset:17408
	ds_read_b128 v[200:203], v146 offset:16384
	ds_read_b128 v[204:207], v146 offset:17408
	ds_read_b128 v[208:211], v145 offset:16384
	ds_read_b128 v[212:215], v145 offset:17408
	ds_read_b128 v[216:219], v144 offset:16384
	ds_read_b128 v[236:239], v144 offset:17408
	global_load_lds_dwordx4 v160, s[86:87]
	v_add_u32_e32 v160, 0x2000, v143
	v_add_u32_e32 v162, s60, v138
	s_add_i32 m0, s100, 0x2000
	s_nop 0
	global_load_lds_dwordx4 v162, s[86:87]
	s_barrier
	s_waitcnt lgkmcnt(0)
	v_mfma_f32_16x16x32_bf16 v[60:63], v[190:193], v[174:177], v[60:63]
	v_mfma_f32_16x16x32_bf16 v[56:59], v[190:193], v[182:185], v[56:59]
	v_mfma_f32_16x16x32_bf16 v[52:55], v[200:203], v[174:177], v[52:55]
	v_mfma_f32_16x16x32_bf16 v[48:51], v[200:203], v[182:185], v[48:51]
	v_mfma_f32_16x16x32_bf16 v[44:47], v[208:211], v[174:177], v[44:47]
	v_mfma_f32_16x16x32_bf16 v[40:43], v[208:211], v[182:185], v[40:43]
	v_mfma_f32_16x16x32_bf16 v[36:39], v[216:219], v[174:177], v[36:39]
	v_mfma_f32_16x16x32_bf16 v[32:35], v[216:219], v[182:185], v[32:35]
	v_mfma_f32_16x16x32_bf16 v[60:63], v[196:199], v[178:181], v[60:63]
	v_mfma_f32_16x16x32_bf16 v[56:59], v[196:199], v[186:189], v[56:59]
	v_mfma_f32_16x16x32_bf16 v[52:55], v[204:207], v[178:181], v[52:55]
	v_mfma_f32_16x16x32_bf16 v[48:51], v[204:207], v[186:189], v[48:51]
	v_mfma_f32_16x16x32_bf16 v[44:47], v[212:215], v[178:181], v[44:47]
	v_mfma_f32_16x16x32_bf16 v[40:43], v[212:215], v[186:189], v[40:43]
	v_mfma_f32_16x16x32_bf16 v[36:39], v[236:239], v[178:181], v[36:39]
	v_mfma_f32_16x16x32_bf16 v[32:35], v[236:239], v[186:189], v[32:35]
	s_barrier
	v_add_u32_e32 v161, 0x14000, v143
	v_add_u32_e32 v162, s70, v136
	s_add_i32 m0, s100, 0x14000
	v_add_u32_e32 v174, s70, v134
	global_load_lds_dwordx4 v162, s[86:87]
	v_add_u32_e32 v162, 0x16000, v143
	s_nop 0
	s_add_i32 m0, s100, 0x16000
	s_nop 0
	global_load_lds_dwordx4 v174, s[86:87]
	s_waitcnt vmcnt(6)
	s_barrier
; #define P8_STAGE(P,BASE,br,kt) do{const bfr* _ub=(BASE)+((long)(br)*K+(long)(kt)*BK); \
;     __builtin_amdgcn_global_load_lds((const unsigned*)(_ub+so0),(unsigned*)((char*)(P)+wid*1024),16,0,0); \
;     __builtin_amdgcn_global_load_lds((const unsigned*)(_ub+so1),(unsigned*)((char*)(P)+wid*1024+8192),16,0,0);}while(0)
; #define P8_LDA(dst,b,h) _Pragma("unroll") for(int m=0;m<4;++m) _Pragma("unroll") for(int k=0;k<2;++k) \
;     dst[m][k]=*reinterpret_cast<const bf16x8*>((char*)P8_SA(b,h)+lds_byte(wr*64+m*16+fr,k*32+fq*8))
; #define P8_LDB(dst,b,h) _Pragma("unroll") for(int n=0;n<2;++n) _Pragma("unroll") for(int k=0;k<2;++k) \
;     dst[n][k]=*reinterpret_cast<const bf16x8*>((char*)P8_SB(b,h)+lds_byte(wc*32+n*16+fr,k*32+fq*8))
; #define P8_MMA(ai,bj,At,Bt) do{__builtin_amdgcn_s_setprio(1); \
;     _Pragma("unroll") for(int m=0;m<4;++m) _Pragma("unroll") for(int n=0;n<2;++n) _Pragma("unroll") for(int k=0;k<2;++k) \
;       acc[ai][bj][m][n]=__builtin_amdgcn_mfma_f32_16x16x32_bf16(At[m][k],Bt[n][k],acc[ai][bj][m][n],0,0,0); \
;     __builtin_amdgcn_s_setprio(0);}while(0)
; #define P8_WAIT_V(n) asm volatile("s_waitcnt vmcnt(" #n ")":::"memory")
; #define P8_WAIT_L(n) asm volatile("s_waitcnt lgkmcnt(" #n ")":::"memory")
; #define P8_BAR __builtin_amdgcn_s_barrier()
; #define P8_SCHED __builtin_amdgcn_sched_barrier(0)
; template <class EPI>
; DEVI void gemm8_tile(const bfr* __restrict__ A, const bfr* __restrict__ Bt, int K, int brow, int bcol, int nbrow, int nbcol, char* shmc, EPI epi) {
;     ...
;     P8_WAIT_V(6); P8_BAR; P8_MMA(1,1,At,B1); P8_BAR;
;     P8_LDB(B0,1,0); P8_SCHED; P8_LDA(At,1,0); P8_STAGE(P8_SA(0,1),A,brow+128,t+2);
;     P8_WAIT_L(8); P8_BAR; P8_WAIT_L(0); P8_MMA(0,0,At,B0); P8_BAR; P8_SCHED;
;     P8_LDB(B1,1,1); P8_STAGE(P8_SB(1,0),Bt,bcol,t+3);
;     P8_BAR; P8_WAIT_L(0); P8_MMA(0,1,At,B1); P8_BAR;
;     P8_LDA(At,1,1); P8_STAGE(P8_SA(1,0),A,brow,t+3);
;     P8_BAR; P8_WAIT_L(0); P8_MMA(1,0,At,B0); P8_BAR; P8_SCHED;
	v_mfma_f32_16x16x32_bf16 v[28:31], v[190:193], v[220:223], v[28:31]
	v_mfma_f32_16x16x32_bf16 v[24:27], v[190:193], v[228:231], v[24:27]
	v_mfma_f32_16x16x32_bf16 v[20:23], v[200:203], v[220:223], v[20:23]
	v_mfma_f32_16x16x32_bf16 v[16:19], v[200:203], v[228:231], v[16:19]
	v_mfma_f32_16x16x32_bf16 v[12:15], v[208:211], v[220:223], v[12:15]
	v_mfma_f32_16x16x32_bf16 v[8:11], v[208:211], v[228:231], v[8:11]
	v_mfma_f32_16x16x32_bf16 v[4:7], v[216:219], v[220:223], v[4:7]
	v_mfma_f32_16x16x32_bf16 v[0:3], v[216:219], v[228:231], v[0:3]
	v_mfma_f32_16x16x32_bf16 v[28:31], v[196:199], v[224:227], v[28:31]
	v_mfma_f32_16x16x32_bf16 v[24:27], v[196:199], v[232:235], v[24:27]
	v_mfma_f32_16x16x32_bf16 v[20:23], v[204:207], v[224:227], v[20:23]
	v_mfma_f32_16x16x32_bf16 v[16:19], v[204:207], v[232:235], v[16:19]
	v_mfma_f32_16x16x32_bf16 v[12:15], v[212:215], v[224:227], v[12:15]
	v_mfma_f32_16x16x32_bf16 v[8:11], v[212:215], v[232:235], v[8:11]
	v_mfma_f32_16x16x32_bf16 v[4:7], v[236:239], v[224:227], v[4:7]
	v_mfma_f32_16x16x32_bf16 v[0:3], v[236:239], v[232:235], v[0:3]
	s_barrier
	ds_read_b128 v[174:177], v149
	ds_read_b128 v[178:181], v149 offset:1024
	ds_read_b128 v[182:185], v149 offset:2048
	ds_read_b128 v[186:189], v149 offset:3072
	v_add_u32_e32 v163, 0x4000, v143
	v_add_u32_e32 v170, 0x6000, v143
	v_add_u32_e32 v224, s82, v140
	s_add_i32 m0, s100, 0x4000
	ds_read_b128 v[190:193], v147 offset:32768
	ds_read_b128 v[196:199], v147 offset:33792
	ds_read_b128 v[200:203], v146 offset:32768
	ds_read_b128 v[204:207], v146 offset:33792
	ds_read_b128 v[208:211], v145 offset:32768
	ds_read_b128 v[212:215], v145 offset:33792
	ds_read_b128 v[216:219], v144 offset:32768
	ds_read_b128 v[220:223], v144 offset:33792
	global_load_lds_dwordx4 v224, s[86:87]
	v_add_u32_e32 v224, s82, v138
	s_add_i32 m0, s100, 0x6000
	s_nop 0
	global_load_lds_dwordx4 v224, s[86:87]
	s_waitcnt lgkmcnt(8)
	s_barrier
	s_waitcnt lgkmcnt(0)
	v_mfma_f32_16x16x32_bf16 v[124:127], v[190:193], v[174:177], v[124:127]
	v_mfma_f32_16x16x32_bf16 v[120:123], v[190:193], v[182:185], v[120:123]
	v_mfma_f32_16x16x32_bf16 v[116:119], v[200:203], v[174:177], v[116:119]
	v_mfma_f32_16x16x32_bf16 v[112:115], v[200:203], v[182:185], v[112:115]
	v_mfma_f32_16x16x32_bf16 v[108:111], v[208:211], v[174:177], v[108:111]
	v_mfma_f32_16x16x32_bf16 v[104:107], v[208:211], v[182:185], v[104:107]
	v_mfma_f32_16x16x32_bf16 v[100:103], v[216:219], v[174:177], v[100:103]
	v_mfma_f32_16x16x32_bf16 v[96:99], v[216:219], v[182:185], v[96:99]
	v_mfma_f32_16x16x32_bf16 v[124:127], v[196:199], v[178:181], v[124:127]
	v_mfma_f32_16x16x32_bf16 v[120:123], v[196:199], v[186:189], v[120:123]
	v_mfma_f32_16x16x32_bf16 v[116:119], v[204:207], v[178:181], v[116:119]
	v_mfma_f32_16x16x32_bf16 v[112:115], v[204:207], v[186:189], v[112:115]
	v_mfma_f32_16x16x32_bf16 v[108:111], v[212:215], v[178:181], v[108:111]
	v_mfma_f32_16x16x32_bf16 v[104:107], v[212:215], v[186:189], v[104:107]
	v_mfma_f32_16x16x32_bf16 v[100:103], v[220:223], v[178:181], v[100:103]
	v_mfma_f32_16x16x32_bf16 v[96:99], v[220:223], v[186:189], v[96:99]
	s_barrier
	v_add_u32_e32 v248, s74, v136
	s_add_i32 m0, s100, 0x18000
	ds_read_b128 v[224:227], v148
	ds_read_b128 v[228:231], v148 offset:1024
	ds_read_b128 v[232:235], v148 offset:2048
	ds_read_b128 v[236:239], v148 offset:3072
	global_load_lds_dwordx4 v248, s[86:87]
	v_add_u32_e32 v248, s74, v134
	s_add_i32 m0, s100, 0x1a000
	s_nop 0
	global_load_lds_dwordx4 v248, s[86:87]
	s_barrier
	s_waitcnt lgkmcnt(0)
	v_mfma_f32_16x16x32_bf16 v[92:95], v[190:193], v[224:227], v[92:95]
	v_mfma_f32_16x16x32_bf16 v[88:91], v[190:193], v[232:235], v[88:91]
	v_mfma_f32_16x16x32_bf16 v[84:87], v[200:203], v[224:227], v[84:87]
	v_mfma_f32_16x16x32_bf16 v[80:83], v[200:203], v[232:235], v[80:83]
	v_mfma_f32_16x16x32_bf16 v[76:79], v[208:211], v[224:227], v[76:79]
	v_mfma_f32_16x16x32_bf16 v[72:75], v[208:211], v[232:235], v[72:75]
	v_mfma_f32_16x16x32_bf16 v[68:71], v[216:219], v[224:227], v[68:71]
	v_mfma_f32_16x16x32_bf16 v[64:67], v[216:219], v[232:235], v[64:67]
	v_mfma_f32_16x16x32_bf16 v[92:95], v[196:199], v[228:231], v[92:95]
	v_mfma_f32_16x16x32_bf16 v[88:91], v[196:199], v[236:239], v[88:91]
	v_mfma_f32_16x16x32_bf16 v[84:87], v[204:207], v[228:231], v[84:87]
	v_mfma_f32_16x16x32_bf16 v[80:83], v[204:207], v[236:239], v[80:83]
	v_mfma_f32_16x16x32_bf16 v[76:79], v[212:215], v[228:231], v[76:79]
	v_mfma_f32_16x16x32_bf16 v[72:75], v[212:215], v[236:239], v[72:75]
	v_mfma_f32_16x16x32_bf16 v[68:71], v[220:223], v[228:231], v[68:71]
	v_mfma_f32_16x16x32_bf16 v[64:67], v[220:223], v[236:239], v[64:67]
	v_add_u32_e32 v240, s92, v140
	s_add_i32 m0, s100, 0x8000
	s_barrier
	ds_read_b128 v[190:193], v147 offset:49152
	ds_read_b128 v[196:199], v147 offset:50176
	ds_read_b128 v[200:203], v146 offset:49152
	ds_read_b128 v[204:207], v146 offset:50176
	ds_read_b128 v[208:211], v145 offset:49152
	ds_read_b128 v[212:215], v145 offset:50176
	ds_read_b128 v[216:219], v144 offset:49152
	ds_read_b128 v[220:223], v144 offset:50176
	global_load_lds_dwordx4 v240, s[86:87]
	v_add_u32_e32 v240, s92, v138
	s_add_i32 m0, s100, 0xa000
	s_nop 0
	global_load_lds_dwordx4 v240, s[86:87]
	s_barrier
; #define P8_STAGE(P,BASE,br,kt) do{const bfr* _ub=(BASE)+((long)(br)*K+(long)(kt)*BK); \
;     __builtin_amdgcn_global_load_lds((const unsigned*)(_ub+so0),(unsigned*)((char*)(P)+wid*1024),16,0,0); \
;     __builtin_amdgcn_global_load_lds((const unsigned*)(_ub+so1),(unsigned*)((char*)(P)+wid*1024+8192),16,0,0);}while(0)
; #define P8_LDA(dst,b,h) _Pragma("unroll") for(int m=0;m<4;++m) _Pragma("unroll") for(int k=0;k<2;++k) \
;     dst[m][k]=*reinterpret_cast<const bf16x8*>((char*)P8_SA(b,h)+lds_byte(wr*64+m*16+fr,k*32+fq*8))
; #define P8_LDB(dst,b,h) _Pragma("unroll") for(int n=0;n<2;++n) _Pragma("unroll") for(int k=0;k<2;++k) \
;     dst[n][k]=*reinterpret_cast<const bf16x8*>((char*)P8_SB(b,h)+lds_byte(wc*32+n*16+fr,k*32+fq*8))
; #define P8_MMA(ai,bj,At,Bt) do{__builtin_amdgcn_s_setprio(1); \
;     _Pragma("unroll") for(int m=0;m<4;++m) _Pragma("unroll") for(int n=0;n<2;++n) _Pragma("unroll") for(int k=0;k<2;++k) \
;       acc[ai][bj][m][n]=__builtin_amdgcn_mfma_f32_16x16x32_bf16(At[m][k],Bt[n][k],acc[ai][bj][m][n],0,0,0); \
;     __builtin_amdgcn_s_setprio(0);}while(0)
; #define P8_WAIT_V(n) asm volatile("s_waitcnt vmcnt(" #n ")":::"memory")
; #define P8_WAIT_L(n) asm volatile("s_waitcnt lgkmcnt(" #n ")":::"memory")
; #define P8_BAR __builtin_amdgcn_s_barrier()
; #define P8_SCHED __builtin_amdgcn_sched_barrier(0)
; template <class EPI>
; DEVI void gemm8_tile(const bfr* __restrict__ A, const bfr* __restrict__ Bt, int K, int brow, int bcol, int nbrow, int nbcol, char* shmc, EPI epi) {
;     ...
;     P8_LDA(At,1,1); P8_STAGE(P8_SA(1,0),A,brow,t+3);
;     P8_BAR; P8_WAIT_L(0); P8_MMA(1,0,At,B0); P8_BAR; P8_SCHED;
;     P8_STAGE(P8_SB(1,1),Bt,bcol+128,t+3);
;     P8_WAIT_V(6); P8_BAR; P8_MMA(1,1,At,B1); P8_BAR;
;   }
;   { P8_LDB(B0,0,0); P8_LDA(At,0,0); P8_STAGE(P8_SA(1,1),A,brow+128,nt-1);
;     P8_BAR; P8_WAIT_L(0); P8_MMA(0,0,At,B0); P8_BAR;
;     P8_LDB(B1,0,1); P8_BAR; P8_WAIT_L(0); P8_MMA(0,1,At,B1); P8_BAR;
	s_waitcnt lgkmcnt(0)
	v_mfma_f32_16x16x32_bf16 v[60:63], v[190:193], v[174:177], v[60:63]
	v_mfma_f32_16x16x32_bf16 v[56:59], v[190:193], v[182:185], v[56:59]
	v_mfma_f32_16x16x32_bf16 v[52:55], v[200:203], v[174:177], v[52:55]
	v_mfma_f32_16x16x32_bf16 v[48:51], v[200:203], v[182:185], v[48:51]
	v_mfma_f32_16x16x32_bf16 v[44:47], v[208:211], v[174:177], v[44:47]
	v_mfma_f32_16x16x32_bf16 v[40:43], v[208:211], v[182:185], v[40:43]
	v_mfma_f32_16x16x32_bf16 v[36:39], v[216:219], v[174:177], v[36:39]
	v_mfma_f32_16x16x32_bf16 v[32:35], v[216:219], v[182:185], v[32:35]
	v_mfma_f32_16x16x32_bf16 v[60:63], v[196:199], v[178:181], v[60:63]
	v_mfma_f32_16x16x32_bf16 v[56:59], v[196:199], v[186:189], v[56:59]
	v_mfma_f32_16x16x32_bf16 v[52:55], v[204:207], v[178:181], v[52:55]
	v_mfma_f32_16x16x32_bf16 v[48:51], v[204:207], v[186:189], v[48:51]
	v_mfma_f32_16x16x32_bf16 v[44:47], v[212:215], v[178:181], v[44:47]
	v_mfma_f32_16x16x32_bf16 v[40:43], v[212:215], v[186:189], v[40:43]
	v_mfma_f32_16x16x32_bf16 v[36:39], v[220:223], v[178:181], v[36:39]
	v_mfma_f32_16x16x32_bf16 v[32:35], v[220:223], v[186:189], v[32:35]
	s_barrier
	v_add_u32_e32 v174, s78, v136
	s_add_i32 m0, s100, 0x1c000
	s_nop 0
	global_load_lds_dwordx4 v174, s[86:87]
	v_add_u32_e32 v174, s78, v134
	s_add_i32 m0, s100, 0x1e000
	s_nop 0
	global_load_lds_dwordx4 v174, s[86:87]
	s_waitcnt vmcnt(6)
	s_barrier
	v_mfma_f32_16x16x32_bf16 v[28:31], v[190:193], v[224:227], v[28:31]
	v_mfma_f32_16x16x32_bf16 v[24:27], v[190:193], v[232:235], v[24:27]
	v_mfma_f32_16x16x32_bf16 v[20:23], v[200:203], v[224:227], v[20:23]
	v_mfma_f32_16x16x32_bf16 v[16:19], v[200:203], v[232:235], v[16:19]
	v_mfma_f32_16x16x32_bf16 v[12:15], v[208:211], v[224:227], v[12:15]
	v_mfma_f32_16x16x32_bf16 v[8:11], v[208:211], v[232:235], v[8:11]
	v_mfma_f32_16x16x32_bf16 v[4:7], v[216:219], v[224:227], v[4:7]
	v_mfma_f32_16x16x32_bf16 v[0:3], v[216:219], v[232:235], v[0:3]
	v_mfma_f32_16x16x32_bf16 v[28:31], v[196:199], v[228:231], v[28:31]
	v_mfma_f32_16x16x32_bf16 v[24:27], v[196:199], v[236:239], v[24:27]
	v_mfma_f32_16x16x32_bf16 v[20:23], v[204:207], v[228:231], v[20:23]
	v_mfma_f32_16x16x32_bf16 v[16:19], v[204:207], v[236:239], v[16:19]
	v_mfma_f32_16x16x32_bf16 v[12:15], v[212:215], v[228:231], v[12:15]
	v_mfma_f32_16x16x32_bf16 v[8:11], v[212:215], v[236:239], v[8:11]
	v_mfma_f32_16x16x32_bf16 v[4:7], v[220:223], v[228:231], v[4:7]
	v_mfma_f32_16x16x32_bf16 v[0:3], v[220:223], v[236:239], v[0:3]
	s_add_i32 s0, s0, 2
	v_lshl_add_u64 v[134:135], v[134:135], 0, s[80:81]
	v_lshl_add_u64 v[136:137], v[136:137], 0, s[80:81]
	v_lshl_add_u64 v[138:139], v[138:139], 0, s[80:81]
	s_cmp_lt_u32 s0, 28
	v_lshl_add_u64 v[140:141], v[140:141], 0, s[80:81]
	s_barrier
	s_cbranch_scc1 .LBB0_286
	s_or_b32 s0, s8, 0x80
	s_ashr_i32 s1, s0, 31
	s_lshl_b64 s[0:1], s[0:1], 12
	s_add_u32 s0, s29, s0
	s_addc_u32 s1, s68, s1
	ds_read_b128 v[134:137], v157
	ds_read_b128 v[138:141], v157 offset:1024
	ds_read_b128 v[150:153], v157 offset:2048
	ds_read_b128 v[174:177], v157 offset:3072
	ds_read_b128 v[178:181], v147
	ds_read_b128 v[182:185], v147 offset:1024
	ds_read_b128 v[186:189], v146
	ds_read_b128 v[190:193], v146 offset:1024
	ds_read_b128 v[196:199], v145
	ds_read_b128 v[200:203], v145 offset:1024
	ds_read_b128 v[204:207], v144
	ds_read_b128 v[208:211], v144 offset:1024
	v_lshl_add_u64 v[156:157], v[166:167], 1, s[0:1]
	s_mov_b64 s[54:55], 0xf80
	v_lshl_add_u64 v[156:157], v[156:157], 0, s[54:55]
	s_add_i32 m0, s100, 0xc000
	v_lshl_add_u64 v[132:133], v[132:133], 1, s[0:1]
	global_load_lds_dwordx4 v[156:157], off
	v_lshl_add_u64 v[132:133], v[132:133], 0, s[54:55]
	s_add_i32 m0, s100, 0xe000
	s_nop 0
	global_load_lds_dwordx4 v[132:133], off
	s_barrier
	s_waitcnt lgkmcnt(0)
	s_setprio 1
	s_waitcnt lgkmcnt(0)
	v_mfma_f32_16x16x32_bf16 v[124:127], v[178:181], v[134:137], v[124:127]
	v_mfma_f32_16x16x32_bf16 v[116:119], v[186:189], v[134:137], v[116:119]
	v_mfma_f32_16x16x32_bf16 v[112:115], v[186:189], v[150:153], v[112:115]
	v_mfma_f32_16x16x32_bf16 v[96:99], v[204:207], v[150:153], v[96:99]
	v_mfma_f32_16x16x32_bf16 v[124:127], v[182:185], v[138:141], v[124:127]
	v_mfma_f32_16x16x32_bf16 v[120:123], v[178:181], v[150:153], v[120:123]
	v_mfma_f32_16x16x32_bf16 v[116:119], v[190:193], v[138:141], v[116:119]
	v_mfma_f32_16x16x32_bf16 v[112:115], v[190:193], v[174:177], v[112:115]
	v_mfma_f32_16x16x32_bf16 v[108:111], v[196:199], v[134:137], v[108:111]
	v_mfma_f32_16x16x32_bf16 v[104:107], v[196:199], v[150:153], v[104:107]
	v_mfma_f32_16x16x32_bf16 v[100:103], v[204:207], v[134:137], v[100:103]
	v_mfma_f32_16x16x32_bf16 v[96:99], v[208:211], v[174:177], v[96:99]
	v_mfma_f32_16x16x32_bf16 v[212:215], v[182:185], v[174:177], v[120:123]
	v_mfma_f32_16x16x32_bf16 v[216:219], v[200:203], v[138:141], v[108:111]
	v_mfma_f32_16x16x32_bf16 v[220:223], v[200:203], v[174:177], v[104:107]
	v_mfma_f32_16x16x32_bf16 v[224:227], v[208:211], v[138:141], v[100:103]
	s_setprio 0
	s_barrier
	s_nop 0
	ds_read_b128 v[100:103], v155
	ds_read_b128 v[104:107], v155 offset:1024
	ds_read_b128 v[108:111], v155 offset:2048
	ds_read_b128 v[120:123], v155 offset:3072
	s_barrier
; #define P8_LDA(dst,b,h) _Pragma("unroll") for(int m=0;m<4;++m) _Pragma("unroll") for(int k=0;k<2;++k) \
;     dst[m][k]=*reinterpret_cast<const bf16x8*>((char*)P8_SA(b,h)+lds_byte(wr*64+m*16+fr,k*32+fq*8))
; #define P8_LDB(dst,b,h) _Pragma("unroll") for(int n=0;n<2;++n) _Pragma("unroll") for(int k=0;k<2;++k) \
;     dst[n][k]=*reinterpret_cast<const bf16x8*>((char*)P8_SB(b,h)+lds_byte(wc*32+n*16+fr,k*32+fq*8))
; #define P8_MMA(ai,bj,At,Bt) do{__builtin_amdgcn_s_setprio(1); \
;     _Pragma("unroll") for(int m=0;m<4;++m) _Pragma("unroll") for(int n=0;n<2;++n) _Pragma("unroll") for(int k=0;k<2;++k) \
;       acc[ai][bj][m][n]=__builtin_amdgcn_mfma_f32_16x16x32_bf16(At[m][k],Bt[n][k],acc[ai][bj][m][n],0,0,0); \
;     __builtin_amdgcn_s_setprio(0);}while(0)
; #define P8_WAIT_V(n) asm volatile("s_waitcnt vmcnt(" #n ")":::"memory")
; #define P8_WAIT_L(n) asm volatile("s_waitcnt lgkmcnt(" #n ")":::"memory")
; #define P8_BAR __builtin_amdgcn_s_barrier()
; template <class EPI>
; DEVI void gemm8_tile(const bfr* __restrict__ A, const bfr* __restrict__ Bt, int K, int brow, int bcol, int nbrow, int nbcol, char* shmc, EPI epi) {
;     ...
;     P8_LDB(B1,0,1); P8_BAR; P8_WAIT_L(0); P8_MMA(0,1,At,B1); P8_BAR;
;     P8_LDA(At,0,1); P8_WAIT_V(4); P8_BAR; P8_WAIT_L(0); P8_MMA(1,0,At,B0); P8_MMA(1,1,At,B1); P8_BAR; }
;   { P8_LDB(B0,1,0); P8_LDA(At,1,0); P8_WAIT_V(2); P8_BAR; P8_WAIT_L(0); P8_MMA(0,0,At,B0); P8_BAR;
	s_waitcnt lgkmcnt(0)
	s_setprio 1
	s_waitcnt lgkmcnt(0)
	v_mfma_f32_16x16x32_bf16 v[92:95], v[178:181], v[100:103], v[92:95]
	v_mfma_f32_16x16x32_bf16 v[84:87], v[186:189], v[100:103], v[84:87]
	v_mfma_f32_16x16x32_bf16 v[80:83], v[186:189], v[108:111], v[80:83]
	v_mfma_f32_16x16x32_bf16 v[64:67], v[204:207], v[108:111], v[64:67]
	v_mfma_f32_16x16x32_bf16 v[92:95], v[182:185], v[104:107], v[92:95]
	v_mfma_f32_16x16x32_bf16 v[88:91], v[178:181], v[108:111], v[88:91]
	v_mfma_f32_16x16x32_bf16 v[84:87], v[190:193], v[104:107], v[84:87]
	v_mfma_f32_16x16x32_bf16 v[80:83], v[190:193], v[120:123], v[80:83]
	v_mfma_f32_16x16x32_bf16 v[76:79], v[196:199], v[100:103], v[76:79]
	v_mfma_f32_16x16x32_bf16 v[72:75], v[196:199], v[108:111], v[72:75]
	v_mfma_f32_16x16x32_bf16 v[68:71], v[204:207], v[100:103], v[68:71]
	v_mfma_f32_16x16x32_bf16 v[64:67], v[208:211], v[120:123], v[64:67]
	v_mfma_f32_16x16x32_bf16 v[154:157], v[182:185], v[120:123], v[88:91]
	v_mfma_f32_16x16x32_bf16 v[178:181], v[200:203], v[104:107], v[76:79]
	v_mfma_f32_16x16x32_bf16 v[182:185], v[200:203], v[120:123], v[72:75]
	v_mfma_f32_16x16x32_bf16 v[186:189], v[208:211], v[104:107], v[68:71]
	s_setprio 0
	s_barrier
	s_nop 0
	ds_read_b128 v[68:71], v147 offset:16384
	ds_read_b128 v[72:75], v147 offset:17408
	ds_read_b128 v[76:79], v146 offset:16384
	ds_read_b128 v[88:91], v146 offset:17408
	ds_read_b128 v[190:193], v145 offset:16384
	ds_read_b128 v[196:199], v145 offset:17408
	ds_read_b128 v[200:203], v144 offset:16384
	ds_read_b128 v[204:207], v144 offset:17408
	s_waitcnt vmcnt(4)
	s_barrier
	s_waitcnt lgkmcnt(0)
	s_setprio 1
	s_waitcnt lgkmcnt(0)
	v_mfma_f32_16x16x32_bf16 v[60:63], v[68:71], v[134:137], v[60:63]
	v_mfma_f32_16x16x32_bf16 v[52:55], v[76:79], v[134:137], v[52:55]
	v_mfma_f32_16x16x32_bf16 v[48:51], v[76:79], v[150:153], v[48:51]
	v_mfma_f32_16x16x32_bf16 v[32:35], v[200:203], v[150:153], v[32:35]
	v_mfma_f32_16x16x32_bf16 v[60:63], v[72:75], v[138:141], v[60:63]
	v_mfma_f32_16x16x32_bf16 v[56:59], v[68:71], v[150:153], v[56:59]
	v_mfma_f32_16x16x32_bf16 v[52:55], v[88:91], v[138:141], v[52:55]
	v_mfma_f32_16x16x32_bf16 v[48:51], v[88:91], v[174:177], v[48:51]
	v_mfma_f32_16x16x32_bf16 v[44:47], v[190:193], v[134:137], v[44:47]
	v_mfma_f32_16x16x32_bf16 v[40:43], v[190:193], v[150:153], v[40:43]
	v_mfma_f32_16x16x32_bf16 v[36:39], v[200:203], v[134:137], v[36:39]
	v_mfma_f32_16x16x32_bf16 v[32:35], v[204:207], v[174:177], v[32:35]
	v_mfma_f32_16x16x32_bf16 v[208:211], v[72:75], v[174:177], v[56:59]
	v_mfma_f32_16x16x32_bf16 v[228:231], v[196:199], v[138:141], v[44:47]
	v_mfma_f32_16x16x32_bf16 v[232:235], v[196:199], v[174:177], v[40:43]
	v_mfma_f32_16x16x32_bf16 v[132:135], v[204:207], v[138:141], v[36:39]
	s_setprio 0
	s_setprio 1
	v_mfma_f32_16x16x32_bf16 v[28:31], v[68:71], v[100:103], v[28:31]
	v_mfma_f32_16x16x32_bf16 v[20:23], v[76:79], v[100:103], v[20:23]
	v_mfma_f32_16x16x32_bf16 v[16:19], v[76:79], v[108:111], v[16:19]
	v_mfma_f32_16x16x32_bf16 v[0:3], v[200:203], v[108:111], v[0:3]
	v_mfma_f32_16x16x32_bf16 v[28:31], v[72:75], v[104:107], v[28:31]
	v_mfma_f32_16x16x32_bf16 v[24:27], v[68:71], v[108:111], v[24:27]
	v_mfma_f32_16x16x32_bf16 v[20:23], v[88:91], v[104:107], v[20:23]
	v_mfma_f32_16x16x32_bf16 v[16:19], v[88:91], v[120:123], v[16:19]
	v_mfma_f32_16x16x32_bf16 v[12:15], v[190:193], v[100:103], v[12:15]
	v_mfma_f32_16x16x32_bf16 v[8:11], v[190:193], v[108:111], v[8:11]
	v_mfma_f32_16x16x32_bf16 v[4:7], v[200:203], v[100:103], v[4:7]
	v_mfma_f32_16x16x32_bf16 v[0:3], v[204:207], v[120:123], v[0:3]
	v_mfma_f32_16x16x32_bf16 v[136:139], v[72:75], v[120:123], v[24:27]
	v_mfma_f32_16x16x32_bf16 v[150:153], v[196:199], v[104:107], v[12:15]
	v_mfma_f32_16x16x32_bf16 v[172:175], v[196:199], v[120:123], v[8:11]
	v_mfma_f32_16x16x32_bf16 v[190:193], v[204:207], v[104:107], v[4:7]
	s_setprio 0
	s_barrier
	s_nop 0
	ds_read_b128 v[4:7], v149
	ds_read_b128 v[8:11], v149 offset:1024
	ds_read_b128 v[12:15], v149 offset:2048
	ds_read_b128 v[24:27], v149 offset:3072
	ds_read_b128 v[36:39], v147 offset:32768
	ds_read_b128 v[40:43], v147 offset:33792
	ds_read_b128 v[44:47], v146 offset:32768
	ds_read_b128 v[56:59], v146 offset:33792
	ds_read_b128 v[68:71], v145 offset:32768
	ds_read_b128 v[196:199], v145 offset:33792
	ds_read_b128 v[200:203], v144 offset:32768
	ds_read_b128 v[204:207], v144 offset:33792
	s_waitcnt vmcnt(2)
	s_barrier
; #define P8_LDA(dst,b,h) _Pragma("unroll") for(int m=0;m<4;++m) _Pragma("unroll") for(int k=0;k<2;++k) \
;     dst[m][k]=*reinterpret_cast<const bf16x8*>((char*)P8_SA(b,h)+lds_byte(wr*64+m*16+fr,k*32+fq*8))
; #define P8_LDB(dst,b,h) _Pragma("unroll") for(int n=0;n<2;++n) _Pragma("unroll") for(int k=0;k<2;++k) \
;     dst[n][k]=*reinterpret_cast<const bf16x8*>((char*)P8_SB(b,h)+lds_byte(wc*32+n*16+fr,k*32+fq*8))
; #define P8_MMA(ai,bj,At,Bt) do{__builtin_amdgcn_s_setprio(1); \
;     _Pragma("unroll") for(int m=0;m<4;++m) _Pragma("unroll") for(int n=0;n<2;++n) _Pragma("unroll") for(int k=0;k<2;++k) \
;       acc[ai][bj][m][n]=__builtin_amdgcn_mfma_f32_16x16x32_bf16(At[m][k],Bt[n][k],acc[ai][bj][m][n],0,0,0); \
;     __builtin_amdgcn_s_setprio(0);}while(0)
; #define P8_WAIT_V(n) asm volatile("s_waitcnt vmcnt(" #n ")":::"memory")
; #define P8_WAIT_L(n) asm volatile("s_waitcnt lgkmcnt(" #n ")":::"memory")
; #define P8_BAR __builtin_amdgcn_s_barrier()
; template <class EPI>
; DEVI void gemm8_tile(const bfr* __restrict__ A, const bfr* __restrict__ Bt, int K, int brow, int bcol, int nbrow, int nbcol, char* shmc, EPI epi) {
;     ...
;   { P8_LDB(B0,1,0); P8_LDA(At,1,0); P8_WAIT_V(2); P8_BAR; P8_WAIT_L(0); P8_MMA(0,0,At,B0); P8_BAR;
;     P8_LDB(B1,1,1); P8_WAIT_V(0); P8_BAR; P8_WAIT_L(0); P8_MMA(0,1,At,B1); P8_BAR;
;     P8_LDA(At,1,1); P8_BAR; P8_WAIT_L(0); P8_MMA(1,0,At,B0); P8_MMA(1,1,At,B1); P8_BAR; }
;   if(wr==0)P8_BAR;
	s_waitcnt lgkmcnt(0)
	s_setprio 1
	s_waitcnt lgkmcnt(0)
	v_mfma_f32_16x16x32_bf16 v[72:75], v[36:39], v[4:7], v[124:127]
	v_mfma_f32_16x16x32_bf16 v[120:123], v[40:43], v[8:11], v[72:75]
	v_mfma_f32_16x16x32_bf16 v[72:75], v[36:39], v[12:15], v[212:215]
	v_mfma_f32_16x16x32_bf16 v[104:107], v[40:43], v[24:27], v[72:75]
	v_mfma_f32_16x16x32_bf16 v[72:75], v[44:47], v[4:7], v[116:119]
	v_mfma_f32_16x16x32_bf16 v[124:127], v[56:59], v[8:11], v[72:75]
	v_mfma_f32_16x16x32_bf16 v[72:75], v[44:47], v[12:15], v[112:115]
	v_mfma_f32_16x16x32_bf16 v[108:111], v[56:59], v[24:27], v[72:75]
	v_mfma_f32_16x16x32_bf16 v[72:75], v[68:71], v[4:7], v[216:219]
	v_mfma_f32_16x16x32_bf16 v[112:115], v[196:199], v[8:11], v[72:75]
	v_mfma_f32_16x16x32_bf16 v[72:75], v[68:71], v[12:15], v[220:223]
	v_mfma_f32_16x16x32_bf16 v[100:103], v[196:199], v[24:27], v[72:75]
	v_mfma_f32_16x16x32_bf16 v[72:75], v[200:203], v[4:7], v[224:227]
	v_mfma_f32_16x16x32_bf16 v[116:119], v[204:207], v[8:11], v[72:75]
	v_mfma_f32_16x16x32_bf16 v[72:75], v[200:203], v[12:15], v[96:99]
	v_mfma_f32_16x16x32_bf16 v[96:99], v[204:207], v[24:27], v[72:75]
	s_setprio 0
	s_barrier
	ds_read_b128 v[212:215], v148
	ds_read_b128 v[216:219], v148 offset:1024
	ds_read_b128 v[220:223], v148 offset:2048
	ds_read_b128 v[224:227], v148 offset:3072
	s_waitcnt vmcnt(0)
	s_barrier
	s_waitcnt lgkmcnt(0)
	s_setprio 1
	s_waitcnt lgkmcnt(0)
	v_mfma_f32_16x16x32_bf16 v[72:75], v[36:39], v[212:215], v[92:95]
	v_mfma_f32_16x16x32_bf16 v[36:39], v[36:39], v[220:223], v[154:157]
	v_mfma_f32_16x16x32_bf16 v[88:91], v[40:43], v[216:219], v[72:75]
	v_mfma_f32_16x16x32_bf16 v[72:75], v[40:43], v[224:227], v[36:39]
	v_mfma_f32_16x16x32_bf16 v[36:39], v[44:47], v[212:215], v[84:87]
	v_mfma_f32_16x16x32_bf16 v[92:95], v[56:59], v[216:219], v[36:39]
	v_mfma_f32_16x16x32_bf16 v[36:39], v[44:47], v[220:223], v[80:83]
	v_mfma_f32_16x16x32_bf16 v[76:79], v[56:59], v[224:227], v[36:39]
	v_mfma_f32_16x16x32_bf16 v[36:39], v[68:71], v[212:215], v[178:181]
	v_mfma_f32_16x16x32_bf16 v[80:83], v[196:199], v[216:219], v[36:39]
	v_mfma_f32_16x16x32_bf16 v[36:39], v[68:71], v[220:223], v[182:185]
	v_mfma_f32_16x16x32_bf16 v[68:71], v[196:199], v[224:227], v[36:39]
	v_mfma_f32_16x16x32_bf16 v[36:39], v[200:203], v[212:215], v[186:189]
	v_mfma_f32_16x16x32_bf16 v[84:87], v[204:207], v[216:219], v[36:39]
	v_mfma_f32_16x16x32_bf16 v[36:39], v[200:203], v[220:223], v[64:67]
	v_mfma_f32_16x16x32_bf16 v[64:67], v[204:207], v[224:227], v[36:39]
	s_setprio 0
	s_barrier
	ds_read_b128 v[154:157], v147 offset:49152
	ds_read_b128 v[176:179], v147 offset:50176
	ds_read_b128 v[180:183], v146 offset:49152
	ds_read_b128 v[146:149], v146 offset:50176
	ds_read_b128 v[184:187], v145 offset:49152
	ds_read_b128 v[196:199], v145 offset:50176
	ds_read_b128 v[200:203], v144 offset:49152
	ds_read_b128 v[204:207], v144 offset:50176
	s_barrier
	s_waitcnt lgkmcnt(0)
	s_setprio 1
	s_waitcnt lgkmcnt(0)
	v_mfma_f32_16x16x32_bf16 v[36:39], v[154:157], v[4:7], v[60:63]
	v_mfma_f32_16x16x32_bf16 v[56:59], v[176:179], v[8:11], v[36:39]
	v_mfma_f32_16x16x32_bf16 v[36:39], v[154:157], v[12:15], v[208:211]
	v_mfma_f32_16x16x32_bf16 v[40:43], v[176:179], v[24:27], v[36:39]
	v_mfma_f32_16x16x32_bf16 v[36:39], v[180:183], v[4:7], v[52:55]
	v_mfma_f32_16x16x32_bf16 v[60:63], v[146:149], v[8:11], v[36:39]
	v_mfma_f32_16x16x32_bf16 v[36:39], v[180:183], v[12:15], v[48:51]
	v_mfma_f32_16x16x32_bf16 v[44:47], v[146:149], v[24:27], v[36:39]
	v_mfma_f32_16x16x32_bf16 v[36:39], v[184:187], v[4:7], v[228:231]
	v_mfma_f32_16x16x32_bf16 v[4:7], v[200:203], v[4:7], v[132:135]
	v_mfma_f32_16x16x32_bf16 v[48:51], v[196:199], v[8:11], v[36:39]
	v_mfma_f32_16x16x32_bf16 v[36:39], v[184:187], v[12:15], v[232:235]
	v_mfma_f32_16x16x32_bf16 v[52:55], v[204:207], v[8:11], v[4:7]
	v_mfma_f32_16x16x32_bf16 v[4:7], v[200:203], v[12:15], v[32:35]
	v_mfma_f32_16x16x32_bf16 v[36:39], v[196:199], v[24:27], v[36:39]
	v_mfma_f32_16x16x32_bf16 v[32:35], v[204:207], v[24:27], v[4:7]
	s_setprio 0
	s_setprio 1
	v_mfma_f32_16x16x32_bf16 v[4:7], v[154:157], v[212:215], v[28:31]
	v_mfma_f32_16x16x32_bf16 v[24:27], v[176:179], v[216:219], v[4:7]
	v_mfma_f32_16x16x32_bf16 v[4:7], v[154:157], v[220:223], v[136:139]
	v_mfma_f32_16x16x32_bf16 v[8:11], v[176:179], v[224:227], v[4:7]
	v_mfma_f32_16x16x32_bf16 v[4:7], v[180:183], v[212:215], v[20:23]
	v_mfma_f32_16x16x32_bf16 v[28:31], v[146:149], v[216:219], v[4:7]
	v_mfma_f32_16x16x32_bf16 v[4:7], v[180:183], v[220:223], v[16:19]
	v_mfma_f32_16x16x32_bf16 v[12:15], v[146:149], v[224:227], v[4:7]
	v_mfma_f32_16x16x32_bf16 v[4:7], v[184:187], v[212:215], v[150:153]
	v_mfma_f32_16x16x32_bf16 v[16:19], v[196:199], v[216:219], v[4:7]
	v_mfma_f32_16x16x32_bf16 v[4:7], v[184:187], v[220:223], v[172:175]
	v_mfma_f32_16x16x32_bf16 v[20:23], v[200:203], v[212:215], v[190:193]
	v_mfma_f32_16x16x32_bf16 v[0:3], v[200:203], v[220:223], v[0:3]
	v_mfma_f32_16x16x32_bf16 v[4:7], v[196:199], v[224:227], v[4:7]
	v_mfma_f32_16x16x32_bf16 v[20:23], v[204:207], v[216:219], v[20:23]
	v_mfma_f32_16x16x32_bf16 v[0:3], v[204:207], v[224:227], v[0:3]
	s_setprio 0
	v_cmp_gt_u32_e32 vcc, s57, v142
	s_barrier
	s_and_saveexec_b64 s[0:1], vcc
	s_cbranch_execz .LBB0_289
	s_barrier

; #define P8_STAGE(P,BASE,br,kt) do{const bfr* _ub=(BASE)+((long)(br)*K+(long)(kt)*BK); \
;     __builtin_amdgcn_global_load_lds((const unsigned*)(_ub+so0),(unsigned*)((char*)(P)+wid*1024),16,0,0); \
;     __builtin_amdgcn_global_load_lds((const unsigned*)(_ub+so1),(unsigned*)((char*)(P)+wid*1024+8192),16,0,0);}while(0)
; #define P8_LDA(dst,b,h) _Pragma("unroll") for(int m=0;m<4;++m) _Pragma("unroll") for(int k=0;k<2;++k) \
;     dst[m][k]=*reinterpret_cast<const bf16x8*>((char*)P8_SA(b,h)+lds_byte(wr*64+m*16+fr,k*32+fq*8))
; #define P8_LDB(dst,b,h) _Pragma("unroll") for(int n=0;n<2;++n) _Pragma("unroll") for(int k=0;k<2;++k) \
;     dst[n][k]=*reinterpret_cast<const bf16x8*>((char*)P8_SB(b,h)+lds_byte(wc*32+n*16+fr,k*32+fq*8))
; #define P8_MMA(ai,bj,At,Bt) do{__builtin_amdgcn_s_setprio(1); \
;     _Pragma("unroll") for(int m=0;m<4;++m) _Pragma("unroll") for(int n=0;n<2;++n) _Pragma("unroll") for(int k=0;k<2;++k) \
;       acc[ai][bj][m][n]=__builtin_amdgcn_mfma_f32_16x16x32_bf16(At[m][k],Bt[n][k],acc[ai][bj][m][n],0,0,0); \
;     __builtin_amdgcn_s_setprio(0);}while(0)
; #define P8_WAIT_V(n) asm volatile("s_waitcnt vmcnt(" #n ")":::"memory")
; #define P8_WAIT_L(n) asm volatile("s_waitcnt lgkmcnt(" #n ")":::"memory")
; #define P8_BAR __builtin_amdgcn_s_barrier()
; #define P8_SCHED __builtin_amdgcn_sched_barrier(0)
; template <class EPI>
; DEVI void gemm8_tile(const bfr* __restrict__ A, const bfr* __restrict__ Bt, int K, int brow, int bcol, int nbrow, int nbcol, char* shmc, EPI epi) {
;     ...
;     P8_LDB(B0,0,0); P8_SCHED; P8_LDA(At,0,0); P8_STAGE(P8_SA(1,1),A,brow+128,t+1);
;     P8_WAIT_L(8); P8_BAR; P8_WAIT_L(0); P8_MMA(0,0,At,B0); P8_BAR; P8_SCHED;
;     P8_LDB(B1,0,1); P8_STAGE(P8_SB(0,0),Bt,bcol,t+2);
;     P8_BAR; P8_WAIT_L(0); P8_MMA(0,1,At,B1); P8_BAR;
;     P8_LDA(At,0,1); P8_STAGE(P8_SA(0,0),A,brow,t+2);
;     P8_BAR; P8_WAIT_L(0); P8_MMA(1,0,At,B0); P8_BAR; P8_SCHED;
;     P8_STAGE(P8_SB(0,1),Bt,bcol+128,t+2);
;     P8_WAIT_V(6); P8_BAR; P8_MMA(1,1,At,B1); P8_BAR;
.LBB0_382:
	ds_read_b128 v[174:177], v157
	ds_read_b128 v[178:181], v157 offset:1024
	ds_read_b128 v[182:185], v157 offset:2048
	ds_read_b128 v[186:189], v157 offset:3072
	v_add_u32_e32 v171, 0xc000, v143
	v_add_u32_e32 v172, 0xe000, v143
	v_add_u32_e32 v158, s54, v140
	s_add_i32 m0, s100, 0xc000
	ds_read_b128 v[160:163], v147
	ds_read_b128 v[190:193], v147 offset:1024
	ds_read_b128 v[196:199], v146
	ds_read_b128 v[208:211], v146 offset:1024
	ds_read_b128 v[212:215], v145
	ds_read_b128 v[216:219], v145 offset:1024
	ds_read_b128 v[220:223], v144
	ds_read_b128 v[224:227], v144 offset:1024
	global_load_lds_dwordx4 v158, s[86:87]
	v_add_u32_e32 v158, s54, v138
	s_add_i32 m0, s100, 0xe000
	s_nop 0
	global_load_lds_dwordx4 v158, s[86:87]
	s_waitcnt lgkmcnt(8)
	s_barrier
	s_waitcnt lgkmcnt(0)
	v_mfma_f32_16x16x32_bf16 v[124:127], v[160:163], v[174:177], v[124:127]
	v_mfma_f32_16x16x32_bf16 v[120:123], v[160:163], v[182:185], v[120:123]
	v_mfma_f32_16x16x32_bf16 v[116:119], v[196:199], v[174:177], v[116:119]
	v_mfma_f32_16x16x32_bf16 v[112:115], v[196:199], v[182:185], v[112:115]
	v_mfma_f32_16x16x32_bf16 v[108:111], v[212:215], v[174:177], v[108:111]
	v_mfma_f32_16x16x32_bf16 v[104:107], v[212:215], v[182:185], v[104:107]
	v_mfma_f32_16x16x32_bf16 v[100:103], v[220:223], v[174:177], v[100:103]
	v_mfma_f32_16x16x32_bf16 v[96:99], v[220:223], v[182:185], v[96:99]
	v_mfma_f32_16x16x32_bf16 v[124:127], v[190:193], v[178:181], v[124:127]
	v_mfma_f32_16x16x32_bf16 v[120:123], v[190:193], v[186:189], v[120:123]
	v_mfma_f32_16x16x32_bf16 v[116:119], v[208:211], v[178:181], v[116:119]
	v_mfma_f32_16x16x32_bf16 v[112:115], v[208:211], v[186:189], v[112:115]
	v_mfma_f32_16x16x32_bf16 v[108:111], v[216:219], v[178:181], v[108:111]
	v_mfma_f32_16x16x32_bf16 v[104:107], v[216:219], v[186:189], v[104:107]
	v_mfma_f32_16x16x32_bf16 v[100:103], v[224:227], v[178:181], v[100:103]
	v_mfma_f32_16x16x32_bf16 v[96:99], v[224:227], v[186:189], v[96:99]
	s_barrier
	v_add_u32_e32 v158, 0x10000, v143
	v_add_u32_e32 v206, s60, v136
	s_add_i32 m0, s100, 0x10000
	v_add_u32_e32 v159, 0x12000, v143
	ds_read_b128 v[228:231], v154
	ds_read_b128 v[232:235], v154 offset:1024
	ds_read_b128 v[236:239], v154 offset:2048
	ds_read_b128 v[240:243], v154 offset:3072
	global_load_lds_dwordx4 v206, s[86:87]
	v_add_u32_e32 v244, s60, v134
	s_add_i32 m0, s100, 0x12000
	s_nop 0
	global_load_lds_dwordx4 v244, s[86:87]
	s_barrier
	s_waitcnt lgkmcnt(0)
	v_mfma_f32_16x16x32_bf16 v[92:95], v[160:163], v[228:231], v[92:95]
	v_mfma_f32_16x16x32_bf16 v[88:91], v[160:163], v[236:239], v[88:91]
	v_mfma_f32_16x16x32_bf16 v[84:87], v[196:199], v[228:231], v[84:87]
	v_mfma_f32_16x16x32_bf16 v[80:83], v[196:199], v[236:239], v[80:83]
	v_mfma_f32_16x16x32_bf16 v[76:79], v[212:215], v[228:231], v[76:79]
	v_mfma_f32_16x16x32_bf16 v[72:75], v[212:215], v[236:239], v[72:75]
	v_mfma_f32_16x16x32_bf16 v[68:71], v[220:223], v[228:231], v[68:71]
	v_mfma_f32_16x16x32_bf16 v[64:67], v[220:223], v[236:239], v[64:67]
	v_mfma_f32_16x16x32_bf16 v[92:95], v[190:193], v[232:235], v[92:95]
	v_mfma_f32_16x16x32_bf16 v[88:91], v[190:193], v[240:243], v[88:91]
	v_mfma_f32_16x16x32_bf16 v[84:87], v[208:211], v[232:235], v[84:87]
	v_mfma_f32_16x16x32_bf16 v[80:83], v[208:211], v[240:243], v[80:83]
	v_mfma_f32_16x16x32_bf16 v[76:79], v[216:219], v[232:235], v[76:79]
	v_mfma_f32_16x16x32_bf16 v[72:75], v[216:219], v[240:243], v[72:75]
	v_mfma_f32_16x16x32_bf16 v[68:71], v[224:227], v[232:235], v[68:71]
	v_mfma_f32_16x16x32_bf16 v[64:67], v[224:227], v[240:243], v[64:67]
	v_add_u32_e32 v160, s82, v140
	s_mov_b32 m0, s100
	s_barrier
	ds_read_b128 v[190:193], v147 offset:16384
	ds_read_b128 v[196:199], v147 offset:17408
	ds_read_b128 v[208:211], v146 offset:16384
	ds_read_b128 v[212:215], v146 offset:17408
	ds_read_b128 v[216:219], v145 offset:16384
	ds_read_b128 v[220:223], v145 offset:17408
	ds_read_b128 v[224:227], v144 offset:16384
	ds_read_b128 v[244:247], v144 offset:17408
	global_load_lds_dwordx4 v160, s[86:87]
	v_add_u32_e32 v160, 0x2000, v143
	v_add_u32_e32 v162, s82, v138
	s_add_i32 m0, s100, 0x2000
	s_nop 0
	global_load_lds_dwordx4 v162, s[86:87]
	s_barrier
	s_waitcnt lgkmcnt(0)
	v_mfma_f32_16x16x32_bf16 v[60:63], v[190:193], v[174:177], v[60:63]
	v_mfma_f32_16x16x32_bf16 v[56:59], v[190:193], v[182:185], v[56:59]
	v_mfma_f32_16x16x32_bf16 v[52:55], v[208:211], v[174:177], v[52:55]
	v_mfma_f32_16x16x32_bf16 v[48:51], v[208:211], v[182:185], v[48:51]
	v_mfma_f32_16x16x32_bf16 v[44:47], v[216:219], v[174:177], v[44:47]
	v_mfma_f32_16x16x32_bf16 v[40:43], v[216:219], v[182:185], v[40:43]
	v_mfma_f32_16x16x32_bf16 v[36:39], v[224:227], v[174:177], v[36:39]
	v_mfma_f32_16x16x32_bf16 v[32:35], v[224:227], v[182:185], v[32:35]
	v_mfma_f32_16x16x32_bf16 v[60:63], v[196:199], v[178:181], v[60:63]
	v_mfma_f32_16x16x32_bf16 v[56:59], v[196:199], v[186:189], v[56:59]
	v_mfma_f32_16x16x32_bf16 v[52:55], v[212:215], v[178:181], v[52:55]
	v_mfma_f32_16x16x32_bf16 v[48:51], v[212:215], v[186:189], v[48:51]
	v_mfma_f32_16x16x32_bf16 v[44:47], v[220:223], v[178:181], v[44:47]
	v_mfma_f32_16x16x32_bf16 v[40:43], v[220:223], v[186:189], v[40:43]
	v_mfma_f32_16x16x32_bf16 v[36:39], v[244:247], v[178:181], v[36:39]
	v_mfma_f32_16x16x32_bf16 v[32:35], v[244:247], v[186:189], v[32:35]
	s_barrier
	v_add_u32_e32 v161, 0x14000, v143
	v_add_u32_e32 v162, s92, v136
	s_add_i32 m0, s100, 0x14000
	v_add_u32_e32 v174, s92, v134
	global_load_lds_dwordx4 v162, s[86:87]
	v_add_u32_e32 v162, 0x16000, v143
	s_nop 0
	s_add_i32 m0, s100, 0x16000
	s_nop 0
	global_load_lds_dwordx4 v174, s[86:87]
	s_waitcnt vmcnt(6)
	s_barrier
; #define P8_STAGE(P,BASE,br,kt) do{const bfr* _ub=(BASE)+((long)(br)*K+(long)(kt)*BK); \
;     __builtin_amdgcn_global_load_lds((const unsigned*)(_ub+so0),(unsigned*)((char*)(P)+wid*1024),16,0,0); \
;     __builtin_amdgcn_global_load_lds((const unsigned*)(_ub+so1),(unsigned*)((char*)(P)+wid*1024+8192),16,0,0);}while(0)
; #define P8_LDA(dst,b,h) _Pragma("unroll") for(int m=0;m<4;++m) _Pragma("unroll") for(int k=0;k<2;++k) \
;     dst[m][k]=*reinterpret_cast<const bf16x8*>((char*)P8_SA(b,h)+lds_byte(wr*64+m*16+fr,k*32+fq*8))
; #define P8_LDB(dst,b,h) _Pragma("unroll") for(int n=0;n<2;++n) _Pragma("unroll") for(int k=0;k<2;++k) \
;     dst[n][k]=*reinterpret_cast<const bf16x8*>((char*)P8_SB(b,h)+lds_byte(wc*32+n*16+fr,k*32+fq*8))
; #define P8_MMA(ai,bj,At,Bt) do{__builtin_amdgcn_s_setprio(1); \
;     _Pragma("unroll") for(int m=0;m<4;++m) _Pragma("unroll") for(int n=0;n<2;++n) _Pragma("unroll") for(int k=0;k<2;++k) \
;       acc[ai][bj][m][n]=__builtin_amdgcn_mfma_f32_16x16x32_bf16(At[m][k],Bt[n][k],acc[ai][bj][m][n],0,0,0); \
;     __builtin_amdgcn_s_setprio(0);}while(0)
; #define P8_WAIT_V(n) asm volatile("s_waitcnt vmcnt(" #n ")":::"memory")
; #define P8_WAIT_L(n) asm volatile("s_waitcnt lgkmcnt(" #n ")":::"memory")
; #define P8_BAR __builtin_amdgcn_s_barrier()
; #define P8_SCHED __builtin_amdgcn_sched_barrier(0)
; template <class EPI>
; DEVI void gemm8_tile(const bfr* __restrict__ A, const bfr* __restrict__ Bt, int K, int brow, int bcol, int nbrow, int nbcol, char* shmc, EPI epi) {
;     ...
;     P8_WAIT_V(6); P8_BAR; P8_MMA(1,1,At,B1); P8_BAR;
;     P8_LDB(B0,1,0); P8_SCHED; P8_LDA(At,1,0); P8_STAGE(P8_SA(0,1),A,brow+128,t+2);
;     P8_WAIT_L(8); P8_BAR; P8_WAIT_L(0); P8_MMA(0,0,At,B0); P8_BAR; P8_SCHED;
;     P8_LDB(B1,1,1); P8_STAGE(P8_SB(1,0),Bt,bcol,t+3);
;     P8_BAR; P8_WAIT_L(0); P8_MMA(0,1,At,B1); P8_BAR;
;     P8_LDA(At,1,1); P8_STAGE(P8_SA(1,0),A,brow,t+3);
;     P8_BAR; P8_WAIT_L(0); P8_MMA(1,0,At,B0); P8_BAR; P8_SCHED;
	v_mfma_f32_16x16x32_bf16 v[28:31], v[190:193], v[228:231], v[28:31]
	v_mfma_f32_16x16x32_bf16 v[24:27], v[190:193], v[236:239], v[24:27]
	v_mfma_f32_16x16x32_bf16 v[20:23], v[208:211], v[228:231], v[20:23]
	v_mfma_f32_16x16x32_bf16 v[16:19], v[208:211], v[236:239], v[16:19]
	v_mfma_f32_16x16x32_bf16 v[12:15], v[216:219], v[228:231], v[12:15]
	v_mfma_f32_16x16x32_bf16 v[8:11], v[216:219], v[236:239], v[8:11]
	v_mfma_f32_16x16x32_bf16 v[4:7], v[224:227], v[228:231], v[4:7]
	v_mfma_f32_16x16x32_bf16 v[0:3], v[224:227], v[236:239], v[0:3]
	v_mfma_f32_16x16x32_bf16 v[28:31], v[196:199], v[232:235], v[28:31]
	v_mfma_f32_16x16x32_bf16 v[24:27], v[196:199], v[240:243], v[24:27]
	v_mfma_f32_16x16x32_bf16 v[20:23], v[212:215], v[232:235], v[20:23]
	v_mfma_f32_16x16x32_bf16 v[16:19], v[212:215], v[240:243], v[16:19]
	v_mfma_f32_16x16x32_bf16 v[12:15], v[220:223], v[232:235], v[12:15]
	v_mfma_f32_16x16x32_bf16 v[8:11], v[220:223], v[240:243], v[8:11]
	v_mfma_f32_16x16x32_bf16 v[4:7], v[244:247], v[232:235], v[4:7]
	v_mfma_f32_16x16x32_bf16 v[0:3], v[244:247], v[240:243], v[0:3]
	s_barrier
	ds_read_b128 v[174:177], v149
	ds_read_b128 v[178:181], v149 offset:1024
	ds_read_b128 v[182:185], v149 offset:2048
	ds_read_b128 v[186:189], v149 offset:3072
	v_add_u32_e32 v163, 0x4000, v143
	v_add_u32_e32 v170, 0x6000, v143
	v_add_u32_e32 v232, s94, v140
	s_add_i32 m0, s100, 0x4000
	ds_read_b128 v[190:193], v147 offset:32768
	ds_read_b128 v[196:199], v147 offset:33792
	ds_read_b128 v[208:211], v146 offset:32768
	ds_read_b128 v[212:215], v146 offset:33792
	ds_read_b128 v[216:219], v145 offset:32768
	ds_read_b128 v[220:223], v145 offset:33792
	ds_read_b128 v[224:227], v144 offset:32768
	ds_read_b128 v[228:231], v144 offset:33792
	global_load_lds_dwordx4 v232, s[86:87]
	v_add_u32_e32 v232, s94, v138
	s_add_i32 m0, s100, 0x6000
	s_nop 0
	global_load_lds_dwordx4 v232, s[86:87]
	s_waitcnt lgkmcnt(8)
	s_barrier
	s_waitcnt lgkmcnt(0)
	v_mfma_f32_16x16x32_bf16 v[124:127], v[190:193], v[174:177], v[124:127]
	v_mfma_f32_16x16x32_bf16 v[120:123], v[190:193], v[182:185], v[120:123]
	v_mfma_f32_16x16x32_bf16 v[116:119], v[208:211], v[174:177], v[116:119]
	v_mfma_f32_16x16x32_bf16 v[112:115], v[208:211], v[182:185], v[112:115]
	v_mfma_f32_16x16x32_bf16 v[108:111], v[216:219], v[174:177], v[108:111]
	v_mfma_f32_16x16x32_bf16 v[104:107], v[216:219], v[182:185], v[104:107]
	v_mfma_f32_16x16x32_bf16 v[100:103], v[224:227], v[174:177], v[100:103]
	v_mfma_f32_16x16x32_bf16 v[96:99], v[224:227], v[182:185], v[96:99]
	v_mfma_f32_16x16x32_bf16 v[124:127], v[196:199], v[178:181], v[124:127]
	v_mfma_f32_16x16x32_bf16 v[120:123], v[196:199], v[186:189], v[120:123]
	v_mfma_f32_16x16x32_bf16 v[116:119], v[212:215], v[178:181], v[116:119]
	v_mfma_f32_16x16x32_bf16 v[112:115], v[212:215], v[186:189], v[112:115]
	v_mfma_f32_16x16x32_bf16 v[108:111], v[220:223], v[178:181], v[108:111]
	v_mfma_f32_16x16x32_bf16 v[104:107], v[220:223], v[186:189], v[104:107]
	v_mfma_f32_16x16x32_bf16 v[100:103], v[228:231], v[178:181], v[100:103]
	v_mfma_f32_16x16x32_bf16 v[96:99], v[228:231], v[186:189], v[96:99]
	s_barrier
	v_add_u32_e32 v248, s96, v136
	s_add_i32 m0, s100, 0x18000
	ds_read_b128 v[232:235], v148
	ds_read_b128 v[236:239], v148 offset:1024
	ds_read_b128 v[240:243], v148 offset:2048
	ds_read_b128 v[244:247], v148 offset:3072
	global_load_lds_dwordx4 v248, s[86:87]
	v_add_u32_e32 v248, s96, v134
	s_add_i32 m0, s100, 0x1a000
	s_nop 0
	global_load_lds_dwordx4 v248, s[86:87]
	s_barrier
	s_waitcnt lgkmcnt(0)
	v_mfma_f32_16x16x32_bf16 v[92:95], v[190:193], v[232:235], v[92:95]
	v_mfma_f32_16x16x32_bf16 v[88:91], v[190:193], v[240:243], v[88:91]
	v_mfma_f32_16x16x32_bf16 v[84:87], v[208:211], v[232:235], v[84:87]
	v_mfma_f32_16x16x32_bf16 v[80:83], v[208:211], v[240:243], v[80:83]
	v_mfma_f32_16x16x32_bf16 v[76:79], v[216:219], v[232:235], v[76:79]
	v_mfma_f32_16x16x32_bf16 v[72:75], v[216:219], v[240:243], v[72:75]
	v_mfma_f32_16x16x32_bf16 v[68:71], v[224:227], v[232:235], v[68:71]
	v_mfma_f32_16x16x32_bf16 v[64:67], v[224:227], v[240:243], v[64:67]
	v_mfma_f32_16x16x32_bf16 v[92:95], v[196:199], v[236:239], v[92:95]
	v_mfma_f32_16x16x32_bf16 v[88:91], v[196:199], v[244:247], v[88:91]
	v_mfma_f32_16x16x32_bf16 v[84:87], v[212:215], v[236:239], v[84:87]
	v_mfma_f32_16x16x32_bf16 v[80:83], v[212:215], v[244:247], v[80:83]
	v_mfma_f32_16x16x32_bf16 v[76:79], v[220:223], v[236:239], v[76:79]
	v_mfma_f32_16x16x32_bf16 v[72:75], v[220:223], v[244:247], v[72:75]
	v_mfma_f32_16x16x32_bf16 v[68:71], v[228:231], v[236:239], v[68:71]
	v_mfma_f32_16x16x32_bf16 v[64:67], v[228:231], v[244:247], v[64:67]
	v_add_u32_e32 v200, vcc_lo, v140
	s_add_i32 m0, s100, 0x8000
	s_barrier
	ds_read_b128 v[190:193], v147 offset:49152
	ds_read_b128 v[196:199], v147 offset:50176
	ds_read_b128 v[208:211], v146 offset:49152
	ds_read_b128 v[212:215], v146 offset:50176
	ds_read_b128 v[216:219], v145 offset:49152
	ds_read_b128 v[220:223], v145 offset:50176
	ds_read_b128 v[224:227], v144 offset:49152
	ds_read_b128 v[228:231], v144 offset:50176
	global_load_lds_dwordx4 v200, s[86:87]
	v_add_u32_e32 v200, vcc_lo, v138
	s_add_i32 m0, s100, 0xa000
	s_nop 0
	global_load_lds_dwordx4 v200, s[86:87]
	s_barrier
; #define P8_STAGE(P,BASE,br,kt) do{const bfr* _ub=(BASE)+((long)(br)*K+(long)(kt)*BK); \
;     __builtin_amdgcn_global_load_lds((const unsigned*)(_ub+so0),(unsigned*)((char*)(P)+wid*1024),16,0,0); \
;     __builtin_amdgcn_global_load_lds((const unsigned*)(_ub+so1),(unsigned*)((char*)(P)+wid*1024+8192),16,0,0);}while(0)
; #define P8_LDA(dst,b,h) _Pragma("unroll") for(int m=0;m<4;++m) _Pragma("unroll") for(int k=0;k<2;++k) \
;     dst[m][k]=*reinterpret_cast<const bf16x8*>((char*)P8_SA(b,h)+lds_byte(wr*64+m*16+fr,k*32+fq*8))
; #define P8_LDB(dst,b,h) _Pragma("unroll") for(int n=0;n<2;++n) _Pragma("unroll") for(int k=0;k<2;++k) \
;     dst[n][k]=*reinterpret_cast<const bf16x8*>((char*)P8_SB(b,h)+lds_byte(wc*32+n*16+fr,k*32+fq*8))
; #define P8_MMA(ai,bj,At,Bt) do{__builtin_amdgcn_s_setprio(1); \
;     _Pragma("unroll") for(int m=0;m<4;++m) _Pragma("unroll") for(int n=0;n<2;++n) _Pragma("unroll") for(int k=0;k<2;++k) \
;       acc[ai][bj][m][n]=__builtin_amdgcn_mfma_f32_16x16x32_bf16(At[m][k],Bt[n][k],acc[ai][bj][m][n],0,0,0); \
;     __builtin_amdgcn_s_setprio(0);}while(0)
; #define P8_WAIT_V(n) asm volatile("s_waitcnt vmcnt(" #n ")":::"memory")
; #define P8_WAIT_L(n) asm volatile("s_waitcnt lgkmcnt(" #n ")":::"memory")
; #define P8_BAR __builtin_amdgcn_s_barrier()
; #define P8_SCHED __builtin_amdgcn_sched_barrier(0)
; template <class EPI>
; DEVI void gemm8_tile(const bfr* __restrict__ A, const bfr* __restrict__ Bt, int K, int brow, int bcol, int nbrow, int nbcol, char* shmc, EPI epi) {
;     ...
;     P8_LDA(At,1,1); P8_STAGE(P8_SA(1,0),A,brow,t+3);
;     P8_BAR; P8_WAIT_L(0); P8_MMA(1,0,At,B0); P8_BAR; P8_SCHED;
;     P8_STAGE(P8_SB(1,1),Bt,bcol+128,t+3);
;     P8_WAIT_V(6); P8_BAR; P8_MMA(1,1,At,B1); P8_BAR;
;   }
;   { P8_LDB(B0,0,0); P8_LDA(At,0,0); P8_STAGE(P8_SA(1,1),A,brow+128,nt-1);
;     P8_BAR; P8_WAIT_L(0); P8_MMA(0,0,At,B0); P8_BAR;
;     P8_LDB(B1,0,1); P8_BAR; P8_WAIT_L(0); P8_MMA(0,1,At,B1); P8_BAR;
	s_waitcnt lgkmcnt(0)
	v_mfma_f32_16x16x32_bf16 v[60:63], v[190:193], v[174:177], v[60:63]
	v_mfma_f32_16x16x32_bf16 v[56:59], v[190:193], v[182:185], v[56:59]
	v_mfma_f32_16x16x32_bf16 v[52:55], v[208:211], v[174:177], v[52:55]
	v_mfma_f32_16x16x32_bf16 v[48:51], v[208:211], v[182:185], v[48:51]
	v_mfma_f32_16x16x32_bf16 v[44:47], v[216:219], v[174:177], v[44:47]
	v_mfma_f32_16x16x32_bf16 v[40:43], v[216:219], v[182:185], v[40:43]
	v_mfma_f32_16x16x32_bf16 v[36:39], v[224:227], v[174:177], v[36:39]
	v_mfma_f32_16x16x32_bf16 v[32:35], v[224:227], v[182:185], v[32:35]
	v_mfma_f32_16x16x32_bf16 v[60:63], v[196:199], v[178:181], v[60:63]
	v_mfma_f32_16x16x32_bf16 v[56:59], v[196:199], v[186:189], v[56:59]
	v_mfma_f32_16x16x32_bf16 v[52:55], v[212:215], v[178:181], v[52:55]
	v_mfma_f32_16x16x32_bf16 v[48:51], v[212:215], v[186:189], v[48:51]
	v_mfma_f32_16x16x32_bf16 v[44:47], v[220:223], v[178:181], v[44:47]
	v_mfma_f32_16x16x32_bf16 v[40:43], v[220:223], v[186:189], v[40:43]
	v_mfma_f32_16x16x32_bf16 v[36:39], v[228:231], v[178:181], v[36:39]
	v_mfma_f32_16x16x32_bf16 v[32:35], v[228:231], v[186:189], v[32:35]
	s_barrier
	v_add_u32_e32 v174, s28, v136
	s_add_i32 m0, s100, 0x1c000
	s_nop 0
	global_load_lds_dwordx4 v174, s[86:87]
	v_add_u32_e32 v174, s28, v134
	s_add_i32 m0, s100, 0x1e000
	s_nop 0
	global_load_lds_dwordx4 v174, s[86:87]
	s_waitcnt vmcnt(6)
	s_barrier
	v_mfma_f32_16x16x32_bf16 v[28:31], v[190:193], v[232:235], v[28:31]
	v_mfma_f32_16x16x32_bf16 v[24:27], v[190:193], v[240:243], v[24:27]
	v_mfma_f32_16x16x32_bf16 v[20:23], v[208:211], v[232:235], v[20:23]
	v_mfma_f32_16x16x32_bf16 v[16:19], v[208:211], v[240:243], v[16:19]
	v_mfma_f32_16x16x32_bf16 v[12:15], v[216:219], v[232:235], v[12:15]
	v_mfma_f32_16x16x32_bf16 v[8:11], v[216:219], v[240:243], v[8:11]
	v_mfma_f32_16x16x32_bf16 v[4:7], v[224:227], v[232:235], v[4:7]
	v_mfma_f32_16x16x32_bf16 v[0:3], v[224:227], v[240:243], v[0:3]
	v_mfma_f32_16x16x32_bf16 v[28:31], v[196:199], v[236:239], v[28:31]
	v_mfma_f32_16x16x32_bf16 v[24:27], v[196:199], v[244:247], v[24:27]
	v_mfma_f32_16x16x32_bf16 v[20:23], v[212:215], v[236:239], v[20:23]
	v_mfma_f32_16x16x32_bf16 v[16:19], v[212:215], v[244:247], v[16:19]
	v_mfma_f32_16x16x32_bf16 v[12:15], v[220:223], v[236:239], v[12:15]
	v_mfma_f32_16x16x32_bf16 v[8:11], v[220:223], v[244:247], v[8:11]
	v_mfma_f32_16x16x32_bf16 v[4:7], v[228:231], v[236:239], v[4:7]
	v_mfma_f32_16x16x32_bf16 v[0:3], v[228:231], v[244:247], v[0:3]
	s_add_i32 s0, s0, 2
	v_lshl_add_u64 v[134:135], v[134:135], 0, s[80:81]
	v_lshl_add_u64 v[136:137], v[136:137], 0, s[80:81]
	v_lshl_add_u64 v[138:139], v[138:139], 0, s[80:81]
	s_cmpk_lt_u32 s0, 0x7c
	v_lshl_add_u64 v[140:141], v[140:141], 0, s[80:81]
	s_barrier
	s_cbranch_scc1 .LBB0_382
	s_or_b32 s0, s10, 0x80
	s_ashr_i32 s1, s0, 31
	s_lshl_b64 s[0:1], s[0:1], 14
	s_add_u32 s0, s31, s0
	s_addc_u32 s1, s64, s1
	s_add_u32 s0, s0, 0x3f80
	s_addc_u32 s1, s1, 0
	ds_read_b128 v[134:137], v157
	ds_read_b128 v[138:141], v157 offset:1024
	ds_read_b128 v[150:153], v157 offset:2048
	ds_read_b128 v[174:177], v157 offset:3072
	ds_read_b128 v[178:181], v147
	ds_read_b128 v[182:185], v147 offset:1024
	ds_read_b128 v[186:189], v146
	ds_read_b128 v[190:193], v146 offset:1024
	ds_read_b128 v[196:199], v145
	ds_read_b128 v[208:211], v145 offset:1024
	ds_read_b128 v[212:215], v144
	ds_read_b128 v[216:219], v144 offset:1024
	v_lshl_add_u64 v[156:157], v[166:167], 1, s[0:1]
	s_add_i32 m0, s100, 0xc000
	v_lshl_add_u64 v[132:133], v[132:133], 1, s[0:1]
	global_load_lds_dwordx4 v[156:157], off
	s_add_i32 m0, s100, 0xe000
	s_nop 0
	global_load_lds_dwordx4 v[132:133], off
	s_barrier
	s_waitcnt lgkmcnt(0)
	s_setprio 1
	s_waitcnt lgkmcnt(0)
	v_mfma_f32_16x16x32_bf16 v[124:127], v[178:181], v[134:137], v[124:127]
	v_mfma_f32_16x16x32_bf16 v[116:119], v[186:189], v[134:137], v[116:119]
	v_mfma_f32_16x16x32_bf16 v[112:115], v[186:189], v[150:153], v[112:115]
	v_mfma_f32_16x16x32_bf16 v[96:99], v[212:215], v[150:153], v[96:99]
	v_mfma_f32_16x16x32_bf16 v[124:127], v[182:185], v[138:141], v[124:127]
	v_mfma_f32_16x16x32_bf16 v[120:123], v[178:181], v[150:153], v[120:123]
	v_mfma_f32_16x16x32_bf16 v[116:119], v[190:193], v[138:141], v[116:119]
	v_mfma_f32_16x16x32_bf16 v[112:115], v[190:193], v[174:177], v[112:115]
	v_mfma_f32_16x16x32_bf16 v[108:111], v[196:199], v[134:137], v[108:111]
	v_mfma_f32_16x16x32_bf16 v[104:107], v[196:199], v[150:153], v[104:107]
	v_mfma_f32_16x16x32_bf16 v[100:103], v[212:215], v[134:137], v[100:103]
	v_mfma_f32_16x16x32_bf16 v[96:99], v[216:219], v[174:177], v[96:99]
	v_mfma_f32_16x16x32_bf16 v[220:223], v[182:185], v[174:177], v[120:123]
	v_mfma_f32_16x16x32_bf16 v[224:227], v[208:211], v[138:141], v[108:111]
	v_mfma_f32_16x16x32_bf16 v[228:231], v[208:211], v[174:177], v[104:107]
	v_mfma_f32_16x16x32_bf16 v[232:235], v[216:219], v[138:141], v[100:103]
	s_setprio 0
	s_barrier
	s_nop 0
	ds_read_b128 v[100:103], v154
	ds_read_b128 v[104:107], v154 offset:1024
	ds_read_b128 v[108:111], v154 offset:2048
	ds_read_b128 v[120:123], v154 offset:3072
	s_barrier
; #define P8_LDA(dst,b,h) _Pragma("unroll") for(int m=0;m<4;++m) _Pragma("unroll") for(int k=0;k<2;++k) \
;     dst[m][k]=*reinterpret_cast<const bf16x8*>((char*)P8_SA(b,h)+lds_byte(wr*64+m*16+fr,k*32+fq*8))
; #define P8_LDB(dst,b,h) _Pragma("unroll") for(int n=0;n<2;++n) _Pragma("unroll") for(int k=0;k<2;++k) \
;     dst[n][k]=*reinterpret_cast<const bf16x8*>((char*)P8_SB(b,h)+lds_byte(wc*32+n*16+fr,k*32+fq*8))
; #define P8_MMA(ai,bj,At,Bt) do{__builtin_amdgcn_s_setprio(1); \
;     _Pragma("unroll") for(int m=0;m<4;++m) _Pragma("unroll") for(int n=0;n<2;++n) _Pragma("unroll") for(int k=0;k<2;++k) \
;       acc[ai][bj][m][n]=__builtin_amdgcn_mfma_f32_16x16x32_bf16(At[m][k],Bt[n][k],acc[ai][bj][m][n],0,0,0); \
;     __builtin_amdgcn_s_setprio(0);}while(0)
; #define P8_WAIT_V(n) asm volatile("s_waitcnt vmcnt(" #n ")":::"memory")
; #define P8_WAIT_L(n) asm volatile("s_waitcnt lgkmcnt(" #n ")":::"memory")
; #define P8_BAR __builtin_amdgcn_s_barrier()
; template <class EPI>
; DEVI void gemm8_tile(const bfr* __restrict__ A, const bfr* __restrict__ Bt, int K, int brow, int bcol, int nbrow, int nbcol, char* shmc, EPI epi) {
;     ...
;     P8_LDB(B1,0,1); P8_BAR; P8_WAIT_L(0); P8_MMA(0,1,At,B1); P8_BAR;
;     P8_LDA(At,0,1); P8_WAIT_V(4); P8_BAR; P8_WAIT_L(0); P8_MMA(1,0,At,B0); P8_MMA(1,1,At,B1); P8_BAR; }
;   { P8_LDB(B0,1,0); P8_LDA(At,1,0); P8_WAIT_V(2); P8_BAR; P8_WAIT_L(0); P8_MMA(0,0,At,B0); P8_BAR;
	s_waitcnt lgkmcnt(0)
	s_setprio 1
	s_waitcnt lgkmcnt(0)
	v_mfma_f32_16x16x32_bf16 v[92:95], v[178:181], v[100:103], v[92:95]
	v_mfma_f32_16x16x32_bf16 v[84:87], v[186:189], v[100:103], v[84:87]
	v_mfma_f32_16x16x32_bf16 v[80:83], v[186:189], v[108:111], v[80:83]
	v_mfma_f32_16x16x32_bf16 v[64:67], v[212:215], v[108:111], v[64:67]
	v_mfma_f32_16x16x32_bf16 v[92:95], v[182:185], v[104:107], v[92:95]
	v_mfma_f32_16x16x32_bf16 v[88:91], v[178:181], v[108:111], v[88:91]
	v_mfma_f32_16x16x32_bf16 v[84:87], v[190:193], v[104:107], v[84:87]
	v_mfma_f32_16x16x32_bf16 v[80:83], v[190:193], v[120:123], v[80:83]
	v_mfma_f32_16x16x32_bf16 v[76:79], v[196:199], v[100:103], v[76:79]
	v_mfma_f32_16x16x32_bf16 v[72:75], v[196:199], v[108:111], v[72:75]
	v_mfma_f32_16x16x32_bf16 v[68:71], v[212:215], v[100:103], v[68:71]
	v_mfma_f32_16x16x32_bf16 v[64:67], v[216:219], v[120:123], v[64:67]
	v_mfma_f32_16x16x32_bf16 v[154:157], v[182:185], v[120:123], v[88:91]
	v_mfma_f32_16x16x32_bf16 v[178:181], v[208:211], v[104:107], v[76:79]
	v_mfma_f32_16x16x32_bf16 v[182:185], v[208:211], v[120:123], v[72:75]
	v_mfma_f32_16x16x32_bf16 v[186:189], v[216:219], v[104:107], v[68:71]
	s_setprio 0
	s_barrier
	s_nop 0
	ds_read_b128 v[68:71], v147 offset:16384
	ds_read_b128 v[72:75], v147 offset:17408
	ds_read_b128 v[76:79], v146 offset:16384
	ds_read_b128 v[88:91], v146 offset:17408
	ds_read_b128 v[190:193], v145 offset:16384
	ds_read_b128 v[196:199], v145 offset:17408
	ds_read_b128 v[208:211], v144 offset:16384
	ds_read_b128 v[212:215], v144 offset:17408
	s_waitcnt vmcnt(4)
	s_barrier
	s_waitcnt lgkmcnt(0)
	s_setprio 1
	s_waitcnt lgkmcnt(0)
	v_mfma_f32_16x16x32_bf16 v[60:63], v[68:71], v[134:137], v[60:63]
	v_mfma_f32_16x16x32_bf16 v[52:55], v[76:79], v[134:137], v[52:55]
	v_mfma_f32_16x16x32_bf16 v[48:51], v[76:79], v[150:153], v[48:51]
	v_mfma_f32_16x16x32_bf16 v[32:35], v[208:211], v[150:153], v[32:35]
	v_mfma_f32_16x16x32_bf16 v[60:63], v[72:75], v[138:141], v[60:63]
	v_mfma_f32_16x16x32_bf16 v[56:59], v[68:71], v[150:153], v[56:59]
	v_mfma_f32_16x16x32_bf16 v[52:55], v[88:91], v[138:141], v[52:55]
	v_mfma_f32_16x16x32_bf16 v[48:51], v[88:91], v[174:177], v[48:51]
	v_mfma_f32_16x16x32_bf16 v[44:47], v[190:193], v[134:137], v[44:47]
	v_mfma_f32_16x16x32_bf16 v[40:43], v[190:193], v[150:153], v[40:43]
	v_mfma_f32_16x16x32_bf16 v[36:39], v[208:211], v[134:137], v[36:39]
	v_mfma_f32_16x16x32_bf16 v[32:35], v[212:215], v[174:177], v[32:35]
	v_mfma_f32_16x16x32_bf16 v[216:219], v[72:75], v[174:177], v[56:59]
	v_mfma_f32_16x16x32_bf16 v[236:239], v[196:199], v[138:141], v[44:47]
	v_mfma_f32_16x16x32_bf16 v[240:243], v[196:199], v[174:177], v[40:43]
	v_mfma_f32_16x16x32_bf16 v[132:135], v[212:215], v[138:141], v[36:39]
	s_setprio 0
	s_setprio 1
	v_mfma_f32_16x16x32_bf16 v[28:31], v[68:71], v[100:103], v[28:31]
	v_mfma_f32_16x16x32_bf16 v[20:23], v[76:79], v[100:103], v[20:23]
	v_mfma_f32_16x16x32_bf16 v[16:19], v[76:79], v[108:111], v[16:19]
	v_mfma_f32_16x16x32_bf16 v[0:3], v[208:211], v[108:111], v[0:3]
	v_mfma_f32_16x16x32_bf16 v[28:31], v[72:75], v[104:107], v[28:31]
	v_mfma_f32_16x16x32_bf16 v[24:27], v[68:71], v[108:111], v[24:27]
	v_mfma_f32_16x16x32_bf16 v[20:23], v[88:91], v[104:107], v[20:23]
	v_mfma_f32_16x16x32_bf16 v[16:19], v[88:91], v[120:123], v[16:19]
	v_mfma_f32_16x16x32_bf16 v[12:15], v[190:193], v[100:103], v[12:15]
	v_mfma_f32_16x16x32_bf16 v[8:11], v[190:193], v[108:111], v[8:11]
	v_mfma_f32_16x16x32_bf16 v[4:7], v[208:211], v[100:103], v[4:7]
	v_mfma_f32_16x16x32_bf16 v[0:3], v[212:215], v[120:123], v[0:3]
	v_mfma_f32_16x16x32_bf16 v[136:139], v[72:75], v[120:123], v[24:27]
	v_mfma_f32_16x16x32_bf16 v[150:153], v[196:199], v[104:107], v[12:15]
	v_mfma_f32_16x16x32_bf16 v[172:175], v[196:199], v[120:123], v[8:11]
	v_mfma_f32_16x16x32_bf16 v[190:193], v[212:215], v[104:107], v[4:7]
	s_setprio 0
	s_barrier
	s_nop 0
	ds_read_b128 v[4:7], v149
	ds_read_b128 v[8:11], v149 offset:1024
	ds_read_b128 v[12:15], v149 offset:2048
	ds_read_b128 v[24:27], v149 offset:3072
	ds_read_b128 v[36:39], v147 offset:32768
	ds_read_b128 v[40:43], v147 offset:33792
	ds_read_b128 v[44:47], v146 offset:32768
	ds_read_b128 v[56:59], v146 offset:33792
	ds_read_b128 v[68:71], v145 offset:32768
	ds_read_b128 v[196:199], v145 offset:33792
	ds_read_b128 v[208:211], v144 offset:32768
	ds_read_b128 v[212:215], v144 offset:33792
	s_waitcnt vmcnt(2)
	s_barrier
; #define P8_LDA(dst,b,h) _Pragma("unroll") for(int m=0;m<4;++m) _Pragma("unroll") for(int k=0;k<2;++k) \
;     dst[m][k]=*reinterpret_cast<const bf16x8*>((char*)P8_SA(b,h)+lds_byte(wr*64+m*16+fr,k*32+fq*8))
; #define P8_LDB(dst,b,h) _Pragma("unroll") for(int n=0;n<2;++n) _Pragma("unroll") for(int k=0;k<2;++k) \
;     dst[n][k]=*reinterpret_cast<const bf16x8*>((char*)P8_SB(b,h)+lds_byte(wc*32+n*16+fr,k*32+fq*8))
; #define P8_MMA(ai,bj,At,Bt) do{__builtin_amdgcn_s_setprio(1); \
;     _Pragma("unroll") for(int m=0;m<4;++m) _Pragma("unroll") for(int n=0;n<2;++n) _Pragma("unroll") for(int k=0;k<2;++k) \
;       acc[ai][bj][m][n]=__builtin_amdgcn_mfma_f32_16x16x32_bf16(At[m][k],Bt[n][k],acc[ai][bj][m][n],0,0,0); \
;     __builtin_amdgcn_s_setprio(0);}while(0)
; #define P8_WAIT_V(n) asm volatile("s_waitcnt vmcnt(" #n ")":::"memory")
; #define P8_WAIT_L(n) asm volatile("s_waitcnt lgkmcnt(" #n ")":::"memory")
; #define P8_BAR __builtin_amdgcn_s_barrier()
; template <class EPI>
; DEVI void gemm8_tile(const bfr* __restrict__ A, const bfr* __restrict__ Bt, int K, int brow, int bcol, int nbrow, int nbcol, char* shmc, EPI epi) {
;     ...
;   { P8_LDB(B0,1,0); P8_LDA(At,1,0); P8_WAIT_V(2); P8_BAR; P8_WAIT_L(0); P8_MMA(0,0,At,B0); P8_BAR;
;     P8_LDB(B1,1,1); P8_WAIT_V(0); P8_BAR; P8_WAIT_L(0); P8_MMA(0,1,At,B1); P8_BAR;
;     P8_LDA(At,1,1); P8_BAR; P8_WAIT_L(0); P8_MMA(1,0,At,B0); P8_MMA(1,1,At,B1); P8_BAR; }
;   if(wr==0)P8_BAR;
	s_waitcnt lgkmcnt(0)
	s_setprio 1
	s_waitcnt lgkmcnt(0)
	v_mfma_f32_16x16x32_bf16 v[72:75], v[36:39], v[4:7], v[124:127]
	v_mfma_f32_16x16x32_bf16 v[120:123], v[40:43], v[8:11], v[72:75]
	v_mfma_f32_16x16x32_bf16 v[72:75], v[36:39], v[12:15], v[220:223]
	v_mfma_f32_16x16x32_bf16 v[104:107], v[40:43], v[24:27], v[72:75]
	v_mfma_f32_16x16x32_bf16 v[72:75], v[44:47], v[4:7], v[116:119]
	v_mfma_f32_16x16x32_bf16 v[124:127], v[56:59], v[8:11], v[72:75]
	v_mfma_f32_16x16x32_bf16 v[72:75], v[44:47], v[12:15], v[112:115]
	v_mfma_f32_16x16x32_bf16 v[108:111], v[56:59], v[24:27], v[72:75]
	v_mfma_f32_16x16x32_bf16 v[72:75], v[68:71], v[4:7], v[224:227]
	v_mfma_f32_16x16x32_bf16 v[112:115], v[196:199], v[8:11], v[72:75]
	v_mfma_f32_16x16x32_bf16 v[72:75], v[68:71], v[12:15], v[228:231]
	v_mfma_f32_16x16x32_bf16 v[100:103], v[196:199], v[24:27], v[72:75]
	v_mfma_f32_16x16x32_bf16 v[72:75], v[208:211], v[4:7], v[232:235]
	v_mfma_f32_16x16x32_bf16 v[116:119], v[212:215], v[8:11], v[72:75]
	v_mfma_f32_16x16x32_bf16 v[72:75], v[208:211], v[12:15], v[96:99]
	v_mfma_f32_16x16x32_bf16 v[96:99], v[212:215], v[24:27], v[72:75]
	s_setprio 0
	s_barrier
	ds_read_b128 v[220:223], v148
	ds_read_b128 v[224:227], v148 offset:1024
	ds_read_b128 v[228:231], v148 offset:2048
	ds_read_b128 v[232:235], v148 offset:3072
	s_waitcnt vmcnt(0)
	s_barrier
	s_waitcnt lgkmcnt(0)
	s_setprio 1
	s_waitcnt lgkmcnt(0)
	v_mfma_f32_16x16x32_bf16 v[72:75], v[36:39], v[220:223], v[92:95]
	v_mfma_f32_16x16x32_bf16 v[36:39], v[36:39], v[228:231], v[154:157]
	v_mfma_f32_16x16x32_bf16 v[88:91], v[40:43], v[224:227], v[72:75]
	v_mfma_f32_16x16x32_bf16 v[72:75], v[40:43], v[232:235], v[36:39]
	v_mfma_f32_16x16x32_bf16 v[36:39], v[44:47], v[220:223], v[84:87]
	v_mfma_f32_16x16x32_bf16 v[92:95], v[56:59], v[224:227], v[36:39]
	v_mfma_f32_16x16x32_bf16 v[36:39], v[44:47], v[228:231], v[80:83]
	v_mfma_f32_16x16x32_bf16 v[76:79], v[56:59], v[232:235], v[36:39]
	v_mfma_f32_16x16x32_bf16 v[36:39], v[68:71], v[220:223], v[178:181]
	v_mfma_f32_16x16x32_bf16 v[80:83], v[196:199], v[224:227], v[36:39]
	v_mfma_f32_16x16x32_bf16 v[36:39], v[68:71], v[228:231], v[182:185]
	v_mfma_f32_16x16x32_bf16 v[68:71], v[196:199], v[232:235], v[36:39]
	v_mfma_f32_16x16x32_bf16 v[36:39], v[208:211], v[220:223], v[186:189]
	v_mfma_f32_16x16x32_bf16 v[84:87], v[212:215], v[224:227], v[36:39]
	v_mfma_f32_16x16x32_bf16 v[36:39], v[208:211], v[228:231], v[64:67]
	v_mfma_f32_16x16x32_bf16 v[64:67], v[212:215], v[232:235], v[36:39]
	s_setprio 0
	s_barrier
	ds_read_b128 v[154:157], v147 offset:49152
	ds_read_b128 v[176:179], v147 offset:50176
	ds_read_b128 v[180:183], v146 offset:49152
	ds_read_b128 v[146:149], v146 offset:50176
	ds_read_b128 v[184:187], v145 offset:49152
	ds_read_b128 v[196:199], v145 offset:50176
	ds_read_b128 v[208:211], v144 offset:49152
	ds_read_b128 v[212:215], v144 offset:50176
	s_barrier
	s_waitcnt lgkmcnt(0)
	s_setprio 1
	s_waitcnt lgkmcnt(0)
	v_mfma_f32_16x16x32_bf16 v[36:39], v[154:157], v[4:7], v[60:63]
	v_mfma_f32_16x16x32_bf16 v[56:59], v[176:179], v[8:11], v[36:39]
	v_mfma_f32_16x16x32_bf16 v[36:39], v[154:157], v[12:15], v[216:219]
	v_mfma_f32_16x16x32_bf16 v[40:43], v[176:179], v[24:27], v[36:39]
	v_mfma_f32_16x16x32_bf16 v[36:39], v[180:183], v[4:7], v[52:55]
	v_mfma_f32_16x16x32_bf16 v[60:63], v[146:149], v[8:11], v[36:39]
	v_mfma_f32_16x16x32_bf16 v[36:39], v[180:183], v[12:15], v[48:51]
	v_mfma_f32_16x16x32_bf16 v[44:47], v[146:149], v[24:27], v[36:39]
	v_mfma_f32_16x16x32_bf16 v[36:39], v[184:187], v[4:7], v[236:239]
	v_mfma_f32_16x16x32_bf16 v[4:7], v[208:211], v[4:7], v[132:135]
	v_mfma_f32_16x16x32_bf16 v[48:51], v[196:199], v[8:11], v[36:39]
	v_mfma_f32_16x16x32_bf16 v[36:39], v[184:187], v[12:15], v[240:243]
	v_mfma_f32_16x16x32_bf16 v[52:55], v[212:215], v[8:11], v[4:7]
	v_mfma_f32_16x16x32_bf16 v[4:7], v[208:211], v[12:15], v[32:35]
	v_mfma_f32_16x16x32_bf16 v[36:39], v[196:199], v[24:27], v[36:39]
	v_mfma_f32_16x16x32_bf16 v[32:35], v[212:215], v[24:27], v[4:7]
	s_setprio 0
	s_setprio 1
	v_mfma_f32_16x16x32_bf16 v[4:7], v[154:157], v[220:223], v[28:31]
	v_mfma_f32_16x16x32_bf16 v[24:27], v[176:179], v[224:227], v[4:7]
	v_mfma_f32_16x16x32_bf16 v[4:7], v[154:157], v[228:231], v[136:139]
	v_mfma_f32_16x16x32_bf16 v[8:11], v[176:179], v[232:235], v[4:7]
	v_mfma_f32_16x16x32_bf16 v[4:7], v[180:183], v[220:223], v[20:23]
	v_mfma_f32_16x16x32_bf16 v[28:31], v[146:149], v[224:227], v[4:7]
	v_mfma_f32_16x16x32_bf16 v[4:7], v[180:183], v[228:231], v[16:19]
	v_mfma_f32_16x16x32_bf16 v[12:15], v[146:149], v[232:235], v[4:7]
	v_mfma_f32_16x16x32_bf16 v[4:7], v[184:187], v[220:223], v[150:153]
	v_mfma_f32_16x16x32_bf16 v[16:19], v[196:199], v[224:227], v[4:7]
	v_mfma_f32_16x16x32_bf16 v[4:7], v[184:187], v[228:231], v[172:175]
	v_mfma_f32_16x16x32_bf16 v[20:23], v[208:211], v[220:223], v[190:193]
	v_mfma_f32_16x16x32_bf16 v[0:3], v[208:211], v[228:231], v[0:3]
	v_mfma_f32_16x16x32_bf16 v[4:7], v[196:199], v[232:235], v[4:7]
	v_mfma_f32_16x16x32_bf16 v[20:23], v[212:215], v[224:227], v[20:23]
	v_mfma_f32_16x16x32_bf16 v[0:3], v[212:215], v[232:235], v[0:3]
	s_setprio 0
	v_cmp_gt_u32_e32 vcc, s57, v142
	s_barrier
	s_and_saveexec_b64 s[0:1], vcc
	s_cbranch_execz .LBB0_385
	s_barrier

; #define P8_STAGE(P,BASE,br,kt) do{const bfr* _ub=(BASE)+((long)(br)*K+(long)(kt)*BK); \
;     __builtin_amdgcn_global_load_lds((const unsigned*)(_ub+so0),(unsigned*)((char*)(P)+wid*1024),16,0,0); \
;     __builtin_amdgcn_global_load_lds((const unsigned*)(_ub+so1),(unsigned*)((char*)(P)+wid*1024+8192),16,0,0);}while(0)
; #define P8_LDA(dst,b,h) _Pragma("unroll") for(int m=0;m<4;++m) _Pragma("unroll") for(int k=0;k<2;++k) \
;     dst[m][k]=*reinterpret_cast<const bf16x8*>((char*)P8_SA(b,h)+lds_byte(wr*64+m*16+fr,k*32+fq*8))
; #define P8_LDB(dst,b,h) _Pragma("unroll") for(int n=0;n<2;++n) _Pragma("unroll") for(int k=0;k<2;++k) \
;     dst[n][k]=*reinterpret_cast<const bf16x8*>((char*)P8_SB(b,h)+lds_byte(wc*32+n*16+fr,k*32+fq*8))
; #define P8_MMA(ai,bj,At,Bt) do{__builtin_amdgcn_s_setprio(1); \
;     _Pragma("unroll") for(int m=0;m<4;++m) _Pragma("unroll") for(int n=0;n<2;++n) _Pragma("unroll") for(int k=0;k<2;++k) \
;       acc[ai][bj][m][n]=__builtin_amdgcn_mfma_f32_16x16x32_bf16(At[m][k],Bt[n][k],acc[ai][bj][m][n],0,0,0); \
;     __builtin_amdgcn_s_setprio(0);}while(0)
; #define P8_WAIT_V(n) asm volatile("s_waitcnt vmcnt(" #n ")":::"memory")
; #define P8_WAIT_L(n) asm volatile("s_waitcnt lgkmcnt(" #n ")":::"memory")
; #define P8_BAR __builtin_amdgcn_s_barrier()
; #define P8_SCHED __builtin_amdgcn_sched_barrier(0)
; template <class EPI>
; DEVI void gemm8_tile(const bfr* __restrict__ A, const bfr* __restrict__ Bt, int K, int brow, int bcol, int nbrow, int nbcol, char* shmc, EPI epi) {
;     ...
;     P8_LDB(B0,0,0); P8_SCHED; P8_LDA(At,0,0); P8_STAGE(P8_SA(1,1),A,brow+128,t+1);
;     P8_WAIT_L(8); P8_BAR; P8_WAIT_L(0); P8_MMA(0,0,At,B0); P8_BAR; P8_SCHED;
;     P8_LDB(B1,0,1); P8_STAGE(P8_SB(0,0),Bt,bcol,t+2);
;     P8_BAR; P8_WAIT_L(0); P8_MMA(0,1,At,B1); P8_BAR;
;     P8_LDA(At,0,1); P8_STAGE(P8_SA(0,0),A,brow,t+2);
;     P8_BAR; P8_WAIT_L(0); P8_MMA(1,0,At,B0); P8_BAR; P8_SCHED;
;     P8_STAGE(P8_SB(0,1),Bt,bcol+128,t+2);
;     P8_WAIT_V(6); P8_BAR; P8_MMA(1,1,At,B1); P8_BAR;
.LBB0_401:
	ds_read_b128 v[174:177], v157
	ds_read_b128 v[178:181], v157 offset:1024
	ds_read_b128 v[182:185], v157 offset:2048
	ds_read_b128 v[186:189], v157 offset:3072
	v_add_u32_e32 v171, 0xc000, v143
	v_add_u32_e32 v172, 0xe000, v143
	v_add_u32_e32 v158, s54, v136
	s_add_i32 m0, s100, 0xc000
	ds_read_b128 v[160:163], v147
	ds_read_b128 v[190:193], v147 offset:1024
	ds_read_b128 v[196:199], v146
	ds_read_b128 v[208:211], v146 offset:1024
	ds_read_b128 v[212:215], v145
	ds_read_b128 v[216:219], v145 offset:1024
	ds_read_b128 v[220:223], v144
	ds_read_b128 v[224:227], v144 offset:1024
	global_load_lds_dwordx4 v158, s[86:87]
	v_add_u32_e32 v158, s54, v134
	s_add_i32 m0, s100, 0xe000
	s_nop 0
	global_load_lds_dwordx4 v158, s[86:87]
	s_waitcnt lgkmcnt(8)
	s_barrier
	s_waitcnt lgkmcnt(0)
	v_mfma_f32_16x16x32_bf16 v[124:127], v[160:163], v[174:177], v[124:127]
	v_mfma_f32_16x16x32_bf16 v[120:123], v[160:163], v[182:185], v[120:123]
	v_mfma_f32_16x16x32_bf16 v[116:119], v[196:199], v[174:177], v[116:119]
	v_mfma_f32_16x16x32_bf16 v[112:115], v[196:199], v[182:185], v[112:115]
	v_mfma_f32_16x16x32_bf16 v[108:111], v[212:215], v[174:177], v[108:111]
	v_mfma_f32_16x16x32_bf16 v[104:107], v[212:215], v[182:185], v[104:107]
	v_mfma_f32_16x16x32_bf16 v[100:103], v[220:223], v[174:177], v[100:103]
	v_mfma_f32_16x16x32_bf16 v[96:99], v[220:223], v[182:185], v[96:99]
	v_mfma_f32_16x16x32_bf16 v[124:127], v[190:193], v[178:181], v[124:127]
	v_mfma_f32_16x16x32_bf16 v[120:123], v[190:193], v[186:189], v[120:123]
	v_mfma_f32_16x16x32_bf16 v[116:119], v[208:211], v[178:181], v[116:119]
	v_mfma_f32_16x16x32_bf16 v[112:115], v[208:211], v[186:189], v[112:115]
	v_mfma_f32_16x16x32_bf16 v[108:111], v[216:219], v[178:181], v[108:111]
	v_mfma_f32_16x16x32_bf16 v[104:107], v[216:219], v[186:189], v[104:107]
	v_mfma_f32_16x16x32_bf16 v[100:103], v[224:227], v[178:181], v[100:103]
	v_mfma_f32_16x16x32_bf16 v[96:99], v[224:227], v[186:189], v[96:99]
	s_barrier
	v_add_u32_e32 v158, 0x10000, v143
	v_add_u32_e32 v206, s66, v140
	s_add_i32 m0, s100, 0x10000
	v_add_u32_e32 v159, 0x12000, v143
	ds_read_b128 v[228:231], v155
	ds_read_b128 v[232:235], v155 offset:1024
	ds_read_b128 v[236:239], v155 offset:2048
	ds_read_b128 v[240:243], v155 offset:3072
	global_load_lds_dwordx4 v206, s[86:87]
	v_add_u32_e32 v244, s66, v138
	s_add_i32 m0, s100, 0x12000
	s_nop 0
	global_load_lds_dwordx4 v244, s[86:87]
	s_barrier
	s_waitcnt lgkmcnt(0)
	v_mfma_f32_16x16x32_bf16 v[92:95], v[160:163], v[228:231], v[92:95]
	v_mfma_f32_16x16x32_bf16 v[88:91], v[160:163], v[236:239], v[88:91]
	v_mfma_f32_16x16x32_bf16 v[84:87], v[196:199], v[228:231], v[84:87]
	v_mfma_f32_16x16x32_bf16 v[80:83], v[196:199], v[236:239], v[80:83]
	v_mfma_f32_16x16x32_bf16 v[76:79], v[212:215], v[228:231], v[76:79]
	v_mfma_f32_16x16x32_bf16 v[72:75], v[212:215], v[236:239], v[72:75]
	v_mfma_f32_16x16x32_bf16 v[68:71], v[220:223], v[228:231], v[68:71]
	v_mfma_f32_16x16x32_bf16 v[64:67], v[220:223], v[236:239], v[64:67]
	v_mfma_f32_16x16x32_bf16 v[92:95], v[190:193], v[232:235], v[92:95]
	v_mfma_f32_16x16x32_bf16 v[88:91], v[190:193], v[240:243], v[88:91]
	v_mfma_f32_16x16x32_bf16 v[84:87], v[208:211], v[232:235], v[84:87]
	v_mfma_f32_16x16x32_bf16 v[80:83], v[208:211], v[240:243], v[80:83]
	v_mfma_f32_16x16x32_bf16 v[76:79], v[216:219], v[232:235], v[76:79]
	v_mfma_f32_16x16x32_bf16 v[72:75], v[216:219], v[240:243], v[72:75]
	v_mfma_f32_16x16x32_bf16 v[68:71], v[224:227], v[232:235], v[68:71]
	v_mfma_f32_16x16x32_bf16 v[64:67], v[224:227], v[240:243], v[64:67]
	v_add_u32_e32 v160, s60, v136
	s_mov_b32 m0, s100
	s_barrier
	ds_read_b128 v[190:193], v147 offset:16384
	ds_read_b128 v[196:199], v147 offset:17408
	ds_read_b128 v[208:211], v146 offset:16384
	ds_read_b128 v[212:215], v146 offset:17408
	ds_read_b128 v[216:219], v145 offset:16384
	ds_read_b128 v[220:223], v145 offset:17408
	ds_read_b128 v[224:227], v144 offset:16384
	ds_read_b128 v[244:247], v144 offset:17408
	global_load_lds_dwordx4 v160, s[86:87]
	v_add_u32_e32 v160, 0x2000, v143
	v_add_u32_e32 v162, s60, v134
	s_add_i32 m0, s100, 0x2000
	s_nop 0
	global_load_lds_dwordx4 v162, s[86:87]
	s_barrier
	s_waitcnt lgkmcnt(0)
	v_mfma_f32_16x16x32_bf16 v[60:63], v[190:193], v[174:177], v[60:63]
	v_mfma_f32_16x16x32_bf16 v[56:59], v[190:193], v[182:185], v[56:59]
	v_mfma_f32_16x16x32_bf16 v[52:55], v[208:211], v[174:177], v[52:55]
	v_mfma_f32_16x16x32_bf16 v[48:51], v[208:211], v[182:185], v[48:51]
	v_mfma_f32_16x16x32_bf16 v[44:47], v[216:219], v[174:177], v[44:47]
	v_mfma_f32_16x16x32_bf16 v[40:43], v[216:219], v[182:185], v[40:43]
	v_mfma_f32_16x16x32_bf16 v[36:39], v[224:227], v[174:177], v[36:39]
	v_mfma_f32_16x16x32_bf16 v[32:35], v[224:227], v[182:185], v[32:35]
	v_mfma_f32_16x16x32_bf16 v[60:63], v[196:199], v[178:181], v[60:63]
	v_mfma_f32_16x16x32_bf16 v[56:59], v[196:199], v[186:189], v[56:59]
	v_mfma_f32_16x16x32_bf16 v[52:55], v[212:215], v[178:181], v[52:55]
	v_mfma_f32_16x16x32_bf16 v[48:51], v[212:215], v[186:189], v[48:51]
	v_mfma_f32_16x16x32_bf16 v[44:47], v[220:223], v[178:181], v[44:47]
	v_mfma_f32_16x16x32_bf16 v[40:43], v[220:223], v[186:189], v[40:43]
	v_mfma_f32_16x16x32_bf16 v[36:39], v[244:247], v[178:181], v[36:39]
	v_mfma_f32_16x16x32_bf16 v[32:35], v[244:247], v[186:189], v[32:35]
	s_barrier
	v_add_u32_e32 v161, 0x14000, v143
	v_add_u32_e32 v162, s70, v140
	s_add_i32 m0, s100, 0x14000
	v_add_u32_e32 v174, s70, v138
	global_load_lds_dwordx4 v162, s[86:87]
	v_add_u32_e32 v162, 0x16000, v143
	s_nop 0
	s_add_i32 m0, s100, 0x16000
	s_nop 0
	global_load_lds_dwordx4 v174, s[86:87]
	s_waitcnt vmcnt(6)
	s_barrier
; #define P8_STAGE(P,BASE,br,kt) do{const bfr* _ub=(BASE)+((long)(br)*K+(long)(kt)*BK); \
;     __builtin_amdgcn_global_load_lds((const unsigned*)(_ub+so0),(unsigned*)((char*)(P)+wid*1024),16,0,0); \
;     __builtin_amdgcn_global_load_lds((const unsigned*)(_ub+so1),(unsigned*)((char*)(P)+wid*1024+8192),16,0,0);}while(0)
; #define P8_LDA(dst,b,h) _Pragma("unroll") for(int m=0;m<4;++m) _Pragma("unroll") for(int k=0;k<2;++k) \
;     dst[m][k]=*reinterpret_cast<const bf16x8*>((char*)P8_SA(b,h)+lds_byte(wr*64+m*16+fr,k*32+fq*8))
; #define P8_LDB(dst,b,h) _Pragma("unroll") for(int n=0;n<2;++n) _Pragma("unroll") for(int k=0;k<2;++k) \
;     dst[n][k]=*reinterpret_cast<const bf16x8*>((char*)P8_SB(b,h)+lds_byte(wc*32+n*16+fr,k*32+fq*8))
; #define P8_MMA(ai,bj,At,Bt) do{__builtin_amdgcn_s_setprio(1); \
;     _Pragma("unroll") for(int m=0;m<4;++m) _Pragma("unroll") for(int n=0;n<2;++n) _Pragma("unroll") for(int k=0;k<2;++k) \
;       acc[ai][bj][m][n]=__builtin_amdgcn_mfma_f32_16x16x32_bf16(At[m][k],Bt[n][k],acc[ai][bj][m][n],0,0,0); \
;     __builtin_amdgcn_s_setprio(0);}while(0)
; #define P8_WAIT_V(n) asm volatile("s_waitcnt vmcnt(" #n ")":::"memory")
; #define P8_WAIT_L(n) asm volatile("s_waitcnt lgkmcnt(" #n ")":::"memory")
; #define P8_BAR __builtin_amdgcn_s_barrier()
; #define P8_SCHED __builtin_amdgcn_sched_barrier(0)
; template <class EPI>
; DEVI void gemm8_tile(const bfr* __restrict__ A, const bfr* __restrict__ Bt, int K, int brow, int bcol, int nbrow, int nbcol, char* shmc, EPI epi) {
;     ...
;     P8_WAIT_V(6); P8_BAR; P8_MMA(1,1,At,B1); P8_BAR;
;     P8_LDB(B0,1,0); P8_SCHED; P8_LDA(At,1,0); P8_STAGE(P8_SA(0,1),A,brow+128,t+2);
;     P8_WAIT_L(8); P8_BAR; P8_WAIT_L(0); P8_MMA(0,0,At,B0); P8_BAR; P8_SCHED;
;     P8_LDB(B1,1,1); P8_STAGE(P8_SB(1,0),Bt,bcol,t+3);
;     P8_BAR; P8_WAIT_L(0); P8_MMA(0,1,At,B1); P8_BAR;
;     P8_LDA(At,1,1); P8_STAGE(P8_SA(1,0),A,brow,t+3);
;     P8_BAR; P8_WAIT_L(0); P8_MMA(1,0,At,B0); P8_BAR; P8_SCHED;
	v_mfma_f32_16x16x32_bf16 v[28:31], v[190:193], v[228:231], v[28:31]
	v_mfma_f32_16x16x32_bf16 v[24:27], v[190:193], v[236:239], v[24:27]
	v_mfma_f32_16x16x32_bf16 v[20:23], v[208:211], v[228:231], v[20:23]
	v_mfma_f32_16x16x32_bf16 v[16:19], v[208:211], v[236:239], v[16:19]
	v_mfma_f32_16x16x32_bf16 v[12:15], v[216:219], v[228:231], v[12:15]
	v_mfma_f32_16x16x32_bf16 v[8:11], v[216:219], v[236:239], v[8:11]
	v_mfma_f32_16x16x32_bf16 v[4:7], v[224:227], v[228:231], v[4:7]
	v_mfma_f32_16x16x32_bf16 v[0:3], v[224:227], v[236:239], v[0:3]
	v_mfma_f32_16x16x32_bf16 v[28:31], v[196:199], v[232:235], v[28:31]
	v_mfma_f32_16x16x32_bf16 v[24:27], v[196:199], v[240:243], v[24:27]
	v_mfma_f32_16x16x32_bf16 v[20:23], v[212:215], v[232:235], v[20:23]
	v_mfma_f32_16x16x32_bf16 v[16:19], v[212:215], v[240:243], v[16:19]
	v_mfma_f32_16x16x32_bf16 v[12:15], v[220:223], v[232:235], v[12:15]
	v_mfma_f32_16x16x32_bf16 v[8:11], v[220:223], v[240:243], v[8:11]
	v_mfma_f32_16x16x32_bf16 v[4:7], v[244:247], v[232:235], v[4:7]
	v_mfma_f32_16x16x32_bf16 v[0:3], v[244:247], v[240:243], v[0:3]
	s_barrier
	ds_read_b128 v[174:177], v149
	ds_read_b128 v[178:181], v149 offset:1024
	ds_read_b128 v[182:185], v149 offset:2048
	ds_read_b128 v[186:189], v149 offset:3072
	v_add_u32_e32 v163, 0x4000, v143
	v_add_u32_e32 v170, 0x6000, v143
	v_add_u32_e32 v232, s68, v136
	s_add_i32 m0, s100, 0x4000
	ds_read_b128 v[190:193], v147 offset:32768
	ds_read_b128 v[196:199], v147 offset:33792
	ds_read_b128 v[208:211], v146 offset:32768
	ds_read_b128 v[212:215], v146 offset:33792
	ds_read_b128 v[216:219], v145 offset:32768
	ds_read_b128 v[220:223], v145 offset:33792
	ds_read_b128 v[224:227], v144 offset:32768
	ds_read_b128 v[228:231], v144 offset:33792
	global_load_lds_dwordx4 v232, s[86:87]
	v_add_u32_e32 v232, s68, v134
	s_add_i32 m0, s100, 0x6000
	s_nop 0
	global_load_lds_dwordx4 v232, s[86:87]
	s_waitcnt lgkmcnt(8)
	s_barrier
	s_waitcnt lgkmcnt(0)
	v_mfma_f32_16x16x32_bf16 v[124:127], v[190:193], v[174:177], v[124:127]
	v_mfma_f32_16x16x32_bf16 v[120:123], v[190:193], v[182:185], v[120:123]
	v_mfma_f32_16x16x32_bf16 v[116:119], v[208:211], v[174:177], v[116:119]
	v_mfma_f32_16x16x32_bf16 v[112:115], v[208:211], v[182:185], v[112:115]
	v_mfma_f32_16x16x32_bf16 v[108:111], v[216:219], v[174:177], v[108:111]
	v_mfma_f32_16x16x32_bf16 v[104:107], v[216:219], v[182:185], v[104:107]
	v_mfma_f32_16x16x32_bf16 v[100:103], v[224:227], v[174:177], v[100:103]
	v_mfma_f32_16x16x32_bf16 v[96:99], v[224:227], v[182:185], v[96:99]
	v_mfma_f32_16x16x32_bf16 v[124:127], v[196:199], v[178:181], v[124:127]
	v_mfma_f32_16x16x32_bf16 v[120:123], v[196:199], v[186:189], v[120:123]
	v_mfma_f32_16x16x32_bf16 v[116:119], v[212:215], v[178:181], v[116:119]
	v_mfma_f32_16x16x32_bf16 v[112:115], v[212:215], v[186:189], v[112:115]
	v_mfma_f32_16x16x32_bf16 v[108:111], v[220:223], v[178:181], v[108:111]
	v_mfma_f32_16x16x32_bf16 v[104:107], v[220:223], v[186:189], v[104:107]
	v_mfma_f32_16x16x32_bf16 v[100:103], v[228:231], v[178:181], v[100:103]
	v_mfma_f32_16x16x32_bf16 v[96:99], v[228:231], v[186:189], v[96:99]
	s_barrier
	v_add_u32_e32 v248, s74, v140
	s_add_i32 m0, s100, 0x18000
	ds_read_b128 v[232:235], v148
	ds_read_b128 v[236:239], v148 offset:1024
	ds_read_b128 v[240:243], v148 offset:2048
	ds_read_b128 v[244:247], v148 offset:3072
	global_load_lds_dwordx4 v248, s[86:87]
	v_add_u32_e32 v248, s74, v138
	s_add_i32 m0, s100, 0x1a000
	s_nop 0
	global_load_lds_dwordx4 v248, s[86:87]
	s_barrier
	s_waitcnt lgkmcnt(0)
	v_mfma_f32_16x16x32_bf16 v[92:95], v[190:193], v[232:235], v[92:95]
	v_mfma_f32_16x16x32_bf16 v[88:91], v[190:193], v[240:243], v[88:91]
	v_mfma_f32_16x16x32_bf16 v[84:87], v[208:211], v[232:235], v[84:87]
	v_mfma_f32_16x16x32_bf16 v[80:83], v[208:211], v[240:243], v[80:83]
	v_mfma_f32_16x16x32_bf16 v[76:79], v[216:219], v[232:235], v[76:79]
	v_mfma_f32_16x16x32_bf16 v[72:75], v[216:219], v[240:243], v[72:75]
	v_mfma_f32_16x16x32_bf16 v[68:71], v[224:227], v[232:235], v[68:71]
	v_mfma_f32_16x16x32_bf16 v[64:67], v[224:227], v[240:243], v[64:67]
	v_mfma_f32_16x16x32_bf16 v[92:95], v[196:199], v[236:239], v[92:95]
	v_mfma_f32_16x16x32_bf16 v[88:91], v[196:199], v[244:247], v[88:91]
	v_mfma_f32_16x16x32_bf16 v[84:87], v[212:215], v[236:239], v[84:87]
	v_mfma_f32_16x16x32_bf16 v[80:83], v[212:215], v[244:247], v[80:83]
	v_mfma_f32_16x16x32_bf16 v[76:79], v[220:223], v[236:239], v[76:79]
	v_mfma_f32_16x16x32_bf16 v[72:75], v[220:223], v[244:247], v[72:75]
	v_mfma_f32_16x16x32_bf16 v[68:71], v[228:231], v[236:239], v[68:71]
	v_mfma_f32_16x16x32_bf16 v[64:67], v[228:231], v[244:247], v[64:67]
	v_add_u32_e32 v200, s72, v136
	s_add_i32 m0, s100, 0x8000
	s_barrier
	ds_read_b128 v[190:193], v147 offset:49152
	ds_read_b128 v[196:199], v147 offset:50176
	ds_read_b128 v[208:211], v146 offset:49152
	ds_read_b128 v[212:215], v146 offset:50176
	ds_read_b128 v[216:219], v145 offset:49152
	ds_read_b128 v[220:223], v145 offset:50176
	ds_read_b128 v[224:227], v144 offset:49152
	ds_read_b128 v[228:231], v144 offset:50176
	global_load_lds_dwordx4 v200, s[86:87]
	v_add_u32_e32 v200, s72, v134
	s_add_i32 m0, s100, 0xa000
	s_nop 0
	global_load_lds_dwordx4 v200, s[86:87]
	s_barrier
; #define P8_STAGE(P,BASE,br,kt) do{const bfr* _ub=(BASE)+((long)(br)*K+(long)(kt)*BK); \
;     __builtin_amdgcn_global_load_lds((const unsigned*)(_ub+so0),(unsigned*)((char*)(P)+wid*1024),16,0,0); \
;     __builtin_amdgcn_global_load_lds((const unsigned*)(_ub+so1),(unsigned*)((char*)(P)+wid*1024+8192),16,0,0);}while(0)
; #define P8_LDA(dst,b,h) _Pragma("unroll") for(int m=0;m<4;++m) _Pragma("unroll") for(int k=0;k<2;++k) \
;     dst[m][k]=*reinterpret_cast<const bf16x8*>((char*)P8_SA(b,h)+lds_byte(wr*64+m*16+fr,k*32+fq*8))
; #define P8_LDB(dst,b,h) _Pragma("unroll") for(int n=0;n<2;++n) _Pragma("unroll") for(int k=0;k<2;++k) \
;     dst[n][k]=*reinterpret_cast<const bf16x8*>((char*)P8_SB(b,h)+lds_byte(wc*32+n*16+fr,k*32+fq*8))
; #define P8_MMA(ai,bj,At,Bt) do{__builtin_amdgcn_s_setprio(1); \
;     _Pragma("unroll") for(int m=0;m<4;++m) _Pragma("unroll") for(int n=0;n<2;++n) _Pragma("unroll") for(int k=0;k<2;++k) \
;       acc[ai][bj][m][n]=__builtin_amdgcn_mfma_f32_16x16x32_bf16(At[m][k],Bt[n][k],acc[ai][bj][m][n],0,0,0); \
;     __builtin_amdgcn_s_setprio(0);}while(0)
; #define P8_WAIT_V(n) asm volatile("s_waitcnt vmcnt(" #n ")":::"memory")
; #define P8_WAIT_L(n) asm volatile("s_waitcnt lgkmcnt(" #n ")":::"memory")
; #define P8_BAR __builtin_amdgcn_s_barrier()
; #define P8_SCHED __builtin_amdgcn_sched_barrier(0)
; template <class EPI>
; DEVI void gemm8_tile(const bfr* __restrict__ A, const bfr* __restrict__ Bt, int K, int brow, int bcol, int nbrow, int nbcol, char* shmc, EPI epi) {
;     ...
;     P8_LDA(At,1,1); P8_STAGE(P8_SA(1,0),A,brow,t+3);
;     P8_BAR; P8_WAIT_L(0); P8_MMA(1,0,At,B0); P8_BAR; P8_SCHED;
;     P8_STAGE(P8_SB(1,1),Bt,bcol+128,t+3);
;     P8_WAIT_V(6); P8_BAR; P8_MMA(1,1,At,B1); P8_BAR;
;   }
;   { P8_LDB(B0,0,0); P8_LDA(At,0,0); P8_STAGE(P8_SA(1,1),A,brow+128,nt-1);
;     P8_BAR; P8_WAIT_L(0); P8_MMA(0,0,At,B0); P8_BAR;
;     P8_LDB(B1,0,1); P8_BAR; P8_WAIT_L(0); P8_MMA(0,1,At,B1); P8_BAR;
	s_waitcnt lgkmcnt(0)
	v_mfma_f32_16x16x32_bf16 v[60:63], v[190:193], v[174:177], v[60:63]
	v_mfma_f32_16x16x32_bf16 v[56:59], v[190:193], v[182:185], v[56:59]
	v_mfma_f32_16x16x32_bf16 v[52:55], v[208:211], v[174:177], v[52:55]
	v_mfma_f32_16x16x32_bf16 v[48:51], v[208:211], v[182:185], v[48:51]
	v_mfma_f32_16x16x32_bf16 v[44:47], v[216:219], v[174:177], v[44:47]
	v_mfma_f32_16x16x32_bf16 v[40:43], v[216:219], v[182:185], v[40:43]
	v_mfma_f32_16x16x32_bf16 v[36:39], v[224:227], v[174:177], v[36:39]
	v_mfma_f32_16x16x32_bf16 v[32:35], v[224:227], v[182:185], v[32:35]
	v_mfma_f32_16x16x32_bf16 v[60:63], v[196:199], v[178:181], v[60:63]
	v_mfma_f32_16x16x32_bf16 v[56:59], v[196:199], v[186:189], v[56:59]
	v_mfma_f32_16x16x32_bf16 v[52:55], v[212:215], v[178:181], v[52:55]
	v_mfma_f32_16x16x32_bf16 v[48:51], v[212:215], v[186:189], v[48:51]
	v_mfma_f32_16x16x32_bf16 v[44:47], v[220:223], v[178:181], v[44:47]
	v_mfma_f32_16x16x32_bf16 v[40:43], v[220:223], v[186:189], v[40:43]
	v_mfma_f32_16x16x32_bf16 v[36:39], v[228:231], v[178:181], v[36:39]
	v_mfma_f32_16x16x32_bf16 v[32:35], v[228:231], v[186:189], v[32:35]
	s_barrier
	v_add_u32_e32 v174, s78, v140
	s_add_i32 m0, s100, 0x1c000
	s_nop 0
	global_load_lds_dwordx4 v174, s[86:87]
	v_add_u32_e32 v174, s78, v138
	s_add_i32 m0, s100, 0x1e000
	s_nop 0
	global_load_lds_dwordx4 v174, s[86:87]
	s_waitcnt vmcnt(6)
	s_barrier
	v_mfma_f32_16x16x32_bf16 v[28:31], v[190:193], v[232:235], v[28:31]
	v_mfma_f32_16x16x32_bf16 v[24:27], v[190:193], v[240:243], v[24:27]
	v_mfma_f32_16x16x32_bf16 v[20:23], v[208:211], v[232:235], v[20:23]
	v_mfma_f32_16x16x32_bf16 v[16:19], v[208:211], v[240:243], v[16:19]
	v_mfma_f32_16x16x32_bf16 v[12:15], v[216:219], v[232:235], v[12:15]
	v_mfma_f32_16x16x32_bf16 v[8:11], v[216:219], v[240:243], v[8:11]
	v_mfma_f32_16x16x32_bf16 v[4:7], v[224:227], v[232:235], v[4:7]
	v_mfma_f32_16x16x32_bf16 v[0:3], v[224:227], v[240:243], v[0:3]
	v_mfma_f32_16x16x32_bf16 v[28:31], v[196:199], v[236:239], v[28:31]
	v_mfma_f32_16x16x32_bf16 v[24:27], v[196:199], v[244:247], v[24:27]
	v_mfma_f32_16x16x32_bf16 v[20:23], v[212:215], v[236:239], v[20:23]
	v_mfma_f32_16x16x32_bf16 v[16:19], v[212:215], v[244:247], v[16:19]
	v_mfma_f32_16x16x32_bf16 v[12:15], v[220:223], v[236:239], v[12:15]
	v_mfma_f32_16x16x32_bf16 v[8:11], v[220:223], v[244:247], v[8:11]
	v_mfma_f32_16x16x32_bf16 v[4:7], v[228:231], v[236:239], v[4:7]
	v_mfma_f32_16x16x32_bf16 v[0:3], v[228:231], v[244:247], v[0:3]
	s_add_i32 s0, s0, 2
	v_lshl_add_u64 v[134:135], v[134:135], 0, s[80:81]
	v_lshl_add_u64 v[136:137], v[136:137], 0, s[80:81]
	v_lshl_add_u64 v[138:139], v[138:139], 0, s[80:81]
	s_cmp_lt_u32 s0, 28
	v_lshl_add_u64 v[140:141], v[140:141], 0, s[80:81]
	s_barrier
	s_cbranch_scc1 .LBB0_401
	s_or_b32 s0, s34, 0x80
	s_ashr_i32 s1, s0, 31
	s_lshl_b64 s[0:1], s[0:1], 12
	s_add_u32 s0, s31, s0
	s_addc_u32 s1, s64, s1
	ds_read_b128 v[134:137], v157
	ds_read_b128 v[138:141], v157 offset:1024
	ds_read_b128 v[150:153], v157 offset:2048
	ds_read_b128 v[174:177], v157 offset:3072
	ds_read_b128 v[178:181], v147
	ds_read_b128 v[182:185], v147 offset:1024
	ds_read_b128 v[186:189], v146
	ds_read_b128 v[190:193], v146 offset:1024
	ds_read_b128 v[196:199], v145
	ds_read_b128 v[208:211], v145 offset:1024
	ds_read_b128 v[212:215], v144
	ds_read_b128 v[216:219], v144 offset:1024
	v_lshl_add_u64 v[156:157], v[166:167], 1, s[0:1]
	s_mov_b64 s[54:55], 0xf80
	v_lshl_add_u64 v[156:157], v[156:157], 0, s[54:55]
	s_add_i32 m0, s100, 0xc000
	v_lshl_add_u64 v[132:133], v[132:133], 1, s[0:1]
	global_load_lds_dwordx4 v[156:157], off
	v_lshl_add_u64 v[132:133], v[132:133], 0, s[54:55]
	s_add_i32 m0, s100, 0xe000
	s_nop 0
	global_load_lds_dwordx4 v[132:133], off
	s_barrier
	s_waitcnt lgkmcnt(0)
	s_setprio 1
	s_waitcnt lgkmcnt(0)
	v_mfma_f32_16x16x32_bf16 v[124:127], v[178:181], v[134:137], v[124:127]
	v_mfma_f32_16x16x32_bf16 v[116:119], v[186:189], v[134:137], v[116:119]
	v_mfma_f32_16x16x32_bf16 v[112:115], v[186:189], v[150:153], v[112:115]
	v_mfma_f32_16x16x32_bf16 v[100:103], v[212:215], v[134:137], v[100:103]
	v_mfma_f32_16x16x32_bf16 v[124:127], v[182:185], v[138:141], v[124:127]
	v_mfma_f32_16x16x32_bf16 v[120:123], v[178:181], v[150:153], v[120:123]
	v_mfma_f32_16x16x32_bf16 v[116:119], v[190:193], v[138:141], v[116:119]
	v_mfma_f32_16x16x32_bf16 v[112:115], v[190:193], v[174:177], v[112:115]
	v_mfma_f32_16x16x32_bf16 v[108:111], v[196:199], v[134:137], v[108:111]
	v_mfma_f32_16x16x32_bf16 v[104:107], v[196:199], v[150:153], v[104:107]
	v_mfma_f32_16x16x32_bf16 v[100:103], v[216:219], v[138:141], v[100:103]
	v_mfma_f32_16x16x32_bf16 v[96:99], v[212:215], v[150:153], v[96:99]
	v_mfma_f32_16x16x32_bf16 v[220:223], v[182:185], v[174:177], v[120:123]
	v_mfma_f32_16x16x32_bf16 v[224:227], v[208:211], v[138:141], v[108:111]
	v_mfma_f32_16x16x32_bf16 v[228:231], v[208:211], v[174:177], v[104:107]
	v_mfma_f32_16x16x32_bf16 v[232:235], v[216:219], v[174:177], v[96:99]
	s_setprio 0
	s_barrier
	s_nop 1
	ds_read_b128 v[96:99], v155
	ds_read_b128 v[104:107], v155 offset:1024
	ds_read_b128 v[108:111], v155 offset:2048
	ds_read_b128 v[120:123], v155 offset:3072
	s_barrier
; #define P8_LDA(dst,b,h) _Pragma("unroll") for(int m=0;m<4;++m) _Pragma("unroll") for(int k=0;k<2;++k) \
;     dst[m][k]=*reinterpret_cast<const bf16x8*>((char*)P8_SA(b,h)+lds_byte(wr*64+m*16+fr,k*32+fq*8))
; #define P8_LDB(dst,b,h) _Pragma("unroll") for(int n=0;n<2;++n) _Pragma("unroll") for(int k=0;k<2;++k) \
;     dst[n][k]=*reinterpret_cast<const bf16x8*>((char*)P8_SB(b,h)+lds_byte(wc*32+n*16+fr,k*32+fq*8))
; #define P8_MMA(ai,bj,At,Bt) do{__builtin_amdgcn_s_setprio(1); \
;     _Pragma("unroll") for(int m=0;m<4;++m) _Pragma("unroll") for(int n=0;n<2;++n) _Pragma("unroll") for(int k=0;k<2;++k) \
;       acc[ai][bj][m][n]=__builtin_amdgcn_mfma_f32_16x16x32_bf16(At[m][k],Bt[n][k],acc[ai][bj][m][n],0,0,0); \
;     __builtin_amdgcn_s_setprio(0);}while(0)
; #define P8_WAIT_V(n) asm volatile("s_waitcnt vmcnt(" #n ")":::"memory")
; #define P8_WAIT_L(n) asm volatile("s_waitcnt lgkmcnt(" #n ")":::"memory")
; #define P8_BAR __builtin_amdgcn_s_barrier()
; template <class EPI>
; DEVI void gemm8_tile(const bfr* __restrict__ A, const bfr* __restrict__ Bt, int K, int brow, int bcol, int nbrow, int nbcol, char* shmc, EPI epi) {
;     ...
;     P8_LDB(B1,0,1); P8_BAR; P8_WAIT_L(0); P8_MMA(0,1,At,B1); P8_BAR;
;     P8_LDA(At,0,1); P8_WAIT_V(4); P8_BAR; P8_WAIT_L(0); P8_MMA(1,0,At,B0); P8_MMA(1,1,At,B1); P8_BAR; }
;   { P8_LDB(B0,1,0); P8_LDA(At,1,0); P8_WAIT_V(2); P8_BAR; P8_WAIT_L(0); P8_MMA(0,0,At,B0); P8_BAR;
	s_waitcnt lgkmcnt(0)
	s_setprio 1
	s_waitcnt lgkmcnt(0)
	v_mfma_f32_16x16x32_bf16 v[92:95], v[178:181], v[96:99], v[92:95]
	v_mfma_f32_16x16x32_bf16 v[84:87], v[186:189], v[96:99], v[84:87]
	v_mfma_f32_16x16x32_bf16 v[80:83], v[186:189], v[108:111], v[80:83]
	v_mfma_f32_16x16x32_bf16 v[68:71], v[212:215], v[96:99], v[68:71]
	v_mfma_f32_16x16x32_bf16 v[92:95], v[182:185], v[104:107], v[92:95]
	v_mfma_f32_16x16x32_bf16 v[88:91], v[178:181], v[108:111], v[88:91]
	v_mfma_f32_16x16x32_bf16 v[84:87], v[190:193], v[104:107], v[84:87]
	v_mfma_f32_16x16x32_bf16 v[80:83], v[190:193], v[120:123], v[80:83]
	v_mfma_f32_16x16x32_bf16 v[76:79], v[196:199], v[96:99], v[76:79]
	v_mfma_f32_16x16x32_bf16 v[72:75], v[196:199], v[108:111], v[72:75]
	v_mfma_f32_16x16x32_bf16 v[68:71], v[216:219], v[104:107], v[68:71]
	v_mfma_f32_16x16x32_bf16 v[64:67], v[212:215], v[108:111], v[64:67]
	v_mfma_f32_16x16x32_bf16 v[154:157], v[182:185], v[120:123], v[88:91]
	v_mfma_f32_16x16x32_bf16 v[178:181], v[208:211], v[104:107], v[76:79]
	v_mfma_f32_16x16x32_bf16 v[182:185], v[208:211], v[120:123], v[72:75]
	v_mfma_f32_16x16x32_bf16 v[186:189], v[216:219], v[120:123], v[64:67]
	s_setprio 0
	s_barrier
	s_nop 1
	ds_read_b128 v[64:67], v147 offset:16384
	ds_read_b128 v[72:75], v147 offset:17408
	ds_read_b128 v[76:79], v146 offset:16384
	ds_read_b128 v[88:91], v146 offset:17408
	ds_read_b128 v[190:193], v145 offset:16384
	ds_read_b128 v[196:199], v145 offset:17408
	ds_read_b128 v[208:211], v144 offset:16384
	ds_read_b128 v[212:215], v144 offset:17408
	s_waitcnt vmcnt(4)
	s_barrier
	s_waitcnt lgkmcnt(0)
	s_setprio 1
	s_waitcnt lgkmcnt(0)
	v_mfma_f32_16x16x32_bf16 v[60:63], v[64:67], v[134:137], v[60:63]
	v_mfma_f32_16x16x32_bf16 v[52:55], v[76:79], v[134:137], v[52:55]
	v_mfma_f32_16x16x32_bf16 v[48:51], v[76:79], v[150:153], v[48:51]
	v_mfma_f32_16x16x32_bf16 v[36:39], v[208:211], v[134:137], v[36:39]
	v_mfma_f32_16x16x32_bf16 v[60:63], v[72:75], v[138:141], v[60:63]
	v_mfma_f32_16x16x32_bf16 v[56:59], v[64:67], v[150:153], v[56:59]
	v_mfma_f32_16x16x32_bf16 v[52:55], v[88:91], v[138:141], v[52:55]
	v_mfma_f32_16x16x32_bf16 v[48:51], v[88:91], v[174:177], v[48:51]
	v_mfma_f32_16x16x32_bf16 v[44:47], v[190:193], v[134:137], v[44:47]
	v_mfma_f32_16x16x32_bf16 v[40:43], v[190:193], v[150:153], v[40:43]
	v_mfma_f32_16x16x32_bf16 v[36:39], v[212:215], v[138:141], v[36:39]
	v_mfma_f32_16x16x32_bf16 v[32:35], v[208:211], v[150:153], v[32:35]
	v_mfma_f32_16x16x32_bf16 v[216:219], v[72:75], v[174:177], v[56:59]
	v_mfma_f32_16x16x32_bf16 v[236:239], v[196:199], v[138:141], v[44:47]
	v_mfma_f32_16x16x32_bf16 v[240:243], v[196:199], v[174:177], v[40:43]
	v_mfma_f32_16x16x32_bf16 v[132:135], v[212:215], v[174:177], v[32:35]
	s_setprio 0
	s_setprio 1
	v_mfma_f32_16x16x32_bf16 v[28:31], v[64:67], v[96:99], v[28:31]
	v_mfma_f32_16x16x32_bf16 v[20:23], v[76:79], v[96:99], v[20:23]
	v_mfma_f32_16x16x32_bf16 v[16:19], v[76:79], v[108:111], v[16:19]
	v_mfma_f32_16x16x32_bf16 v[4:7], v[208:211], v[96:99], v[4:7]
	v_mfma_f32_16x16x32_bf16 v[28:31], v[72:75], v[104:107], v[28:31]
	v_mfma_f32_16x16x32_bf16 v[24:27], v[64:67], v[108:111], v[24:27]
	v_mfma_f32_16x16x32_bf16 v[20:23], v[88:91], v[104:107], v[20:23]
	v_mfma_f32_16x16x32_bf16 v[16:19], v[88:91], v[120:123], v[16:19]
	v_mfma_f32_16x16x32_bf16 v[12:15], v[190:193], v[96:99], v[12:15]
	v_mfma_f32_16x16x32_bf16 v[8:11], v[190:193], v[108:111], v[8:11]
	v_mfma_f32_16x16x32_bf16 v[4:7], v[212:215], v[104:107], v[4:7]
	v_mfma_f32_16x16x32_bf16 v[0:3], v[208:211], v[108:111], v[0:3]
	v_mfma_f32_16x16x32_bf16 v[136:139], v[72:75], v[120:123], v[24:27]
	v_mfma_f32_16x16x32_bf16 v[150:153], v[196:199], v[104:107], v[12:15]
	v_mfma_f32_16x16x32_bf16 v[172:175], v[196:199], v[120:123], v[8:11]
	v_mfma_f32_16x16x32_bf16 v[190:193], v[212:215], v[120:123], v[0:3]
	s_setprio 0
	s_barrier
	s_nop 1
	ds_read_b128 v[0:3], v149
	ds_read_b128 v[8:11], v149 offset:1024
	ds_read_b128 v[12:15], v149 offset:2048
	ds_read_b128 v[24:27], v149 offset:3072
	ds_read_b128 v[32:35], v147 offset:32768
	ds_read_b128 v[40:43], v147 offset:33792
	ds_read_b128 v[44:47], v146 offset:32768
	ds_read_b128 v[56:59], v146 offset:33792
	ds_read_b128 v[64:67], v145 offset:32768
	ds_read_b128 v[196:199], v145 offset:33792
	ds_read_b128 v[208:211], v144 offset:32768
	ds_read_b128 v[212:215], v144 offset:33792
	s_waitcnt vmcnt(2)
	s_barrier
; #define P8_LDA(dst,b,h) _Pragma("unroll") for(int m=0;m<4;++m) _Pragma("unroll") for(int k=0;k<2;++k) \
;     dst[m][k]=*reinterpret_cast<const bf16x8*>((char*)P8_SA(b,h)+lds_byte(wr*64+m*16+fr,k*32+fq*8))
; #define P8_LDB(dst,b,h) _Pragma("unroll") for(int n=0;n<2;++n) _Pragma("unroll") for(int k=0;k<2;++k) \
;     dst[n][k]=*reinterpret_cast<const bf16x8*>((char*)P8_SB(b,h)+lds_byte(wc*32+n*16+fr,k*32+fq*8))
; #define P8_MMA(ai,bj,At,Bt) do{__builtin_amdgcn_s_setprio(1); \
;     _Pragma("unroll") for(int m=0;m<4;++m) _Pragma("unroll") for(int n=0;n<2;++n) _Pragma("unroll") for(int k=0;k<2;++k) \
;       acc[ai][bj][m][n]=__builtin_amdgcn_mfma_f32_16x16x32_bf16(At[m][k],Bt[n][k],acc[ai][bj][m][n],0,0,0); \
;     __builtin_amdgcn_s_setprio(0);}while(0)
; #define P8_WAIT_V(n) asm volatile("s_waitcnt vmcnt(" #n ")":::"memory")
; #define P8_WAIT_L(n) asm volatile("s_waitcnt lgkmcnt(" #n ")":::"memory")
; #define P8_BAR __builtin_amdgcn_s_barrier()
; template <class EPI>
; DEVI void gemm8_tile(const bfr* __restrict__ A, const bfr* __restrict__ Bt, int K, int brow, int bcol, int nbrow, int nbcol, char* shmc, EPI epi) {
;     ...
;   { P8_LDB(B0,1,0); P8_LDA(At,1,0); P8_WAIT_V(2); P8_BAR; P8_WAIT_L(0); P8_MMA(0,0,At,B0); P8_BAR;
;     P8_LDB(B1,1,1); P8_WAIT_V(0); P8_BAR; P8_WAIT_L(0); P8_MMA(0,1,At,B1); P8_BAR;
;     P8_LDA(At,1,1); P8_BAR; P8_WAIT_L(0); P8_MMA(1,0,At,B0); P8_MMA(1,1,At,B1); P8_BAR; }
;   if(wr==0)P8_BAR;
	s_waitcnt lgkmcnt(0)
	s_setprio 1
	s_waitcnt lgkmcnt(0)
	v_mfma_f32_16x16x32_bf16 v[72:75], v[32:35], v[0:3], v[124:127]
	v_mfma_f32_16x16x32_bf16 v[120:123], v[40:43], v[8:11], v[72:75]
	v_mfma_f32_16x16x32_bf16 v[72:75], v[32:35], v[12:15], v[220:223]
	v_mfma_f32_16x16x32_bf16 v[104:107], v[40:43], v[24:27], v[72:75]
	v_mfma_f32_16x16x32_bf16 v[72:75], v[44:47], v[0:3], v[116:119]
	v_mfma_f32_16x16x32_bf16 v[124:127], v[56:59], v[8:11], v[72:75]
	v_mfma_f32_16x16x32_bf16 v[72:75], v[44:47], v[12:15], v[112:115]
	v_mfma_f32_16x16x32_bf16 v[108:111], v[56:59], v[24:27], v[72:75]
	v_mfma_f32_16x16x32_bf16 v[72:75], v[64:67], v[0:3], v[224:227]
	v_mfma_f32_16x16x32_bf16 v[112:115], v[196:199], v[8:11], v[72:75]
	v_mfma_f32_16x16x32_bf16 v[72:75], v[64:67], v[12:15], v[228:231]
	v_mfma_f32_16x16x32_bf16 v[96:99], v[196:199], v[24:27], v[72:75]
	v_mfma_f32_16x16x32_bf16 v[72:75], v[208:211], v[0:3], v[100:103]
	v_mfma_f32_16x16x32_bf16 v[116:119], v[212:215], v[8:11], v[72:75]
	v_mfma_f32_16x16x32_bf16 v[72:75], v[208:211], v[12:15], v[232:235]
	v_mfma_f32_16x16x32_bf16 v[100:103], v[212:215], v[24:27], v[72:75]
	s_setprio 0
	s_barrier
	ds_read_b128 v[220:223], v148
	ds_read_b128 v[224:227], v148 offset:1024
	ds_read_b128 v[228:231], v148 offset:2048
	ds_read_b128 v[232:235], v148 offset:3072
	s_waitcnt vmcnt(0)
	s_barrier
	s_waitcnt lgkmcnt(0)
	s_setprio 1
	s_waitcnt lgkmcnt(0)
	v_mfma_f32_16x16x32_bf16 v[72:75], v[32:35], v[220:223], v[92:95]
	v_mfma_f32_16x16x32_bf16 v[32:35], v[32:35], v[228:231], v[154:157]
	v_mfma_f32_16x16x32_bf16 v[88:91], v[40:43], v[224:227], v[72:75]
	v_mfma_f32_16x16x32_bf16 v[72:75], v[40:43], v[232:235], v[32:35]
	v_mfma_f32_16x16x32_bf16 v[32:35], v[44:47], v[220:223], v[84:87]
	v_mfma_f32_16x16x32_bf16 v[92:95], v[56:59], v[224:227], v[32:35]
	v_mfma_f32_16x16x32_bf16 v[32:35], v[44:47], v[228:231], v[80:83]
	v_mfma_f32_16x16x32_bf16 v[76:79], v[56:59], v[232:235], v[32:35]
	v_mfma_f32_16x16x32_bf16 v[32:35], v[64:67], v[220:223], v[178:181]
	v_mfma_f32_16x16x32_bf16 v[80:83], v[196:199], v[224:227], v[32:35]
	v_mfma_f32_16x16x32_bf16 v[32:35], v[64:67], v[228:231], v[182:185]
	v_mfma_f32_16x16x32_bf16 v[64:67], v[196:199], v[232:235], v[32:35]
	v_mfma_f32_16x16x32_bf16 v[32:35], v[208:211], v[220:223], v[68:71]
	v_mfma_f32_16x16x32_bf16 v[84:87], v[212:215], v[224:227], v[32:35]
	v_mfma_f32_16x16x32_bf16 v[32:35], v[208:211], v[228:231], v[186:189]
	v_mfma_f32_16x16x32_bf16 v[68:71], v[212:215], v[232:235], v[32:35]
	s_setprio 0
	s_barrier
	ds_read_b128 v[154:157], v147 offset:49152
	ds_read_b128 v[176:179], v147 offset:50176
	ds_read_b128 v[180:183], v146 offset:49152
	ds_read_b128 v[146:149], v146 offset:50176
	ds_read_b128 v[184:187], v145 offset:49152
	ds_read_b128 v[196:199], v145 offset:50176
	ds_read_b128 v[208:211], v144 offset:49152
	ds_read_b128 v[212:215], v144 offset:50176
	s_barrier
	s_waitcnt lgkmcnt(0)
	s_setprio 1
	s_waitcnt lgkmcnt(0)
	v_mfma_f32_16x16x32_bf16 v[32:35], v[154:157], v[0:3], v[60:63]
	v_mfma_f32_16x16x32_bf16 v[56:59], v[176:179], v[8:11], v[32:35]
	v_mfma_f32_16x16x32_bf16 v[32:35], v[154:157], v[12:15], v[216:219]
	v_mfma_f32_16x16x32_bf16 v[40:43], v[176:179], v[24:27], v[32:35]
	v_mfma_f32_16x16x32_bf16 v[32:35], v[180:183], v[0:3], v[52:55]
	v_mfma_f32_16x16x32_bf16 v[60:63], v[146:149], v[8:11], v[32:35]
	v_mfma_f32_16x16x32_bf16 v[32:35], v[180:183], v[12:15], v[48:51]
	v_mfma_f32_16x16x32_bf16 v[44:47], v[146:149], v[24:27], v[32:35]
	v_mfma_f32_16x16x32_bf16 v[32:35], v[184:187], v[0:3], v[236:239]
	v_mfma_f32_16x16x32_bf16 v[0:3], v[208:211], v[0:3], v[36:39]
	v_mfma_f32_16x16x32_bf16 v[48:51], v[196:199], v[8:11], v[32:35]
	v_mfma_f32_16x16x32_bf16 v[32:35], v[184:187], v[12:15], v[240:243]
	v_mfma_f32_16x16x32_bf16 v[52:55], v[212:215], v[8:11], v[0:3]
	v_mfma_f32_16x16x32_bf16 v[0:3], v[208:211], v[12:15], v[132:135]
	v_mfma_f32_16x16x32_bf16 v[32:35], v[196:199], v[24:27], v[32:35]
	v_mfma_f32_16x16x32_bf16 v[36:39], v[212:215], v[24:27], v[0:3]
	s_setprio 0
	s_setprio 1
	v_mfma_f32_16x16x32_bf16 v[0:3], v[154:157], v[220:223], v[28:31]
	v_mfma_f32_16x16x32_bf16 v[24:27], v[176:179], v[224:227], v[0:3]
	v_mfma_f32_16x16x32_bf16 v[0:3], v[154:157], v[228:231], v[136:139]
	v_mfma_f32_16x16x32_bf16 v[8:11], v[176:179], v[232:235], v[0:3]
	v_mfma_f32_16x16x32_bf16 v[0:3], v[180:183], v[220:223], v[20:23]
	v_mfma_f32_16x16x32_bf16 v[28:31], v[146:149], v[224:227], v[0:3]
	v_mfma_f32_16x16x32_bf16 v[0:3], v[180:183], v[228:231], v[16:19]
	v_mfma_f32_16x16x32_bf16 v[12:15], v[146:149], v[232:235], v[0:3]
	v_mfma_f32_16x16x32_bf16 v[0:3], v[184:187], v[220:223], v[150:153]
	v_mfma_f32_16x16x32_bf16 v[4:7], v[208:211], v[220:223], v[4:7]
	v_mfma_f32_16x16x32_bf16 v[16:19], v[196:199], v[224:227], v[0:3]
	v_mfma_f32_16x16x32_bf16 v[0:3], v[184:187], v[228:231], v[172:175]
	v_mfma_f32_16x16x32_bf16 v[20:23], v[212:215], v[224:227], v[4:7]
	v_mfma_f32_16x16x32_bf16 v[4:7], v[208:211], v[228:231], v[190:193]
	v_mfma_f32_16x16x32_bf16 v[0:3], v[196:199], v[232:235], v[0:3]
	v_mfma_f32_16x16x32_bf16 v[4:7], v[212:215], v[232:235], v[4:7]
	s_setprio 0
	v_cmp_gt_u32_e32 vcc, s57, v142
	s_barrier
	s_and_saveexec_b64 s[0:1], vcc
	s_cbranch_execz .LBB0_404
	s_barrier
